# counted lgkmcnt waits interleaved with MFMAs in all 15 GEMM K-loops (replaces lgkmcnt(0) drains before each MFMA block)
# speedup vs baseline: 1.0007x; 1.0007x over previous
; #define PG8_STAGE(bufoff, gbase, voff) do { _Pragma("unroll") for (int _i = 0; _i < 2; ++_i) \
;         __builtin_amdgcn_global_load_lds((const unsigned*)((const char*)(gbase) + (voff)[_i]), (LAS unsigned*)(lds + (bufoff) + ldsw + _i * 8192), 16, 0, 0); } while (0)
; #define PG8_LDA(dst, b, h) do { _Pragma("unroll") for (int m = 0; m < 4; ++m) _Pragma("unroll") for (int k = 0; k < 2; ++k) dst[m][k] = *(const LAS bf16x8*)(lds + PG8_SA(b, h) + aoff + m * 2048 + k * 1024); } while (0)
; #define PG8_LDB(dst, b, h) do { _Pragma("unroll") for (int n = 0; n < 2; ++n) _Pragma("unroll") for (int k = 0; k < 2; ++k) dst[n][k] = *(const LAS bf16x8*)(lds + PG8_SB(b, h) + boff + n * 2048 + k * 1024); } while (0)
; #define PG8_MMA(ai, bj, At, Bt) do { __builtin_amdgcn_s_setprio(1); _Pragma("unroll") for (int m = 0; m < 4; ++m) _Pragma("unroll") for (int n = 0; n < 2; ++n) _Pragma("unroll") for (int k = 0; k < 2; ++k) \
;         acc[ai][bj][m][n] = __builtin_amdgcn_mfma_f32_16x16x32_bf16(Bt[n][k], At[m][k], acc[ai][bj][m][n], 0, 0, 0); __builtin_amdgcn_s_setprio(0); } while (0)
; #define PG8_WAIT_L(n) asm volatile("s_waitcnt lgkmcnt(" #n ")" ::: "memory")
; #define PG8_BAR __builtin_amdgcn_s_barrier()
; #define PG8_SCHED __builtin_amdgcn_sched_barrier(0)
; template <class Map, class Epi>
; DI void gemm_phase(LAS unsigned char* lds, const Map& MP, const Epi& E, const int nM, const int nN, const int K, const int lda, const int ldb) {
;     ...
;             PG8_LDB(B0, 0, 0); PG8_SCHED; PG8_LDA(At, 0, 0); PG8_STAGE(PG8_SA(1, 1), a1 + hstepA, voffA);
;             PG8_WAIT_L(8); PG8_BAR; PG8_WAIT_L(0); PG8_MMA(0, 0, At, B0); PG8_BAR; PG8_SCHED;
;             PG8_LDB(B1, 0, 1); PG8_STAGE(PG8_SB(0, 0), b2, voffB);
;             PG8_BAR; PG8_WAIT_L(0); PG8_MMA(0, 1, At, B1); PG8_BAR;
;             PG8_LDA(At, 0, 1); PG8_STAGE(PG8_SA(0, 0), a2, voffA);
;             PG8_BAR; PG8_WAIT_L(0); PG8_MMA(1, 0, At, B0); PG8_BAR; PG8_SCHED;
.LBB1_229:
	ds_read_b128 v[72:75], v167
	ds_read_b128 v[76:79], v167 offset:1024
	ds_read_b128 v[80:83], v167 offset:2048
	ds_read_b128 v[84:87], v167 offset:3072
	s_add_u32 s26, s24, 0xfff80080
	s_addc_u32 s27, s25, -1
	s_cmp_eq_u32 s57, 4
	s_cselect_b32 s29, s17, s27
	s_cselect_b32 s28, s43, s26
	s_cselect_b32 s27, s53, s56
	s_cselect_b32 s26, s54, s55
	v_lshl_add_u64 v[194:195], s[24:25], 0, v[154:155]
	s_add_i32 m0, s2, 0xc000
	ds_read_b128 v[160:163], v168
	ds_read_b128 v[170:173], v168 offset:1024
	ds_read_b128 v[174:177], v168 offset:2048
	ds_read_b128 v[178:181], v168 offset:3072
	ds_read_b128 v[182:185], v168 offset:4096
	ds_read_b128 v[186:189], v168 offset:5120
	ds_read_b128 v[190:193], v168 offset:6144
	ds_read_b128 v[198:201], v168 offset:7168
	global_load_lds_dwordx4 v[194:195], off
	v_lshl_add_u64 v[194:195], s[24:25], 0, v[152:153]
	s_add_i32 m0, s2, 0xe000
	s_nop 0
	global_load_lds_dwordx4 v[194:195], off
	s_waitcnt lgkmcnt(8)
	s_barrier
	s_setprio 1
	s_waitcnt lgkmcnt(7)
	v_mfma_f32_16x16x32_bf16 v[140:143], v[72:75], v[160:163], v[140:143]
	v_mfma_f32_16x16x32_bf16 v[136:139], v[80:83], v[160:163], v[136:139]
	s_waitcnt lgkmcnt(5)
	v_mfma_f32_16x16x32_bf16 v[124:127], v[72:75], v[174:177], v[124:127]
	v_mfma_f32_16x16x32_bf16 v[120:123], v[80:83], v[174:177], v[120:123]
	s_waitcnt lgkmcnt(3)
	v_mfma_f32_16x16x32_bf16 v[108:111], v[72:75], v[182:185], v[108:111]
	v_mfma_f32_16x16x32_bf16 v[104:107], v[80:83], v[182:185], v[104:107]
	s_waitcnt lgkmcnt(1)
	v_mfma_f32_16x16x32_bf16 v[92:95], v[72:75], v[190:193], v[92:95]
	v_mfma_f32_16x16x32_bf16 v[88:91], v[80:83], v[190:193], v[88:91]
	v_mfma_f32_16x16x32_bf16 v[140:143], v[76:79], v[170:173], v[140:143]
	v_mfma_f32_16x16x32_bf16 v[136:139], v[84:87], v[170:173], v[136:139]
	v_mfma_f32_16x16x32_bf16 v[124:127], v[76:79], v[178:181], v[124:127]
	v_mfma_f32_16x16x32_bf16 v[120:123], v[84:87], v[178:181], v[120:123]
	v_mfma_f32_16x16x32_bf16 v[108:111], v[76:79], v[186:189], v[108:111]
	v_mfma_f32_16x16x32_bf16 v[104:107], v[84:87], v[186:189], v[104:107]
	s_waitcnt lgkmcnt(0)
	v_mfma_f32_16x16x32_bf16 v[92:95], v[76:79], v[198:201], v[92:95]
	v_mfma_f32_16x16x32_bf16 v[88:91], v[84:87], v[198:201], v[88:91]
	s_setprio 0
	s_barrier
	s_add_i32 s58, s48, s34
	v_lshl_add_u64 v[194:195], s[26:27], 0, v[148:149]
	s_mov_b32 m0, s58
	ds_read_b128 v[202:205], v169
	ds_read_b128 v[206:209], v169 offset:1024
	ds_read_b128 v[210:213], v169 offset:2048
	ds_read_b128 v[214:217], v169 offset:3072
	global_load_lds_dwordx4 v[194:195], off
	v_lshl_add_u64 v[218:219], s[26:27], 0, v[144:145]
	s_add_i32 m0, s58, 0x2000
	s_nop 0
	global_load_lds_dwordx4 v[218:219], off
	s_barrier
	s_setprio 1
	s_waitcnt lgkmcnt(3)
	v_mfma_f32_16x16x32_bf16 v[132:135], v[202:205], v[160:163], v[132:135]
	s_waitcnt lgkmcnt(1)
	v_mfma_f32_16x16x32_bf16 v[128:131], v[210:213], v[160:163], v[128:131]
	v_mfma_f32_16x16x32_bf16 v[116:119], v[202:205], v[174:177], v[116:119]
	v_mfma_f32_16x16x32_bf16 v[112:115], v[210:213], v[174:177], v[112:115]
	v_mfma_f32_16x16x32_bf16 v[100:103], v[202:205], v[182:185], v[100:103]
	v_mfma_f32_16x16x32_bf16 v[96:99], v[210:213], v[182:185], v[96:99]
	v_mfma_f32_16x16x32_bf16 v[68:71], v[202:205], v[190:193], v[68:71]
	v_mfma_f32_16x16x32_bf16 v[64:67], v[210:213], v[190:193], v[64:67]
	v_mfma_f32_16x16x32_bf16 v[132:135], v[206:209], v[170:173], v[132:135]
	s_waitcnt lgkmcnt(0)
	v_mfma_f32_16x16x32_bf16 v[128:131], v[214:217], v[170:173], v[128:131]
	v_mfma_f32_16x16x32_bf16 v[116:119], v[206:209], v[178:181], v[116:119]
	v_mfma_f32_16x16x32_bf16 v[112:115], v[214:217], v[178:181], v[112:115]
	v_mfma_f32_16x16x32_bf16 v[100:103], v[206:209], v[186:189], v[100:103]
	v_mfma_f32_16x16x32_bf16 v[96:99], v[214:217], v[186:189], v[96:99]
	v_mfma_f32_16x16x32_bf16 v[68:71], v[206:209], v[198:201], v[68:71]
	v_mfma_f32_16x16x32_bf16 v[64:67], v[214:217], v[198:201], v[64:67]
	s_setprio 0
	s_mov_b32 m0, s2
	v_lshl_add_u64 v[220:221], s[28:29], 0, v[150:151]
	s_barrier
	ds_read_b128 v[160:163], v168 offset:16384
	ds_read_b128 v[170:173], v168 offset:17408
	ds_read_b128 v[174:177], v168 offset:18432
	ds_read_b128 v[178:181], v168 offset:19456
	ds_read_b128 v[182:185], v168 offset:20480
	ds_read_b128 v[186:189], v168 offset:21504
	ds_read_b128 v[190:193], v168 offset:22528
	ds_read_b128 v[198:201], v168 offset:23552
	global_load_lds_dwordx4 v[220:221], off
	v_lshl_add_u64 v[222:223], s[28:29], 0, v[146:147]
	s_mov_b32 m0, s4
	s_nop 0
	global_load_lds_dwordx4 v[222:223], off
	s_barrier
	s_setprio 1
	s_waitcnt lgkmcnt(7)
	v_mfma_f32_16x16x32_bf16 v[60:63], v[72:75], v[160:163], v[60:63]
	v_mfma_f32_16x16x32_bf16 v[56:59], v[80:83], v[160:163], v[56:59]
	s_waitcnt lgkmcnt(5)
	v_mfma_f32_16x16x32_bf16 v[44:47], v[72:75], v[174:177], v[44:47]
	v_mfma_f32_16x16x32_bf16 v[40:43], v[80:83], v[174:177], v[40:43]
	s_waitcnt lgkmcnt(3)
	v_mfma_f32_16x16x32_bf16 v[28:31], v[72:75], v[182:185], v[28:31]
	v_mfma_f32_16x16x32_bf16 v[24:27], v[80:83], v[182:185], v[24:27]
	s_waitcnt lgkmcnt(1)
	v_mfma_f32_16x16x32_bf16 v[12:15], v[72:75], v[190:193], v[12:15]
	v_mfma_f32_16x16x32_bf16 v[8:11], v[80:83], v[190:193], v[8:11]
	v_mfma_f32_16x16x32_bf16 v[60:63], v[76:79], v[170:173], v[60:63]
	v_mfma_f32_16x16x32_bf16 v[56:59], v[84:87], v[170:173], v[56:59]
	v_mfma_f32_16x16x32_bf16 v[44:47], v[76:79], v[178:181], v[44:47]
	v_mfma_f32_16x16x32_bf16 v[40:43], v[84:87], v[178:181], v[40:43]
	v_mfma_f32_16x16x32_bf16 v[28:31], v[76:79], v[186:189], v[28:31]
	v_mfma_f32_16x16x32_bf16 v[24:27], v[84:87], v[186:189], v[24:27]
	s_waitcnt lgkmcnt(0)
	v_mfma_f32_16x16x32_bf16 v[12:15], v[76:79], v[198:201], v[12:15]
	v_mfma_f32_16x16x32_bf16 v[8:11], v[84:87], v[198:201], v[8:11]
	s_setprio 0
	s_barrier
; #define PG8_STAGE(bufoff, gbase, voff) do { _Pragma("unroll") for (int _i = 0; _i < 2; ++_i) \
;         __builtin_amdgcn_global_load_lds((const unsigned*)((const char*)(gbase) + (voff)[_i]), (LAS unsigned*)(lds + (bufoff) + ldsw + _i * 8192), 16, 0, 0); } while (0)
; #define PG8_LDA(dst, b, h) do { _Pragma("unroll") for (int m = 0; m < 4; ++m) _Pragma("unroll") for (int k = 0; k < 2; ++k) dst[m][k] = *(const LAS bf16x8*)(lds + PG8_SA(b, h) + aoff + m * 2048 + k * 1024); } while (0)
; #define PG8_LDB(dst, b, h) do { _Pragma("unroll") for (int n = 0; n < 2; ++n) _Pragma("unroll") for (int k = 0; k < 2; ++k) dst[n][k] = *(const LAS bf16x8*)(lds + PG8_SB(b, h) + boff + n * 2048 + k * 1024); } while (0)
; #define PG8_MMA(ai, bj, At, Bt) do { __builtin_amdgcn_s_setprio(1); _Pragma("unroll") for (int m = 0; m < 4; ++m) _Pragma("unroll") for (int n = 0; n < 2; ++n) _Pragma("unroll") for (int k = 0; k < 2; ++k) \
;         acc[ai][bj][m][n] = __builtin_amdgcn_mfma_f32_16x16x32_bf16(Bt[n][k], At[m][k], acc[ai][bj][m][n], 0, 0, 0); __builtin_amdgcn_s_setprio(0); } while (0)
; #define PG8_WAIT_V(n) asm volatile("s_waitcnt vmcnt(" #n ")" ::: "memory")
; #define PG8_WAIT_L(n) asm volatile("s_waitcnt lgkmcnt(" #n ")" ::: "memory")
; #define PG8_BAR __builtin_amdgcn_s_barrier()
; #define PG8_SCHED __builtin_amdgcn_sched_barrier(0)
; template <class Map, class Epi>
; DI void gemm_phase(LAS unsigned char* lds, const Map& MP, const Epi& E, const int nM, const int nN, const int K, const int lda, const int ldb) {
;     ...
;             PG8_STAGE(PG8_SB(0, 1), b2 + hstepB, voffB);
;             PG8_WAIT_V(6); PG8_BAR; PG8_MMA(1, 1, At, B1); PG8_BAR;
;             PG8_LDB(B0, 1, 0); PG8_SCHED; PG8_LDA(At, 1, 0); PG8_STAGE(PG8_SA(0, 1), a2 + hstepA, voffA);
;             PG8_WAIT_L(8); PG8_BAR; PG8_WAIT_L(0); PG8_MMA(0, 0, At, B0); PG8_BAR; PG8_SCHED;
;             PG8_LDB(B1, 1, 1); PG8_STAGE(PG8_SB(1, 0), b3, voffB);
	s_add_u32 s58, s26, 0x20000
	s_addc_u32 s59, s27, 0
	s_add_i32 s60, s49, s34
	v_lshl_add_u64 v[72:73], s[58:59], 0, v[148:149]
	s_mov_b32 m0, s60
	s_nop 0
	global_load_lds_dwordx4 v[72:73], off
	v_lshl_add_u64 v[72:73], s[58:59], 0, v[144:145]
	s_add_i32 m0, s60, 0x2000
	s_nop 0
	global_load_lds_dwordx4 v[72:73], off
	s_waitcnt vmcnt(6)
	s_barrier
	s_setprio 1
	v_mfma_f32_16x16x32_bf16 v[52:55], v[202:205], v[160:163], v[52:55]
	v_mfma_f32_16x16x32_bf16 v[48:51], v[210:213], v[160:163], v[48:51]
	v_mfma_f32_16x16x32_bf16 v[36:39], v[202:205], v[174:177], v[36:39]
	v_mfma_f32_16x16x32_bf16 v[32:35], v[210:213], v[174:177], v[32:35]
	v_mfma_f32_16x16x32_bf16 v[20:23], v[202:205], v[182:185], v[20:23]
	v_mfma_f32_16x16x32_bf16 v[16:19], v[210:213], v[182:185], v[16:19]
	v_mfma_f32_16x16x32_bf16 v[4:7], v[202:205], v[190:193], v[4:7]
	v_mfma_f32_16x16x32_bf16 v[0:3], v[210:213], v[190:193], v[0:3]
	v_mfma_f32_16x16x32_bf16 v[52:55], v[206:209], v[170:173], v[52:55]
	v_mfma_f32_16x16x32_bf16 v[48:51], v[214:217], v[170:173], v[48:51]
	v_mfma_f32_16x16x32_bf16 v[36:39], v[206:209], v[178:181], v[36:39]
	v_mfma_f32_16x16x32_bf16 v[32:35], v[214:217], v[178:181], v[32:35]
	v_mfma_f32_16x16x32_bf16 v[20:23], v[206:209], v[186:189], v[20:23]
	v_mfma_f32_16x16x32_bf16 v[16:19], v[214:217], v[186:189], v[16:19]
	v_mfma_f32_16x16x32_bf16 v[4:7], v[206:209], v[198:201], v[4:7]
	v_mfma_f32_16x16x32_bf16 v[0:3], v[214:217], v[198:201], v[0:3]
	s_setprio 0
	s_add_i32 s58, 0, 0x18000
	v_add_u32_e32 v84, s58, v166
	s_barrier
	ds_read_b128 v[72:75], v84
	ds_read_b128 v[76:79], v84 offset:1024
	ds_read_b128 v[80:83], v84 offset:2048
	ds_read_b128 v[84:87], v84 offset:3072
	s_add_u32 s28, s28, 0x80000
	s_addc_u32 s29, s29, 0
	s_mov_b32 m0, s5
	v_lshl_add_u64 v[202:203], s[28:29], 0, v[150:151]
	ds_read_b128 v[160:163], v168 offset:32768
	ds_read_b128 v[170:173], v168 offset:33792
	ds_read_b128 v[174:177], v168 offset:34816
	ds_read_b128 v[178:181], v168 offset:35840
	ds_read_b128 v[182:185], v168 offset:36864
	ds_read_b128 v[186:189], v168 offset:37888
	ds_read_b128 v[190:193], v168 offset:38912
	ds_read_b128 v[198:201], v168 offset:39936
	global_load_lds_dwordx4 v[202:203], off
	v_lshl_add_u64 v[202:203], s[28:29], 0, v[146:147]
	s_mov_b32 m0, s23
	s_nop 0
	global_load_lds_dwordx4 v[202:203], off
	s_waitcnt lgkmcnt(8)
	s_barrier
	s_setprio 1
	s_waitcnt lgkmcnt(7)
	v_mfma_f32_16x16x32_bf16 v[140:143], v[72:75], v[160:163], v[140:143]
	v_mfma_f32_16x16x32_bf16 v[136:139], v[80:83], v[160:163], v[136:139]
	s_waitcnt lgkmcnt(5)
	v_mfma_f32_16x16x32_bf16 v[124:127], v[72:75], v[174:177], v[124:127]
	v_mfma_f32_16x16x32_bf16 v[120:123], v[80:83], v[174:177], v[120:123]
	s_waitcnt lgkmcnt(3)
	v_mfma_f32_16x16x32_bf16 v[108:111], v[72:75], v[182:185], v[108:111]
	v_mfma_f32_16x16x32_bf16 v[104:107], v[80:83], v[182:185], v[104:107]
	s_waitcnt lgkmcnt(1)
	v_mfma_f32_16x16x32_bf16 v[92:95], v[72:75], v[190:193], v[92:95]
	v_mfma_f32_16x16x32_bf16 v[88:91], v[80:83], v[190:193], v[88:91]
	v_mfma_f32_16x16x32_bf16 v[140:143], v[76:79], v[170:173], v[140:143]
	v_mfma_f32_16x16x32_bf16 v[136:139], v[84:87], v[170:173], v[136:139]
	v_mfma_f32_16x16x32_bf16 v[124:127], v[76:79], v[178:181], v[124:127]
	v_mfma_f32_16x16x32_bf16 v[120:123], v[84:87], v[178:181], v[120:123]
	v_mfma_f32_16x16x32_bf16 v[108:111], v[76:79], v[186:189], v[108:111]
	v_mfma_f32_16x16x32_bf16 v[104:107], v[84:87], v[186:189], v[104:107]
	s_waitcnt lgkmcnt(0)
	v_mfma_f32_16x16x32_bf16 v[92:95], v[76:79], v[198:201], v[92:95]
	v_mfma_f32_16x16x32_bf16 v[88:91], v[84:87], v[198:201], v[88:91]
	s_setprio 0
	s_barrier
	s_add_i32 s28, 0, 0x1c000
	s_add_i32 s29, s58, s34
	v_add_u32_e32 v196, s28, v166
	v_lshl_add_u64 v[194:195], v[194:195], 0, s[12:13]
	s_mov_b32 m0, s29
	ds_read_b128 v[202:205], v196
	ds_read_b128 v[206:209], v196 offset:1024
	ds_read_b128 v[210:213], v196 offset:2048
	ds_read_b128 v[214:217], v196 offset:3072
	global_load_lds_dwordx4 v[194:195], off
	v_lshl_add_u64 v[194:195], v[218:219], 0, s[12:13]
	s_add_i32 m0, s29, 0x2000
	s_nop 0
	global_load_lds_dwordx4 v[194:195], off
	s_barrier
; #define PG8_STAGE(bufoff, gbase, voff) do { _Pragma("unroll") for (int _i = 0; _i < 2; ++_i) \
;         __builtin_amdgcn_global_load_lds((const unsigned*)((const char*)(gbase) + (voff)[_i]), (LAS unsigned*)(lds + (bufoff) + ldsw + _i * 8192), 16, 0, 0); } while (0)
; #define PG8_LDA(dst, b, h) do { _Pragma("unroll") for (int m = 0; m < 4; ++m) _Pragma("unroll") for (int k = 0; k < 2; ++k) dst[m][k] = *(const LAS bf16x8*)(lds + PG8_SA(b, h) + aoff + m * 2048 + k * 1024); } while (0)
; #define PG8_MMA(ai, bj, At, Bt) do { __builtin_amdgcn_s_setprio(1); _Pragma("unroll") for (int m = 0; m < 4; ++m) _Pragma("unroll") for (int n = 0; n < 2; ++n) _Pragma("unroll") for (int k = 0; k < 2; ++k) \
;         acc[ai][bj][m][n] = __builtin_amdgcn_mfma_f32_16x16x32_bf16(Bt[n][k], At[m][k], acc[ai][bj][m][n], 0, 0, 0); __builtin_amdgcn_s_setprio(0); } while (0)
; #define PG8_WAIT_V(n) asm volatile("s_waitcnt vmcnt(" #n ")" ::: "memory")
; #define PG8_WAIT_L(n) asm volatile("s_waitcnt lgkmcnt(" #n ")" ::: "memory")
; #define PG8_BAR __builtin_amdgcn_s_barrier()
; #define PG8_SCHED __builtin_amdgcn_sched_barrier(0)
;     DI void operator()(const f32x4 (&acc)[2][2][4][2], const Unit& u, int wr, int wc, int fr, int fq) const {
;         const int row0 = u.pm * BM + wr * 64 + fr, col0 = u.pn * BM + wc * 32 + 8 * fq;
;         f32x4 sc[2][2];
; #pragma unroll
;         for (int bj = 0; bj < 2; ++bj)
; #pragma unroll
;             for (int n = 0; n < 2; ++n) sc[bj][n] = scale ? *(const f32x4*)(scale + col0 + bj * HALF + 4 * n) : (f32x4){1.f, 1.f, 1.f, 1.f};
; #pragma unroll
; template <class Map, class Epi>
; DI void gemm_phase(LAS unsigned char* lds, const Map& MP, const Epi& E, const int nM, const int nN, const int K, const int lda, const int ldb) {
;     ...
;             PG8_BAR; PG8_WAIT_L(0); PG8_MMA(0, 1, At, B1); PG8_BAR;
;             PG8_LDA(At, 1, 1); PG8_STAGE(PG8_SA(1, 0), a3, voffA);
;             PG8_BAR; PG8_WAIT_L(0); PG8_MMA(1, 0, At, B0); PG8_BAR; PG8_SCHED;
;             PG8_STAGE(PG8_SB(1, 1), b3 + hstepB, voffB);
;             PG8_WAIT_V(6); PG8_BAR; PG8_MMA(1, 1, At, B1); PG8_BAR;
	s_setprio 1
	s_waitcnt lgkmcnt(3)
	v_mfma_f32_16x16x32_bf16 v[132:135], v[202:205], v[160:163], v[132:135]
	s_waitcnt lgkmcnt(1)
	v_mfma_f32_16x16x32_bf16 v[128:131], v[210:213], v[160:163], v[128:131]
	v_mfma_f32_16x16x32_bf16 v[116:119], v[202:205], v[174:177], v[116:119]
	v_mfma_f32_16x16x32_bf16 v[112:115], v[210:213], v[174:177], v[112:115]
	v_mfma_f32_16x16x32_bf16 v[100:103], v[202:205], v[182:185], v[100:103]
	v_mfma_f32_16x16x32_bf16 v[96:99], v[210:213], v[182:185], v[96:99]
	v_mfma_f32_16x16x32_bf16 v[68:71], v[202:205], v[190:193], v[68:71]
	v_mfma_f32_16x16x32_bf16 v[64:67], v[210:213], v[190:193], v[64:67]
	v_mfma_f32_16x16x32_bf16 v[132:135], v[206:209], v[170:173], v[132:135]
	s_waitcnt lgkmcnt(0)
	v_mfma_f32_16x16x32_bf16 v[128:131], v[214:217], v[170:173], v[128:131]
	v_mfma_f32_16x16x32_bf16 v[116:119], v[206:209], v[178:181], v[116:119]
	v_mfma_f32_16x16x32_bf16 v[112:115], v[214:217], v[178:181], v[112:115]
	v_mfma_f32_16x16x32_bf16 v[100:103], v[206:209], v[186:189], v[100:103]
	v_mfma_f32_16x16x32_bf16 v[96:99], v[214:217], v[186:189], v[96:99]
	v_mfma_f32_16x16x32_bf16 v[68:71], v[206:209], v[198:201], v[68:71]
	v_mfma_f32_16x16x32_bf16 v[64:67], v[214:217], v[198:201], v[64:67]
	s_setprio 0
	s_mov_b32 m0, s39
	v_lshl_add_u64 v[194:195], v[220:221], 0, s[12:13]
	s_barrier
	ds_read_b128 v[160:163], v168 offset:49152
	ds_read_b128 v[170:173], v168 offset:50176
	ds_read_b128 v[174:177], v168 offset:51200
	ds_read_b128 v[178:181], v168 offset:52224
	ds_read_b128 v[182:185], v168 offset:53248
	ds_read_b128 v[186:189], v168 offset:54272
	ds_read_b128 v[190:193], v168 offset:55296
	ds_read_b128 v[198:201], v168 offset:56320
	global_load_lds_dwordx4 v[194:195], off
	v_lshl_add_u64 v[194:195], v[222:223], 0, s[12:13]
	s_mov_b32 m0, s46
	s_nop 0
	global_load_lds_dwordx4 v[194:195], off
	s_barrier
	s_setprio 1
	s_waitcnt lgkmcnt(7)
	v_mfma_f32_16x16x32_bf16 v[60:63], v[72:75], v[160:163], v[60:63]
	v_mfma_f32_16x16x32_bf16 v[56:59], v[80:83], v[160:163], v[56:59]
	s_waitcnt lgkmcnt(5)
	v_mfma_f32_16x16x32_bf16 v[44:47], v[72:75], v[174:177], v[44:47]
	v_mfma_f32_16x16x32_bf16 v[40:43], v[80:83], v[174:177], v[40:43]
	s_waitcnt lgkmcnt(3)
	v_mfma_f32_16x16x32_bf16 v[28:31], v[72:75], v[182:185], v[28:31]
	v_mfma_f32_16x16x32_bf16 v[24:27], v[80:83], v[182:185], v[24:27]
	s_waitcnt lgkmcnt(1)
	v_mfma_f32_16x16x32_bf16 v[12:15], v[72:75], v[190:193], v[12:15]
	v_mfma_f32_16x16x32_bf16 v[8:11], v[80:83], v[190:193], v[8:11]
	v_mfma_f32_16x16x32_bf16 v[60:63], v[76:79], v[170:173], v[60:63]
	v_mfma_f32_16x16x32_bf16 v[56:59], v[84:87], v[170:173], v[56:59]
	v_mfma_f32_16x16x32_bf16 v[44:47], v[76:79], v[178:181], v[44:47]
	v_mfma_f32_16x16x32_bf16 v[40:43], v[84:87], v[178:181], v[40:43]
	v_mfma_f32_16x16x32_bf16 v[28:31], v[76:79], v[186:189], v[28:31]
	v_mfma_f32_16x16x32_bf16 v[24:27], v[84:87], v[186:189], v[24:27]
	s_waitcnt lgkmcnt(0)
	v_mfma_f32_16x16x32_bf16 v[12:15], v[76:79], v[198:201], v[12:15]
	v_mfma_f32_16x16x32_bf16 v[8:11], v[84:87], v[198:201], v[8:11]
	s_setprio 0
	s_barrier
	s_add_u32 s26, s26, 0x20080
	s_addc_u32 s27, s27, 0
	s_add_i32 s28, s28, s34
	v_lshl_add_u64 v[72:73], s[26:27], 0, v[148:149]
	s_mov_b32 m0, s28
	s_nop 0
	global_load_lds_dwordx4 v[72:73], off
	v_lshl_add_u64 v[72:73], s[26:27], 0, v[144:145]
	s_add_i32 m0, s28, 0x2000
	s_nop 0
	global_load_lds_dwordx4 v[72:73], off
	s_waitcnt vmcnt(6)
	s_barrier
	s_setprio 1
	v_mfma_f32_16x16x32_bf16 v[52:55], v[202:205], v[160:163], v[52:55]
	v_mfma_f32_16x16x32_bf16 v[48:51], v[210:213], v[160:163], v[48:51]
	v_mfma_f32_16x16x32_bf16 v[36:39], v[202:205], v[174:177], v[36:39]
	v_mfma_f32_16x16x32_bf16 v[32:35], v[210:213], v[174:177], v[32:35]
	v_mfma_f32_16x16x32_bf16 v[20:23], v[202:205], v[182:185], v[20:23]
	v_mfma_f32_16x16x32_bf16 v[16:19], v[210:213], v[182:185], v[16:19]
	v_mfma_f32_16x16x32_bf16 v[4:7], v[202:205], v[190:193], v[4:7]
	v_mfma_f32_16x16x32_bf16 v[0:3], v[210:213], v[190:193], v[0:3]
	v_mfma_f32_16x16x32_bf16 v[52:55], v[206:209], v[170:173], v[52:55]
	v_mfma_f32_16x16x32_bf16 v[48:51], v[214:217], v[170:173], v[48:51]
	v_mfma_f32_16x16x32_bf16 v[36:39], v[206:209], v[178:181], v[36:39]
	v_mfma_f32_16x16x32_bf16 v[32:35], v[214:217], v[178:181], v[32:35]
	v_mfma_f32_16x16x32_bf16 v[20:23], v[206:209], v[186:189], v[20:23]
	v_mfma_f32_16x16x32_bf16 v[16:19], v[214:217], v[186:189], v[16:19]
	v_mfma_f32_16x16x32_bf16 v[4:7], v[206:209], v[198:201], v[4:7]
	v_mfma_f32_16x16x32_bf16 v[0:3], v[214:217], v[198:201], v[0:3]
	s_setprio 0
	s_add_i32 s57, s57, 2
	s_add_u32 s55, s55, 0x100
	s_addc_u32 s56, s56, 0
	s_add_u32 s24, s24, 0x100
	s_addc_u32 s25, s25, 0
	s_cmp_gt_u32 s57, 5
	s_barrier
	s_cbranch_scc0 .LBB1_229
	s_lshl_b32 s17, s42, 8
	v_mov_b32_e32 v170, v164
	v_mov_b32_e32 v72, v165
	s_or_b32 s17, s17, s38
	v_mov_b32_e32 v80, 1.0
	v_lshl_add_u32 v160, v72, 3, s17
	v_ashrrev_i32_e32 v161, 31, v160
	v_cndmask_b32_e64 v72, 0, 1, s[14:15]
	v_lshl_add_u64 v[162:163], v[160:161], 2, s[8:9]
	v_cmp_ne_u32_e64 s[42:43], 1, v72
	s_andn2_b64 vcc, exec, s[14:15]
	v_mov_b32_e32 v84, 1.0
	v_mov_b32_e32 v85, 1.0
	v_mov_b32_e32 v86, 1.0
	v_mov_b32_e32 v87, 1.0
	s_cbranch_vccnz .LBB1_232
	global_load_dwordx4 v[84:87], v[162:163], off

; #define PG8_STAGE(bufoff, gbase, voff) do { _Pragma("unroll") for (int _i = 0; _i < 2; ++_i) \
;         __builtin_amdgcn_global_load_lds((const unsigned*)((const char*)(gbase) + (voff)[_i]), (LAS unsigned*)(lds + (bufoff) + ldsw + _i * 8192), 16, 0, 0); } while (0)
; #define PG8_LDA(dst, b, h) do { _Pragma("unroll") for (int m = 0; m < 4; ++m) _Pragma("unroll") for (int k = 0; k < 2; ++k) dst[m][k] = *(const LAS bf16x8*)(lds + PG8_SA(b, h) + aoff + m * 2048 + k * 1024); } while (0)
; #define PG8_LDB(dst, b, h) do { _Pragma("unroll") for (int n = 0; n < 2; ++n) _Pragma("unroll") for (int k = 0; k < 2; ++k) dst[n][k] = *(const LAS bf16x8*)(lds + PG8_SB(b, h) + boff + n * 2048 + k * 1024); } while (0)
; #define PG8_MMA(ai, bj, At, Bt) do { __builtin_amdgcn_s_setprio(1); _Pragma("unroll") for (int m = 0; m < 4; ++m) _Pragma("unroll") for (int n = 0; n < 2; ++n) _Pragma("unroll") for (int k = 0; k < 2; ++k) \
;         acc[ai][bj][m][n] = __builtin_amdgcn_mfma_f32_16x16x32_bf16(Bt[n][k], At[m][k], acc[ai][bj][m][n], 0, 0, 0); __builtin_amdgcn_s_setprio(0); } while (0)
; #define PG8_WAIT_L(n) asm volatile("s_waitcnt lgkmcnt(" #n ")" ::: "memory")
; #define PG8_BAR __builtin_amdgcn_s_barrier()
; #define PG8_SCHED __builtin_amdgcn_sched_barrier(0)
; template <class Map, class Epi>
; DI void gemm_phase(LAS unsigned char* lds, const Map& MP, const Epi& E, const int nM, const int nN, const int K, const int lda, const int ldb) {
;     ...
;             PG8_LDB(B0, 0, 0); PG8_SCHED; PG8_LDA(At, 0, 0); PG8_STAGE(PG8_SA(1, 1), a1 + hstepA, voffA);
;             PG8_WAIT_L(8); PG8_BAR; PG8_WAIT_L(0); PG8_MMA(0, 0, At, B0); PG8_BAR; PG8_SCHED;
;             PG8_LDB(B1, 0, 1); PG8_STAGE(PG8_SB(0, 0), b2, voffB);
;             PG8_BAR; PG8_WAIT_L(0); PG8_MMA(0, 1, At, B1); PG8_BAR;
;             PG8_LDA(At, 0, 1); PG8_STAGE(PG8_SA(0, 0), a2, voffA);
;             PG8_BAR; PG8_WAIT_L(0); PG8_MMA(1, 0, At, B0); PG8_BAR; PG8_SCHED;
.LBB1_380:
	ds_read_b128 v[80:83], v189
	ds_read_b128 v[84:87], v189 offset:1024
	ds_read_b128 v[88:91], v189 offset:2048
	ds_read_b128 v[92:95], v189 offset:3072
	s_add_u32 s28, s44, 0xfff80080
	s_addc_u32 s29, s45, -1
	s_cmp_eq_u32 vcc_hi, 28
	s_cselect_b32 s47, s23, s29
	s_cselect_b32 s46, s61, s28
	s_cselect_b32 s29, s21, vcc_lo
	s_cselect_b32 s28, s58, s59
	v_lshl_add_u64 v[184:185], s[44:45], 0, v[178:179]
	s_add_i32 m0, s38, 0xc000
	ds_read_b128 v[96:99], v190
	ds_read_b128 v[100:103], v190 offset:1024
	ds_read_b128 v[108:111], v190 offset:2048
	ds_read_b128 v[112:115], v190 offset:3072
	ds_read_b128 v[160:163], v190 offset:4096
	ds_read_b128 v[164:167], v190 offset:5120
	ds_read_b128 v[198:201], v190 offset:6144
	ds_read_b128 v[202:205], v190 offset:7168
	global_load_lds_dwordx4 v[184:185], off
	v_lshl_add_u64 v[184:185], s[44:45], 0, v[176:177]
	s_add_i32 m0, s38, 0xe000
	s_nop 0
	global_load_lds_dwordx4 v[184:185], off
	s_waitcnt lgkmcnt(8)
	s_barrier
	s_setprio 1
	s_waitcnt lgkmcnt(7)
	v_mfma_f32_16x16x32_bf16 v[148:151], v[80:83], v[96:99], v[148:151]
	v_mfma_f32_16x16x32_bf16 v[144:147], v[88:91], v[96:99], v[144:147]
	s_waitcnt lgkmcnt(5)
	v_mfma_f32_16x16x32_bf16 v[136:139], v[80:83], v[108:111], v[136:139]
	v_mfma_f32_16x16x32_bf16 v[128:131], v[88:91], v[108:111], v[128:131]
	s_waitcnt lgkmcnt(3)
	v_mfma_f32_16x16x32_bf16 v[120:123], v[80:83], v[160:163], v[120:123]
	v_mfma_f32_16x16x32_bf16 v[104:107], v[88:91], v[160:163], v[104:107]
	s_waitcnt lgkmcnt(1)
	v_mfma_f32_16x16x32_bf16 v[76:79], v[80:83], v[198:201], v[76:79]
	v_mfma_f32_16x16x32_bf16 v[72:75], v[88:91], v[198:201], v[72:75]
	v_mfma_f32_16x16x32_bf16 v[148:151], v[84:87], v[100:103], v[148:151]
	v_mfma_f32_16x16x32_bf16 v[144:147], v[92:95], v[100:103], v[144:147]
	v_mfma_f32_16x16x32_bf16 v[136:139], v[84:87], v[112:115], v[136:139]
	v_mfma_f32_16x16x32_bf16 v[128:131], v[92:95], v[112:115], v[128:131]
	v_mfma_f32_16x16x32_bf16 v[120:123], v[84:87], v[164:167], v[120:123]
	v_mfma_f32_16x16x32_bf16 v[104:107], v[92:95], v[164:167], v[104:107]
	s_waitcnt lgkmcnt(0)
	v_mfma_f32_16x16x32_bf16 v[76:79], v[84:87], v[202:205], v[76:79]
	v_mfma_f32_16x16x32_bf16 v[72:75], v[92:95], v[202:205], v[72:75]
	s_setprio 0
	s_barrier
	s_add_i32 s68, s5, s37
	v_lshl_add_u64 v[184:185], s[28:29], 0, v[172:173]
	s_mov_b32 m0, s68
	ds_read_b128 v[206:209], v191
	ds_read_b128 v[210:213], v191 offset:1024
	ds_read_b128 v[214:217], v191 offset:2048
	ds_read_b128 v[218:221], v191 offset:3072
	global_load_lds_dwordx4 v[184:185], off
	v_lshl_add_u64 v[194:195], s[28:29], 0, v[168:169]
	s_add_i32 m0, s68, 0x2000
	s_nop 0
	global_load_lds_dwordx4 v[194:195], off
	s_barrier
	s_setprio 1
	s_waitcnt lgkmcnt(3)
	v_mfma_f32_16x16x32_bf16 v[156:159], v[206:209], v[96:99], v[156:159]
	s_waitcnt lgkmcnt(1)
	v_mfma_f32_16x16x32_bf16 v[96:99], v[214:217], v[96:99], v[152:155]
	v_mfma_f32_16x16x32_bf16 v[156:159], v[210:213], v[100:103], v[156:159]
	s_waitcnt lgkmcnt(0)
	v_mfma_f32_16x16x32_bf16 v[96:99], v[218:221], v[100:103], v[96:99]
	v_mfma_f32_16x16x32_bf16 v[100:103], v[206:209], v[108:111], v[140:143]
	v_mfma_f32_16x16x32_bf16 v[108:111], v[214:217], v[108:111], v[132:135]
	v_mfma_f32_16x16x32_bf16 v[116:119], v[214:217], v[160:163], v[116:119]
	v_mfma_f32_16x16x32_bf16 v[68:71], v[206:209], v[198:201], v[68:71]
	v_mfma_f32_16x16x32_bf16 v[64:67], v[214:217], v[198:201], v[64:67]
	v_mfma_f32_16x16x32_bf16 v[100:103], v[210:213], v[112:115], v[100:103]
	v_mfma_f32_16x16x32_bf16 v[108:111], v[218:221], v[112:115], v[108:111]
	v_mfma_f32_16x16x32_bf16 v[112:115], v[206:209], v[160:163], v[124:127]
	v_mfma_f32_16x16x32_bf16 v[116:119], v[218:221], v[164:167], v[116:119]
	v_mfma_f32_16x16x32_bf16 v[68:71], v[210:213], v[202:205], v[68:71]
	v_mfma_f32_16x16x32_bf16 v[64:67], v[218:221], v[202:205], v[64:67]
	v_mfma_f32_16x16x32_bf16 v[112:115], v[210:213], v[164:167], v[112:115]
	s_setprio 0
	s_mov_b32 m0, s38
	v_lshl_add_u64 v[226:227], s[46:47], 0, v[174:175]
	s_barrier
	ds_read_b128 v[124:127], v190 offset:16384
	ds_read_b128 v[132:135], v190 offset:17408
	ds_read_b128 v[140:143], v190 offset:18432
	ds_read_b128 v[152:155], v190 offset:19456
	ds_read_b128 v[160:163], v190 offset:20480
	ds_read_b128 v[164:167], v190 offset:21504
	ds_read_b128 v[198:201], v190 offset:22528
	ds_read_b128 v[202:205], v190 offset:23552
	global_load_lds_dwordx4 v[226:227], off
	v_lshl_add_u64 v[234:235], s[46:47], 0, v[170:171]
	s_mov_b32 m0, s39
	s_nop 0
	global_load_lds_dwordx4 v[234:235], off
	s_barrier
	s_setprio 1
	s_waitcnt lgkmcnt(7)
	v_mfma_f32_16x16x32_bf16 v[60:63], v[80:83], v[124:127], v[60:63]
	v_mfma_f32_16x16x32_bf16 v[48:51], v[88:91], v[124:127], v[48:51]
	s_waitcnt lgkmcnt(5)
	v_mfma_f32_16x16x32_bf16 v[40:43], v[80:83], v[140:143], v[40:43]
	v_mfma_f32_16x16x32_bf16 v[32:35], v[88:91], v[140:143], v[32:35]
	s_waitcnt lgkmcnt(3)
	v_mfma_f32_16x16x32_bf16 v[24:27], v[80:83], v[160:163], v[24:27]
	v_mfma_f32_16x16x32_bf16 v[16:19], v[88:91], v[160:163], v[16:19]
	s_waitcnt lgkmcnt(1)
	v_mfma_f32_16x16x32_bf16 v[12:15], v[80:83], v[198:201], v[12:15]
	v_mfma_f32_16x16x32_bf16 v[8:11], v[88:91], v[198:201], v[8:11]
	v_mfma_f32_16x16x32_bf16 v[60:63], v[84:87], v[132:135], v[60:63]
	v_mfma_f32_16x16x32_bf16 v[48:51], v[92:95], v[132:135], v[48:51]
	v_mfma_f32_16x16x32_bf16 v[40:43], v[84:87], v[152:155], v[40:43]
	v_mfma_f32_16x16x32_bf16 v[32:35], v[92:95], v[152:155], v[32:35]
	v_mfma_f32_16x16x32_bf16 v[24:27], v[84:87], v[164:167], v[24:27]
	v_mfma_f32_16x16x32_bf16 v[16:19], v[92:95], v[164:167], v[16:19]
	s_waitcnt lgkmcnt(0)
	v_mfma_f32_16x16x32_bf16 v[12:15], v[84:87], v[202:205], v[12:15]
	v_mfma_f32_16x16x32_bf16 v[8:11], v[92:95], v[202:205], v[8:11]
	s_setprio 0
	s_barrier
; #define PG8_STAGE(bufoff, gbase, voff) do { _Pragma("unroll") for (int _i = 0; _i < 2; ++_i) \
;         __builtin_amdgcn_global_load_lds((const unsigned*)((const char*)(gbase) + (voff)[_i]), (LAS unsigned*)(lds + (bufoff) + ldsw + _i * 8192), 16, 0, 0); } while (0)
; #define PG8_LDA(dst, b, h) do { _Pragma("unroll") for (int m = 0; m < 4; ++m) _Pragma("unroll") for (int k = 0; k < 2; ++k) dst[m][k] = *(const LAS bf16x8*)(lds + PG8_SA(b, h) + aoff + m * 2048 + k * 1024); } while (0)
; #define PG8_LDB(dst, b, h) do { _Pragma("unroll") for (int n = 0; n < 2; ++n) _Pragma("unroll") for (int k = 0; k < 2; ++k) dst[n][k] = *(const LAS bf16x8*)(lds + PG8_SB(b, h) + boff + n * 2048 + k * 1024); } while (0)
; #define PG8_MMA(ai, bj, At, Bt) do { __builtin_amdgcn_s_setprio(1); _Pragma("unroll") for (int m = 0; m < 4; ++m) _Pragma("unroll") for (int n = 0; n < 2; ++n) _Pragma("unroll") for (int k = 0; k < 2; ++k) \
;         acc[ai][bj][m][n] = __builtin_amdgcn_mfma_f32_16x16x32_bf16(Bt[n][k], At[m][k], acc[ai][bj][m][n], 0, 0, 0); __builtin_amdgcn_s_setprio(0); } while (0)
; #define PG8_WAIT_V(n) asm volatile("s_waitcnt vmcnt(" #n ")" ::: "memory")
; #define PG8_WAIT_L(n) asm volatile("s_waitcnt lgkmcnt(" #n ")" ::: "memory")
; #define PG8_BAR __builtin_amdgcn_s_barrier()
; #define PG8_SCHED __builtin_amdgcn_sched_barrier(0)
; template <class Map, class Epi>
; DI void gemm_phase(LAS unsigned char* lds, const Map& MP, const Epi& E, const int nM, const int nN, const int K, const int lda, const int ldb) {
;     ...
;             PG8_STAGE(PG8_SB(0, 1), b2 + hstepB, voffB);
;             PG8_WAIT_V(6); PG8_BAR; PG8_MMA(1, 1, At, B1); PG8_BAR;
;             PG8_LDB(B0, 1, 0); PG8_SCHED; PG8_LDA(At, 1, 0); PG8_STAGE(PG8_SA(0, 1), a2 + hstepA, voffA);
;             PG8_WAIT_L(8); PG8_BAR; PG8_WAIT_L(0); PG8_MMA(0, 0, At, B0); PG8_BAR; PG8_SCHED;
;             PG8_LDB(B1, 1, 1); PG8_STAGE(PG8_SB(1, 0), b3, voffB);
;             PG8_BAR; PG8_WAIT_L(0); PG8_MMA(0, 1, At, B1); PG8_BAR;
;             PG8_LDA(At, 1, 1); PG8_STAGE(PG8_SA(1, 0), a3, voffA);
	s_add_u32 s68, s28, 0x80000
	s_addc_u32 s69, s29, 0
	s_add_i32 s70, s2, s37
	v_lshl_add_u64 v[80:81], s[68:69], 0, v[172:173]
	s_mov_b32 m0, s70
	s_nop 0
	global_load_lds_dwordx4 v[80:81], off
	v_lshl_add_u64 v[80:81], s[68:69], 0, v[168:169]
	s_add_i32 m0, s70, 0x2000
	s_nop 0
	global_load_lds_dwordx4 v[80:81], off
	s_waitcnt vmcnt(6)
	s_barrier
	s_setprio 1
	v_mfma_f32_16x16x32_bf16 v[56:59], v[206:209], v[124:127], v[56:59]
	v_mfma_f32_16x16x32_bf16 v[52:55], v[214:217], v[124:127], v[52:55]
	v_mfma_f32_16x16x32_bf16 v[44:47], v[206:209], v[140:143], v[44:47]
	v_mfma_f32_16x16x32_bf16 v[36:39], v[214:217], v[140:143], v[36:39]
	v_mfma_f32_16x16x32_bf16 v[28:31], v[206:209], v[160:163], v[28:31]
	v_mfma_f32_16x16x32_bf16 v[20:23], v[214:217], v[160:163], v[20:23]
	v_mfma_f32_16x16x32_bf16 v[4:7], v[206:209], v[198:201], v[4:7]
	v_mfma_f32_16x16x32_bf16 v[0:3], v[214:217], v[198:201], v[0:3]
	v_mfma_f32_16x16x32_bf16 v[56:59], v[210:213], v[132:135], v[56:59]
	v_mfma_f32_16x16x32_bf16 v[52:55], v[218:221], v[132:135], v[52:55]
	v_mfma_f32_16x16x32_bf16 v[44:47], v[210:213], v[152:155], v[44:47]
	v_mfma_f32_16x16x32_bf16 v[36:39], v[218:221], v[152:155], v[36:39]
	v_mfma_f32_16x16x32_bf16 v[28:31], v[210:213], v[164:167], v[28:31]
	v_mfma_f32_16x16x32_bf16 v[20:23], v[218:221], v[164:167], v[20:23]
	v_mfma_f32_16x16x32_bf16 v[4:7], v[210:213], v[202:205], v[4:7]
	v_mfma_f32_16x16x32_bf16 v[0:3], v[218:221], v[202:205], v[0:3]
	s_setprio 0
	s_add_i32 s68, 0, 0x18000
	v_add_u32_e32 v92, s68, v188
	s_barrier
	ds_read_b128 v[80:83], v92
	ds_read_b128 v[84:87], v92 offset:1024
	ds_read_b128 v[88:91], v92 offset:2048
	ds_read_b128 v[92:95], v92 offset:3072
	s_add_u32 s46, s46, 0x80000
	s_addc_u32 s47, s47, 0
	s_mov_b32 m0, s56
	v_lshl_add_u64 v[140:141], s[46:47], 0, v[174:175]
	ds_read_b128 v[124:127], v190 offset:32768
	ds_read_b128 v[132:135], v190 offset:33792
	ds_read_b128 v[160:163], v190 offset:34816
	ds_read_b128 v[164:167], v190 offset:35840
	ds_read_b128 v[198:201], v190 offset:36864
	ds_read_b128 v[202:205], v190 offset:37888
	ds_read_b128 v[206:209], v190 offset:38912
	ds_read_b128 v[210:213], v190 offset:39936
	global_load_lds_dwordx4 v[140:141], off
	v_lshl_add_u64 v[140:141], s[46:47], 0, v[170:171]
	s_mov_b32 m0, s57
	s_nop 0
	global_load_lds_dwordx4 v[140:141], off
	s_waitcnt lgkmcnt(8)
	s_barrier
	s_setprio 1
	s_waitcnt lgkmcnt(7)
	v_mfma_f32_16x16x32_bf16 v[140:143], v[80:83], v[124:127], v[148:151]
	s_waitcnt lgkmcnt(6)
	v_mfma_f32_16x16x32_bf16 v[148:151], v[84:87], v[132:135], v[140:143]
	v_mfma_f32_16x16x32_bf16 v[140:143], v[88:91], v[124:127], v[144:147]
	s_waitcnt lgkmcnt(5)
	v_mfma_f32_16x16x32_bf16 v[136:139], v[80:83], v[160:163], v[136:139]
	v_mfma_f32_16x16x32_bf16 v[128:131], v[88:91], v[160:163], v[128:131]
	s_waitcnt lgkmcnt(3)
	v_mfma_f32_16x16x32_bf16 v[120:123], v[80:83], v[198:201], v[120:123]
	v_mfma_f32_16x16x32_bf16 v[104:107], v[88:91], v[198:201], v[104:107]
	s_waitcnt lgkmcnt(1)
	v_mfma_f32_16x16x32_bf16 v[76:79], v[80:83], v[206:209], v[76:79]
	v_mfma_f32_16x16x32_bf16 v[72:75], v[88:91], v[206:209], v[72:75]
	v_mfma_f32_16x16x32_bf16 v[144:147], v[92:95], v[132:135], v[140:143]
	v_mfma_f32_16x16x32_bf16 v[136:139], v[84:87], v[164:167], v[136:139]
	v_mfma_f32_16x16x32_bf16 v[128:131], v[92:95], v[164:167], v[128:131]
	v_mfma_f32_16x16x32_bf16 v[120:123], v[84:87], v[202:205], v[120:123]
	v_mfma_f32_16x16x32_bf16 v[104:107], v[92:95], v[202:205], v[104:107]
	s_waitcnt lgkmcnt(0)
	v_mfma_f32_16x16x32_bf16 v[76:79], v[84:87], v[210:213], v[76:79]
	v_mfma_f32_16x16x32_bf16 v[72:75], v[92:95], v[210:213], v[72:75]
	s_setprio 0
	s_barrier
	s_add_i32 s46, 0, 0x1c000
	v_add_u32_e32 v140, s46, v188
	s_add_i32 s47, s68, s37
	ds_read_b128 v[214:217], v140
	ds_read_b128 v[218:221], v140 offset:1024
	ds_read_b128 v[222:225], v140 offset:2048
	ds_read_b128 v[230:233], v140 offset:3072
	v_lshl_add_u64 v[140:141], v[184:185], 0, s[14:15]
	s_mov_b32 m0, s47
	s_nop 0
	global_load_lds_dwordx4 v[140:141], off
	v_lshl_add_u64 v[140:141], v[194:195], 0, s[14:15]
	s_add_i32 m0, s47, 0x2000
	s_nop 0
	global_load_lds_dwordx4 v[140:141], off
	s_barrier
	s_setprio 1
	s_waitcnt lgkmcnt(1)
	v_mfma_f32_16x16x32_bf16 v[96:99], v[222:225], v[124:127], v[96:99]
	v_mfma_f32_16x16x32_bf16 v[140:143], v[214:217], v[124:127], v[156:159]
	s_waitcnt lgkmcnt(0)
	v_mfma_f32_16x16x32_bf16 v[152:155], v[230:233], v[132:135], v[96:99]
	v_mfma_f32_16x16x32_bf16 v[96:99], v[214:217], v[160:163], v[100:103]
	v_mfma_f32_16x16x32_bf16 v[156:159], v[218:221], v[132:135], v[140:143]
	v_mfma_f32_16x16x32_bf16 v[140:143], v[218:221], v[164:167], v[96:99]
	v_mfma_f32_16x16x32_bf16 v[96:99], v[222:225], v[160:163], v[108:111]
	v_mfma_f32_16x16x32_bf16 v[132:135], v[230:233], v[164:167], v[96:99]
	v_mfma_f32_16x16x32_bf16 v[96:99], v[214:217], v[198:201], v[112:115]
	v_mfma_f32_16x16x32_bf16 v[124:127], v[218:221], v[202:205], v[96:99]
	v_mfma_f32_16x16x32_bf16 v[96:99], v[222:225], v[198:201], v[116:119]
	v_mfma_f32_16x16x32_bf16 v[68:71], v[214:217], v[206:209], v[68:71]
	v_mfma_f32_16x16x32_bf16 v[64:67], v[222:225], v[206:209], v[64:67]
	v_mfma_f32_16x16x32_bf16 v[116:119], v[230:233], v[202:205], v[96:99]
	v_mfma_f32_16x16x32_bf16 v[68:71], v[218:221], v[210:213], v[68:71]
	v_mfma_f32_16x16x32_bf16 v[64:67], v[230:233], v[210:213], v[64:67]
	s_setprio 0
	s_mov_b32 m0, s62
	v_lshl_add_u64 v[184:185], v[226:227], 0, s[14:15]
	s_barrier
; #define PG8_STAGE(bufoff, gbase, voff) do { _Pragma("unroll") for (int _i = 0; _i < 2; ++_i) \
;         __builtin_amdgcn_global_load_lds((const unsigned*)((const char*)(gbase) + (voff)[_i]), (LAS unsigned*)(lds + (bufoff) + ldsw + _i * 8192), 16, 0, 0); } while (0)
; #define PG8_LDA(dst, b, h) do { _Pragma("unroll") for (int m = 0; m < 4; ++m) _Pragma("unroll") for (int k = 0; k < 2; ++k) dst[m][k] = *(const LAS bf16x8*)(lds + PG8_SA(b, h) + aoff + m * 2048 + k * 1024); } while (0)
; #define PG8_MMA(ai, bj, At, Bt) do { __builtin_amdgcn_s_setprio(1); _Pragma("unroll") for (int m = 0; m < 4; ++m) _Pragma("unroll") for (int n = 0; n < 2; ++n) _Pragma("unroll") for (int k = 0; k < 2; ++k) \
;         acc[ai][bj][m][n] = __builtin_amdgcn_mfma_f32_16x16x32_bf16(Bt[n][k], At[m][k], acc[ai][bj][m][n], 0, 0, 0); __builtin_amdgcn_s_setprio(0); } while (0)
; #define PG8_WAIT_V(n) asm volatile("s_waitcnt vmcnt(" #n ")" ::: "memory")
; #define PG8_WAIT_L(n) asm volatile("s_waitcnt lgkmcnt(" #n ")" ::: "memory")
; #define PG8_BAR __builtin_amdgcn_s_barrier()
; #define PG8_SCHED __builtin_amdgcn_sched_barrier(0)
; template <class Map, class Epi>
; DI void gemm_phase(LAS unsigned char* lds, const Map& MP, const Epi& E, const int nM, const int nN, const int K, const int lda, const int ldb) {
;     ...
;             PG8_LDA(At, 1, 1); PG8_STAGE(PG8_SA(1, 0), a3, voffA);
;             PG8_BAR; PG8_WAIT_L(0); PG8_MMA(1, 0, At, B0); PG8_BAR; PG8_SCHED;
;             PG8_STAGE(PG8_SB(1, 1), b3 + hstepB, voffB);
;             PG8_WAIT_V(6); PG8_BAR; PG8_MMA(1, 1, At, B1); PG8_BAR;
	ds_read_b128 v[96:99], v190 offset:49152
	ds_read_b128 v[100:103], v190 offset:50176
	ds_read_b128 v[108:111], v190 offset:51200
	ds_read_b128 v[112:115], v190 offset:52224
	ds_read_b128 v[160:163], v190 offset:53248
	ds_read_b128 v[164:167], v190 offset:54272
	ds_read_b128 v[198:201], v190 offset:55296
	ds_read_b128 v[202:205], v190 offset:56320
	global_load_lds_dwordx4 v[184:185], off
	v_lshl_add_u64 v[184:185], v[234:235], 0, s[14:15]
	s_mov_b32 m0, s63
	s_nop 0
	global_load_lds_dwordx4 v[184:185], off
	s_barrier
	s_setprio 1
	s_waitcnt lgkmcnt(7)
	v_mfma_f32_16x16x32_bf16 v[60:63], v[80:83], v[96:99], v[60:63]
	v_mfma_f32_16x16x32_bf16 v[48:51], v[88:91], v[96:99], v[48:51]
	s_waitcnt lgkmcnt(5)
	v_mfma_f32_16x16x32_bf16 v[40:43], v[80:83], v[108:111], v[40:43]
	v_mfma_f32_16x16x32_bf16 v[32:35], v[88:91], v[108:111], v[32:35]
	s_waitcnt lgkmcnt(3)
	v_mfma_f32_16x16x32_bf16 v[24:27], v[80:83], v[160:163], v[24:27]
	v_mfma_f32_16x16x32_bf16 v[16:19], v[88:91], v[160:163], v[16:19]
	s_waitcnt lgkmcnt(1)
	v_mfma_f32_16x16x32_bf16 v[12:15], v[80:83], v[198:201], v[12:15]
	v_mfma_f32_16x16x32_bf16 v[8:11], v[88:91], v[198:201], v[8:11]
	v_mfma_f32_16x16x32_bf16 v[60:63], v[84:87], v[100:103], v[60:63]
	v_mfma_f32_16x16x32_bf16 v[48:51], v[92:95], v[100:103], v[48:51]
	v_mfma_f32_16x16x32_bf16 v[40:43], v[84:87], v[112:115], v[40:43]
	v_mfma_f32_16x16x32_bf16 v[32:35], v[92:95], v[112:115], v[32:35]
	v_mfma_f32_16x16x32_bf16 v[24:27], v[84:87], v[164:167], v[24:27]
	v_mfma_f32_16x16x32_bf16 v[16:19], v[92:95], v[164:167], v[16:19]
	s_waitcnt lgkmcnt(0)
	v_mfma_f32_16x16x32_bf16 v[12:15], v[84:87], v[202:205], v[12:15]
	v_mfma_f32_16x16x32_bf16 v[8:11], v[92:95], v[202:205], v[8:11]
	s_setprio 0
	s_barrier
	s_add_u32 s28, s28, 0x80080
	s_addc_u32 s29, s29, 0
	s_add_i32 s46, s46, s37
	v_lshl_add_u64 v[80:81], s[28:29], 0, v[172:173]
	s_mov_b32 m0, s46
	s_nop 0
	global_load_lds_dwordx4 v[80:81], off
	v_lshl_add_u64 v[80:81], s[28:29], 0, v[168:169]
	s_add_i32 m0, s46, 0x2000
	s_nop 0
	global_load_lds_dwordx4 v[80:81], off
	s_waitcnt vmcnt(6)
	s_barrier
	s_setprio 1
	v_mfma_f32_16x16x32_bf16 v[56:59], v[214:217], v[96:99], v[56:59]
	v_mfma_f32_16x16x32_bf16 v[52:55], v[222:225], v[96:99], v[52:55]
	v_mfma_f32_16x16x32_bf16 v[44:47], v[214:217], v[108:111], v[44:47]
	v_mfma_f32_16x16x32_bf16 v[36:39], v[222:225], v[108:111], v[36:39]
	v_mfma_f32_16x16x32_bf16 v[28:31], v[214:217], v[160:163], v[28:31]
	v_mfma_f32_16x16x32_bf16 v[20:23], v[222:225], v[160:163], v[20:23]
	v_mfma_f32_16x16x32_bf16 v[4:7], v[214:217], v[198:201], v[4:7]
	v_mfma_f32_16x16x32_bf16 v[0:3], v[222:225], v[198:201], v[0:3]
	v_mfma_f32_16x16x32_bf16 v[56:59], v[218:221], v[100:103], v[56:59]
	v_mfma_f32_16x16x32_bf16 v[52:55], v[230:233], v[100:103], v[52:55]
	v_mfma_f32_16x16x32_bf16 v[44:47], v[218:221], v[112:115], v[44:47]
	v_mfma_f32_16x16x32_bf16 v[36:39], v[230:233], v[112:115], v[36:39]
	v_mfma_f32_16x16x32_bf16 v[28:31], v[218:221], v[164:167], v[28:31]
	v_mfma_f32_16x16x32_bf16 v[20:23], v[230:233], v[164:167], v[20:23]
	v_mfma_f32_16x16x32_bf16 v[4:7], v[218:221], v[202:205], v[4:7]
	v_mfma_f32_16x16x32_bf16 v[0:3], v[230:233], v[202:205], v[0:3]
	s_setprio 0
	s_add_i32 vcc_hi, vcc_hi, 2
	s_add_u32 s59, s59, 0x100
	s_addc_u32 vcc_lo, vcc_lo, 0
	s_add_u32 s44, s44, 0x100
	s_addc_u32 s45, s45, 0
	s_cmp_gt_u32 vcc_hi, 29
	s_barrier
	s_cbranch_scc0 .LBB1_380
; DI float silu_mul(float g, float v) { return g * v * __builtin_amdgcn_rcpf(1.0f + __builtin_amdgcn_exp2f(-LOG2E * g)); }
;     DI void operator()(const f32x4 (&acc)[2][2][4][2], const Unit& u, int wr, int wc, int fr, int fq) const {
;         const int row0 = u.pm * BM + wr * 64 + fr, ch0 = u.pn * 128 + wc * 32 + 8 * fq;
;         f32x4 w0[2], w1[2], w2[2], bb[2];
; #pragma unroll
;         for (int n = 0; n < 2; ++n) { w0[n] = *(const f32x4*)(cw + ch0 + 4 * n); w1[n] = *(const f32x4*)(cw + DFF + ch0 + 4 * n); w2[n] = *(const f32x4*)(cw + 2 * DFF + ch0 + 4 * n); bb[n] = *(const f32x4*)(cb + ch0 + 4 * n); }
; #pragma unroll
;         for (int ai = 0; ai < 2; ++ai)
; #pragma unroll
;             for (int m = 0; m < 4; ++m) {
;                 const bool efirst = (m == 0) && (fr == 0), elast = (m == 3) && (fr == 15);
;                 const int row = row0 + ai * HALF + m * 16;
;                 f32x4 gc[2];
; #pragma unroll
;                 for (int n = 0; n < 2; ++n) {
;                     const f32x4 g = acc[ai][0][m][n];
;                     const f32x4 gprev = acc[ai][0][m > 0 ? m - 1 : 0][n], gnext = acc[ai][0][m < 3 ? m + 1 : 3][n];
;                     f32x4 up, dn;
; #pragma unroll
;                     for (int e = 0; e < 4; ++e) {
;                         const float pu = (m > 0 && fr == 15) ? gprev[e] : g[e];
;                         const float pd = (m < 3 && fr == 0) ? gnext[e] : g[e];
;                         up[e] = dpp_ror1(pu); dn[e] = dpp_ror15(pd);
;                     }
;                     if (efirst) up = (f32x4){0.f, 0.f, 0.f, 0.f};
;                     if (elast) dn = (f32x4){0.f, 0.f, 0.f, 0.f};
;                     gc[n] = w0[n] * up + w1[n] * g + w2[n] * dn + bb[n];
;                 }
;                 if (efirst || elast) {
;                     const size_t eo = (size_t)((row >> 6) * 2 + (elast ? 1 : 0)) * DFF + ch0;
; #pragma unroll
;                     for (int n = 0; n < 2; ++n) { *(f32x4*)(EP + eo + 4 * n) = gc[n]; *(f32x4*)(ER + eo + 4 * n) = acc[ai][0][m][n]; *(f32x4*)(EV + eo + 4 * n) = acc[ai][1][m][n]; }
;                 } else {
;                     const f32x4 v0 = acc[ai][1][m][0], v1 = acc[ai][1][m][1];
;                     u32x4 o;
;                     o[0] = pack2(silu_mul(gc[0][0], v0[0]), silu_mul(gc[0][1], v0[1])); o[1] = pack2(silu_mul(gc[0][2], v0[2]), silu_mul(gc[0][3], v0[3]));
	s_lshl_b32 s23, s43, 7
	v_mov_b32_e32 v194, v186
	v_mov_b32_e32 v80, v187
	s_or_b32 s23, s23, s67
	v_mov_b32_e32 v160, 0
	v_lshl_add_u32 v184, v80, 3, s23
	v_ashrrev_i32_e32 v185, 31, v184
	v_lshlrev_b64 v[80:81], 2, v[184:185]
	v_lshl_add_u64 v[84:85], s[52:53], 0, v[80:81]
	v_lshl_add_u64 v[88:89], s[16:17], 0, v[80:81]
	v_lshl_add_u64 v[92:93], s[18:19], 0, v[80:81]
	v_lshl_add_u64 v[112:113], s[54:55], 0, v[80:81]
	global_load_dwordx4 v[80:83], v[84:85], off offset:16
	global_load_dwordx4 v[96:99], v[84:85], off
	s_nop 0
	global_load_dwordx4 v[84:87], v[88:89], off offset:16
	global_load_dwordx4 v[100:103], v[88:89], off
	s_nop 0
	global_load_dwordx4 v[88:91], v[92:93], off offset:16
	global_load_dwordx4 v[108:111], v[92:93], off
	s_nop 0
	global_load_dwordx4 v[92:95], v[112:113], off offset:16
	s_nop 0
	global_load_dwordx4 v[112:115], v[112:113], off
	v_cmp_eq_u32_e32 vcc, 0, v194
	v_mov_b32_e32 v164, 0
	v_mov_b32_e32 v195, 0
	v_cndmask_b32_e32 v161, v148, v136, vcc
	v_cndmask_b32_e32 v162, v149, v137, vcc
	v_cndmask_b32_e32 v163, v150, v138, vcc
	v_mov_b32_dpp v160, v161 row_ror:15 row_mask:0xf bank_mask:0xf
	v_mov_b32_e32 v161, 0
	v_mov_b32_e32 v166, 0
	v_mov_b32_e32 v167, 0
	v_mov_b32_dpp v161, v162 row_ror:15 row_mask:0xf bank_mask:0xf
	v_mov_b32_e32 v162, 0
	v_mov_b32_dpp v164, v150 row_ror:1 row_mask:0xf bank_mask:0xf
	v_cndmask_b32_e32 v165, v151, v139, vcc
	v_mov_b32_dpp v162, v163 row_ror:15 row_mask:0xf bank_mask:0xf
	v_mov_b32_dpp v195, v151 row_ror:1 row_mask:0xf bank_mask:0xf
	v_mov_b32_e32 v163, 0
	v_mov_b32_dpp v166, v148 row_ror:1 row_mask:0xf bank_mask:0xf
	v_mov_b32_dpp v167, v149 row_ror:1 row_mask:0xf bank_mask:0xf
	v_mov_b32_dpp v163, v165 row_ror:15 row_mask:0xf bank_mask:0xf
	v_cndmask_b32_e64 v165, v195, 0, vcc
	v_cndmask_b32_e64 v164, v164, 0, vcc
	v_cndmask_b32_e64 v167, v167, 0, vcc
	v_cndmask_b32_e64 v166, v166, 0, vcc
	v_mov_b32_e32 v195, 0
	v_mov_b32_e32 v196, 0
	v_mov_b32_e32 v198, 0
	v_mov_b32_e32 v200, 0
	v_mov_b32_dpp v195, v144 row_ror:1 row_mask:0xf bank_mask:0xf
	v_mov_b32_dpp v196, v145 row_ror:1 row_mask:0xf bank_mask:0xf
	v_mov_b32_dpp v198, v146 row_ror:1 row_mask:0xf bank_mask:0xf
	v_cndmask_b32_e32 v199, v147, v131, vcc
	v_mov_b32_dpp v200, v147 row_ror:1 row_mask:0xf bank_mask:0xf
	v_cndmask_b32_e64 v198, v198, 0, vcc
	v_cndmask_b32_e64 v201, v196, 0, vcc
	s_lshl_b32 s21, s42, 8
	s_add_i32 s21, s21, s49
	v_add_u32_e32 v193, s21, v194
	v_cmp_ne_u32_e64 s[46:47], 0, v194
	s_waitcnt vmcnt(0)
	v_pk_mul_f32 v[164:165], v[98:99], v[164:165]
	v_pk_mul_f32 v[166:167], v[96:97], v[166:167]
	v_pk_fma_f32 v[164:165], v[150:151], v[102:103], v[164:165]
	v_pk_fma_f32 v[166:167], v[148:149], v[100:101], v[166:167]
	v_pk_fma_f32 v[162:163], v[110:111], v[162:163], v[164:165]
	v_cndmask_b32_e32 v165, v144, v128, vcc
	v_mov_b32_e32 v164, 0
	v_pk_fma_f32 v[160:161], v[108:109], v[160:161], v[166:167]
	v_cndmask_b32_e32 v166, v145, v129, vcc
	v_mov_b32_dpp v164, v165 row_ror:15 row_mask:0xf bank_mask:0xf
	v_mov_b32_e32 v165, 0
	v_cndmask_b32_e32 v167, v146, v130, vcc
	v_pk_add_f32 v[162:163], v[114:115], v[162:163]
	v_mov_b32_dpp v165, v166 row_ror:15 row_mask:0xf bank_mask:0xf
	v_mov_b32_e32 v166, 0
	v_pk_add_f32 v[160:161], v[112:113], v[160:161]
	s_nop 0
	v_mov_b32_dpp v166, v167 row_ror:15 row_mask:0xf bank_mask:0xf
	v_mov_b32_e32 v167, 0
	s_nop 1
	v_mov_b32_dpp v167, v199 row_ror:15 row_mask:0xf bank_mask:0xf
	v_cndmask_b32_e64 v199, v200, 0, vcc
	v_cndmask_b32_e64 v200, v195, 0, vcc
	v_pk_mul_f32 v[200:201], v[80:81], v[200:201]
	v_pk_mul_f32 v[198:199], v[82:83], v[198:199]
	v_pk_fma_f32 v[200:201], v[144:145], v[84:85], v[200:201]
	v_pk_fma_f32 v[198:199], v[146:147], v[86:87], v[198:199]
	v_pk_fma_f32 v[164:165], v[88:89], v[164:165], v[200:201]
	v_pk_fma_f32 v[166:167], v[90:91], v[166:167], v[198:199]
	v_pk_add_f32 v[164:165], v[92:93], v[164:165]
	v_pk_add_f32 v[166:167], v[94:95], v[166:167]
	s_and_saveexec_b64 s[28:29], s[46:47]
	s_xor_b64 s[28:29], exec, s[28:29]
	s_cbranch_execz .LBB1_383
	v_mul_f32_e32 v195, 0xbfb8aa3b, v160
	v_exp_f32_e32 v195, v195
	v_mul_f32_e32 v196, 0xbfb8aa3b, v161
	v_exp_f32_e32 v196, v196
	v_pk_mul_f32 v[160:161], v[156:157], v[160:161]
	v_add_f32_e32 v195, 1.0, v195
	v_rcp_f32_e32 v198, v195
	v_add_f32_e32 v196, 1.0, v196
	v_mul_f32_e32 v195, 0xbfb8aa3b, v162
	v_rcp_f32_e32 v199, v196
	v_exp_f32_e32 v195, v195
	v_mul_f32_e32 v196, 0xbfb8aa3b, v163
	v_exp_f32_e32 v196, v196
	v_pk_mul_f32 v[160:161], v[160:161], v[198:199]
	v_add_f32_e32 v195, 1.0, v195
	v_rcp_f32_e32 v200, v195
	v_add_f32_e32 v195, 1.0, v196
	v_rcp_f32_e32 v201, v195
	v_cvt_pk_bf16_f32 v160, v160, v161
	v_mul_f32_e32 v161, 0xbfb8aa3b, v164
	v_exp_f32_e32 v195, v161
	v_mul_f32_e32 v161, 0xbfb8aa3b, v165
	v_exp_f32_e32 v196, v161
	v_pk_mul_f32 v[162:163], v[158:159], v[162:163]
	v_pk_mul_f32 v[164:165], v[152:153], v[164:165]
	v_pk_mul_f32 v[162:163], v[162:163], v[200:201]
	s_nop 0
	v_cvt_pk_bf16_f32 v161, v162, v163
	v_add_f32_e32 v162, 1.0, v195
	v_mul_f32_e32 v195, 0xbfb8aa3b, v166
	v_add_f32_e32 v163, 1.0, v196
	v_exp_f32_e32 v195, v195
	v_mul_f32_e32 v196, 0xbfb8aa3b, v167
	v_exp_f32_e32 v196, v196
	v_rcp_f32_e32 v162, v162
	v_add_f32_e32 v195, 1.0, v195
	v_rcp_f32_e32 v198, v195
	v_add_f32_e32 v195, 1.0, v196
	v_rcp_f32_e32 v163, v163
	v_rcp_f32_e32 v199, v195
	v_pk_mul_f32 v[166:167], v[154:155], v[166:167]
	v_pk_mul_f32 v[162:163], v[164:165], v[162:163]
	v_pk_mul_f32 v[164:165], v[166:167], v[198:199]
	v_cvt_pk_bf16_f32 v162, v162, v163
	v_cvt_pk_bf16_f32 v163, v164, v165
	v_mov_b64_e32 v[164:165], s[6:7]
	v_mad_i64_i32 v[164:165], s[42:43], v193, s30, v[164:165]
	v_lshl_add_u64 v[164:165], v[184:185], 1, v[164:165]
	flat_store_dwordx4 v[164:165], v[160:163]

; #define PG8_STAGE(bufoff, gbase, voff) do { _Pragma("unroll") for (int _i = 0; _i < 2; ++_i) \
;         __builtin_amdgcn_global_load_lds((const unsigned*)((const char*)(gbase) + (voff)[_i]), (LAS unsigned*)(lds + (bufoff) + ldsw + _i * 8192), 16, 0, 0); } while (0)
; #define PG8_LDA(dst, b, h) do { _Pragma("unroll") for (int m = 0; m < 4; ++m) _Pragma("unroll") for (int k = 0; k < 2; ++k) dst[m][k] = *(const LAS bf16x8*)(lds + PG8_SA(b, h) + aoff + m * 2048 + k * 1024); } while (0)
; #define PG8_LDB(dst, b, h) do { _Pragma("unroll") for (int n = 0; n < 2; ++n) _Pragma("unroll") for (int k = 0; k < 2; ++k) dst[n][k] = *(const LAS bf16x8*)(lds + PG8_SB(b, h) + boff + n * 2048 + k * 1024); } while (0)
; #define PG8_MMA(ai, bj, At, Bt) do { __builtin_amdgcn_s_setprio(1); _Pragma("unroll") for (int m = 0; m < 4; ++m) _Pragma("unroll") for (int n = 0; n < 2; ++n) _Pragma("unroll") for (int k = 0; k < 2; ++k) \
;         acc[ai][bj][m][n] = __builtin_amdgcn_mfma_f32_16x16x32_bf16(Bt[n][k], At[m][k], acc[ai][bj][m][n], 0, 0, 0); __builtin_amdgcn_s_setprio(0); } while (0)
; #define PG8_WAIT_L(n) asm volatile("s_waitcnt lgkmcnt(" #n ")" ::: "memory")
; #define PG8_BAR __builtin_amdgcn_s_barrier()
; #define PG8_SCHED __builtin_amdgcn_sched_barrier(0)
; template <class Map, class Epi>
; DI void gemm_phase(LAS unsigned char* lds, const Map& MP, const Epi& E, const int nM, const int nN, const int K, const int lda, const int ldb) {
;     ...
;             PG8_LDB(B0, 0, 0); PG8_SCHED; PG8_LDA(At, 0, 0); PG8_STAGE(PG8_SA(1, 1), a1 + hstepA, voffA);
;             PG8_WAIT_L(8); PG8_BAR; PG8_WAIT_L(0); PG8_MMA(0, 0, At, B0); PG8_BAR; PG8_SCHED;
;             PG8_LDB(B1, 0, 1); PG8_STAGE(PG8_SB(0, 0), b2, voffB);
;             PG8_BAR; PG8_WAIT_L(0); PG8_MMA(0, 1, At, B1); PG8_BAR;
;             PG8_LDA(At, 0, 1); PG8_STAGE(PG8_SA(0, 0), a2, voffA);
;             PG8_BAR; PG8_WAIT_L(0); PG8_MMA(1, 0, At, B0); PG8_BAR; PG8_SCHED;
.LBB1_550:
	ds_read_b128 v[152:155], v149
	ds_read_b128 v[156:159], v149 offset:1024
	ds_read_b128 v[160:163], v149 offset:2048
	ds_read_b128 v[164:167], v149 offset:3072
	s_add_u32 s10, s8, 0x100
	s_addc_u32 s11, s9, 0
	s_cmpk_eq_i32 s3, 0x54
	s_cselect_b32 s15, s43, s11
	s_cselect_b32 s14, s42, s10
	s_cselect_b32 s13, s7, s38
	s_cselect_b32 s12, s6, s5
	v_lshl_add_u64 v[144:145], s[8:9], 0, v[138:139]
	s_add_i32 m0, s24, 0xc000
	ds_read_b128 v[168:171], v150
	ds_read_b128 v[172:175], v150 offset:1024
	ds_read_b128 v[176:179], v150 offset:2048
	ds_read_b128 v[180:183], v150 offset:3072
	ds_read_b128 v[184:187], v150 offset:4096
	ds_read_b128 v[188:191], v150 offset:5120
	ds_read_b128 v[192:195], v150 offset:6144
	ds_read_b128 v[198:201], v150 offset:7168
	global_load_lds_dwordx4 v[144:145], off
	v_lshl_add_u64 v[144:145], s[8:9], 0, v[136:137]
	s_add_i32 m0, s24, 0xe000
	s_nop 0
	global_load_lds_dwordx4 v[144:145], off
	s_waitcnt lgkmcnt(8)
	s_barrier
	s_setprio 1
	s_waitcnt lgkmcnt(7)
	v_mfma_f32_16x16x32_bf16 v[124:127], v[152:155], v[168:171], v[124:127]
	v_mfma_f32_16x16x32_bf16 v[120:123], v[160:163], v[168:171], v[120:123]
	s_waitcnt lgkmcnt(5)
	v_mfma_f32_16x16x32_bf16 v[108:111], v[152:155], v[176:179], v[108:111]
	v_mfma_f32_16x16x32_bf16 v[104:107], v[160:163], v[176:179], v[104:107]
	s_waitcnt lgkmcnt(3)
	v_mfma_f32_16x16x32_bf16 v[92:95], v[152:155], v[184:187], v[92:95]
	v_mfma_f32_16x16x32_bf16 v[88:91], v[160:163], v[184:187], v[88:91]
	s_waitcnt lgkmcnt(1)
	v_mfma_f32_16x16x32_bf16 v[76:79], v[152:155], v[192:195], v[76:79]
	v_mfma_f32_16x16x32_bf16 v[72:75], v[160:163], v[192:195], v[72:75]
	v_mfma_f32_16x16x32_bf16 v[124:127], v[156:159], v[172:175], v[124:127]
	v_mfma_f32_16x16x32_bf16 v[120:123], v[164:167], v[172:175], v[120:123]
	v_mfma_f32_16x16x32_bf16 v[108:111], v[156:159], v[180:183], v[108:111]
	v_mfma_f32_16x16x32_bf16 v[104:107], v[164:167], v[180:183], v[104:107]
	v_mfma_f32_16x16x32_bf16 v[92:95], v[156:159], v[188:191], v[92:95]
	v_mfma_f32_16x16x32_bf16 v[88:91], v[164:167], v[188:191], v[88:91]
	s_waitcnt lgkmcnt(0)
	v_mfma_f32_16x16x32_bf16 v[76:79], v[156:159], v[198:201], v[76:79]
	v_mfma_f32_16x16x32_bf16 v[72:75], v[164:167], v[198:201], v[72:75]
	s_setprio 0
	s_barrier
	s_add_i32 s8, s35, s22
	v_lshl_add_u64 v[144:145], s[12:13], 0, v[132:133]
	s_mov_b32 m0, s8
	ds_read_b128 v[202:205], v151
	ds_read_b128 v[206:209], v151 offset:1024
	ds_read_b128 v[210:213], v151 offset:2048
	ds_read_b128 v[214:217], v151 offset:3072
	global_load_lds_dwordx4 v[144:145], off
	v_lshl_add_u64 v[218:219], s[12:13], 0, v[128:129]
	s_add_i32 m0, s8, 0x2000
	s_nop 0
	global_load_lds_dwordx4 v[218:219], off
	s_barrier
	s_setprio 1
	s_waitcnt lgkmcnt(3)
	v_mfma_f32_16x16x32_bf16 v[116:119], v[202:205], v[168:171], v[116:119]
	s_waitcnt lgkmcnt(1)
	v_mfma_f32_16x16x32_bf16 v[112:115], v[210:213], v[168:171], v[112:115]
	v_mfma_f32_16x16x32_bf16 v[100:103], v[202:205], v[176:179], v[100:103]
	v_mfma_f32_16x16x32_bf16 v[96:99], v[210:213], v[176:179], v[96:99]
	v_mfma_f32_16x16x32_bf16 v[84:87], v[202:205], v[184:187], v[84:87]
	v_mfma_f32_16x16x32_bf16 v[80:83], v[210:213], v[184:187], v[80:83]
	v_mfma_f32_16x16x32_bf16 v[68:71], v[202:205], v[192:195], v[68:71]
	v_mfma_f32_16x16x32_bf16 v[64:67], v[210:213], v[192:195], v[64:67]
	v_mfma_f32_16x16x32_bf16 v[116:119], v[206:209], v[172:175], v[116:119]
	s_waitcnt lgkmcnt(0)
	v_mfma_f32_16x16x32_bf16 v[112:115], v[214:217], v[172:175], v[112:115]
	v_mfma_f32_16x16x32_bf16 v[100:103], v[206:209], v[180:183], v[100:103]
	v_mfma_f32_16x16x32_bf16 v[96:99], v[214:217], v[180:183], v[96:99]
	v_mfma_f32_16x16x32_bf16 v[84:87], v[206:209], v[188:191], v[84:87]
	v_mfma_f32_16x16x32_bf16 v[80:83], v[214:217], v[188:191], v[80:83]
	v_mfma_f32_16x16x32_bf16 v[68:71], v[206:209], v[198:201], v[68:71]
	v_mfma_f32_16x16x32_bf16 v[64:67], v[214:217], v[198:201], v[64:67]
	s_setprio 0
	s_mov_b32 m0, s24
	v_lshl_add_u64 v[220:221], s[14:15], 0, v[134:135]
	s_barrier
	ds_read_b128 v[168:171], v150 offset:16384
	ds_read_b128 v[172:175], v150 offset:17408
	ds_read_b128 v[176:179], v150 offset:18432
	ds_read_b128 v[180:183], v150 offset:19456
	ds_read_b128 v[184:187], v150 offset:20480
	ds_read_b128 v[188:191], v150 offset:21504
	ds_read_b128 v[192:195], v150 offset:22528
	ds_read_b128 v[198:201], v150 offset:23552
	global_load_lds_dwordx4 v[220:221], off
	v_lshl_add_u64 v[222:223], s[14:15], 0, v[130:131]
	s_mov_b32 m0, s25
	s_nop 0
	global_load_lds_dwordx4 v[222:223], off
	s_barrier
	s_setprio 1
	s_waitcnt lgkmcnt(7)
	v_mfma_f32_16x16x32_bf16 v[60:63], v[152:155], v[168:171], v[60:63]
	v_mfma_f32_16x16x32_bf16 v[56:59], v[160:163], v[168:171], v[56:59]
	s_waitcnt lgkmcnt(5)
	v_mfma_f32_16x16x32_bf16 v[44:47], v[152:155], v[176:179], v[44:47]
	v_mfma_f32_16x16x32_bf16 v[40:43], v[160:163], v[176:179], v[40:43]
	s_waitcnt lgkmcnt(3)
	v_mfma_f32_16x16x32_bf16 v[28:31], v[152:155], v[184:187], v[28:31]
	v_mfma_f32_16x16x32_bf16 v[24:27], v[160:163], v[184:187], v[24:27]
	s_waitcnt lgkmcnt(1)
	v_mfma_f32_16x16x32_bf16 v[12:15], v[152:155], v[192:195], v[12:15]
	v_mfma_f32_16x16x32_bf16 v[8:11], v[160:163], v[192:195], v[8:11]
	v_mfma_f32_16x16x32_bf16 v[60:63], v[156:159], v[172:175], v[60:63]
	v_mfma_f32_16x16x32_bf16 v[56:59], v[164:167], v[172:175], v[56:59]
	v_mfma_f32_16x16x32_bf16 v[44:47], v[156:159], v[180:183], v[44:47]
	v_mfma_f32_16x16x32_bf16 v[40:43], v[164:167], v[180:183], v[40:43]
	v_mfma_f32_16x16x32_bf16 v[28:31], v[156:159], v[188:191], v[28:31]
	v_mfma_f32_16x16x32_bf16 v[24:27], v[164:167], v[188:191], v[24:27]
	s_waitcnt lgkmcnt(0)
	v_mfma_f32_16x16x32_bf16 v[12:15], v[156:159], v[198:201], v[12:15]
	v_mfma_f32_16x16x32_bf16 v[8:11], v[164:167], v[198:201], v[8:11]
	s_setprio 0
	s_barrier
; #define PG8_STAGE(bufoff, gbase, voff) do { _Pragma("unroll") for (int _i = 0; _i < 2; ++_i) \
;         __builtin_amdgcn_global_load_lds((const unsigned*)((const char*)(gbase) + (voff)[_i]), (LAS unsigned*)(lds + (bufoff) + ldsw + _i * 8192), 16, 0, 0); } while (0)
; #define PG8_LDA(dst, b, h) do { _Pragma("unroll") for (int m = 0; m < 4; ++m) _Pragma("unroll") for (int k = 0; k < 2; ++k) dst[m][k] = *(const LAS bf16x8*)(lds + PG8_SA(b, h) + aoff + m * 2048 + k * 1024); } while (0)
; #define PG8_LDB(dst, b, h) do { _Pragma("unroll") for (int n = 0; n < 2; ++n) _Pragma("unroll") for (int k = 0; k < 2; ++k) dst[n][k] = *(const LAS bf16x8*)(lds + PG8_SB(b, h) + boff + n * 2048 + k * 1024); } while (0)
; #define PG8_MMA(ai, bj, At, Bt) do { __builtin_amdgcn_s_setprio(1); _Pragma("unroll") for (int m = 0; m < 4; ++m) _Pragma("unroll") for (int n = 0; n < 2; ++n) _Pragma("unroll") for (int k = 0; k < 2; ++k) \
;         acc[ai][bj][m][n] = __builtin_amdgcn_mfma_f32_16x16x32_bf16(Bt[n][k], At[m][k], acc[ai][bj][m][n], 0, 0, 0); __builtin_amdgcn_s_setprio(0); } while (0)
; #define PG8_WAIT_V(n) asm volatile("s_waitcnt vmcnt(" #n ")" ::: "memory")
; #define PG8_WAIT_L(n) asm volatile("s_waitcnt lgkmcnt(" #n ")" ::: "memory")
; #define PG8_BAR __builtin_amdgcn_s_barrier()
; #define PG8_SCHED __builtin_amdgcn_sched_barrier(0)
; template <class Map, class Epi>
; DI void gemm_phase(LAS unsigned char* lds, const Map& MP, const Epi& E, const int nM, const int nN, const int K, const int lda, const int ldb) {
;     ...
;             PG8_STAGE(PG8_SB(0, 1), b2 + hstepB, voffB);
;             PG8_WAIT_V(6); PG8_BAR; PG8_MMA(1, 1, At, B1); PG8_BAR;
;             PG8_LDB(B0, 1, 0); PG8_SCHED; PG8_LDA(At, 1, 0); PG8_STAGE(PG8_SA(0, 1), a2 + hstepA, voffA);
;             PG8_WAIT_L(8); PG8_BAR; PG8_WAIT_L(0); PG8_MMA(0, 0, At, B0); PG8_BAR; PG8_SCHED;
;             PG8_LDB(B1, 1, 1); PG8_STAGE(PG8_SB(1, 0), b3, voffB);
;             PG8_BAR; PG8_WAIT_L(0); PG8_MMA(0, 1, At, B1); PG8_BAR;
;             PG8_LDA(At, 1, 1); PG8_STAGE(PG8_SA(1, 0), a3, voffA);
	s_add_u32 s8, s12, 0x160000
	s_addc_u32 s9, s13, 0
	s_add_i32 s39, s36, s22
	v_lshl_add_u64 v[152:153], s[8:9], 0, v[132:133]
	s_mov_b32 m0, s39
	s_nop 0
	global_load_lds_dwordx4 v[152:153], off
	v_lshl_add_u64 v[152:153], s[8:9], 0, v[128:129]
	s_add_i32 m0, s39, 0x2000
	s_nop 0
	global_load_lds_dwordx4 v[152:153], off
	s_waitcnt vmcnt(6)
	s_barrier
	s_setprio 1
	v_mfma_f32_16x16x32_bf16 v[52:55], v[202:205], v[168:171], v[52:55]
	v_mfma_f32_16x16x32_bf16 v[48:51], v[210:213], v[168:171], v[48:51]
	v_mfma_f32_16x16x32_bf16 v[36:39], v[202:205], v[176:179], v[36:39]
	v_mfma_f32_16x16x32_bf16 v[32:35], v[210:213], v[176:179], v[32:35]
	v_mfma_f32_16x16x32_bf16 v[20:23], v[202:205], v[184:187], v[20:23]
	v_mfma_f32_16x16x32_bf16 v[16:19], v[210:213], v[184:187], v[16:19]
	v_mfma_f32_16x16x32_bf16 v[4:7], v[202:205], v[192:195], v[4:7]
	v_mfma_f32_16x16x32_bf16 v[0:3], v[210:213], v[192:195], v[0:3]
	v_mfma_f32_16x16x32_bf16 v[52:55], v[206:209], v[172:175], v[52:55]
	v_mfma_f32_16x16x32_bf16 v[48:51], v[214:217], v[172:175], v[48:51]
	v_mfma_f32_16x16x32_bf16 v[36:39], v[206:209], v[180:183], v[36:39]
	v_mfma_f32_16x16x32_bf16 v[32:35], v[214:217], v[180:183], v[32:35]
	v_mfma_f32_16x16x32_bf16 v[20:23], v[206:209], v[188:191], v[20:23]
	v_mfma_f32_16x16x32_bf16 v[16:19], v[214:217], v[188:191], v[16:19]
	v_mfma_f32_16x16x32_bf16 v[4:7], v[206:209], v[198:201], v[4:7]
	v_mfma_f32_16x16x32_bf16 v[0:3], v[214:217], v[198:201], v[0:3]
	s_setprio 0
	s_add_i32 s39, 0, 0x18000
	v_add_u32_e32 v164, s39, v148
	s_barrier
	ds_read_b128 v[152:155], v164
	ds_read_b128 v[156:159], v164 offset:1024
	ds_read_b128 v[160:163], v164 offset:2048
	ds_read_b128 v[164:167], v164 offset:3072
	s_add_u32 s8, s14, 0x160000
	s_addc_u32 s9, s15, 0
	s_mov_b32 m0, s26
	v_lshl_add_u64 v[202:203], s[8:9], 0, v[134:135]
	ds_read_b128 v[168:171], v150 offset:32768
	ds_read_b128 v[172:175], v150 offset:33792
	ds_read_b128 v[176:179], v150 offset:34816
	ds_read_b128 v[180:183], v150 offset:35840
	ds_read_b128 v[184:187], v150 offset:36864
	ds_read_b128 v[188:191], v150 offset:37888
	ds_read_b128 v[192:195], v150 offset:38912
	ds_read_b128 v[198:201], v150 offset:39936
	global_load_lds_dwordx4 v[202:203], off
	v_lshl_add_u64 v[202:203], s[8:9], 0, v[130:131]
	s_mov_b32 m0, s27
	s_nop 0
	global_load_lds_dwordx4 v[202:203], off
	s_waitcnt lgkmcnt(8)
	s_barrier
	s_setprio 1
	s_waitcnt lgkmcnt(7)
	v_mfma_f32_16x16x32_bf16 v[124:127], v[152:155], v[168:171], v[124:127]
	v_mfma_f32_16x16x32_bf16 v[120:123], v[160:163], v[168:171], v[120:123]
	s_waitcnt lgkmcnt(5)
	v_mfma_f32_16x16x32_bf16 v[108:111], v[152:155], v[176:179], v[108:111]
	v_mfma_f32_16x16x32_bf16 v[104:107], v[160:163], v[176:179], v[104:107]
	s_waitcnt lgkmcnt(3)
	v_mfma_f32_16x16x32_bf16 v[92:95], v[152:155], v[184:187], v[92:95]
	v_mfma_f32_16x16x32_bf16 v[88:91], v[160:163], v[184:187], v[88:91]
	s_waitcnt lgkmcnt(1)
	v_mfma_f32_16x16x32_bf16 v[76:79], v[152:155], v[192:195], v[76:79]
	v_mfma_f32_16x16x32_bf16 v[72:75], v[160:163], v[192:195], v[72:75]
	v_mfma_f32_16x16x32_bf16 v[124:127], v[156:159], v[172:175], v[124:127]
	v_mfma_f32_16x16x32_bf16 v[120:123], v[164:167], v[172:175], v[120:123]
	v_mfma_f32_16x16x32_bf16 v[108:111], v[156:159], v[180:183], v[108:111]
	v_mfma_f32_16x16x32_bf16 v[104:107], v[164:167], v[180:183], v[104:107]
	v_mfma_f32_16x16x32_bf16 v[92:95], v[156:159], v[188:191], v[92:95]
	v_mfma_f32_16x16x32_bf16 v[88:91], v[164:167], v[188:191], v[88:91]
	s_waitcnt lgkmcnt(0)
	v_mfma_f32_16x16x32_bf16 v[76:79], v[156:159], v[198:201], v[76:79]
	v_mfma_f32_16x16x32_bf16 v[72:75], v[164:167], v[198:201], v[72:75]
	s_setprio 0
	s_barrier
	s_add_i32 s14, 0, 0x1c000
	s_add_i32 s8, s39, s22
	v_add_u32_e32 v196, s14, v148
	v_lshl_add_u64 v[144:145], v[144:145], 0, s[52:53]
	s_mov_b32 m0, s8
	ds_read_b128 v[202:205], v196
	ds_read_b128 v[206:209], v196 offset:1024
	ds_read_b128 v[210:213], v196 offset:2048
	ds_read_b128 v[214:217], v196 offset:3072
	global_load_lds_dwordx4 v[144:145], off
	v_lshl_add_u64 v[144:145], v[218:219], 0, s[52:53]
	s_add_i32 m0, s8, 0x2000
	s_nop 0
	global_load_lds_dwordx4 v[144:145], off
	s_barrier
	s_setprio 1
	s_waitcnt lgkmcnt(3)
	v_mfma_f32_16x16x32_bf16 v[116:119], v[202:205], v[168:171], v[116:119]
	s_waitcnt lgkmcnt(1)
	v_mfma_f32_16x16x32_bf16 v[112:115], v[210:213], v[168:171], v[112:115]
	v_mfma_f32_16x16x32_bf16 v[100:103], v[202:205], v[176:179], v[100:103]
	v_mfma_f32_16x16x32_bf16 v[96:99], v[210:213], v[176:179], v[96:99]
	v_mfma_f32_16x16x32_bf16 v[84:87], v[202:205], v[184:187], v[84:87]
	v_mfma_f32_16x16x32_bf16 v[80:83], v[210:213], v[184:187], v[80:83]
	v_mfma_f32_16x16x32_bf16 v[68:71], v[202:205], v[192:195], v[68:71]
	v_mfma_f32_16x16x32_bf16 v[64:67], v[210:213], v[192:195], v[64:67]
	v_mfma_f32_16x16x32_bf16 v[116:119], v[206:209], v[172:175], v[116:119]
	s_waitcnt lgkmcnt(0)
	v_mfma_f32_16x16x32_bf16 v[112:115], v[214:217], v[172:175], v[112:115]
	v_mfma_f32_16x16x32_bf16 v[100:103], v[206:209], v[180:183], v[100:103]
	v_mfma_f32_16x16x32_bf16 v[96:99], v[214:217], v[180:183], v[96:99]
	v_mfma_f32_16x16x32_bf16 v[84:87], v[206:209], v[188:191], v[84:87]
	v_mfma_f32_16x16x32_bf16 v[80:83], v[214:217], v[188:191], v[80:83]
	v_mfma_f32_16x16x32_bf16 v[68:71], v[206:209], v[198:201], v[68:71]
	v_mfma_f32_16x16x32_bf16 v[64:67], v[214:217], v[198:201], v[64:67]
	s_setprio 0
	s_mov_b32 m0, s30
	v_lshl_add_u64 v[144:145], v[220:221], 0, s[52:53]
	s_barrier
; DI unsigned pack2(float a, float b) { f32x2 v = {a, b}; hwbf16x2 r = __builtin_convertvector(v, hwbf16x2); return __builtin_bit_cast(unsigned, r); }
; DI float bflo(unsigned w) { return __uint_as_float(w << 16); }
; DI float bfhi(unsigned w) { return __uint_as_float(w & 0xffff0000u); }
;     DI void operator()(const f32x4 (&acc)[2][2][4][2], const Unit& u, int wr, int wc, int fr, int fq) const {
;         const int row0 = u.pm * BM + wr * 64 + fr, col0 = u.pn * BM + wc * 32 + 8 * fq;
;         f32x4 sc[2][2];
; #pragma unroll
;         for (int bj = 0; bj < 2; ++bj)
; #pragma unroll
;             for (int n = 0; n < 2; ++n) sc[bj][n] = scale ? *(const f32x4*)(scale + col0 + bj * HALF + 4 * n) : (f32x4){1.f, 1.f, 1.f, 1.f};
; #pragma unroll
;         for (int ai = 0; ai < 2; ++ai)
; #pragma unroll
;             for (int m = 0; m < 4; ++m) { const size_t ro = (size_t)(row0 + ai * HALF + m * 16) * D + col0;
; #pragma unroll
;                 for (int bj = 0; bj < 2; ++bj) {
;                     f32x4 x0, x1;
;                     if constexpr (IB) { const u32x4 w = *(const u32x4*)((const bf16_t*)Xin + ro + bj * HALF);
;                         x0 = (f32x4){bflo(w[0]), bfhi(w[0]), bflo(w[1]), bfhi(w[1])}; x1 = (f32x4){bflo(w[2]), bfhi(w[2]), bflo(w[3]), bfhi(w[3])}; }
;                     else { x0 = *(const f32x4*)((const float*)Xin + ro + bj * HALF); x1 = *(const f32x4*)((const float*)Xin + ro + bj * HALF + 4); }
;                     x0 += acc[ai][bj][m][0] * sc[bj][0]; x1 += acc[ai][bj][m][1] * sc[bj][1];
;                     if constexpr (OB) { u32x4 o; o[0] = pack2(x0[0], x0[1]); o[1] = pack2(x0[2], x0[3]); o[2] = pack2(x1[0], x1[1]); o[3] = pack2(x1[2], x1[3]);
;                         *(u32x4*)((bf16_t*)Xout + ro + bj * HALF) = o; }
;                     else { *(f32x4*)((float*)Xout + ro + bj * HALF) = x0; *(f32x4*)((float*)Xout + ro + bj * HALF + 4) = x1; } } }
; template <class Map, class Epi>
; DI void gemm_phase(LAS unsigned char* lds, const Map& MP, const Epi& E, const int nM, const int nN, const int K, const int lda, const int ldb) {
;     ...
;             PG8_LDA(At, 1, 1); PG8_STAGE(PG8_SA(1, 0), a3, voffA);
;             PG8_BAR; PG8_WAIT_L(0); PG8_MMA(1, 0, At, B0); PG8_BAR; PG8_SCHED;
;             PG8_STAGE(PG8_SB(1, 1), b3 + hstepB, voffB);
;             PG8_WAIT_V(6); PG8_BAR; PG8_MMA(1, 1, At, B1); PG8_BAR;
	ds_read_b128 v[168:171], v150 offset:49152
	ds_read_b128 v[172:175], v150 offset:50176
	ds_read_b128 v[176:179], v150 offset:51200
	ds_read_b128 v[180:183], v150 offset:52224
	ds_read_b128 v[184:187], v150 offset:53248
	ds_read_b128 v[188:191], v150 offset:54272
	ds_read_b128 v[192:195], v150 offset:55296
	ds_read_b128 v[198:201], v150 offset:56320
	global_load_lds_dwordx4 v[144:145], off
	v_lshl_add_u64 v[144:145], v[222:223], 0, s[52:53]
	s_mov_b32 m0, s31
	s_nop 0
	global_load_lds_dwordx4 v[144:145], off
	s_barrier
	s_setprio 1
	s_waitcnt lgkmcnt(7)
	v_mfma_f32_16x16x32_bf16 v[60:63], v[152:155], v[168:171], v[60:63]
	v_mfma_f32_16x16x32_bf16 v[56:59], v[160:163], v[168:171], v[56:59]
	s_waitcnt lgkmcnt(5)
	v_mfma_f32_16x16x32_bf16 v[44:47], v[152:155], v[176:179], v[44:47]
	v_mfma_f32_16x16x32_bf16 v[40:43], v[160:163], v[176:179], v[40:43]
	s_waitcnt lgkmcnt(3)
	v_mfma_f32_16x16x32_bf16 v[28:31], v[152:155], v[184:187], v[28:31]
	v_mfma_f32_16x16x32_bf16 v[24:27], v[160:163], v[184:187], v[24:27]
	s_waitcnt lgkmcnt(1)
	v_mfma_f32_16x16x32_bf16 v[12:15], v[152:155], v[192:195], v[12:15]
	v_mfma_f32_16x16x32_bf16 v[8:11], v[160:163], v[192:195], v[8:11]
	v_mfma_f32_16x16x32_bf16 v[60:63], v[156:159], v[172:175], v[60:63]
	v_mfma_f32_16x16x32_bf16 v[56:59], v[164:167], v[172:175], v[56:59]
	v_mfma_f32_16x16x32_bf16 v[44:47], v[156:159], v[180:183], v[44:47]
	v_mfma_f32_16x16x32_bf16 v[40:43], v[164:167], v[180:183], v[40:43]
	v_mfma_f32_16x16x32_bf16 v[28:31], v[156:159], v[188:191], v[28:31]
	v_mfma_f32_16x16x32_bf16 v[24:27], v[164:167], v[188:191], v[24:27]
	s_waitcnt lgkmcnt(0)
	v_mfma_f32_16x16x32_bf16 v[12:15], v[156:159], v[198:201], v[12:15]
	v_mfma_f32_16x16x32_bf16 v[8:11], v[164:167], v[198:201], v[8:11]
	s_setprio 0
	s_barrier
	s_add_u32 s8, s12, 0x160080
	s_addc_u32 s9, s13, 0
	s_add_i32 s12, s14, s22
	v_lshl_add_u64 v[144:145], s[8:9], 0, v[132:133]
	s_mov_b32 m0, s12
	s_nop 0
	global_load_lds_dwordx4 v[144:145], off
	v_lshl_add_u64 v[144:145], s[8:9], 0, v[128:129]
	s_add_i32 m0, s12, 0x2000
	s_nop 0
	global_load_lds_dwordx4 v[144:145], off
	s_waitcnt vmcnt(6)
	s_barrier
	s_setprio 1
	v_mfma_f32_16x16x32_bf16 v[52:55], v[202:205], v[168:171], v[52:55]
	v_mfma_f32_16x16x32_bf16 v[48:51], v[210:213], v[168:171], v[48:51]
	v_mfma_f32_16x16x32_bf16 v[36:39], v[202:205], v[176:179], v[36:39]
	v_mfma_f32_16x16x32_bf16 v[32:35], v[210:213], v[176:179], v[32:35]
	v_mfma_f32_16x16x32_bf16 v[20:23], v[202:205], v[184:187], v[20:23]
	v_mfma_f32_16x16x32_bf16 v[16:19], v[210:213], v[184:187], v[16:19]
	v_mfma_f32_16x16x32_bf16 v[4:7], v[202:205], v[192:195], v[4:7]
	v_mfma_f32_16x16x32_bf16 v[0:3], v[210:213], v[192:195], v[0:3]
	v_mfma_f32_16x16x32_bf16 v[52:55], v[206:209], v[172:175], v[52:55]
	v_mfma_f32_16x16x32_bf16 v[48:51], v[214:217], v[172:175], v[48:51]
	v_mfma_f32_16x16x32_bf16 v[36:39], v[206:209], v[180:183], v[36:39]
	v_mfma_f32_16x16x32_bf16 v[32:35], v[214:217], v[180:183], v[32:35]
	v_mfma_f32_16x16x32_bf16 v[20:23], v[206:209], v[188:191], v[20:23]
	v_mfma_f32_16x16x32_bf16 v[16:19], v[214:217], v[188:191], v[16:19]
	v_mfma_f32_16x16x32_bf16 v[4:7], v[206:209], v[198:201], v[4:7]
	v_mfma_f32_16x16x32_bf16 v[0:3], v[214:217], v[198:201], v[0:3]
	s_setprio 0
	s_add_i32 s3, s3, 2
	s_add_u32 s5, s5, 0x100
	s_addc_u32 s38, s38, 0
	s_cmpk_gt_u32 s3, 0x55
	s_mov_b64 s[8:9], s[10:11]
	s_barrier
	s_cbranch_scc0 .LBB1_550
	v_mov_b32_e32 v144, v146
	v_mov_b32_e32 v152, v147
	s_lshl_b32 s2, s2, 8
	s_add_i32 s2, s2, s29
	s_lshl_b32 s3, s4, 8
	v_add_u32_e32 v152, s2, v152
	s_or_b32 s3, s3, s54
	v_ashrrev_i32_e32 v153, 31, v152
	v_lshl_add_u32 v144, v144, 3, s3
	v_lshlrev_b64 v[152:153], 12, v[152:153]
	v_ashrrev_i32_e32 v145, 31, v144
	v_lshl_add_u64 v[152:153], s[46:47], 0, v[152:153]
	v_lshl_add_u64 v[144:145], v[144:145], 1, v[152:153]
	flat_load_dwordx4 v[152:155], v[144:145]
	s_mov_b64 s[2:3], 0x10000
	s_mov_b32 s4, s37
	s_mov_b64 s[10:11], s[6:7]
	s_mov_b64 s[8:9], s[42:43]
	s_waitcnt vmcnt(0) lgkmcnt(0)
	v_lshlrev_b32_e32 v156, 16, v152
	v_and_b32_e32 v157, 0xffff0000, v152
	v_lshlrev_b32_e32 v152, 16, v153
	v_and_b32_e32 v153, 0xffff0000, v153
	v_lshlrev_b32_e32 v158, 16, v154
	v_and_b32_e32 v159, 0xffff0000, v154
	v_lshlrev_b32_e32 v154, 16, v155
	v_and_b32_e32 v155, 0xffff0000, v155
	v_pk_add_f32 v[126:127], v[126:127], v[152:153]
	v_pk_add_f32 v[124:125], v[124:125], v[156:157]
	v_pk_add_f32 v[152:153], v[122:123], v[154:155]
	v_pk_add_f32 v[122:123], v[120:121], v[158:159]
	v_cvt_pk_bf16_f32 v120, v124, v125
	v_cvt_pk_bf16_f32 v121, v126, v127
	v_cvt_pk_bf16_f32 v122, v122, v123
	v_cvt_pk_bf16_f32 v123, v152, v153
	flat_store_dwordx4 v[144:145], v[120:123]
	flat_load_dwordx4 v[120:123], v[144:145] offset:256
	s_waitcnt vmcnt(0) lgkmcnt(0)
	v_lshlrev_b32_e32 v124, 16, v120
	v_and_b32_e32 v125, 0xffff0000, v120
	v_lshlrev_b32_e32 v120, 16, v121
	v_and_b32_e32 v121, 0xffff0000, v121
	v_lshlrev_b32_e32 v126, 16, v122
	v_and_b32_e32 v127, 0xffff0000, v122
	v_lshlrev_b32_e32 v122, 16, v123
	v_and_b32_e32 v123, 0xffff0000, v123
	v_pk_add_f32 v[116:117], v[116:117], v[124:125]
	v_pk_add_f32 v[118:119], v[118:119], v[120:121]
	v_pk_add_f32 v[120:121], v[114:115], v[122:123]
	v_pk_add_f32 v[114:115], v[112:113], v[126:127]
	v_cvt_pk_bf16_f32 v112, v116, v117
	v_lshl_add_u64 v[116:117], v[144:145], 0, s[2:3]
	s_mov_b32 s2, 0x10000
	v_cvt_pk_bf16_f32 v113, v118, v119
	v_add_co_u32_e32 v118, vcc, s2, v144
	v_cvt_pk_bf16_f32 v114, v114, v115
	v_cvt_pk_bf16_f32 v115, v120, v121
	v_addc_co_u32_e32 v119, vcc, 0, v145, vcc
	flat_store_dwordx4 v[144:145], v[112:115] offset:256
	flat_load_dwordx4 v[112:115], v[118:119]
	s_mov_b64 s[2:3], 0x20000
	s_waitcnt vmcnt(0) lgkmcnt(0)
; DI unsigned pack2(float a, float b) { f32x2 v = {a, b}; hwbf16x2 r = __builtin_convertvector(v, hwbf16x2); return __builtin_bit_cast(unsigned, r); }
; DI float bflo(unsigned w) { return __uint_as_float(w << 16); }
; DI float bfhi(unsigned w) { return __uint_as_float(w & 0xffff0000u); }
;     DI void operator()(const f32x4 (&acc)[2][2][4][2], const Unit& u, int wr, int wc, int fr, int fq) const {
;     ...
;         for (int ai = 0; ai < 2; ++ai)
; #pragma unroll
;             for (int m = 0; m < 4; ++m) { const size_t ro = (size_t)(row0 + ai * HALF + m * 16) * D + col0;
; #pragma unroll
;                 for (int bj = 0; bj < 2; ++bj) {
;                     f32x4 x0, x1;
;                     if constexpr (IB) { const u32x4 w = *(const u32x4*)((const bf16_t*)Xin + ro + bj * HALF);
;                         x0 = (f32x4){bflo(w[0]), bfhi(w[0]), bflo(w[1]), bfhi(w[1])}; x1 = (f32x4){bflo(w[2]), bfhi(w[2]), bflo(w[3]), bfhi(w[3])}; }
;                     else { x0 = *(const f32x4*)((const float*)Xin + ro + bj * HALF); x1 = *(const f32x4*)((const float*)Xin + ro + bj * HALF + 4); }
;                     x0 += acc[ai][bj][m][0] * sc[bj][0]; x1 += acc[ai][bj][m][1] * sc[bj][1];
;                     if constexpr (OB) { u32x4 o; o[0] = pack2(x0[0], x0[1]); o[1] = pack2(x0[2], x0[3]); o[2] = pack2(x1[0], x1[1]); o[3] = pack2(x1[2], x1[3]);
;                         *(u32x4*)((bf16_t*)Xout + ro + bj * HALF) = o; }
;                     else { *(f32x4*)((float*)Xout + ro + bj * HALF) = x0; *(f32x4*)((float*)Xout + ro + bj * HALF + 4) = x1; } } }
	v_lshlrev_b32_e32 v120, 16, v112
	v_and_b32_e32 v121, 0xffff0000, v112
	v_lshlrev_b32_e32 v112, 16, v113
	v_and_b32_e32 v113, 0xffff0000, v113
	v_lshlrev_b32_e32 v122, 16, v114
	v_and_b32_e32 v123, 0xffff0000, v114
	v_lshlrev_b32_e32 v114, 16, v115
	v_and_b32_e32 v115, 0xffff0000, v115
	v_pk_add_f32 v[110:111], v[110:111], v[112:113]
	v_pk_add_f32 v[108:109], v[108:109], v[120:121]
	v_pk_add_f32 v[112:113], v[106:107], v[114:115]
	v_pk_add_f32 v[106:107], v[104:105], v[122:123]
	v_cvt_pk_bf16_f32 v104, v108, v109
	v_cvt_pk_bf16_f32 v105, v110, v111
	v_cvt_pk_bf16_f32 v106, v106, v107
	v_cvt_pk_bf16_f32 v107, v112, v113
	flat_store_dwordx4 v[118:119], v[104:107]
	flat_load_dwordx4 v[104:107], v[116:117] offset:256
	s_waitcnt vmcnt(0) lgkmcnt(0)
	v_lshlrev_b32_e32 v108, 16, v104
	v_and_b32_e32 v109, 0xffff0000, v104
	v_lshlrev_b32_e32 v104, 16, v105
	v_and_b32_e32 v105, 0xffff0000, v105
	v_lshlrev_b32_e32 v110, 16, v106
	v_and_b32_e32 v111, 0xffff0000, v106
	v_lshlrev_b32_e32 v106, 16, v107
	v_and_b32_e32 v107, 0xffff0000, v107
	v_pk_add_f32 v[100:101], v[100:101], v[108:109]
	v_pk_add_f32 v[102:103], v[102:103], v[104:105]
	v_pk_add_f32 v[104:105], v[98:99], v[106:107]
	v_pk_add_f32 v[98:99], v[96:97], v[110:111]
	v_cvt_pk_bf16_f32 v96, v100, v101
	v_lshl_add_u64 v[100:101], v[144:145], 0, s[2:3]
	s_mov_b32 s2, 0x20000
	v_cvt_pk_bf16_f32 v97, v102, v103
	v_add_co_u32_e32 v102, vcc, s2, v144
	v_cvt_pk_bf16_f32 v98, v98, v99
	v_cvt_pk_bf16_f32 v99, v104, v105
	v_addc_co_u32_e32 v103, vcc, 0, v145, vcc
	flat_store_dwordx4 v[116:117], v[96:99] offset:256
	flat_load_dwordx4 v[96:99], v[102:103]
	s_mov_b64 s[2:3], 0x30000
	s_waitcnt vmcnt(0) lgkmcnt(0)
	v_lshlrev_b32_e32 v104, 16, v96
	v_and_b32_e32 v105, 0xffff0000, v96
	v_lshlrev_b32_e32 v96, 16, v97
	v_and_b32_e32 v97, 0xffff0000, v97
	v_lshlrev_b32_e32 v106, 16, v98
	v_and_b32_e32 v107, 0xffff0000, v98
	v_lshlrev_b32_e32 v98, 16, v99
	v_and_b32_e32 v99, 0xffff0000, v99
	v_pk_add_f32 v[94:95], v[94:95], v[96:97]
	v_pk_add_f32 v[92:93], v[92:93], v[104:105]
	v_pk_add_f32 v[96:97], v[90:91], v[98:99]
	v_pk_add_f32 v[90:91], v[88:89], v[106:107]
	v_cvt_pk_bf16_f32 v88, v92, v93
	v_cvt_pk_bf16_f32 v89, v94, v95
	v_cvt_pk_bf16_f32 v90, v90, v91
	v_cvt_pk_bf16_f32 v91, v96, v97
	flat_store_dwordx4 v[102:103], v[88:91]
	flat_load_dwordx4 v[88:91], v[100:101] offset:256
	s_waitcnt vmcnt(0) lgkmcnt(0)
	v_lshlrev_b32_e32 v92, 16, v88
	v_and_b32_e32 v93, 0xffff0000, v88
	v_lshlrev_b32_e32 v88, 16, v89
	v_and_b32_e32 v89, 0xffff0000, v89
	v_lshlrev_b32_e32 v94, 16, v90
	v_and_b32_e32 v95, 0xffff0000, v90
	v_lshlrev_b32_e32 v90, 16, v91
	v_and_b32_e32 v91, 0xffff0000, v91
	v_pk_add_f32 v[86:87], v[86:87], v[88:89]
	v_pk_add_f32 v[84:85], v[84:85], v[92:93]
	v_pk_add_f32 v[88:89], v[82:83], v[90:91]
	v_pk_add_f32 v[82:83], v[80:81], v[94:95]
	v_cvt_pk_bf16_f32 v80, v84, v85
	v_cvt_pk_bf16_f32 v81, v86, v87
	v_cvt_pk_bf16_f32 v82, v82, v83
	v_cvt_pk_bf16_f32 v83, v88, v89
	flat_store_dwordx4 v[100:101], v[80:83] offset:256
	s_nop 1
	v_lshl_add_u64 v[80:81], v[144:145], 0, s[2:3]
	s_mov_b32 s2, 0x30000
	v_add_co_u32_e32 v86, vcc, s2, v144
	s_mov_b64 s[2:3], 0x80000
	s_nop 0
	v_addc_co_u32_e32 v87, vcc, 0, v145, vcc
	flat_load_dwordx4 v[82:85], v[86:87]
	s_waitcnt vmcnt(0) lgkmcnt(0)
	v_lshlrev_b32_e32 v88, 16, v82
	v_and_b32_e32 v89, 0xffff0000, v82
	v_lshlrev_b32_e32 v82, 16, v83
	v_and_b32_e32 v83, 0xffff0000, v83
	v_lshlrev_b32_e32 v90, 16, v84
	v_and_b32_e32 v91, 0xffff0000, v84
	v_lshlrev_b32_e32 v84, 16, v85
	v_and_b32_e32 v85, 0xffff0000, v85
	v_pk_add_f32 v[78:79], v[78:79], v[82:83]
	v_pk_add_f32 v[76:77], v[76:77], v[88:89]
	v_pk_add_f32 v[82:83], v[74:75], v[84:85]
	v_pk_add_f32 v[74:75], v[72:73], v[90:91]
	v_cvt_pk_bf16_f32 v72, v76, v77
	v_cvt_pk_bf16_f32 v73, v78, v79
	v_cvt_pk_bf16_f32 v74, v74, v75
	v_cvt_pk_bf16_f32 v75, v82, v83
	flat_store_dwordx4 v[86:87], v[72:75]
	flat_load_dwordx4 v[72:75], v[80:81] offset:256
	s_waitcnt vmcnt(0) lgkmcnt(0)
	v_lshlrev_b32_e32 v76, 16, v72
	v_and_b32_e32 v77, 0xffff0000, v72
	v_lshlrev_b32_e32 v72, 16, v73
	v_and_b32_e32 v73, 0xffff0000, v73
	v_lshlrev_b32_e32 v78, 16, v74
	v_and_b32_e32 v79, 0xffff0000, v74
	v_lshlrev_b32_e32 v74, 16, v75
	v_and_b32_e32 v75, 0xffff0000, v75
	v_pk_add_f32 v[70:71], v[70:71], v[72:73]
	v_pk_add_f32 v[68:69], v[68:69], v[76:77]
	v_pk_add_f32 v[72:73], v[66:67], v[74:75]
	v_pk_add_f32 v[66:67], v[64:65], v[78:79]
	v_cvt_pk_bf16_f32 v64, v68, v69
	v_cvt_pk_bf16_f32 v65, v70, v71
	v_cvt_pk_bf16_f32 v66, v66, v67
	v_cvt_pk_bf16_f32 v67, v72, v73
	flat_store_dwordx4 v[80:81], v[64:67] offset:256
	s_nop 1
	v_lshl_add_u64 v[64:65], v[144:145], 0, s[2:3]
	s_mov_b32 s2, 0x80000
	v_add_co_u32_e32 v70, vcc, s2, v144
	s_mov_b64 s[2:3], 0x90000
	s_nop 0
	v_addc_co_u32_e32 v71, vcc, 0, v145, vcc
	flat_load_dwordx4 v[66:69], v[70:71]
	s_waitcnt vmcnt(0) lgkmcnt(0)
	v_lshlrev_b32_e32 v72, 16, v66
	v_and_b32_e32 v73, 0xffff0000, v66
	v_lshlrev_b32_e32 v66, 16, v67
	v_and_b32_e32 v67, 0xffff0000, v67
	v_lshlrev_b32_e32 v74, 16, v68
	v_and_b32_e32 v75, 0xffff0000, v68
	v_lshlrev_b32_e32 v68, 16, v69
	v_and_b32_e32 v69, 0xffff0000, v69
	v_pk_add_f32 v[62:63], v[62:63], v[66:67]
	v_pk_add_f32 v[60:61], v[60:61], v[72:73]
	v_pk_add_f32 v[66:67], v[58:59], v[68:69]
	v_pk_add_f32 v[58:59], v[56:57], v[74:75]
	v_cvt_pk_bf16_f32 v56, v60, v61
	v_cvt_pk_bf16_f32 v57, v62, v63
	v_cvt_pk_bf16_f32 v58, v58, v59
	v_cvt_pk_bf16_f32 v59, v66, v67
	flat_store_dwordx4 v[70:71], v[56:59]
	flat_load_dwordx4 v[56:59], v[64:65] offset:256
	s_waitcnt vmcnt(0) lgkmcnt(0)
; DI unsigned pack2(float a, float b) { f32x2 v = {a, b}; hwbf16x2 r = __builtin_convertvector(v, hwbf16x2); return __builtin_bit_cast(unsigned, r); }
; DI float bflo(unsigned w) { return __uint_as_float(w << 16); }
; DI float bfhi(unsigned w) { return __uint_as_float(w & 0xffff0000u); }
;     DI void operator()(const f32x4 (&acc)[2][2][4][2], const Unit& u, int wr, int wc, int fr, int fq) const {
;     ...
;         for (int ai = 0; ai < 2; ++ai)
; #pragma unroll
;             for (int m = 0; m < 4; ++m) { const size_t ro = (size_t)(row0 + ai * HALF + m * 16) * D + col0;
; #pragma unroll
;                 for (int bj = 0; bj < 2; ++bj) {
;                     f32x4 x0, x1;
;                     if constexpr (IB) { const u32x4 w = *(const u32x4*)((const bf16_t*)Xin + ro + bj * HALF);
;                         x0 = (f32x4){bflo(w[0]), bfhi(w[0]), bflo(w[1]), bfhi(w[1])}; x1 = (f32x4){bflo(w[2]), bfhi(w[2]), bflo(w[3]), bfhi(w[3])}; }
;                     else { x0 = *(const f32x4*)((const float*)Xin + ro + bj * HALF); x1 = *(const f32x4*)((const float*)Xin + ro + bj * HALF + 4); }
;                     x0 += acc[ai][bj][m][0] * sc[bj][0]; x1 += acc[ai][bj][m][1] * sc[bj][1];
;                     if constexpr (OB) { u32x4 o; o[0] = pack2(x0[0], x0[1]); o[1] = pack2(x0[2], x0[3]); o[2] = pack2(x1[0], x1[1]); o[3] = pack2(x1[2], x1[3]);
;                         *(u32x4*)((bf16_t*)Xout + ro + bj * HALF) = o; }
;                     else { *(f32x4*)((float*)Xout + ro + bj * HALF) = x0; *(f32x4*)((float*)Xout + ro + bj * HALF + 4) = x1; } } }
	v_lshlrev_b32_e32 v60, 16, v56
	v_and_b32_e32 v61, 0xffff0000, v56
	v_lshlrev_b32_e32 v56, 16, v57
	v_and_b32_e32 v57, 0xffff0000, v57
	v_lshlrev_b32_e32 v62, 16, v58
	v_and_b32_e32 v63, 0xffff0000, v58
	v_lshlrev_b32_e32 v58, 16, v59
	v_and_b32_e32 v59, 0xffff0000, v59
	v_pk_add_f32 v[54:55], v[54:55], v[56:57]
	v_pk_add_f32 v[52:53], v[52:53], v[60:61]
	v_pk_add_f32 v[56:57], v[50:51], v[58:59]
	v_pk_add_f32 v[50:51], v[48:49], v[62:63]
	v_cvt_pk_bf16_f32 v48, v52, v53
	v_cvt_pk_bf16_f32 v49, v54, v55
	v_cvt_pk_bf16_f32 v50, v50, v51
	v_cvt_pk_bf16_f32 v51, v56, v57
	flat_store_dwordx4 v[64:65], v[48:51] offset:256
	s_nop 1
	v_lshl_add_u64 v[48:49], v[144:145], 0, s[2:3]
	s_mov_b32 s2, 0x90000
	v_add_co_u32_e32 v54, vcc, s2, v144
	s_mov_b64 s[2:3], 0xa0000
	s_nop 0
	v_addc_co_u32_e32 v55, vcc, 0, v145, vcc
	flat_load_dwordx4 v[50:53], v[54:55]
	s_waitcnt vmcnt(0) lgkmcnt(0)
	v_lshlrev_b32_e32 v56, 16, v50
	v_and_b32_e32 v57, 0xffff0000, v50
	v_lshlrev_b32_e32 v50, 16, v51
	v_and_b32_e32 v51, 0xffff0000, v51
	v_lshlrev_b32_e32 v58, 16, v52
	v_and_b32_e32 v59, 0xffff0000, v52
	v_lshlrev_b32_e32 v52, 16, v53
	v_and_b32_e32 v53, 0xffff0000, v53
	v_pk_add_f32 v[46:47], v[46:47], v[50:51]
	v_pk_add_f32 v[44:45], v[44:45], v[56:57]
	v_pk_add_f32 v[50:51], v[42:43], v[52:53]
	v_pk_add_f32 v[42:43], v[40:41], v[58:59]
	v_cvt_pk_bf16_f32 v40, v44, v45
	v_cvt_pk_bf16_f32 v41, v46, v47
	v_cvt_pk_bf16_f32 v42, v42, v43
	v_cvt_pk_bf16_f32 v43, v50, v51
	flat_store_dwordx4 v[54:55], v[40:43]
	flat_load_dwordx4 v[40:43], v[48:49] offset:256
	s_waitcnt vmcnt(0) lgkmcnt(0)
	v_lshlrev_b32_e32 v44, 16, v40
	v_and_b32_e32 v45, 0xffff0000, v40
	v_lshlrev_b32_e32 v40, 16, v41
	v_and_b32_e32 v41, 0xffff0000, v41
	v_lshlrev_b32_e32 v46, 16, v42
	v_and_b32_e32 v47, 0xffff0000, v42
	v_lshlrev_b32_e32 v42, 16, v43
	v_and_b32_e32 v43, 0xffff0000, v43
	v_pk_add_f32 v[38:39], v[38:39], v[40:41]
	v_pk_add_f32 v[36:37], v[36:37], v[44:45]
	v_pk_add_f32 v[40:41], v[34:35], v[42:43]
	v_pk_add_f32 v[34:35], v[32:33], v[46:47]
	v_cvt_pk_bf16_f32 v32, v36, v37
	v_cvt_pk_bf16_f32 v33, v38, v39
	v_cvt_pk_bf16_f32 v34, v34, v35
	v_cvt_pk_bf16_f32 v35, v40, v41
	flat_store_dwordx4 v[48:49], v[32:35] offset:256
	s_nop 1
	v_lshl_add_u64 v[32:33], v[144:145], 0, s[2:3]
	s_mov_b32 s2, 0xa0000
	v_add_co_u32_e32 v38, vcc, s2, v144
	s_mov_b64 s[2:3], 0xb0000
	s_nop 0
	v_addc_co_u32_e32 v39, vcc, 0, v145, vcc
	flat_load_dwordx4 v[34:37], v[38:39]
	s_waitcnt vmcnt(0) lgkmcnt(0)
	v_lshlrev_b32_e32 v40, 16, v34
	v_and_b32_e32 v41, 0xffff0000, v34
	v_lshlrev_b32_e32 v34, 16, v35
	v_and_b32_e32 v35, 0xffff0000, v35
	v_lshlrev_b32_e32 v42, 16, v36
	v_and_b32_e32 v43, 0xffff0000, v36
	v_lshlrev_b32_e32 v36, 16, v37
	v_and_b32_e32 v37, 0xffff0000, v37
	v_pk_add_f32 v[30:31], v[30:31], v[34:35]
	v_pk_add_f32 v[28:29], v[28:29], v[40:41]
	v_pk_add_f32 v[34:35], v[26:27], v[36:37]
	v_pk_add_f32 v[26:27], v[24:25], v[42:43]
	v_cvt_pk_bf16_f32 v24, v28, v29
	v_cvt_pk_bf16_f32 v25, v30, v31
	v_cvt_pk_bf16_f32 v26, v26, v27
	v_cvt_pk_bf16_f32 v27, v34, v35
	flat_store_dwordx4 v[38:39], v[24:27]
	flat_load_dwordx4 v[24:27], v[32:33] offset:256
	s_waitcnt vmcnt(0) lgkmcnt(0)
	v_lshlrev_b32_e32 v28, 16, v24
	v_and_b32_e32 v29, 0xffff0000, v24
	v_lshlrev_b32_e32 v24, 16, v25
	v_and_b32_e32 v25, 0xffff0000, v25
	v_lshlrev_b32_e32 v30, 16, v26
	v_and_b32_e32 v31, 0xffff0000, v26
	v_lshlrev_b32_e32 v26, 16, v27
	v_and_b32_e32 v27, 0xffff0000, v27
	v_pk_add_f32 v[22:23], v[22:23], v[24:25]
	v_pk_add_f32 v[20:21], v[20:21], v[28:29]
	v_pk_add_f32 v[24:25], v[18:19], v[26:27]
	v_pk_add_f32 v[18:19], v[16:17], v[30:31]
	v_cvt_pk_bf16_f32 v16, v20, v21
	v_cvt_pk_bf16_f32 v17, v22, v23
	v_cvt_pk_bf16_f32 v18, v18, v19
	v_cvt_pk_bf16_f32 v19, v24, v25
	flat_store_dwordx4 v[32:33], v[16:19] offset:256
	s_nop 1
	v_lshl_add_u64 v[16:17], v[144:145], 0, s[2:3]
	s_mov_b32 s2, 0xb0000
	v_add_co_u32_e32 v22, vcc, s2, v144
	s_mov_b32 s2, s55
	s_nop 0
	v_addc_co_u32_e32 v23, vcc, 0, v145, vcc
	flat_load_dwordx4 v[18:21], v[22:23]
	s_and_b64 vcc, exec, s[40:41]
	s_waitcnt vmcnt(0) lgkmcnt(0)
	v_lshlrev_b32_e32 v24, 16, v18
	v_and_b32_e32 v25, 0xffff0000, v18
	v_lshlrev_b32_e32 v18, 16, v19
	v_and_b32_e32 v19, 0xffff0000, v19
	v_lshlrev_b32_e32 v26, 16, v20
	v_and_b32_e32 v27, 0xffff0000, v20
	v_lshlrev_b32_e32 v20, 16, v21
	v_and_b32_e32 v21, 0xffff0000, v21
	v_pk_add_f32 v[14:15], v[14:15], v[18:19]
	v_pk_add_f32 v[12:13], v[12:13], v[24:25]
	v_pk_add_f32 v[18:19], v[10:11], v[20:21]
	v_pk_add_f32 v[10:11], v[8:9], v[26:27]
	v_cvt_pk_bf16_f32 v8, v12, v13
	v_cvt_pk_bf16_f32 v9, v14, v15
	v_cvt_pk_bf16_f32 v10, v10, v11
	v_cvt_pk_bf16_f32 v11, v18, v19
	flat_store_dwordx4 v[22:23], v[8:11]
	flat_load_dwordx4 v[8:11], v[16:17] offset:256
	s_waitcnt vmcnt(0) lgkmcnt(0)
	v_lshlrev_b32_e32 v12, 16, v8
	v_and_b32_e32 v13, 0xffff0000, v8
	v_lshlrev_b32_e32 v8, 16, v9
	v_and_b32_e32 v9, 0xffff0000, v9
	v_lshlrev_b32_e32 v14, 16, v10
	v_and_b32_e32 v15, 0xffff0000, v10
	v_lshlrev_b32_e32 v10, 16, v11
	v_and_b32_e32 v11, 0xffff0000, v11
	v_pk_add_f32 v[6:7], v[6:7], v[8:9]
	v_pk_add_f32 v[4:5], v[4:5], v[12:13]
	v_pk_add_f32 v[8:9], v[2:3], v[10:11]
	v_pk_add_f32 v[2:3], v[0:1], v[14:15]
	v_cvt_pk_bf16_f32 v0, v4, v5
	v_cvt_pk_bf16_f32 v1, v6, v7
	v_cvt_pk_bf16_f32 v2, v2, v3
	v_cvt_pk_bf16_f32 v3, v8, v9
	flat_store_dwordx4 v[16:17], v[0:3] offset:256
	s_cbranch_vccz .LBB1_543
	s_waitcnt vmcnt(0)
	s_cmpk_gt_u32 s17, 0xff
	s_cbranch_scc1 .LBB1_554
	s_barrier

; #define PG8_STAGE(bufoff, gbase, voff) do { _Pragma("unroll") for (int _i = 0; _i < 2; ++_i) \
;         __builtin_amdgcn_global_load_lds((const unsigned*)((const char*)(gbase) + (voff)[_i]), (LAS unsigned*)(lds + (bufoff) + ldsw + _i * 8192), 16, 0, 0); } while (0)
; #define PG8_LDA(dst, b, h) do { _Pragma("unroll") for (int m = 0; m < 4; ++m) _Pragma("unroll") for (int k = 0; k < 2; ++k) dst[m][k] = *(const LAS bf16x8*)(lds + PG8_SA(b, h) + aoff + m * 2048 + k * 1024); } while (0)
; #define PG8_LDB(dst, b, h) do { _Pragma("unroll") for (int n = 0; n < 2; ++n) _Pragma("unroll") for (int k = 0; k < 2; ++k) dst[n][k] = *(const LAS bf16x8*)(lds + PG8_SB(b, h) + boff + n * 2048 + k * 1024); } while (0)
; #define PG8_MMA(ai, bj, At, Bt) do { __builtin_amdgcn_s_setprio(1); _Pragma("unroll") for (int m = 0; m < 4; ++m) _Pragma("unroll") for (int n = 0; n < 2; ++n) _Pragma("unroll") for (int k = 0; k < 2; ++k) \
;         acc[ai][bj][m][n] = __builtin_amdgcn_mfma_f32_16x16x32_bf16(Bt[n][k], At[m][k], acc[ai][bj][m][n], 0, 0, 0); __builtin_amdgcn_s_setprio(0); } while (0)
; #define PG8_WAIT_L(n) asm volatile("s_waitcnt lgkmcnt(" #n ")" ::: "memory")
; #define PG8_BAR __builtin_amdgcn_s_barrier()
; #define PG8_SCHED __builtin_amdgcn_sched_barrier(0)
; template <class Map, class Epi>
; DI void gemm_phase(LAS unsigned char* lds, const Map& MP, const Epi& E, const int nM, const int nN, const int K, const int lda, const int ldb) {
;     ...
;             PG8_LDB(B0, 0, 0); PG8_SCHED; PG8_LDA(At, 0, 0); PG8_STAGE(PG8_SA(1, 1), a1 + hstepA, voffA);
;             PG8_WAIT_L(8); PG8_BAR; PG8_WAIT_L(0); PG8_MMA(0, 0, At, B0); PG8_BAR; PG8_SCHED;
;             PG8_LDB(B1, 0, 1); PG8_STAGE(PG8_SB(0, 0), b2, voffB);
;             PG8_BAR; PG8_WAIT_L(0); PG8_MMA(0, 1, At, B1); PG8_BAR;
;             PG8_LDA(At, 0, 1); PG8_STAGE(PG8_SA(0, 0), a2, voffA);
;             PG8_BAR; PG8_WAIT_L(0); PG8_MMA(1, 0, At, B0); PG8_BAR; PG8_SCHED;
.LBB1_693:
	ds_read_b128 v[150:153], v147
	ds_read_b128 v[154:157], v147 offset:1024
	ds_read_b128 v[158:161], v147 offset:2048
	ds_read_b128 v[162:165], v147 offset:3072
	s_add_u32 s3, s20, 0xfff80080
	s_addc_u32 s22, s21, -1
	s_cmp_eq_u32 s54, 28
	s_cselect_b32 s25, s15, s22
	s_cselect_b32 s24, s48, s3
	s_cselect_b32 s23, s13, s53
	s_cselect_b32 s22, s49, s52
	v_lshl_add_u64 v[194:195], s[20:21], 0, v[138:139]
	s_add_i32 m0, s31, 0xc000
	ds_read_b128 v[166:169], v148
	ds_read_b128 v[170:173], v148 offset:1024
	ds_read_b128 v[174:177], v148 offset:2048
	ds_read_b128 v[178:181], v148 offset:3072
	ds_read_b128 v[182:185], v148 offset:4096
	ds_read_b128 v[186:189], v148 offset:5120
	ds_read_b128 v[190:193], v148 offset:6144
	ds_read_b128 v[198:201], v148 offset:7168
	global_load_lds_dwordx4 v[194:195], off
	v_lshl_add_u64 v[194:195], s[20:21], 0, v[136:137]
	s_add_i32 m0, s31, 0xe000
	s_nop 0
	global_load_lds_dwordx4 v[194:195], off
	s_waitcnt lgkmcnt(8)
	s_barrier
	s_setprio 1
	s_waitcnt lgkmcnt(7)
	v_mfma_f32_16x16x32_bf16 v[124:127], v[150:153], v[166:169], v[124:127]
	v_mfma_f32_16x16x32_bf16 v[120:123], v[158:161], v[166:169], v[120:123]
	s_waitcnt lgkmcnt(5)
	v_mfma_f32_16x16x32_bf16 v[116:119], v[150:153], v[174:177], v[116:119]
	v_mfma_f32_16x16x32_bf16 v[112:115], v[158:161], v[174:177], v[112:115]
	s_waitcnt lgkmcnt(3)
	v_mfma_f32_16x16x32_bf16 v[100:103], v[150:153], v[182:185], v[100:103]
	v_mfma_f32_16x16x32_bf16 v[96:99], v[158:161], v[182:185], v[96:99]
	s_waitcnt lgkmcnt(1)
	v_mfma_f32_16x16x32_bf16 v[84:87], v[150:153], v[190:193], v[84:87]
	v_mfma_f32_16x16x32_bf16 v[80:83], v[158:161], v[190:193], v[80:83]
	v_mfma_f32_16x16x32_bf16 v[124:127], v[154:157], v[170:173], v[124:127]
	v_mfma_f32_16x16x32_bf16 v[120:123], v[162:165], v[170:173], v[120:123]
	v_mfma_f32_16x16x32_bf16 v[116:119], v[154:157], v[178:181], v[116:119]
	v_mfma_f32_16x16x32_bf16 v[112:115], v[162:165], v[178:181], v[112:115]
	v_mfma_f32_16x16x32_bf16 v[100:103], v[154:157], v[186:189], v[100:103]
	v_mfma_f32_16x16x32_bf16 v[96:99], v[162:165], v[186:189], v[96:99]
	s_waitcnt lgkmcnt(0)
	v_mfma_f32_16x16x32_bf16 v[84:87], v[154:157], v[198:201], v[84:87]
	v_mfma_f32_16x16x32_bf16 v[80:83], v[162:165], v[198:201], v[80:83]
	s_setprio 0
	s_barrier
	s_add_i32 s3, s44, s29
	v_lshl_add_u64 v[194:195], s[22:23], 0, v[132:133]
	s_mov_b32 m0, s3
	ds_read_b128 v[202:205], v149
	ds_read_b128 v[206:209], v149 offset:1024
	ds_read_b128 v[210:213], v149 offset:2048
	ds_read_b128 v[214:217], v149 offset:3072
	global_load_lds_dwordx4 v[194:195], off
	v_lshl_add_u64 v[218:219], s[22:23], 0, v[128:129]
	s_add_i32 m0, s3, 0x2000
	s_nop 0
	global_load_lds_dwordx4 v[218:219], off
	s_barrier
	s_setprio 1
	s_waitcnt lgkmcnt(3)
	v_mfma_f32_16x16x32_bf16 v[108:111], v[202:205], v[166:169], v[108:111]
	s_waitcnt lgkmcnt(1)
	v_mfma_f32_16x16x32_bf16 v[104:107], v[210:213], v[166:169], v[104:107]
	v_mfma_f32_16x16x32_bf16 v[92:95], v[202:205], v[174:177], v[92:95]
	v_mfma_f32_16x16x32_bf16 v[88:91], v[210:213], v[174:177], v[88:91]
	v_mfma_f32_16x16x32_bf16 v[76:79], v[202:205], v[182:185], v[76:79]
	v_mfma_f32_16x16x32_bf16 v[72:75], v[210:213], v[182:185], v[72:75]
	v_mfma_f32_16x16x32_bf16 v[68:71], v[202:205], v[190:193], v[68:71]
	v_mfma_f32_16x16x32_bf16 v[64:67], v[210:213], v[190:193], v[64:67]
	v_mfma_f32_16x16x32_bf16 v[108:111], v[206:209], v[170:173], v[108:111]
	s_waitcnt lgkmcnt(0)
	v_mfma_f32_16x16x32_bf16 v[104:107], v[214:217], v[170:173], v[104:107]
	v_mfma_f32_16x16x32_bf16 v[92:95], v[206:209], v[178:181], v[92:95]
	v_mfma_f32_16x16x32_bf16 v[88:91], v[214:217], v[178:181], v[88:91]
	v_mfma_f32_16x16x32_bf16 v[76:79], v[206:209], v[186:189], v[76:79]
	v_mfma_f32_16x16x32_bf16 v[72:75], v[214:217], v[186:189], v[72:75]
	v_mfma_f32_16x16x32_bf16 v[68:71], v[206:209], v[198:201], v[68:71]
	v_mfma_f32_16x16x32_bf16 v[64:67], v[214:217], v[198:201], v[64:67]
	s_setprio 0
	s_mov_b32 m0, s31
	v_lshl_add_u64 v[220:221], s[24:25], 0, v[134:135]
	s_barrier
	ds_read_b128 v[166:169], v148 offset:16384
	ds_read_b128 v[170:173], v148 offset:17408
	ds_read_b128 v[174:177], v148 offset:18432
	ds_read_b128 v[178:181], v148 offset:19456
	ds_read_b128 v[182:185], v148 offset:20480
	ds_read_b128 v[186:189], v148 offset:21504
	ds_read_b128 v[190:193], v148 offset:22528
	ds_read_b128 v[198:201], v148 offset:23552
	global_load_lds_dwordx4 v[220:221], off
	v_lshl_add_u64 v[222:223], s[24:25], 0, v[130:131]
	s_mov_b32 m0, s11
	s_nop 0
	global_load_lds_dwordx4 v[222:223], off
	s_barrier
	s_setprio 1
	s_waitcnt lgkmcnt(7)
	v_mfma_f32_16x16x32_bf16 v[60:63], v[150:153], v[166:169], v[60:63]
	v_mfma_f32_16x16x32_bf16 v[56:59], v[158:161], v[166:169], v[56:59]
	s_waitcnt lgkmcnt(5)
	v_mfma_f32_16x16x32_bf16 v[52:55], v[150:153], v[174:177], v[52:55]
	v_mfma_f32_16x16x32_bf16 v[48:51], v[158:161], v[174:177], v[48:51]
	s_waitcnt lgkmcnt(3)
	v_mfma_f32_16x16x32_bf16 v[36:39], v[150:153], v[182:185], v[36:39]
	v_mfma_f32_16x16x32_bf16 v[32:35], v[158:161], v[182:185], v[32:35]
	s_waitcnt lgkmcnt(1)
	v_mfma_f32_16x16x32_bf16 v[20:23], v[150:153], v[190:193], v[20:23]
	v_mfma_f32_16x16x32_bf16 v[16:19], v[158:161], v[190:193], v[16:19]
	v_mfma_f32_16x16x32_bf16 v[60:63], v[154:157], v[170:173], v[60:63]
	v_mfma_f32_16x16x32_bf16 v[56:59], v[162:165], v[170:173], v[56:59]
	v_mfma_f32_16x16x32_bf16 v[52:55], v[154:157], v[178:181], v[52:55]
	v_mfma_f32_16x16x32_bf16 v[48:51], v[162:165], v[178:181], v[48:51]
	v_mfma_f32_16x16x32_bf16 v[36:39], v[154:157], v[186:189], v[36:39]
	v_mfma_f32_16x16x32_bf16 v[32:35], v[162:165], v[186:189], v[32:35]
	s_waitcnt lgkmcnt(0)
	v_mfma_f32_16x16x32_bf16 v[20:23], v[154:157], v[198:201], v[20:23]
	v_mfma_f32_16x16x32_bf16 v[16:19], v[162:165], v[198:201], v[16:19]
	s_setprio 0
	s_barrier
; #define PG8_STAGE(bufoff, gbase, voff) do { _Pragma("unroll") for (int _i = 0; _i < 2; ++_i) \
;         __builtin_amdgcn_global_load_lds((const unsigned*)((const char*)(gbase) + (voff)[_i]), (LAS unsigned*)(lds + (bufoff) + ldsw + _i * 8192), 16, 0, 0); } while (0)
; #define PG8_LDA(dst, b, h) do { _Pragma("unroll") for (int m = 0; m < 4; ++m) _Pragma("unroll") for (int k = 0; k < 2; ++k) dst[m][k] = *(const LAS bf16x8*)(lds + PG8_SA(b, h) + aoff + m * 2048 + k * 1024); } while (0)
; #define PG8_LDB(dst, b, h) do { _Pragma("unroll") for (int n = 0; n < 2; ++n) _Pragma("unroll") for (int k = 0; k < 2; ++k) dst[n][k] = *(const LAS bf16x8*)(lds + PG8_SB(b, h) + boff + n * 2048 + k * 1024); } while (0)
; #define PG8_MMA(ai, bj, At, Bt) do { __builtin_amdgcn_s_setprio(1); _Pragma("unroll") for (int m = 0; m < 4; ++m) _Pragma("unroll") for (int n = 0; n < 2; ++n) _Pragma("unroll") for (int k = 0; k < 2; ++k) \
;         acc[ai][bj][m][n] = __builtin_amdgcn_mfma_f32_16x16x32_bf16(Bt[n][k], At[m][k], acc[ai][bj][m][n], 0, 0, 0); __builtin_amdgcn_s_setprio(0); } while (0)
; #define PG8_WAIT_V(n) asm volatile("s_waitcnt vmcnt(" #n ")" ::: "memory")
; #define PG8_WAIT_L(n) asm volatile("s_waitcnt lgkmcnt(" #n ")" ::: "memory")
; #define PG8_BAR __builtin_amdgcn_s_barrier()
; #define PG8_SCHED __builtin_amdgcn_sched_barrier(0)
; template <class Map, class Epi>
; DI void gemm_phase(LAS unsigned char* lds, const Map& MP, const Epi& E, const int nM, const int nN, const int K, const int lda, const int ldb) {
;     ...
;             PG8_STAGE(PG8_SB(0, 1), b2 + hstepB, voffB);
;             PG8_WAIT_V(6); PG8_BAR; PG8_MMA(1, 1, At, B1); PG8_BAR;
;             PG8_LDB(B0, 1, 0); PG8_SCHED; PG8_LDA(At, 1, 0); PG8_STAGE(PG8_SA(0, 1), a2 + hstepA, voffA);
;             PG8_WAIT_L(8); PG8_BAR; PG8_WAIT_L(0); PG8_MMA(0, 0, At, B0); PG8_BAR; PG8_SCHED;
;             PG8_LDB(B1, 1, 1); PG8_STAGE(PG8_SB(1, 0), b3, voffB);
;             PG8_BAR; PG8_WAIT_L(0); PG8_MMA(0, 1, At, B1); PG8_BAR;
;             PG8_LDA(At, 1, 1); PG8_STAGE(PG8_SA(1, 0), a3, voffA);
	s_add_u32 s56, s22, 0x80000
	s_addc_u32 s57, s23, 0
	s_add_i32 s3, s45, s29
	v_lshl_add_u64 v[150:151], s[56:57], 0, v[132:133]
	s_mov_b32 m0, s3
	s_nop 0
	global_load_lds_dwordx4 v[150:151], off
	v_lshl_add_u64 v[150:151], s[56:57], 0, v[128:129]
	s_add_i32 m0, s3, 0x2000
	s_nop 0
	global_load_lds_dwordx4 v[150:151], off
	s_waitcnt vmcnt(6)
	s_barrier
	s_setprio 1
	v_mfma_f32_16x16x32_bf16 v[44:47], v[202:205], v[166:169], v[44:47]
	v_mfma_f32_16x16x32_bf16 v[40:43], v[210:213], v[166:169], v[40:43]
	v_mfma_f32_16x16x32_bf16 v[28:31], v[202:205], v[174:177], v[28:31]
	v_mfma_f32_16x16x32_bf16 v[24:27], v[210:213], v[174:177], v[24:27]
	v_mfma_f32_16x16x32_bf16 v[12:15], v[202:205], v[182:185], v[12:15]
	v_mfma_f32_16x16x32_bf16 v[8:11], v[210:213], v[182:185], v[8:11]
	v_mfma_f32_16x16x32_bf16 v[4:7], v[202:205], v[190:193], v[4:7]
	v_mfma_f32_16x16x32_bf16 v[0:3], v[210:213], v[190:193], v[0:3]
	v_mfma_f32_16x16x32_bf16 v[44:47], v[206:209], v[170:173], v[44:47]
	v_mfma_f32_16x16x32_bf16 v[40:43], v[214:217], v[170:173], v[40:43]
	v_mfma_f32_16x16x32_bf16 v[28:31], v[206:209], v[178:181], v[28:31]
	v_mfma_f32_16x16x32_bf16 v[24:27], v[214:217], v[178:181], v[24:27]
	v_mfma_f32_16x16x32_bf16 v[12:15], v[206:209], v[186:189], v[12:15]
	v_mfma_f32_16x16x32_bf16 v[8:11], v[214:217], v[186:189], v[8:11]
	v_mfma_f32_16x16x32_bf16 v[4:7], v[206:209], v[198:201], v[4:7]
	v_mfma_f32_16x16x32_bf16 v[0:3], v[214:217], v[198:201], v[0:3]
	s_setprio 0
	s_add_i32 s3, 0, 0x18000
	v_add_u32_e32 v162, s3, v146
	s_barrier
	ds_read_b128 v[150:153], v162
	ds_read_b128 v[154:157], v162 offset:1024
	ds_read_b128 v[158:161], v162 offset:2048
	ds_read_b128 v[162:165], v162 offset:3072
	s_add_u32 s24, s24, 0x80000
	s_addc_u32 s25, s25, 0
	s_mov_b32 m0, s34
	v_lshl_add_u64 v[202:203], s[24:25], 0, v[134:135]
	ds_read_b128 v[166:169], v148 offset:32768
	ds_read_b128 v[170:173], v148 offset:33792
	ds_read_b128 v[174:177], v148 offset:34816
	ds_read_b128 v[178:181], v148 offset:35840
	ds_read_b128 v[182:185], v148 offset:36864
	ds_read_b128 v[186:189], v148 offset:37888
	ds_read_b128 v[190:193], v148 offset:38912
	ds_read_b128 v[198:201], v148 offset:39936
	global_load_lds_dwordx4 v[202:203], off
	v_lshl_add_u64 v[202:203], s[24:25], 0, v[130:131]
	s_mov_b32 m0, s35
	s_nop 0
	global_load_lds_dwordx4 v[202:203], off
	s_waitcnt lgkmcnt(8)
	s_barrier
	s_setprio 1
	s_waitcnt lgkmcnt(7)
	v_mfma_f32_16x16x32_bf16 v[124:127], v[150:153], v[166:169], v[124:127]
	v_mfma_f32_16x16x32_bf16 v[120:123], v[158:161], v[166:169], v[120:123]
	s_waitcnt lgkmcnt(5)
	v_mfma_f32_16x16x32_bf16 v[116:119], v[150:153], v[174:177], v[116:119]
	v_mfma_f32_16x16x32_bf16 v[112:115], v[158:161], v[174:177], v[112:115]
	s_waitcnt lgkmcnt(3)
	v_mfma_f32_16x16x32_bf16 v[100:103], v[150:153], v[182:185], v[100:103]
	v_mfma_f32_16x16x32_bf16 v[96:99], v[158:161], v[182:185], v[96:99]
	s_waitcnt lgkmcnt(1)
	v_mfma_f32_16x16x32_bf16 v[84:87], v[150:153], v[190:193], v[84:87]
	v_mfma_f32_16x16x32_bf16 v[80:83], v[158:161], v[190:193], v[80:83]
	v_mfma_f32_16x16x32_bf16 v[124:127], v[154:157], v[170:173], v[124:127]
	v_mfma_f32_16x16x32_bf16 v[120:123], v[162:165], v[170:173], v[120:123]
	v_mfma_f32_16x16x32_bf16 v[116:119], v[154:157], v[178:181], v[116:119]
	v_mfma_f32_16x16x32_bf16 v[112:115], v[162:165], v[178:181], v[112:115]
	v_mfma_f32_16x16x32_bf16 v[100:103], v[154:157], v[186:189], v[100:103]
	v_mfma_f32_16x16x32_bf16 v[96:99], v[162:165], v[186:189], v[96:99]
	s_waitcnt lgkmcnt(0)
	v_mfma_f32_16x16x32_bf16 v[84:87], v[154:157], v[198:201], v[84:87]
	v_mfma_f32_16x16x32_bf16 v[80:83], v[162:165], v[198:201], v[80:83]
	s_setprio 0
	s_barrier
	s_add_i32 s24, 0, 0x1c000
	s_add_i32 s3, s3, s29
	v_add_u32_e32 v196, s24, v146
	v_lshl_add_u64 v[194:195], v[194:195], 0, s[8:9]
	s_mov_b32 m0, s3
	ds_read_b128 v[202:205], v196
	ds_read_b128 v[206:209], v196 offset:1024
	ds_read_b128 v[210:213], v196 offset:2048
	ds_read_b128 v[214:217], v196 offset:3072
	global_load_lds_dwordx4 v[194:195], off
	v_lshl_add_u64 v[194:195], v[218:219], 0, s[8:9]
	s_add_i32 m0, s3, 0x2000
	s_nop 0
	global_load_lds_dwordx4 v[194:195], off
	s_barrier
	s_setprio 1
	s_waitcnt lgkmcnt(3)
	v_mfma_f32_16x16x32_bf16 v[108:111], v[202:205], v[166:169], v[108:111]
	s_waitcnt lgkmcnt(1)
	v_mfma_f32_16x16x32_bf16 v[104:107], v[210:213], v[166:169], v[104:107]
	v_mfma_f32_16x16x32_bf16 v[92:95], v[202:205], v[174:177], v[92:95]
	v_mfma_f32_16x16x32_bf16 v[88:91], v[210:213], v[174:177], v[88:91]
	v_mfma_f32_16x16x32_bf16 v[76:79], v[202:205], v[182:185], v[76:79]
	v_mfma_f32_16x16x32_bf16 v[72:75], v[210:213], v[182:185], v[72:75]
	v_mfma_f32_16x16x32_bf16 v[68:71], v[202:205], v[190:193], v[68:71]
	v_mfma_f32_16x16x32_bf16 v[64:67], v[210:213], v[190:193], v[64:67]
	v_mfma_f32_16x16x32_bf16 v[108:111], v[206:209], v[170:173], v[108:111]
	s_waitcnt lgkmcnt(0)
	v_mfma_f32_16x16x32_bf16 v[104:107], v[214:217], v[170:173], v[104:107]
	v_mfma_f32_16x16x32_bf16 v[92:95], v[206:209], v[178:181], v[92:95]
	v_mfma_f32_16x16x32_bf16 v[88:91], v[214:217], v[178:181], v[88:91]
	v_mfma_f32_16x16x32_bf16 v[76:79], v[206:209], v[186:189], v[76:79]
	v_mfma_f32_16x16x32_bf16 v[72:75], v[214:217], v[186:189], v[72:75]
	v_mfma_f32_16x16x32_bf16 v[68:71], v[206:209], v[198:201], v[68:71]
	v_mfma_f32_16x16x32_bf16 v[64:67], v[214:217], v[198:201], v[64:67]
	s_setprio 0
	s_mov_b32 m0, s39
	v_lshl_add_u64 v[194:195], v[220:221], 0, s[8:9]
	s_barrier
; #define PG8_STAGE(bufoff, gbase, voff) do { _Pragma("unroll") for (int _i = 0; _i < 2; ++_i) \
;         __builtin_amdgcn_global_load_lds((const unsigned*)((const char*)(gbase) + (voff)[_i]), (LAS unsigned*)(lds + (bufoff) + ldsw + _i * 8192), 16, 0, 0); } while (0)
; #define PG8_LDA(dst, b, h) do { _Pragma("unroll") for (int m = 0; m < 4; ++m) _Pragma("unroll") for (int k = 0; k < 2; ++k) dst[m][k] = *(const LAS bf16x8*)(lds + PG8_SA(b, h) + aoff + m * 2048 + k * 1024); } while (0)
; #define PG8_MMA(ai, bj, At, Bt) do { __builtin_amdgcn_s_setprio(1); _Pragma("unroll") for (int m = 0; m < 4; ++m) _Pragma("unroll") for (int n = 0; n < 2; ++n) _Pragma("unroll") for (int k = 0; k < 2; ++k) \
;         acc[ai][bj][m][n] = __builtin_amdgcn_mfma_f32_16x16x32_bf16(Bt[n][k], At[m][k], acc[ai][bj][m][n], 0, 0, 0); __builtin_amdgcn_s_setprio(0); } while (0)
; #define PG8_WAIT_V(n) asm volatile("s_waitcnt vmcnt(" #n ")" ::: "memory")
; #define PG8_WAIT_L(n) asm volatile("s_waitcnt lgkmcnt(" #n ")" ::: "memory")
; #define PG8_BAR __builtin_amdgcn_s_barrier()
; #define PG8_SCHED __builtin_amdgcn_sched_barrier(0)
; template <class Map, class Epi>
; DI void gemm_phase(LAS unsigned char* lds, const Map& MP, const Epi& E, const int nM, const int nN, const int K, const int lda, const int ldb) {
;     ...
;             PG8_LDA(At, 1, 1); PG8_STAGE(PG8_SA(1, 0), a3, voffA);
;             PG8_BAR; PG8_WAIT_L(0); PG8_MMA(1, 0, At, B0); PG8_BAR; PG8_SCHED;
;             PG8_STAGE(PG8_SB(1, 1), b3 + hstepB, voffB);
;             PG8_WAIT_V(6); PG8_BAR; PG8_MMA(1, 1, At, B1); PG8_BAR;
	ds_read_b128 v[166:169], v148 offset:49152
	ds_read_b128 v[170:173], v148 offset:50176
	ds_read_b128 v[174:177], v148 offset:51200
	ds_read_b128 v[178:181], v148 offset:52224
	ds_read_b128 v[182:185], v148 offset:53248
	ds_read_b128 v[186:189], v148 offset:54272
	ds_read_b128 v[190:193], v148 offset:55296
	ds_read_b128 v[198:201], v148 offset:56320
	global_load_lds_dwordx4 v[194:195], off
	v_lshl_add_u64 v[194:195], v[222:223], 0, s[8:9]
	s_mov_b32 m0, s42
	s_nop 0
	global_load_lds_dwordx4 v[194:195], off
	s_barrier
	s_setprio 1
	s_waitcnt lgkmcnt(7)
	v_mfma_f32_16x16x32_bf16 v[60:63], v[150:153], v[166:169], v[60:63]
	v_mfma_f32_16x16x32_bf16 v[56:59], v[158:161], v[166:169], v[56:59]
	s_waitcnt lgkmcnt(5)
	v_mfma_f32_16x16x32_bf16 v[52:55], v[150:153], v[174:177], v[52:55]
	v_mfma_f32_16x16x32_bf16 v[48:51], v[158:161], v[174:177], v[48:51]
	s_waitcnt lgkmcnt(3)
	v_mfma_f32_16x16x32_bf16 v[36:39], v[150:153], v[182:185], v[36:39]
	v_mfma_f32_16x16x32_bf16 v[32:35], v[158:161], v[182:185], v[32:35]
	s_waitcnt lgkmcnt(1)
	v_mfma_f32_16x16x32_bf16 v[20:23], v[150:153], v[190:193], v[20:23]
	v_mfma_f32_16x16x32_bf16 v[16:19], v[158:161], v[190:193], v[16:19]
	v_mfma_f32_16x16x32_bf16 v[60:63], v[154:157], v[170:173], v[60:63]
	v_mfma_f32_16x16x32_bf16 v[56:59], v[162:165], v[170:173], v[56:59]
	v_mfma_f32_16x16x32_bf16 v[52:55], v[154:157], v[178:181], v[52:55]
	v_mfma_f32_16x16x32_bf16 v[48:51], v[162:165], v[178:181], v[48:51]
	v_mfma_f32_16x16x32_bf16 v[36:39], v[154:157], v[186:189], v[36:39]
	v_mfma_f32_16x16x32_bf16 v[32:35], v[162:165], v[186:189], v[32:35]
	s_waitcnt lgkmcnt(0)
	v_mfma_f32_16x16x32_bf16 v[20:23], v[154:157], v[198:201], v[20:23]
	v_mfma_f32_16x16x32_bf16 v[16:19], v[162:165], v[198:201], v[16:19]
	s_setprio 0
	s_barrier
	s_add_u32 s22, s22, 0x80080
	s_addc_u32 s23, s23, 0
	s_add_i32 s3, s24, s29
	v_lshl_add_u64 v[150:151], s[22:23], 0, v[132:133]
	s_mov_b32 m0, s3
	s_nop 0
	global_load_lds_dwordx4 v[150:151], off
	v_lshl_add_u64 v[150:151], s[22:23], 0, v[128:129]
	s_add_i32 m0, s3, 0x2000
	s_nop 0
	global_load_lds_dwordx4 v[150:151], off
	s_waitcnt vmcnt(6)
	s_barrier
	s_setprio 1
	v_mfma_f32_16x16x32_bf16 v[44:47], v[202:205], v[166:169], v[44:47]
	v_mfma_f32_16x16x32_bf16 v[40:43], v[210:213], v[166:169], v[40:43]
	v_mfma_f32_16x16x32_bf16 v[28:31], v[202:205], v[174:177], v[28:31]
	v_mfma_f32_16x16x32_bf16 v[24:27], v[210:213], v[174:177], v[24:27]
	v_mfma_f32_16x16x32_bf16 v[12:15], v[202:205], v[182:185], v[12:15]
	v_mfma_f32_16x16x32_bf16 v[8:11], v[210:213], v[182:185], v[8:11]
	v_mfma_f32_16x16x32_bf16 v[4:7], v[202:205], v[190:193], v[4:7]
	v_mfma_f32_16x16x32_bf16 v[0:3], v[210:213], v[190:193], v[0:3]
	v_mfma_f32_16x16x32_bf16 v[44:47], v[206:209], v[170:173], v[44:47]
	v_mfma_f32_16x16x32_bf16 v[40:43], v[214:217], v[170:173], v[40:43]
	v_mfma_f32_16x16x32_bf16 v[28:31], v[206:209], v[178:181], v[28:31]
	v_mfma_f32_16x16x32_bf16 v[24:27], v[214:217], v[178:181], v[24:27]
	v_mfma_f32_16x16x32_bf16 v[12:15], v[206:209], v[186:189], v[12:15]
	v_mfma_f32_16x16x32_bf16 v[8:11], v[214:217], v[186:189], v[8:11]
	v_mfma_f32_16x16x32_bf16 v[4:7], v[206:209], v[198:201], v[4:7]
	v_mfma_f32_16x16x32_bf16 v[0:3], v[214:217], v[198:201], v[0:3]
	s_setprio 0
	s_add_i32 s54, s54, 2
	s_add_u32 s52, s52, 0x100
	s_addc_u32 s53, s53, 0
	s_add_u32 s20, s20, 0x100
	s_addc_u32 s21, s21, 0
	s_cmp_gt_u32 s54, 29
	s_barrier
	s_cbranch_scc0 .LBB1_693
; DI unsigned pack2(float a, float b) { f32x2 v = {a, b}; hwbf16x2 r = __builtin_convertvector(v, hwbf16x2); return __builtin_bit_cast(unsigned, r); }
;     DI void operator()(const f32x4 (&acc)[2][2][4][2], const Unit& u, int wr, int wc, int fr, int fq) const {
;         bf16_t* O = O1; int ldc = ldc1, pn = u.pn; if (pn >= split) { O = O2; ldc = ldc2; pn -= split; }
;         const int row0 = u.pm * BM + wr * 64 + fr, col0 = pn * BM + wc * 32 + 8 * fq;
; #pragma unroll
;         for (int ai = 0; ai < 2; ++ai)
; #pragma unroll
;             for (int m = 0; m < 4; ++m) { bf16_t* rowp = O + (size_t)(row0 + ai * HALF + m * 16) * ldc + col0;
; #pragma unroll
;                 for (int bj = 0; bj < 2; ++bj) { const f32x4 v0 = acc[ai][bj][m][0], v1 = acc[ai][bj][m][1];
;                     u32x4 o; o[0] = pack2(v0[0], v0[1]); o[1] = pack2(v0[2], v0[3]); o[2] = pack2(v1[0], v1[1]); o[3] = pack2(v1[2], v1[3]);
;                     *(u32x4*)(rowp + bj * HALF) = o; } }
;     }
	s_lshl_b32 s3, s10, 8
	v_mov_b32_e32 v150, v144
	v_mov_b32_e32 v151, v145
	s_add_i32 s3, s3, s37
	v_cvt_pk_bf16_f32 v68, v68, v69
	v_add_u32_e32 v154, s3, v150
	s_lshl_b32 s3, s47, 8
	s_or_b32 s3, s3, s38
	v_lshl_add_u32 v150, v151, 3, s3
	v_ashrrev_i32_e32 v151, 31, v150
	v_lshl_add_u64 v[150:151], v[150:151], 1, s[6:7]
	v_cvt_pk_bf16_f32 v69, v70, v71
	v_cvt_pk_bf16_f32 v70, v64, v65
	v_add_u32_e32 v64, 0x80, v154
	v_mad_i64_i32 v[152:153], s[20:21], v154, s46, v[150:151]
	v_cvt_pk_bf16_f32 v108, v108, v109
	v_cvt_pk_bf16_f32 v109, v110, v111
	v_cvt_pk_bf16_f32 v110, v104, v105
	v_cvt_pk_bf16_f32 v111, v106, v107
	v_add_u32_e32 v104, 16, v154
	v_mad_i64_i32 v[64:65], s[20:21], v64, s46, v[150:151]
	v_cvt_pk_bf16_f32 v44, v44, v45
	v_cvt_pk_bf16_f32 v45, v46, v47
	v_cvt_pk_bf16_f32 v46, v40, v41
	v_cvt_pk_bf16_f32 v47, v42, v43
	v_add_u32_e32 v40, 0x90, v154
	flat_store_dwordx4 v[152:153], v[108:111] offset:256
	v_cvt_pk_bf16_f32 v92, v92, v93
	v_cvt_pk_bf16_f32 v93, v94, v95
	v_mad_i64_i32 v[108:109], s[20:21], v104, s46, v[150:151]
	v_cvt_pk_bf16_f32 v94, v88, v89
	v_cvt_pk_bf16_f32 v95, v90, v91
	v_add_u32_e32 v88, 32, v154
	flat_store_dwordx4 v[64:65], v[44:47] offset:256
	v_cvt_pk_bf16_f32 v28, v28, v29
	v_cvt_pk_bf16_f32 v29, v30, v31
	v_mad_i64_i32 v[44:45], s[20:21], v40, s46, v[150:151]
	v_cvt_pk_bf16_f32 v30, v24, v25
	v_cvt_pk_bf16_f32 v31, v26, v27
	v_add_u32_e32 v24, 0xa0, v154
	flat_store_dwordx4 v[108:109], v[92:95] offset:256
	v_cvt_pk_bf16_f32 v76, v76, v77
	v_cvt_pk_bf16_f32 v77, v78, v79
	v_mad_i64_i32 v[92:93], s[20:21], v88, s46, v[150:151]
	v_cvt_pk_bf16_f32 v78, v72, v73
	v_cvt_pk_bf16_f32 v79, v74, v75
	v_add_u32_e32 v72, 48, v154
	flat_store_dwordx4 v[44:45], v[28:31] offset:256
	v_cvt_pk_bf16_f32 v12, v12, v13
	v_cvt_pk_bf16_f32 v13, v14, v15
	v_mad_i64_i32 v[28:29], s[20:21], v24, s46, v[150:151]
	v_cvt_pk_bf16_f32 v14, v8, v9
	v_cvt_pk_bf16_f32 v15, v10, v11
	v_add_u32_e32 v8, 0xb0, v154
	flat_store_dwordx4 v[92:93], v[76:79] offset:256
	flat_store_dwordx4 v[28:29], v[12:15] offset:256
	v_cvt_pk_bf16_f32 v124, v124, v125
	v_mad_i64_i32 v[76:77], s[20:21], v72, s46, v[150:151]
	v_mad_i64_i32 v[12:13], s[20:21], v8, s46, v[150:151]
	v_cvt_pk_bf16_f32 v125, v126, v127
	v_cvt_pk_bf16_f32 v126, v120, v121
	v_cvt_pk_bf16_f32 v127, v122, v123
	v_cvt_pk_bf16_f32 v104, v116, v117
	v_cvt_pk_bf16_f32 v105, v118, v119
	v_cvt_pk_bf16_f32 v106, v112, v113
	v_cvt_pk_bf16_f32 v107, v114, v115
	v_cvt_pk_bf16_f32 v88, v100, v101
	v_cvt_pk_bf16_f32 v89, v102, v103
	v_cvt_pk_bf16_f32 v90, v96, v97
	v_cvt_pk_bf16_f32 v91, v98, v99
	v_cvt_pk_bf16_f32 v72, v84, v85
	v_cvt_pk_bf16_f32 v73, v86, v87
	v_cvt_pk_bf16_f32 v74, v80, v81
	v_cvt_pk_bf16_f32 v75, v82, v83
	v_cvt_pk_bf16_f32 v71, v66, v67
	v_cvt_pk_bf16_f32 v60, v60, v61
	v_cvt_pk_bf16_f32 v61, v62, v63
	v_cvt_pk_bf16_f32 v62, v56, v57
	v_cvt_pk_bf16_f32 v63, v58, v59
	v_cvt_pk_bf16_f32 v40, v52, v53
	v_cvt_pk_bf16_f32 v41, v54, v55
	v_cvt_pk_bf16_f32 v42, v48, v49
	v_cvt_pk_bf16_f32 v43, v50, v51
	v_cvt_pk_bf16_f32 v24, v36, v37
	v_cvt_pk_bf16_f32 v25, v38, v39
	v_cvt_pk_bf16_f32 v26, v32, v33
	v_cvt_pk_bf16_f32 v27, v34, v35
	v_cvt_pk_bf16_f32 v8, v20, v21
	v_cvt_pk_bf16_f32 v9, v22, v23
	v_cvt_pk_bf16_f32 v10, v16, v17
	v_cvt_pk_bf16_f32 v11, v18, v19
	v_cvt_pk_bf16_f32 v4, v4, v5
	v_cvt_pk_bf16_f32 v5, v6, v7
	v_cvt_pk_bf16_f32 v6, v0, v1
	v_cvt_pk_bf16_f32 v7, v2, v3
	s_and_b64 vcc, exec, s[40:41]
	s_mov_b32 s47, s12
	s_mov_b32 s10, s14
	s_mov_b64 s[20:21], s[18:19]
	s_mov_b64 s[22:23], s[16:17]
	flat_store_dwordx4 v[152:153], v[124:127]
	flat_store_dwordx4 v[108:109], v[104:107]
	flat_store_dwordx4 v[92:93], v[88:91]
	flat_store_dwordx4 v[76:77], v[72:75]
	flat_store_dwordx4 v[76:77], v[68:71] offset:256
	flat_store_dwordx4 v[64:65], v[60:63]
	flat_store_dwordx4 v[44:45], v[40:43]
	flat_store_dwordx4 v[28:29], v[24:27]
	flat_store_dwordx4 v[12:13], v[8:11]
	flat_store_dwordx4 v[12:13], v[4:7] offset:256
	s_cbranch_vccz .LBB1_690
	s_waitcnt vmcnt(0)
	s_cmpk_gt_u32 s4, 0xff
	s_cbranch_scc1 .LBB1_697
	s_barrier

; #define PG8_STAGE(bufoff, gbase, voff) do { _Pragma("unroll") for (int _i = 0; _i < 2; ++_i) \
;         __builtin_amdgcn_global_load_lds((const unsigned*)((const char*)(gbase) + (voff)[_i]), (LAS unsigned*)(lds + (bufoff) + ldsw + _i * 8192), 16, 0, 0); } while (0)
; #define PG8_LDA(dst, b, h) do { _Pragma("unroll") for (int m = 0; m < 4; ++m) _Pragma("unroll") for (int k = 0; k < 2; ++k) dst[m][k] = *(const LAS bf16x8*)(lds + PG8_SA(b, h) + aoff + m * 2048 + k * 1024); } while (0)
; #define PG8_LDB(dst, b, h) do { _Pragma("unroll") for (int n = 0; n < 2; ++n) _Pragma("unroll") for (int k = 0; k < 2; ++k) dst[n][k] = *(const LAS bf16x8*)(lds + PG8_SB(b, h) + boff + n * 2048 + k * 1024); } while (0)
; #define PG8_MMA(ai, bj, At, Bt) do { __builtin_amdgcn_s_setprio(1); _Pragma("unroll") for (int m = 0; m < 4; ++m) _Pragma("unroll") for (int n = 0; n < 2; ++n) _Pragma("unroll") for (int k = 0; k < 2; ++k) \
;         acc[ai][bj][m][n] = __builtin_amdgcn_mfma_f32_16x16x32_bf16(Bt[n][k], At[m][k], acc[ai][bj][m][n], 0, 0, 0); __builtin_amdgcn_s_setprio(0); } while (0)
; #define PG8_WAIT_L(n) asm volatile("s_waitcnt lgkmcnt(" #n ")" ::: "memory")
; #define PG8_BAR __builtin_amdgcn_s_barrier()
; #define PG8_SCHED __builtin_amdgcn_sched_barrier(0)
; template <class Map, class Epi>
; DI void gemm_phase(LAS unsigned char* lds, const Map& MP, const Epi& E, const int nM, const int nN, const int K, const int lda, const int ldb) {
;     ...
;             PG8_LDB(B0, 0, 0); PG8_SCHED; PG8_LDA(At, 0, 0); PG8_STAGE(PG8_SA(1, 1), a1 + hstepA, voffA);
;             PG8_WAIT_L(8); PG8_BAR; PG8_WAIT_L(0); PG8_MMA(0, 0, At, B0); PG8_BAR; PG8_SCHED;
;             PG8_LDB(B1, 0, 1); PG8_STAGE(PG8_SB(0, 0), b2, voffB);
;             PG8_BAR; PG8_WAIT_L(0); PG8_MMA(0, 1, At, B1); PG8_BAR;
;             PG8_LDA(At, 0, 1); PG8_STAGE(PG8_SA(0, 0), a2, voffA);
;             PG8_BAR; PG8_WAIT_L(0); PG8_MMA(1, 0, At, B0); PG8_BAR; PG8_SCHED;
.LBB1_925:
	ds_read_b128 v[152:155], v149
	ds_read_b128 v[156:159], v149 offset:1024
	ds_read_b128 v[160:163], v149 offset:2048
	ds_read_b128 v[164:167], v149 offset:3072
	s_add_u32 s3, s10, 0xfff80080
	s_addc_u32 s12, s11, -1
	s_cmp_eq_u32 s48, 28
	s_cselect_b32 s15, s4, s12
	s_cselect_b32 s14, s5, s3
	s_cselect_b32 s13, s37, s47
	s_cselect_b32 s12, s38, s39
	v_lshl_add_u64 v[144:145], s[10:11], 0, v[138:139]
	s_add_i32 m0, s24, 0xc000
	ds_read_b128 v[168:171], v150
	ds_read_b128 v[172:175], v150 offset:1024
	ds_read_b128 v[176:179], v150 offset:2048
	ds_read_b128 v[180:183], v150 offset:3072
	ds_read_b128 v[184:187], v150 offset:4096
	ds_read_b128 v[188:191], v150 offset:5120
	ds_read_b128 v[192:195], v150 offset:6144
	ds_read_b128 v[198:201], v150 offset:7168
	global_load_lds_dwordx4 v[144:145], off
	v_lshl_add_u64 v[144:145], s[10:11], 0, v[136:137]
	s_add_i32 m0, s24, 0xe000
	s_nop 0
	global_load_lds_dwordx4 v[144:145], off
	s_waitcnt lgkmcnt(8)
	s_barrier
	s_setprio 1
	s_waitcnt lgkmcnt(7)
	v_mfma_f32_16x16x32_bf16 v[124:127], v[152:155], v[168:171], v[124:127]
	v_mfma_f32_16x16x32_bf16 v[120:123], v[160:163], v[168:171], v[120:123]
	s_waitcnt lgkmcnt(5)
	v_mfma_f32_16x16x32_bf16 v[108:111], v[152:155], v[176:179], v[108:111]
	v_mfma_f32_16x16x32_bf16 v[104:107], v[160:163], v[176:179], v[104:107]
	s_waitcnt lgkmcnt(3)
	v_mfma_f32_16x16x32_bf16 v[92:95], v[152:155], v[184:187], v[92:95]
	v_mfma_f32_16x16x32_bf16 v[88:91], v[160:163], v[184:187], v[88:91]
	s_waitcnt lgkmcnt(1)
	v_mfma_f32_16x16x32_bf16 v[76:79], v[152:155], v[192:195], v[76:79]
	v_mfma_f32_16x16x32_bf16 v[72:75], v[160:163], v[192:195], v[72:75]
	v_mfma_f32_16x16x32_bf16 v[124:127], v[156:159], v[172:175], v[124:127]
	v_mfma_f32_16x16x32_bf16 v[120:123], v[164:167], v[172:175], v[120:123]
	v_mfma_f32_16x16x32_bf16 v[108:111], v[156:159], v[180:183], v[108:111]
	v_mfma_f32_16x16x32_bf16 v[104:107], v[164:167], v[180:183], v[104:107]
	v_mfma_f32_16x16x32_bf16 v[92:95], v[156:159], v[188:191], v[92:95]
	v_mfma_f32_16x16x32_bf16 v[88:91], v[164:167], v[188:191], v[88:91]
	s_waitcnt lgkmcnt(0)
	v_mfma_f32_16x16x32_bf16 v[76:79], v[156:159], v[198:201], v[76:79]
	v_mfma_f32_16x16x32_bf16 v[72:75], v[164:167], v[198:201], v[72:75]
	s_setprio 0
	s_barrier
	s_add_i32 s3, s35, s22
	v_lshl_add_u64 v[144:145], s[12:13], 0, v[132:133]
	s_mov_b32 m0, s3
	ds_read_b128 v[202:205], v151
	ds_read_b128 v[206:209], v151 offset:1024
	ds_read_b128 v[210:213], v151 offset:2048
	ds_read_b128 v[214:217], v151 offset:3072
	global_load_lds_dwordx4 v[144:145], off
	v_lshl_add_u64 v[218:219], s[12:13], 0, v[128:129]
	s_add_i32 m0, s3, 0x2000
	s_nop 0
	global_load_lds_dwordx4 v[218:219], off
	s_barrier
	s_setprio 1
	s_waitcnt lgkmcnt(3)
	v_mfma_f32_16x16x32_bf16 v[116:119], v[202:205], v[168:171], v[116:119]
	s_waitcnt lgkmcnt(1)
	v_mfma_f32_16x16x32_bf16 v[112:115], v[210:213], v[168:171], v[112:115]
	v_mfma_f32_16x16x32_bf16 v[100:103], v[202:205], v[176:179], v[100:103]
	v_mfma_f32_16x16x32_bf16 v[96:99], v[210:213], v[176:179], v[96:99]
	v_mfma_f32_16x16x32_bf16 v[84:87], v[202:205], v[184:187], v[84:87]
	v_mfma_f32_16x16x32_bf16 v[80:83], v[210:213], v[184:187], v[80:83]
	v_mfma_f32_16x16x32_bf16 v[68:71], v[202:205], v[192:195], v[68:71]
	v_mfma_f32_16x16x32_bf16 v[64:67], v[210:213], v[192:195], v[64:67]
	v_mfma_f32_16x16x32_bf16 v[116:119], v[206:209], v[172:175], v[116:119]
	s_waitcnt lgkmcnt(0)
	v_mfma_f32_16x16x32_bf16 v[112:115], v[214:217], v[172:175], v[112:115]
	v_mfma_f32_16x16x32_bf16 v[100:103], v[206:209], v[180:183], v[100:103]
	v_mfma_f32_16x16x32_bf16 v[96:99], v[214:217], v[180:183], v[96:99]
	v_mfma_f32_16x16x32_bf16 v[84:87], v[206:209], v[188:191], v[84:87]
	v_mfma_f32_16x16x32_bf16 v[80:83], v[214:217], v[188:191], v[80:83]
	v_mfma_f32_16x16x32_bf16 v[68:71], v[206:209], v[198:201], v[68:71]
	v_mfma_f32_16x16x32_bf16 v[64:67], v[214:217], v[198:201], v[64:67]
	s_setprio 0
	s_mov_b32 m0, s24
	v_lshl_add_u64 v[220:221], s[14:15], 0, v[134:135]
	s_barrier
	ds_read_b128 v[168:171], v150 offset:16384
	ds_read_b128 v[172:175], v150 offset:17408
	ds_read_b128 v[176:179], v150 offset:18432
	ds_read_b128 v[180:183], v150 offset:19456
	ds_read_b128 v[184:187], v150 offset:20480
	ds_read_b128 v[188:191], v150 offset:21504
	ds_read_b128 v[192:195], v150 offset:22528
	ds_read_b128 v[198:201], v150 offset:23552
	global_load_lds_dwordx4 v[220:221], off
	v_lshl_add_u64 v[222:223], s[14:15], 0, v[130:131]
	s_mov_b32 m0, s9
	s_nop 0
	global_load_lds_dwordx4 v[222:223], off
	s_barrier
	s_setprio 1
	s_waitcnt lgkmcnt(7)
	v_mfma_f32_16x16x32_bf16 v[60:63], v[152:155], v[168:171], v[60:63]
	v_mfma_f32_16x16x32_bf16 v[56:59], v[160:163], v[168:171], v[56:59]
	s_waitcnt lgkmcnt(5)
	v_mfma_f32_16x16x32_bf16 v[44:47], v[152:155], v[176:179], v[44:47]
	v_mfma_f32_16x16x32_bf16 v[40:43], v[160:163], v[176:179], v[40:43]
	s_waitcnt lgkmcnt(3)
	v_mfma_f32_16x16x32_bf16 v[28:31], v[152:155], v[184:187], v[28:31]
	v_mfma_f32_16x16x32_bf16 v[24:27], v[160:163], v[184:187], v[24:27]
	s_waitcnt lgkmcnt(1)
	v_mfma_f32_16x16x32_bf16 v[12:15], v[152:155], v[192:195], v[12:15]
	v_mfma_f32_16x16x32_bf16 v[8:11], v[160:163], v[192:195], v[8:11]
	v_mfma_f32_16x16x32_bf16 v[60:63], v[156:159], v[172:175], v[60:63]
	v_mfma_f32_16x16x32_bf16 v[56:59], v[164:167], v[172:175], v[56:59]
	v_mfma_f32_16x16x32_bf16 v[44:47], v[156:159], v[180:183], v[44:47]
	v_mfma_f32_16x16x32_bf16 v[40:43], v[164:167], v[180:183], v[40:43]
	v_mfma_f32_16x16x32_bf16 v[28:31], v[156:159], v[188:191], v[28:31]
	v_mfma_f32_16x16x32_bf16 v[24:27], v[164:167], v[188:191], v[24:27]
	s_waitcnt lgkmcnt(0)
	v_mfma_f32_16x16x32_bf16 v[12:15], v[156:159], v[198:201], v[12:15]
	v_mfma_f32_16x16x32_bf16 v[8:11], v[164:167], v[198:201], v[8:11]
	s_setprio 0
	s_barrier
; #define PG8_STAGE(bufoff, gbase, voff) do { _Pragma("unroll") for (int _i = 0; _i < 2; ++_i) \
;         __builtin_amdgcn_global_load_lds((const unsigned*)((const char*)(gbase) + (voff)[_i]), (LAS unsigned*)(lds + (bufoff) + ldsw + _i * 8192), 16, 0, 0); } while (0)
; #define PG8_LDA(dst, b, h) do { _Pragma("unroll") for (int m = 0; m < 4; ++m) _Pragma("unroll") for (int k = 0; k < 2; ++k) dst[m][k] = *(const LAS bf16x8*)(lds + PG8_SA(b, h) + aoff + m * 2048 + k * 1024); } while (0)
; #define PG8_LDB(dst, b, h) do { _Pragma("unroll") for (int n = 0; n < 2; ++n) _Pragma("unroll") for (int k = 0; k < 2; ++k) dst[n][k] = *(const LAS bf16x8*)(lds + PG8_SB(b, h) + boff + n * 2048 + k * 1024); } while (0)
; #define PG8_MMA(ai, bj, At, Bt) do { __builtin_amdgcn_s_setprio(1); _Pragma("unroll") for (int m = 0; m < 4; ++m) _Pragma("unroll") for (int n = 0; n < 2; ++n) _Pragma("unroll") for (int k = 0; k < 2; ++k) \
;         acc[ai][bj][m][n] = __builtin_amdgcn_mfma_f32_16x16x32_bf16(Bt[n][k], At[m][k], acc[ai][bj][m][n], 0, 0, 0); __builtin_amdgcn_s_setprio(0); } while (0)
; #define PG8_WAIT_V(n) asm volatile("s_waitcnt vmcnt(" #n ")" ::: "memory")
; #define PG8_WAIT_L(n) asm volatile("s_waitcnt lgkmcnt(" #n ")" ::: "memory")
; #define PG8_BAR __builtin_amdgcn_s_barrier()
; #define PG8_SCHED __builtin_amdgcn_sched_barrier(0)
; template <class Map, class Epi>
; DI void gemm_phase(LAS unsigned char* lds, const Map& MP, const Epi& E, const int nM, const int nN, const int K, const int lda, const int ldb) {
;     ...
;             PG8_STAGE(PG8_SB(0, 1), b2 + hstepB, voffB);
;             PG8_WAIT_V(6); PG8_BAR; PG8_MMA(1, 1, At, B1); PG8_BAR;
;             PG8_LDB(B0, 1, 0); PG8_SCHED; PG8_LDA(At, 1, 0); PG8_STAGE(PG8_SA(0, 1), a2 + hstepA, voffA);
;             PG8_WAIT_L(8); PG8_BAR; PG8_WAIT_L(0); PG8_MMA(0, 0, At, B0); PG8_BAR; PG8_SCHED;
;             PG8_LDB(B1, 1, 1); PG8_STAGE(PG8_SB(1, 0), b3, voffB);
;             PG8_BAR; PG8_WAIT_L(0); PG8_MMA(0, 1, At, B1); PG8_BAR;
;             PG8_LDA(At, 1, 1); PG8_STAGE(PG8_SA(1, 0), a3, voffA);
	s_add_u32 s56, s12, 0x80000
	s_addc_u32 s57, s13, 0
	s_add_i32 s3, s36, s22
	v_lshl_add_u64 v[152:153], s[56:57], 0, v[132:133]
	s_mov_b32 m0, s3
	s_nop 0
	global_load_lds_dwordx4 v[152:153], off
	v_lshl_add_u64 v[152:153], s[56:57], 0, v[128:129]
	s_add_i32 m0, s3, 0x2000
	s_nop 0
	global_load_lds_dwordx4 v[152:153], off
	s_waitcnt vmcnt(6)
	s_barrier
	s_setprio 1
	v_mfma_f32_16x16x32_bf16 v[52:55], v[202:205], v[168:171], v[52:55]
	v_mfma_f32_16x16x32_bf16 v[48:51], v[210:213], v[168:171], v[48:51]
	v_mfma_f32_16x16x32_bf16 v[36:39], v[202:205], v[176:179], v[36:39]
	v_mfma_f32_16x16x32_bf16 v[32:35], v[210:213], v[176:179], v[32:35]
	v_mfma_f32_16x16x32_bf16 v[20:23], v[202:205], v[184:187], v[20:23]
	v_mfma_f32_16x16x32_bf16 v[16:19], v[210:213], v[184:187], v[16:19]
	v_mfma_f32_16x16x32_bf16 v[4:7], v[202:205], v[192:195], v[4:7]
	v_mfma_f32_16x16x32_bf16 v[0:3], v[210:213], v[192:195], v[0:3]
	v_mfma_f32_16x16x32_bf16 v[52:55], v[206:209], v[172:175], v[52:55]
	v_mfma_f32_16x16x32_bf16 v[48:51], v[214:217], v[172:175], v[48:51]
	v_mfma_f32_16x16x32_bf16 v[36:39], v[206:209], v[180:183], v[36:39]
	v_mfma_f32_16x16x32_bf16 v[32:35], v[214:217], v[180:183], v[32:35]
	v_mfma_f32_16x16x32_bf16 v[20:23], v[206:209], v[188:191], v[20:23]
	v_mfma_f32_16x16x32_bf16 v[16:19], v[214:217], v[188:191], v[16:19]
	v_mfma_f32_16x16x32_bf16 v[4:7], v[206:209], v[198:201], v[4:7]
	v_mfma_f32_16x16x32_bf16 v[0:3], v[214:217], v[198:201], v[0:3]
	s_setprio 0
	s_add_i32 s3, 0, 0x18000
	v_add_u32_e32 v164, s3, v148
	s_barrier
	ds_read_b128 v[152:155], v164
	ds_read_b128 v[156:159], v164 offset:1024
	ds_read_b128 v[160:163], v164 offset:2048
	ds_read_b128 v[164:167], v164 offset:3072
	s_add_u32 s14, s14, 0x80000
	s_addc_u32 s15, s15, 0
	s_mov_b32 m0, s25
	v_lshl_add_u64 v[202:203], s[14:15], 0, v[134:135]
	ds_read_b128 v[168:171], v150 offset:32768
	ds_read_b128 v[172:175], v150 offset:33792
	ds_read_b128 v[176:179], v150 offset:34816
	ds_read_b128 v[180:183], v150 offset:35840
	ds_read_b128 v[184:187], v150 offset:36864
	ds_read_b128 v[188:191], v150 offset:37888
	ds_read_b128 v[192:195], v150 offset:38912
	ds_read_b128 v[198:201], v150 offset:39936
	global_load_lds_dwordx4 v[202:203], off
	v_lshl_add_u64 v[202:203], s[14:15], 0, v[130:131]
	s_mov_b32 m0, s26
	s_nop 0
	global_load_lds_dwordx4 v[202:203], off
	s_waitcnt lgkmcnt(8)
	s_barrier
	s_setprio 1
	s_waitcnt lgkmcnt(7)
	v_mfma_f32_16x16x32_bf16 v[124:127], v[152:155], v[168:171], v[124:127]
	v_mfma_f32_16x16x32_bf16 v[120:123], v[160:163], v[168:171], v[120:123]
	s_waitcnt lgkmcnt(5)
	v_mfma_f32_16x16x32_bf16 v[108:111], v[152:155], v[176:179], v[108:111]
	v_mfma_f32_16x16x32_bf16 v[104:107], v[160:163], v[176:179], v[104:107]
	s_waitcnt lgkmcnt(3)
	v_mfma_f32_16x16x32_bf16 v[92:95], v[152:155], v[184:187], v[92:95]
	v_mfma_f32_16x16x32_bf16 v[88:91], v[160:163], v[184:187], v[88:91]
	s_waitcnt lgkmcnt(1)
	v_mfma_f32_16x16x32_bf16 v[76:79], v[152:155], v[192:195], v[76:79]
	v_mfma_f32_16x16x32_bf16 v[72:75], v[160:163], v[192:195], v[72:75]
	v_mfma_f32_16x16x32_bf16 v[124:127], v[156:159], v[172:175], v[124:127]
	v_mfma_f32_16x16x32_bf16 v[120:123], v[164:167], v[172:175], v[120:123]
	v_mfma_f32_16x16x32_bf16 v[108:111], v[156:159], v[180:183], v[108:111]
	v_mfma_f32_16x16x32_bf16 v[104:107], v[164:167], v[180:183], v[104:107]
	v_mfma_f32_16x16x32_bf16 v[92:95], v[156:159], v[188:191], v[92:95]
	v_mfma_f32_16x16x32_bf16 v[88:91], v[164:167], v[188:191], v[88:91]
	s_waitcnt lgkmcnt(0)
	v_mfma_f32_16x16x32_bf16 v[76:79], v[156:159], v[198:201], v[76:79]
	v_mfma_f32_16x16x32_bf16 v[72:75], v[164:167], v[198:201], v[72:75]
	s_setprio 0
	s_barrier
	s_add_i32 s14, 0, 0x1c000
	s_add_i32 s3, s3, s22
	v_add_u32_e32 v196, s14, v148
	v_lshl_add_u64 v[144:145], v[144:145], 0, s[44:45]
	s_mov_b32 m0, s3
	ds_read_b128 v[202:205], v196
	ds_read_b128 v[206:209], v196 offset:1024
	ds_read_b128 v[210:213], v196 offset:2048
	ds_read_b128 v[214:217], v196 offset:3072
	global_load_lds_dwordx4 v[144:145], off
	v_lshl_add_u64 v[144:145], v[218:219], 0, s[44:45]
	s_add_i32 m0, s3, 0x2000
	s_nop 0
	global_load_lds_dwordx4 v[144:145], off
	s_barrier
	s_setprio 1
	s_waitcnt lgkmcnt(3)
	v_mfma_f32_16x16x32_bf16 v[116:119], v[202:205], v[168:171], v[116:119]
	s_waitcnt lgkmcnt(1)
	v_mfma_f32_16x16x32_bf16 v[112:115], v[210:213], v[168:171], v[112:115]
	v_mfma_f32_16x16x32_bf16 v[100:103], v[202:205], v[176:179], v[100:103]
	v_mfma_f32_16x16x32_bf16 v[96:99], v[210:213], v[176:179], v[96:99]
	v_mfma_f32_16x16x32_bf16 v[84:87], v[202:205], v[184:187], v[84:87]
	v_mfma_f32_16x16x32_bf16 v[80:83], v[210:213], v[184:187], v[80:83]
	v_mfma_f32_16x16x32_bf16 v[68:71], v[202:205], v[192:195], v[68:71]
	v_mfma_f32_16x16x32_bf16 v[64:67], v[210:213], v[192:195], v[64:67]
	v_mfma_f32_16x16x32_bf16 v[116:119], v[206:209], v[172:175], v[116:119]
	s_waitcnt lgkmcnt(0)
	v_mfma_f32_16x16x32_bf16 v[112:115], v[214:217], v[172:175], v[112:115]
	v_mfma_f32_16x16x32_bf16 v[100:103], v[206:209], v[180:183], v[100:103]
	v_mfma_f32_16x16x32_bf16 v[96:99], v[214:217], v[180:183], v[96:99]
	v_mfma_f32_16x16x32_bf16 v[84:87], v[206:209], v[188:191], v[84:87]
	v_mfma_f32_16x16x32_bf16 v[80:83], v[214:217], v[188:191], v[80:83]
	v_mfma_f32_16x16x32_bf16 v[68:71], v[206:209], v[198:201], v[68:71]
	v_mfma_f32_16x16x32_bf16 v[64:67], v[214:217], v[198:201], v[64:67]
	s_setprio 0
	s_mov_b32 m0, s30
	v_lshl_add_u64 v[144:145], v[220:221], 0, s[44:45]
	s_barrier
; DI unsigned pack2(float a, float b) { f32x2 v = {a, b}; hwbf16x2 r = __builtin_convertvector(v, hwbf16x2); return __builtin_bit_cast(unsigned, r); }
; DI float bflo(unsigned w) { return __uint_as_float(w << 16); }
; DI float bfhi(unsigned w) { return __uint_as_float(w & 0xffff0000u); }
;     DI void operator()(const f32x4 (&acc)[2][2][4][2], const Unit& u, int wr, int wc, int fr, int fq) const {
;         const int row0 = u.pm * BM + wr * 64 + fr, col0 = u.pn * BM + wc * 32 + 8 * fq;
;         f32x4 sc[2][2];
; #pragma unroll
;         for (int bj = 0; bj < 2; ++bj)
; #pragma unroll
;             for (int n = 0; n < 2; ++n) sc[bj][n] = scale ? *(const f32x4*)(scale + col0 + bj * HALF + 4 * n) : (f32x4){1.f, 1.f, 1.f, 1.f};
; #pragma unroll
;         for (int ai = 0; ai < 2; ++ai)
; #pragma unroll
;             for (int m = 0; m < 4; ++m) { const size_t ro = (size_t)(row0 + ai * HALF + m * 16) * D + col0;
; #pragma unroll
;                 for (int bj = 0; bj < 2; ++bj) {
;                     f32x4 x0, x1;
;                     if constexpr (IB) { const u32x4 w = *(const u32x4*)((const bf16_t*)Xin + ro + bj * HALF);
;                         x0 = (f32x4){bflo(w[0]), bfhi(w[0]), bflo(w[1]), bfhi(w[1])}; x1 = (f32x4){bflo(w[2]), bfhi(w[2]), bflo(w[3]), bfhi(w[3])}; }
;                     else { x0 = *(const f32x4*)((const float*)Xin + ro + bj * HALF); x1 = *(const f32x4*)((const float*)Xin + ro + bj * HALF + 4); }
;                     x0 += acc[ai][bj][m][0] * sc[bj][0]; x1 += acc[ai][bj][m][1] * sc[bj][1];
;                     if constexpr (OB) { u32x4 o; o[0] = pack2(x0[0], x0[1]); o[1] = pack2(x0[2], x0[3]); o[2] = pack2(x1[0], x1[1]); o[3] = pack2(x1[2], x1[3]);
;                         *(u32x4*)((bf16_t*)Xout + ro + bj * HALF) = o; }
;                     else { *(f32x4*)((float*)Xout + ro + bj * HALF) = x0; *(f32x4*)((float*)Xout + ro + bj * HALF + 4) = x1; } } }
; template <class Map, class Epi>
; DI void gemm_phase(LAS unsigned char* lds, const Map& MP, const Epi& E, const int nM, const int nN, const int K, const int lda, const int ldb) {
;     ...
;             PG8_LDA(At, 1, 1); PG8_STAGE(PG8_SA(1, 0), a3, voffA);
;             PG8_BAR; PG8_WAIT_L(0); PG8_MMA(1, 0, At, B0); PG8_BAR; PG8_SCHED;
;             PG8_STAGE(PG8_SB(1, 1), b3 + hstepB, voffB);
;             PG8_WAIT_V(6); PG8_BAR; PG8_MMA(1, 1, At, B1); PG8_BAR;
	ds_read_b128 v[168:171], v150 offset:49152
	ds_read_b128 v[172:175], v150 offset:50176
	ds_read_b128 v[176:179], v150 offset:51200
	ds_read_b128 v[180:183], v150 offset:52224
	ds_read_b128 v[184:187], v150 offset:53248
	ds_read_b128 v[188:191], v150 offset:54272
	ds_read_b128 v[192:195], v150 offset:55296
	ds_read_b128 v[198:201], v150 offset:56320
	global_load_lds_dwordx4 v[144:145], off
	v_lshl_add_u64 v[144:145], v[222:223], 0, s[44:45]
	s_mov_b32 m0, s31
	s_nop 0
	global_load_lds_dwordx4 v[144:145], off
	s_barrier
	s_setprio 1
	s_waitcnt lgkmcnt(7)
	v_mfma_f32_16x16x32_bf16 v[60:63], v[152:155], v[168:171], v[60:63]
	v_mfma_f32_16x16x32_bf16 v[56:59], v[160:163], v[168:171], v[56:59]
	s_waitcnt lgkmcnt(5)
	v_mfma_f32_16x16x32_bf16 v[44:47], v[152:155], v[176:179], v[44:47]
	v_mfma_f32_16x16x32_bf16 v[40:43], v[160:163], v[176:179], v[40:43]
	s_waitcnt lgkmcnt(3)
	v_mfma_f32_16x16x32_bf16 v[28:31], v[152:155], v[184:187], v[28:31]
	v_mfma_f32_16x16x32_bf16 v[24:27], v[160:163], v[184:187], v[24:27]
	s_waitcnt lgkmcnt(1)
	v_mfma_f32_16x16x32_bf16 v[12:15], v[152:155], v[192:195], v[12:15]
	v_mfma_f32_16x16x32_bf16 v[8:11], v[160:163], v[192:195], v[8:11]
	v_mfma_f32_16x16x32_bf16 v[60:63], v[156:159], v[172:175], v[60:63]
	v_mfma_f32_16x16x32_bf16 v[56:59], v[164:167], v[172:175], v[56:59]
	v_mfma_f32_16x16x32_bf16 v[44:47], v[156:159], v[180:183], v[44:47]
	v_mfma_f32_16x16x32_bf16 v[40:43], v[164:167], v[180:183], v[40:43]
	v_mfma_f32_16x16x32_bf16 v[28:31], v[156:159], v[188:191], v[28:31]
	v_mfma_f32_16x16x32_bf16 v[24:27], v[164:167], v[188:191], v[24:27]
	s_waitcnt lgkmcnt(0)
	v_mfma_f32_16x16x32_bf16 v[12:15], v[156:159], v[198:201], v[12:15]
	v_mfma_f32_16x16x32_bf16 v[8:11], v[164:167], v[198:201], v[8:11]
	s_setprio 0
	s_barrier
	s_add_u32 s12, s12, 0x80080
	s_addc_u32 s13, s13, 0
	s_add_i32 s3, s14, s22
	v_lshl_add_u64 v[144:145], s[12:13], 0, v[132:133]
	s_mov_b32 m0, s3
	s_nop 0
	global_load_lds_dwordx4 v[144:145], off
	v_lshl_add_u64 v[144:145], s[12:13], 0, v[128:129]
	s_add_i32 m0, s3, 0x2000
	s_nop 0
	global_load_lds_dwordx4 v[144:145], off
	s_waitcnt vmcnt(6)
	s_barrier
	s_setprio 1
	v_mfma_f32_16x16x32_bf16 v[52:55], v[202:205], v[168:171], v[52:55]
	v_mfma_f32_16x16x32_bf16 v[48:51], v[210:213], v[168:171], v[48:51]
	v_mfma_f32_16x16x32_bf16 v[36:39], v[202:205], v[176:179], v[36:39]
	v_mfma_f32_16x16x32_bf16 v[32:35], v[210:213], v[176:179], v[32:35]
	v_mfma_f32_16x16x32_bf16 v[20:23], v[202:205], v[184:187], v[20:23]
	v_mfma_f32_16x16x32_bf16 v[16:19], v[210:213], v[184:187], v[16:19]
	v_mfma_f32_16x16x32_bf16 v[4:7], v[202:205], v[192:195], v[4:7]
	v_mfma_f32_16x16x32_bf16 v[0:3], v[210:213], v[192:195], v[0:3]
	v_mfma_f32_16x16x32_bf16 v[52:55], v[206:209], v[172:175], v[52:55]
	v_mfma_f32_16x16x32_bf16 v[48:51], v[214:217], v[172:175], v[48:51]
	v_mfma_f32_16x16x32_bf16 v[36:39], v[206:209], v[180:183], v[36:39]
	v_mfma_f32_16x16x32_bf16 v[32:35], v[214:217], v[180:183], v[32:35]
	v_mfma_f32_16x16x32_bf16 v[20:23], v[206:209], v[188:191], v[20:23]
	v_mfma_f32_16x16x32_bf16 v[16:19], v[214:217], v[188:191], v[16:19]
	v_mfma_f32_16x16x32_bf16 v[4:7], v[206:209], v[198:201], v[4:7]
	v_mfma_f32_16x16x32_bf16 v[0:3], v[214:217], v[198:201], v[0:3]
	s_setprio 0
	s_add_i32 s48, s48, 2
	s_add_u32 s39, s39, 0x100
	s_addc_u32 s47, s47, 0
	s_add_u32 s10, s10, 0x100
	s_addc_u32 s11, s11, 0
	s_cmp_gt_u32 s48, 29
	s_barrier
	s_cbranch_scc0 .LBB1_925
	v_mov_b32_e32 v152, v147
	v_mov_b32_e32 v144, v146
	s_lshl_b32 s2, s2, 8
	s_or_b32 s2, s2, s29
	v_lshl_add_u32 v144, v144, 3, s2
	s_lshl_b32 s2, s8, 8
	s_add_i32 s2, s2, s28
	v_add_u32_e32 v152, s2, v152
	v_ashrrev_i32_e32 v153, 31, v152
	v_lshlrev_b64 v[152:153], 12, v[152:153]
	v_ashrrev_i32_e32 v145, 31, v144
	v_lshl_add_u64 v[152:153], s[42:43], 0, v[152:153]
	v_lshl_add_u64 v[144:145], v[144:145], 1, v[152:153]
	flat_load_dwordx4 v[152:155], v[144:145]
	s_mov_b64 s[2:3], 0x10000
	s_mov_b32 s8, s52
	s_mov_b64 s[10:11], s[6:7]
	s_mov_b64 s[12:13], s[54:55]
	s_waitcnt vmcnt(0) lgkmcnt(0)
	v_lshlrev_b32_e32 v156, 16, v152
	v_and_b32_e32 v157, 0xffff0000, v152
	v_lshlrev_b32_e32 v152, 16, v153
	v_and_b32_e32 v153, 0xffff0000, v153
	v_lshlrev_b32_e32 v158, 16, v154
	v_and_b32_e32 v159, 0xffff0000, v154
	v_lshlrev_b32_e32 v154, 16, v155
	v_and_b32_e32 v155, 0xffff0000, v155
	v_pk_add_f32 v[126:127], v[126:127], v[152:153]
	v_pk_add_f32 v[124:125], v[124:125], v[156:157]
	v_pk_add_f32 v[152:153], v[122:123], v[154:155]
	v_pk_add_f32 v[122:123], v[120:121], v[158:159]
	v_cvt_pk_bf16_f32 v120, v124, v125
	v_cvt_pk_bf16_f32 v121, v126, v127
	v_cvt_pk_bf16_f32 v122, v122, v123
	v_cvt_pk_bf16_f32 v123, v152, v153
	flat_store_dwordx4 v[144:145], v[120:123]
	flat_load_dwordx4 v[120:123], v[144:145] offset:256
	s_waitcnt vmcnt(0) lgkmcnt(0)
	v_lshlrev_b32_e32 v124, 16, v120
	v_and_b32_e32 v125, 0xffff0000, v120
	v_lshlrev_b32_e32 v120, 16, v121
	v_and_b32_e32 v121, 0xffff0000, v121
	v_lshlrev_b32_e32 v126, 16, v122
	v_and_b32_e32 v127, 0xffff0000, v122
	v_lshlrev_b32_e32 v122, 16, v123
	v_and_b32_e32 v123, 0xffff0000, v123
	v_pk_add_f32 v[116:117], v[116:117], v[124:125]
	v_pk_add_f32 v[118:119], v[118:119], v[120:121]
	v_pk_add_f32 v[120:121], v[114:115], v[122:123]
	v_pk_add_f32 v[114:115], v[112:113], v[126:127]
	v_cvt_pk_bf16_f32 v112, v116, v117
	v_lshl_add_u64 v[116:117], v[144:145], 0, s[2:3]
	s_mov_b32 s2, 0x10000
	v_cvt_pk_bf16_f32 v113, v118, v119
	v_add_co_u32_e32 v118, vcc, s2, v144
	v_cvt_pk_bf16_f32 v114, v114, v115
	v_cvt_pk_bf16_f32 v115, v120, v121
	v_addc_co_u32_e32 v119, vcc, 0, v145, vcc
	flat_store_dwordx4 v[144:145], v[112:115] offset:256
	flat_load_dwordx4 v[112:115], v[118:119]
	s_mov_b64 s[2:3], 0x20000
	s_waitcnt vmcnt(0) lgkmcnt(0)
; DI unsigned pack2(float a, float b) { f32x2 v = {a, b}; hwbf16x2 r = __builtin_convertvector(v, hwbf16x2); return __builtin_bit_cast(unsigned, r); }
; DI float bflo(unsigned w) { return __uint_as_float(w << 16); }
; DI float bfhi(unsigned w) { return __uint_as_float(w & 0xffff0000u); }
;     DI void operator()(const f32x4 (&acc)[2][2][4][2], const Unit& u, int wr, int wc, int fr, int fq) const {
;     ...
;         for (int ai = 0; ai < 2; ++ai)
; #pragma unroll
;             for (int m = 0; m < 4; ++m) { const size_t ro = (size_t)(row0 + ai * HALF + m * 16) * D + col0;
; #pragma unroll
;                 for (int bj = 0; bj < 2; ++bj) {
;                     f32x4 x0, x1;
;                     if constexpr (IB) { const u32x4 w = *(const u32x4*)((const bf16_t*)Xin + ro + bj * HALF);
;                         x0 = (f32x4){bflo(w[0]), bfhi(w[0]), bflo(w[1]), bfhi(w[1])}; x1 = (f32x4){bflo(w[2]), bfhi(w[2]), bflo(w[3]), bfhi(w[3])}; }
;                     else { x0 = *(const f32x4*)((const float*)Xin + ro + bj * HALF); x1 = *(const f32x4*)((const float*)Xin + ro + bj * HALF + 4); }
;                     x0 += acc[ai][bj][m][0] * sc[bj][0]; x1 += acc[ai][bj][m][1] * sc[bj][1];
;                     if constexpr (OB) { u32x4 o; o[0] = pack2(x0[0], x0[1]); o[1] = pack2(x0[2], x0[3]); o[2] = pack2(x1[0], x1[1]); o[3] = pack2(x1[2], x1[3]);
;                         *(u32x4*)((bf16_t*)Xout + ro + bj * HALF) = o; }
;                     else { *(f32x4*)((float*)Xout + ro + bj * HALF) = x0; *(f32x4*)((float*)Xout + ro + bj * HALF + 4) = x1; } } }
	v_lshlrev_b32_e32 v120, 16, v112
	v_and_b32_e32 v121, 0xffff0000, v112
	v_lshlrev_b32_e32 v112, 16, v113
	v_and_b32_e32 v113, 0xffff0000, v113
	v_lshlrev_b32_e32 v122, 16, v114
	v_and_b32_e32 v123, 0xffff0000, v114
	v_lshlrev_b32_e32 v114, 16, v115
	v_and_b32_e32 v115, 0xffff0000, v115
	v_pk_add_f32 v[110:111], v[110:111], v[112:113]
	v_pk_add_f32 v[108:109], v[108:109], v[120:121]
	v_pk_add_f32 v[112:113], v[106:107], v[114:115]
	v_pk_add_f32 v[106:107], v[104:105], v[122:123]
	v_cvt_pk_bf16_f32 v104, v108, v109
	v_cvt_pk_bf16_f32 v105, v110, v111
	v_cvt_pk_bf16_f32 v106, v106, v107
	v_cvt_pk_bf16_f32 v107, v112, v113
	flat_store_dwordx4 v[118:119], v[104:107]
	flat_load_dwordx4 v[104:107], v[116:117] offset:256
	s_waitcnt vmcnt(0) lgkmcnt(0)
	v_lshlrev_b32_e32 v108, 16, v104
	v_and_b32_e32 v109, 0xffff0000, v104
	v_lshlrev_b32_e32 v104, 16, v105
	v_and_b32_e32 v105, 0xffff0000, v105
	v_lshlrev_b32_e32 v110, 16, v106
	v_and_b32_e32 v111, 0xffff0000, v106
	v_lshlrev_b32_e32 v106, 16, v107
	v_and_b32_e32 v107, 0xffff0000, v107
	v_pk_add_f32 v[100:101], v[100:101], v[108:109]
	v_pk_add_f32 v[102:103], v[102:103], v[104:105]
	v_pk_add_f32 v[104:105], v[98:99], v[106:107]
	v_pk_add_f32 v[98:99], v[96:97], v[110:111]
	v_cvt_pk_bf16_f32 v96, v100, v101
	v_lshl_add_u64 v[100:101], v[144:145], 0, s[2:3]
	s_mov_b32 s2, 0x20000
	v_cvt_pk_bf16_f32 v97, v102, v103
	v_add_co_u32_e32 v102, vcc, s2, v144
	v_cvt_pk_bf16_f32 v98, v98, v99
	v_cvt_pk_bf16_f32 v99, v104, v105
	v_addc_co_u32_e32 v103, vcc, 0, v145, vcc
	flat_store_dwordx4 v[116:117], v[96:99] offset:256
	flat_load_dwordx4 v[96:99], v[102:103]
	s_mov_b64 s[2:3], 0x30000
	s_waitcnt vmcnt(0) lgkmcnt(0)
	v_lshlrev_b32_e32 v104, 16, v96
	v_and_b32_e32 v105, 0xffff0000, v96
	v_lshlrev_b32_e32 v96, 16, v97
	v_and_b32_e32 v97, 0xffff0000, v97
	v_lshlrev_b32_e32 v106, 16, v98
	v_and_b32_e32 v107, 0xffff0000, v98
	v_lshlrev_b32_e32 v98, 16, v99
	v_and_b32_e32 v99, 0xffff0000, v99
	v_pk_add_f32 v[94:95], v[94:95], v[96:97]
	v_pk_add_f32 v[92:93], v[92:93], v[104:105]
	v_pk_add_f32 v[96:97], v[90:91], v[98:99]
	v_pk_add_f32 v[90:91], v[88:89], v[106:107]
	v_cvt_pk_bf16_f32 v88, v92, v93
	v_cvt_pk_bf16_f32 v89, v94, v95
	v_cvt_pk_bf16_f32 v90, v90, v91
	v_cvt_pk_bf16_f32 v91, v96, v97
	flat_store_dwordx4 v[102:103], v[88:91]
	flat_load_dwordx4 v[88:91], v[100:101] offset:256
	s_waitcnt vmcnt(0) lgkmcnt(0)
	v_lshlrev_b32_e32 v92, 16, v88
	v_and_b32_e32 v93, 0xffff0000, v88
	v_lshlrev_b32_e32 v88, 16, v89
	v_and_b32_e32 v89, 0xffff0000, v89
	v_lshlrev_b32_e32 v94, 16, v90
	v_and_b32_e32 v95, 0xffff0000, v90
	v_lshlrev_b32_e32 v90, 16, v91
	v_and_b32_e32 v91, 0xffff0000, v91
	v_pk_add_f32 v[86:87], v[86:87], v[88:89]
	v_pk_add_f32 v[84:85], v[84:85], v[92:93]
	v_pk_add_f32 v[88:89], v[82:83], v[90:91]
	v_pk_add_f32 v[82:83], v[80:81], v[94:95]
	v_cvt_pk_bf16_f32 v80, v84, v85
	v_cvt_pk_bf16_f32 v81, v86, v87
	v_cvt_pk_bf16_f32 v82, v82, v83
	v_cvt_pk_bf16_f32 v83, v88, v89
	flat_store_dwordx4 v[100:101], v[80:83] offset:256
	s_nop 1
	v_lshl_add_u64 v[80:81], v[144:145], 0, s[2:3]
	s_mov_b32 s2, 0x30000
	v_add_co_u32_e32 v86, vcc, s2, v144
	s_mov_b64 s[2:3], 0x80000
	s_nop 0
	v_addc_co_u32_e32 v87, vcc, 0, v145, vcc
	flat_load_dwordx4 v[82:85], v[86:87]
	s_waitcnt vmcnt(0) lgkmcnt(0)
	v_lshlrev_b32_e32 v88, 16, v82
	v_and_b32_e32 v89, 0xffff0000, v82
	v_lshlrev_b32_e32 v82, 16, v83
	v_and_b32_e32 v83, 0xffff0000, v83
	v_lshlrev_b32_e32 v90, 16, v84
	v_and_b32_e32 v91, 0xffff0000, v84
	v_lshlrev_b32_e32 v84, 16, v85
	v_and_b32_e32 v85, 0xffff0000, v85
	v_pk_add_f32 v[78:79], v[78:79], v[82:83]
	v_pk_add_f32 v[76:77], v[76:77], v[88:89]
	v_pk_add_f32 v[82:83], v[74:75], v[84:85]
	v_pk_add_f32 v[74:75], v[72:73], v[90:91]
	v_cvt_pk_bf16_f32 v72, v76, v77
	v_cvt_pk_bf16_f32 v73, v78, v79
	v_cvt_pk_bf16_f32 v74, v74, v75
	v_cvt_pk_bf16_f32 v75, v82, v83
	flat_store_dwordx4 v[86:87], v[72:75]
	flat_load_dwordx4 v[72:75], v[80:81] offset:256
	s_waitcnt vmcnt(0) lgkmcnt(0)
	v_lshlrev_b32_e32 v76, 16, v72
	v_and_b32_e32 v77, 0xffff0000, v72
	v_lshlrev_b32_e32 v72, 16, v73
	v_and_b32_e32 v73, 0xffff0000, v73
	v_lshlrev_b32_e32 v78, 16, v74
	v_and_b32_e32 v79, 0xffff0000, v74
	v_lshlrev_b32_e32 v74, 16, v75
	v_and_b32_e32 v75, 0xffff0000, v75
	v_pk_add_f32 v[70:71], v[70:71], v[72:73]
	v_pk_add_f32 v[68:69], v[68:69], v[76:77]
	v_pk_add_f32 v[72:73], v[66:67], v[74:75]
	v_pk_add_f32 v[66:67], v[64:65], v[78:79]
	v_cvt_pk_bf16_f32 v64, v68, v69
	v_cvt_pk_bf16_f32 v65, v70, v71
	v_cvt_pk_bf16_f32 v66, v66, v67
	v_cvt_pk_bf16_f32 v67, v72, v73
	flat_store_dwordx4 v[80:81], v[64:67] offset:256
	s_nop 1
	v_lshl_add_u64 v[64:65], v[144:145], 0, s[2:3]
	s_mov_b32 s2, 0x80000
	v_add_co_u32_e32 v70, vcc, s2, v144
	s_mov_b64 s[2:3], 0x90000
	s_nop 0
	v_addc_co_u32_e32 v71, vcc, 0, v145, vcc
	flat_load_dwordx4 v[66:69], v[70:71]
	s_waitcnt vmcnt(0) lgkmcnt(0)
	v_lshlrev_b32_e32 v72, 16, v66
	v_and_b32_e32 v73, 0xffff0000, v66
	v_lshlrev_b32_e32 v66, 16, v67
	v_and_b32_e32 v67, 0xffff0000, v67
	v_lshlrev_b32_e32 v74, 16, v68
	v_and_b32_e32 v75, 0xffff0000, v68
	v_lshlrev_b32_e32 v68, 16, v69
	v_and_b32_e32 v69, 0xffff0000, v69
	v_pk_add_f32 v[62:63], v[62:63], v[66:67]
	v_pk_add_f32 v[60:61], v[60:61], v[72:73]
	v_pk_add_f32 v[66:67], v[58:59], v[68:69]
	v_pk_add_f32 v[58:59], v[56:57], v[74:75]
	v_cvt_pk_bf16_f32 v56, v60, v61
	v_cvt_pk_bf16_f32 v57, v62, v63
	v_cvt_pk_bf16_f32 v58, v58, v59
	v_cvt_pk_bf16_f32 v59, v66, v67
	flat_store_dwordx4 v[70:71], v[56:59]
	flat_load_dwordx4 v[56:59], v[64:65] offset:256
	s_waitcnt vmcnt(0) lgkmcnt(0)
; DI unsigned pack2(float a, float b) { f32x2 v = {a, b}; hwbf16x2 r = __builtin_convertvector(v, hwbf16x2); return __builtin_bit_cast(unsigned, r); }
; DI float bflo(unsigned w) { return __uint_as_float(w << 16); }
; DI float bfhi(unsigned w) { return __uint_as_float(w & 0xffff0000u); }
;     DI void operator()(const f32x4 (&acc)[2][2][4][2], const Unit& u, int wr, int wc, int fr, int fq) const {
;     ...
;         for (int ai = 0; ai < 2; ++ai)
; #pragma unroll
;             for (int m = 0; m < 4; ++m) { const size_t ro = (size_t)(row0 + ai * HALF + m * 16) * D + col0;
; #pragma unroll
;                 for (int bj = 0; bj < 2; ++bj) {
;                     f32x4 x0, x1;
;                     if constexpr (IB) { const u32x4 w = *(const u32x4*)((const bf16_t*)Xin + ro + bj * HALF);
;                         x0 = (f32x4){bflo(w[0]), bfhi(w[0]), bflo(w[1]), bfhi(w[1])}; x1 = (f32x4){bflo(w[2]), bfhi(w[2]), bflo(w[3]), bfhi(w[3])}; }
;                     else { x0 = *(const f32x4*)((const float*)Xin + ro + bj * HALF); x1 = *(const f32x4*)((const float*)Xin + ro + bj * HALF + 4); }
;                     x0 += acc[ai][bj][m][0] * sc[bj][0]; x1 += acc[ai][bj][m][1] * sc[bj][1];
;                     if constexpr (OB) { u32x4 o; o[0] = pack2(x0[0], x0[1]); o[1] = pack2(x0[2], x0[3]); o[2] = pack2(x1[0], x1[1]); o[3] = pack2(x1[2], x1[3]);
;                         *(u32x4*)((bf16_t*)Xout + ro + bj * HALF) = o; }
;                     else { *(f32x4*)((float*)Xout + ro + bj * HALF) = x0; *(f32x4*)((float*)Xout + ro + bj * HALF + 4) = x1; } } }
	v_lshlrev_b32_e32 v60, 16, v56
	v_and_b32_e32 v61, 0xffff0000, v56
	v_lshlrev_b32_e32 v56, 16, v57
	v_and_b32_e32 v57, 0xffff0000, v57
	v_lshlrev_b32_e32 v62, 16, v58
	v_and_b32_e32 v63, 0xffff0000, v58
	v_lshlrev_b32_e32 v58, 16, v59
	v_and_b32_e32 v59, 0xffff0000, v59
	v_pk_add_f32 v[54:55], v[54:55], v[56:57]
	v_pk_add_f32 v[52:53], v[52:53], v[60:61]
	v_pk_add_f32 v[56:57], v[50:51], v[58:59]
	v_pk_add_f32 v[50:51], v[48:49], v[62:63]
	v_cvt_pk_bf16_f32 v48, v52, v53
	v_cvt_pk_bf16_f32 v49, v54, v55
	v_cvt_pk_bf16_f32 v50, v50, v51
	v_cvt_pk_bf16_f32 v51, v56, v57
	flat_store_dwordx4 v[64:65], v[48:51] offset:256
	s_nop 1
	v_lshl_add_u64 v[48:49], v[144:145], 0, s[2:3]
	s_mov_b32 s2, 0x90000
	v_add_co_u32_e32 v54, vcc, s2, v144
	s_mov_b64 s[2:3], 0xa0000
	s_nop 0
	v_addc_co_u32_e32 v55, vcc, 0, v145, vcc
	flat_load_dwordx4 v[50:53], v[54:55]
	s_waitcnt vmcnt(0) lgkmcnt(0)
	v_lshlrev_b32_e32 v56, 16, v50
	v_and_b32_e32 v57, 0xffff0000, v50
	v_lshlrev_b32_e32 v50, 16, v51
	v_and_b32_e32 v51, 0xffff0000, v51
	v_lshlrev_b32_e32 v58, 16, v52
	v_and_b32_e32 v59, 0xffff0000, v52
	v_lshlrev_b32_e32 v52, 16, v53
	v_and_b32_e32 v53, 0xffff0000, v53
	v_pk_add_f32 v[46:47], v[46:47], v[50:51]
	v_pk_add_f32 v[44:45], v[44:45], v[56:57]
	v_pk_add_f32 v[50:51], v[42:43], v[52:53]
	v_pk_add_f32 v[42:43], v[40:41], v[58:59]
	v_cvt_pk_bf16_f32 v40, v44, v45
	v_cvt_pk_bf16_f32 v41, v46, v47
	v_cvt_pk_bf16_f32 v42, v42, v43
	v_cvt_pk_bf16_f32 v43, v50, v51
	flat_store_dwordx4 v[54:55], v[40:43]
	flat_load_dwordx4 v[40:43], v[48:49] offset:256
	s_waitcnt vmcnt(0) lgkmcnt(0)
	v_lshlrev_b32_e32 v44, 16, v40
	v_and_b32_e32 v45, 0xffff0000, v40
	v_lshlrev_b32_e32 v40, 16, v41
	v_and_b32_e32 v41, 0xffff0000, v41
	v_lshlrev_b32_e32 v46, 16, v42
	v_and_b32_e32 v47, 0xffff0000, v42
	v_lshlrev_b32_e32 v42, 16, v43
	v_and_b32_e32 v43, 0xffff0000, v43
	v_pk_add_f32 v[38:39], v[38:39], v[40:41]
	v_pk_add_f32 v[36:37], v[36:37], v[44:45]
	v_pk_add_f32 v[40:41], v[34:35], v[42:43]
	v_pk_add_f32 v[34:35], v[32:33], v[46:47]
	v_cvt_pk_bf16_f32 v32, v36, v37
	v_cvt_pk_bf16_f32 v33, v38, v39
	v_cvt_pk_bf16_f32 v34, v34, v35
	v_cvt_pk_bf16_f32 v35, v40, v41
	flat_store_dwordx4 v[48:49], v[32:35] offset:256
	s_nop 1
	v_lshl_add_u64 v[32:33], v[144:145], 0, s[2:3]
	s_mov_b32 s2, 0xa0000
	v_add_co_u32_e32 v38, vcc, s2, v144
	s_mov_b64 s[2:3], 0xb0000
	s_nop 0
	v_addc_co_u32_e32 v39, vcc, 0, v145, vcc
	flat_load_dwordx4 v[34:37], v[38:39]
	s_waitcnt vmcnt(0) lgkmcnt(0)
	v_lshlrev_b32_e32 v40, 16, v34
	v_and_b32_e32 v41, 0xffff0000, v34
	v_lshlrev_b32_e32 v34, 16, v35
	v_and_b32_e32 v35, 0xffff0000, v35
	v_lshlrev_b32_e32 v42, 16, v36
	v_and_b32_e32 v43, 0xffff0000, v36
	v_lshlrev_b32_e32 v36, 16, v37
	v_and_b32_e32 v37, 0xffff0000, v37
	v_pk_add_f32 v[30:31], v[30:31], v[34:35]
	v_pk_add_f32 v[28:29], v[28:29], v[40:41]
	v_pk_add_f32 v[34:35], v[26:27], v[36:37]
	v_pk_add_f32 v[26:27], v[24:25], v[42:43]
	v_cvt_pk_bf16_f32 v24, v28, v29
	v_cvt_pk_bf16_f32 v25, v30, v31
	v_cvt_pk_bf16_f32 v26, v26, v27
	v_cvt_pk_bf16_f32 v27, v34, v35
	flat_store_dwordx4 v[38:39], v[24:27]
	flat_load_dwordx4 v[24:27], v[32:33] offset:256
	s_waitcnt vmcnt(0) lgkmcnt(0)
	v_lshlrev_b32_e32 v28, 16, v24
	v_and_b32_e32 v29, 0xffff0000, v24
	v_lshlrev_b32_e32 v24, 16, v25
	v_and_b32_e32 v25, 0xffff0000, v25
	v_lshlrev_b32_e32 v30, 16, v26
	v_and_b32_e32 v31, 0xffff0000, v26
	v_lshlrev_b32_e32 v26, 16, v27
	v_and_b32_e32 v27, 0xffff0000, v27
	v_pk_add_f32 v[22:23], v[22:23], v[24:25]
	v_pk_add_f32 v[20:21], v[20:21], v[28:29]
	v_pk_add_f32 v[24:25], v[18:19], v[26:27]
	v_pk_add_f32 v[18:19], v[16:17], v[30:31]
	v_cvt_pk_bf16_f32 v16, v20, v21
	v_cvt_pk_bf16_f32 v17, v22, v23
	v_cvt_pk_bf16_f32 v18, v18, v19
	v_cvt_pk_bf16_f32 v19, v24, v25
	flat_store_dwordx4 v[32:33], v[16:19] offset:256
	s_nop 1
	v_lshl_add_u64 v[16:17], v[144:145], 0, s[2:3]
	s_mov_b32 s2, 0xb0000
	v_add_co_u32_e32 v22, vcc, s2, v144
	s_mov_b32 s2, s46
	s_nop 0
	v_addc_co_u32_e32 v23, vcc, 0, v145, vcc
	flat_load_dwordx4 v[18:21], v[22:23]
	s_and_b64 vcc, exec, s[40:41]
	s_waitcnt vmcnt(0) lgkmcnt(0)
	v_lshlrev_b32_e32 v24, 16, v18
	v_and_b32_e32 v25, 0xffff0000, v18
	v_lshlrev_b32_e32 v18, 16, v19
	v_and_b32_e32 v19, 0xffff0000, v19
	v_lshlrev_b32_e32 v26, 16, v20
	v_and_b32_e32 v27, 0xffff0000, v20
	v_lshlrev_b32_e32 v20, 16, v21
	v_and_b32_e32 v21, 0xffff0000, v21
	v_pk_add_f32 v[14:15], v[14:15], v[18:19]
	v_pk_add_f32 v[12:13], v[12:13], v[24:25]
	v_pk_add_f32 v[18:19], v[10:11], v[20:21]
	v_pk_add_f32 v[10:11], v[8:9], v[26:27]
	v_cvt_pk_bf16_f32 v8, v12, v13
	v_cvt_pk_bf16_f32 v9, v14, v15
	v_cvt_pk_bf16_f32 v10, v10, v11
	v_cvt_pk_bf16_f32 v11, v18, v19
	flat_store_dwordx4 v[22:23], v[8:11]
	flat_load_dwordx4 v[8:11], v[16:17] offset:256
	s_waitcnt vmcnt(0) lgkmcnt(0)
	v_lshlrev_b32_e32 v12, 16, v8
	v_and_b32_e32 v13, 0xffff0000, v8
	v_lshlrev_b32_e32 v8, 16, v9
	v_and_b32_e32 v9, 0xffff0000, v9
	v_lshlrev_b32_e32 v14, 16, v10
	v_and_b32_e32 v15, 0xffff0000, v10
	v_lshlrev_b32_e32 v10, 16, v11
	v_and_b32_e32 v11, 0xffff0000, v11
	v_pk_add_f32 v[6:7], v[6:7], v[8:9]
	v_pk_add_f32 v[4:5], v[4:5], v[12:13]
	v_pk_add_f32 v[8:9], v[2:3], v[10:11]
	v_pk_add_f32 v[2:3], v[0:1], v[14:15]
	v_cvt_pk_bf16_f32 v0, v4, v5
	v_cvt_pk_bf16_f32 v1, v6, v7
	v_cvt_pk_bf16_f32 v2, v2, v3
	v_cvt_pk_bf16_f32 v3, v8, v9
	flat_store_dwordx4 v[16:17], v[0:3] offset:256
	s_cbranch_vccz .LBB1_922
	s_waitcnt vmcnt(0)
	s_cmpk_gt_u32 s17, 0xff
	s_cbranch_scc1 .LBB1_929
	s_barrier

; #define PG8_STAGE(bufoff, gbase, voff) do { _Pragma("unroll") for (int _i = 0; _i < 2; ++_i) \
;         __builtin_amdgcn_global_load_lds((const unsigned*)((const char*)(gbase) + (voff)[_i]), (LAS unsigned*)(lds + (bufoff) + ldsw + _i * 8192), 16, 0, 0); } while (0)
; #define PG8_LDA(dst, b, h) do { _Pragma("unroll") for (int m = 0; m < 4; ++m) _Pragma("unroll") for (int k = 0; k < 2; ++k) dst[m][k] = *(const LAS bf16x8*)(lds + PG8_SA(b, h) + aoff + m * 2048 + k * 1024); } while (0)
; #define PG8_LDB(dst, b, h) do { _Pragma("unroll") for (int n = 0; n < 2; ++n) _Pragma("unroll") for (int k = 0; k < 2; ++k) dst[n][k] = *(const LAS bf16x8*)(lds + PG8_SB(b, h) + boff + n * 2048 + k * 1024); } while (0)
; #define PG8_MMA(ai, bj, At, Bt) do { __builtin_amdgcn_s_setprio(1); _Pragma("unroll") for (int m = 0; m < 4; ++m) _Pragma("unroll") for (int n = 0; n < 2; ++n) _Pragma("unroll") for (int k = 0; k < 2; ++k) \
;         acc[ai][bj][m][n] = __builtin_amdgcn_mfma_f32_16x16x32_bf16(Bt[n][k], At[m][k], acc[ai][bj][m][n], 0, 0, 0); __builtin_amdgcn_s_setprio(0); } while (0)
; #define PG8_WAIT_L(n) asm volatile("s_waitcnt lgkmcnt(" #n ")" ::: "memory")
; #define PG8_BAR __builtin_amdgcn_s_barrier()
; #define PG8_SCHED __builtin_amdgcn_sched_barrier(0)
; template <class Map, class Epi>
; DI void gemm_phase(LAS unsigned char* lds, const Map& MP, const Epi& E, const int nM, const int nN, const int K, const int lda, const int ldb) {
;     ...
;             PG8_LDB(B0, 0, 0); PG8_SCHED; PG8_LDA(At, 0, 0); PG8_STAGE(PG8_SA(1, 1), a1 + hstepA, voffA);
;             PG8_WAIT_L(8); PG8_BAR; PG8_WAIT_L(0); PG8_MMA(0, 0, At, B0); PG8_BAR; PG8_SCHED;
;             PG8_LDB(B1, 0, 1); PG8_STAGE(PG8_SB(0, 0), b2, voffB);
;             PG8_BAR; PG8_WAIT_L(0); PG8_MMA(0, 1, At, B1); PG8_BAR;
;             PG8_LDA(At, 0, 1); PG8_STAGE(PG8_SA(0, 0), a2, voffA);
;             PG8_BAR; PG8_WAIT_L(0); PG8_MMA(1, 0, At, B0); PG8_BAR; PG8_SCHED;
.LBB1_1069:
	ds_read_b128 v[80:83], v189
	ds_read_b128 v[84:87], v189 offset:1024
	ds_read_b128 v[88:91], v189 offset:2048
	ds_read_b128 v[92:95], v189 offset:3072
	s_add_u32 s24, s42, 0xfff80080
	s_addc_u32 s25, s43, -1
	s_cmp_eq_u32 s3, 28
	s_cselect_b32 s47, s23, s25
	s_cselect_b32 s46, s58, s24
	s_cselect_b32 s25, s21, vcc_hi
	s_cselect_b32 s24, s59, vcc_lo
	v_lshl_add_u64 v[184:185], s[42:43], 0, v[178:179]
	s_add_i32 m0, s38, 0xc000
	ds_read_b128 v[96:99], v190
	ds_read_b128 v[100:103], v190 offset:1024
	ds_read_b128 v[108:111], v190 offset:2048
	ds_read_b128 v[112:115], v190 offset:3072
	ds_read_b128 v[160:163], v190 offset:4096
	ds_read_b128 v[164:167], v190 offset:5120
	ds_read_b128 v[198:201], v190 offset:6144
	ds_read_b128 v[202:205], v190 offset:7168
	global_load_lds_dwordx4 v[184:185], off
	v_lshl_add_u64 v[184:185], s[42:43], 0, v[176:177]
	s_add_i32 m0, s38, 0xe000
	s_nop 0
	global_load_lds_dwordx4 v[184:185], off
	s_waitcnt lgkmcnt(8)
	s_barrier
	s_setprio 1
	s_waitcnt lgkmcnt(7)
	v_mfma_f32_16x16x32_bf16 v[148:151], v[80:83], v[96:99], v[148:151]
	v_mfma_f32_16x16x32_bf16 v[144:147], v[88:91], v[96:99], v[144:147]
	s_waitcnt lgkmcnt(5)
	v_mfma_f32_16x16x32_bf16 v[136:139], v[80:83], v[108:111], v[136:139]
	v_mfma_f32_16x16x32_bf16 v[128:131], v[88:91], v[108:111], v[128:131]
	s_waitcnt lgkmcnt(3)
	v_mfma_f32_16x16x32_bf16 v[120:123], v[80:83], v[160:163], v[120:123]
	v_mfma_f32_16x16x32_bf16 v[104:107], v[88:91], v[160:163], v[104:107]
	s_waitcnt lgkmcnt(1)
	v_mfma_f32_16x16x32_bf16 v[76:79], v[80:83], v[198:201], v[76:79]
	v_mfma_f32_16x16x32_bf16 v[72:75], v[88:91], v[198:201], v[72:75]
	v_mfma_f32_16x16x32_bf16 v[148:151], v[84:87], v[100:103], v[148:151]
	v_mfma_f32_16x16x32_bf16 v[144:147], v[92:95], v[100:103], v[144:147]
	v_mfma_f32_16x16x32_bf16 v[136:139], v[84:87], v[112:115], v[136:139]
	v_mfma_f32_16x16x32_bf16 v[128:131], v[92:95], v[112:115], v[128:131]
	v_mfma_f32_16x16x32_bf16 v[120:123], v[84:87], v[164:167], v[120:123]
	v_mfma_f32_16x16x32_bf16 v[104:107], v[92:95], v[164:167], v[104:107]
	s_waitcnt lgkmcnt(0)
	v_mfma_f32_16x16x32_bf16 v[76:79], v[84:87], v[202:205], v[76:79]
	v_mfma_f32_16x16x32_bf16 v[72:75], v[92:95], v[202:205], v[72:75]
	s_setprio 0
	s_barrier
	s_add_i32 s68, s31, s66
	v_lshl_add_u64 v[184:185], s[24:25], 0, v[172:173]
	s_mov_b32 m0, s68
	ds_read_b128 v[206:209], v191
	ds_read_b128 v[210:213], v191 offset:1024
	ds_read_b128 v[214:217], v191 offset:2048
	ds_read_b128 v[218:221], v191 offset:3072
	global_load_lds_dwordx4 v[184:185], off
	v_lshl_add_u64 v[194:195], s[24:25], 0, v[168:169]
	s_add_i32 m0, s68, 0x2000
	s_nop 0
	global_load_lds_dwordx4 v[194:195], off
	s_barrier
	s_setprio 1
	s_waitcnt lgkmcnt(3)
	v_mfma_f32_16x16x32_bf16 v[156:159], v[206:209], v[96:99], v[156:159]
	s_waitcnt lgkmcnt(1)
	v_mfma_f32_16x16x32_bf16 v[96:99], v[214:217], v[96:99], v[152:155]
	v_mfma_f32_16x16x32_bf16 v[156:159], v[210:213], v[100:103], v[156:159]
	s_waitcnt lgkmcnt(0)
	v_mfma_f32_16x16x32_bf16 v[96:99], v[218:221], v[100:103], v[96:99]
	v_mfma_f32_16x16x32_bf16 v[100:103], v[206:209], v[108:111], v[140:143]
	v_mfma_f32_16x16x32_bf16 v[108:111], v[214:217], v[108:111], v[132:135]
	v_mfma_f32_16x16x32_bf16 v[116:119], v[214:217], v[160:163], v[116:119]
	v_mfma_f32_16x16x32_bf16 v[68:71], v[206:209], v[198:201], v[68:71]
	v_mfma_f32_16x16x32_bf16 v[64:67], v[214:217], v[198:201], v[64:67]
	v_mfma_f32_16x16x32_bf16 v[100:103], v[210:213], v[112:115], v[100:103]
	v_mfma_f32_16x16x32_bf16 v[108:111], v[218:221], v[112:115], v[108:111]
	v_mfma_f32_16x16x32_bf16 v[112:115], v[206:209], v[160:163], v[124:127]
	v_mfma_f32_16x16x32_bf16 v[116:119], v[218:221], v[164:167], v[116:119]
	v_mfma_f32_16x16x32_bf16 v[68:71], v[210:213], v[202:205], v[68:71]
	v_mfma_f32_16x16x32_bf16 v[64:67], v[218:221], v[202:205], v[64:67]
	v_mfma_f32_16x16x32_bf16 v[112:115], v[210:213], v[164:167], v[112:115]
	s_setprio 0
	s_mov_b32 m0, s38
	v_lshl_add_u64 v[226:227], s[46:47], 0, v[174:175]
	s_barrier
	ds_read_b128 v[124:127], v190 offset:16384
	ds_read_b128 v[132:135], v190 offset:17408
	ds_read_b128 v[140:143], v190 offset:18432
	ds_read_b128 v[152:155], v190 offset:19456
	ds_read_b128 v[160:163], v190 offset:20480
	ds_read_b128 v[164:167], v190 offset:21504
	ds_read_b128 v[198:201], v190 offset:22528
	ds_read_b128 v[202:205], v190 offset:23552
	global_load_lds_dwordx4 v[226:227], off
	v_lshl_add_u64 v[234:235], s[46:47], 0, v[170:171]
	s_mov_b32 m0, s39
	s_nop 0
	global_load_lds_dwordx4 v[234:235], off
	s_barrier
	s_setprio 1
	s_waitcnt lgkmcnt(7)
	v_mfma_f32_16x16x32_bf16 v[60:63], v[80:83], v[124:127], v[60:63]
	v_mfma_f32_16x16x32_bf16 v[48:51], v[88:91], v[124:127], v[48:51]
	s_waitcnt lgkmcnt(5)
	v_mfma_f32_16x16x32_bf16 v[40:43], v[80:83], v[140:143], v[40:43]
	v_mfma_f32_16x16x32_bf16 v[32:35], v[88:91], v[140:143], v[32:35]
	s_waitcnt lgkmcnt(3)
	v_mfma_f32_16x16x32_bf16 v[24:27], v[80:83], v[160:163], v[24:27]
	v_mfma_f32_16x16x32_bf16 v[16:19], v[88:91], v[160:163], v[16:19]
	s_waitcnt lgkmcnt(1)
	v_mfma_f32_16x16x32_bf16 v[12:15], v[80:83], v[198:201], v[12:15]
	v_mfma_f32_16x16x32_bf16 v[8:11], v[88:91], v[198:201], v[8:11]
	v_mfma_f32_16x16x32_bf16 v[60:63], v[84:87], v[132:135], v[60:63]
	v_mfma_f32_16x16x32_bf16 v[48:51], v[92:95], v[132:135], v[48:51]
	v_mfma_f32_16x16x32_bf16 v[40:43], v[84:87], v[152:155], v[40:43]
	v_mfma_f32_16x16x32_bf16 v[32:35], v[92:95], v[152:155], v[32:35]
	v_mfma_f32_16x16x32_bf16 v[24:27], v[84:87], v[164:167], v[24:27]
	v_mfma_f32_16x16x32_bf16 v[16:19], v[92:95], v[164:167], v[16:19]
	s_waitcnt lgkmcnt(0)
	v_mfma_f32_16x16x32_bf16 v[12:15], v[84:87], v[202:205], v[12:15]
	v_mfma_f32_16x16x32_bf16 v[8:11], v[92:95], v[202:205], v[8:11]
	s_setprio 0
	s_barrier
; #define PG8_STAGE(bufoff, gbase, voff) do { _Pragma("unroll") for (int _i = 0; _i < 2; ++_i) \
;         __builtin_amdgcn_global_load_lds((const unsigned*)((const char*)(gbase) + (voff)[_i]), (LAS unsigned*)(lds + (bufoff) + ldsw + _i * 8192), 16, 0, 0); } while (0)
; #define PG8_LDA(dst, b, h) do { _Pragma("unroll") for (int m = 0; m < 4; ++m) _Pragma("unroll") for (int k = 0; k < 2; ++k) dst[m][k] = *(const LAS bf16x8*)(lds + PG8_SA(b, h) + aoff + m * 2048 + k * 1024); } while (0)
; #define PG8_LDB(dst, b, h) do { _Pragma("unroll") for (int n = 0; n < 2; ++n) _Pragma("unroll") for (int k = 0; k < 2; ++k) dst[n][k] = *(const LAS bf16x8*)(lds + PG8_SB(b, h) + boff + n * 2048 + k * 1024); } while (0)
; #define PG8_MMA(ai, bj, At, Bt) do { __builtin_amdgcn_s_setprio(1); _Pragma("unroll") for (int m = 0; m < 4; ++m) _Pragma("unroll") for (int n = 0; n < 2; ++n) _Pragma("unroll") for (int k = 0; k < 2; ++k) \
;         acc[ai][bj][m][n] = __builtin_amdgcn_mfma_f32_16x16x32_bf16(Bt[n][k], At[m][k], acc[ai][bj][m][n], 0, 0, 0); __builtin_amdgcn_s_setprio(0); } while (0)
; #define PG8_WAIT_V(n) asm volatile("s_waitcnt vmcnt(" #n ")" ::: "memory")
; #define PG8_WAIT_L(n) asm volatile("s_waitcnt lgkmcnt(" #n ")" ::: "memory")
; #define PG8_BAR __builtin_amdgcn_s_barrier()
; #define PG8_SCHED __builtin_amdgcn_sched_barrier(0)
; template <class Map, class Epi>
; DI void gemm_phase(LAS unsigned char* lds, const Map& MP, const Epi& E, const int nM, const int nN, const int K, const int lda, const int ldb) {
;     ...
;             PG8_STAGE(PG8_SB(0, 1), b2 + hstepB, voffB);
;             PG8_WAIT_V(6); PG8_BAR; PG8_MMA(1, 1, At, B1); PG8_BAR;
;             PG8_LDB(B0, 1, 0); PG8_SCHED; PG8_LDA(At, 1, 0); PG8_STAGE(PG8_SA(0, 1), a2 + hstepA, voffA);
;             PG8_WAIT_L(8); PG8_BAR; PG8_WAIT_L(0); PG8_MMA(0, 0, At, B0); PG8_BAR; PG8_SCHED;
;             PG8_LDB(B1, 1, 1); PG8_STAGE(PG8_SB(1, 0), b3, voffB);
;             PG8_BAR; PG8_WAIT_L(0); PG8_MMA(0, 1, At, B1); PG8_BAR;
;             PG8_LDA(At, 1, 1); PG8_STAGE(PG8_SA(1, 0), a3, voffA);
	s_add_u32 s68, s24, 0x80000
	s_addc_u32 s69, s25, 0
	s_add_i32 s70, s2, s66
	v_lshl_add_u64 v[80:81], s[68:69], 0, v[172:173]
	s_mov_b32 m0, s70
	s_nop 0
	global_load_lds_dwordx4 v[80:81], off
	v_lshl_add_u64 v[80:81], s[68:69], 0, v[168:169]
	s_add_i32 m0, s70, 0x2000
	s_nop 0
	global_load_lds_dwordx4 v[80:81], off
	s_waitcnt vmcnt(6)
	s_barrier
	s_setprio 1
	v_mfma_f32_16x16x32_bf16 v[56:59], v[206:209], v[124:127], v[56:59]
	v_mfma_f32_16x16x32_bf16 v[52:55], v[214:217], v[124:127], v[52:55]
	v_mfma_f32_16x16x32_bf16 v[44:47], v[206:209], v[140:143], v[44:47]
	v_mfma_f32_16x16x32_bf16 v[36:39], v[214:217], v[140:143], v[36:39]
	v_mfma_f32_16x16x32_bf16 v[28:31], v[206:209], v[160:163], v[28:31]
	v_mfma_f32_16x16x32_bf16 v[20:23], v[214:217], v[160:163], v[20:23]
	v_mfma_f32_16x16x32_bf16 v[4:7], v[206:209], v[198:201], v[4:7]
	v_mfma_f32_16x16x32_bf16 v[0:3], v[214:217], v[198:201], v[0:3]
	v_mfma_f32_16x16x32_bf16 v[56:59], v[210:213], v[132:135], v[56:59]
	v_mfma_f32_16x16x32_bf16 v[52:55], v[218:221], v[132:135], v[52:55]
	v_mfma_f32_16x16x32_bf16 v[44:47], v[210:213], v[152:155], v[44:47]
	v_mfma_f32_16x16x32_bf16 v[36:39], v[218:221], v[152:155], v[36:39]
	v_mfma_f32_16x16x32_bf16 v[28:31], v[210:213], v[164:167], v[28:31]
	v_mfma_f32_16x16x32_bf16 v[20:23], v[218:221], v[164:167], v[20:23]
	v_mfma_f32_16x16x32_bf16 v[4:7], v[210:213], v[202:205], v[4:7]
	v_mfma_f32_16x16x32_bf16 v[0:3], v[218:221], v[202:205], v[0:3]
	s_setprio 0
	s_add_i32 s68, 0, 0x18000
	v_add_u32_e32 v92, s68, v188
	s_barrier
	ds_read_b128 v[80:83], v92
	ds_read_b128 v[84:87], v92 offset:1024
	ds_read_b128 v[88:91], v92 offset:2048
	ds_read_b128 v[92:95], v92 offset:3072
	s_add_u32 s46, s46, 0x80000
	s_addc_u32 s47, s47, 0
	s_mov_b32 m0, s56
	v_lshl_add_u64 v[140:141], s[46:47], 0, v[174:175]
	ds_read_b128 v[124:127], v190 offset:32768
	ds_read_b128 v[132:135], v190 offset:33792
	ds_read_b128 v[160:163], v190 offset:34816
	ds_read_b128 v[164:167], v190 offset:35840
	ds_read_b128 v[198:201], v190 offset:36864
	ds_read_b128 v[202:205], v190 offset:37888
	ds_read_b128 v[206:209], v190 offset:38912
	ds_read_b128 v[210:213], v190 offset:39936
	global_load_lds_dwordx4 v[140:141], off
	v_lshl_add_u64 v[140:141], s[46:47], 0, v[170:171]
	s_mov_b32 m0, s57
	s_nop 0
	global_load_lds_dwordx4 v[140:141], off
	s_waitcnt lgkmcnt(8)
	s_barrier
	s_setprio 1
	s_waitcnt lgkmcnt(7)
	v_mfma_f32_16x16x32_bf16 v[140:143], v[80:83], v[124:127], v[148:151]
	s_waitcnt lgkmcnt(6)
	v_mfma_f32_16x16x32_bf16 v[148:151], v[84:87], v[132:135], v[140:143]
	v_mfma_f32_16x16x32_bf16 v[140:143], v[88:91], v[124:127], v[144:147]
	s_waitcnt lgkmcnt(5)
	v_mfma_f32_16x16x32_bf16 v[136:139], v[80:83], v[160:163], v[136:139]
	v_mfma_f32_16x16x32_bf16 v[128:131], v[88:91], v[160:163], v[128:131]
	s_waitcnt lgkmcnt(3)
	v_mfma_f32_16x16x32_bf16 v[120:123], v[80:83], v[198:201], v[120:123]
	v_mfma_f32_16x16x32_bf16 v[104:107], v[88:91], v[198:201], v[104:107]
	s_waitcnt lgkmcnt(1)
	v_mfma_f32_16x16x32_bf16 v[76:79], v[80:83], v[206:209], v[76:79]
	v_mfma_f32_16x16x32_bf16 v[72:75], v[88:91], v[206:209], v[72:75]
	v_mfma_f32_16x16x32_bf16 v[144:147], v[92:95], v[132:135], v[140:143]
	v_mfma_f32_16x16x32_bf16 v[136:139], v[84:87], v[164:167], v[136:139]
	v_mfma_f32_16x16x32_bf16 v[128:131], v[92:95], v[164:167], v[128:131]
	v_mfma_f32_16x16x32_bf16 v[120:123], v[84:87], v[202:205], v[120:123]
	v_mfma_f32_16x16x32_bf16 v[104:107], v[92:95], v[202:205], v[104:107]
	s_waitcnt lgkmcnt(0)
	v_mfma_f32_16x16x32_bf16 v[76:79], v[84:87], v[210:213], v[76:79]
	v_mfma_f32_16x16x32_bf16 v[72:75], v[92:95], v[210:213], v[72:75]
	s_setprio 0
	s_barrier
	s_add_i32 s46, 0, 0x1c000
	v_add_u32_e32 v140, s46, v188
	s_add_i32 s47, s68, s66
	ds_read_b128 v[214:217], v140
	ds_read_b128 v[218:221], v140 offset:1024
	ds_read_b128 v[222:225], v140 offset:2048
	ds_read_b128 v[230:233], v140 offset:3072
	v_lshl_add_u64 v[140:141], v[184:185], 0, s[14:15]
	s_mov_b32 m0, s47
	s_nop 0
	global_load_lds_dwordx4 v[140:141], off
	v_lshl_add_u64 v[140:141], v[194:195], 0, s[14:15]
	s_add_i32 m0, s47, 0x2000
	s_nop 0
	global_load_lds_dwordx4 v[140:141], off
	s_barrier
	s_setprio 1
	s_waitcnt lgkmcnt(1)
	v_mfma_f32_16x16x32_bf16 v[96:99], v[222:225], v[124:127], v[96:99]
	v_mfma_f32_16x16x32_bf16 v[140:143], v[214:217], v[124:127], v[156:159]
	s_waitcnt lgkmcnt(0)
	v_mfma_f32_16x16x32_bf16 v[152:155], v[230:233], v[132:135], v[96:99]
	v_mfma_f32_16x16x32_bf16 v[96:99], v[214:217], v[160:163], v[100:103]
	v_mfma_f32_16x16x32_bf16 v[156:159], v[218:221], v[132:135], v[140:143]
	v_mfma_f32_16x16x32_bf16 v[140:143], v[218:221], v[164:167], v[96:99]
	v_mfma_f32_16x16x32_bf16 v[96:99], v[222:225], v[160:163], v[108:111]
	v_mfma_f32_16x16x32_bf16 v[132:135], v[230:233], v[164:167], v[96:99]
	v_mfma_f32_16x16x32_bf16 v[96:99], v[214:217], v[198:201], v[112:115]
	v_mfma_f32_16x16x32_bf16 v[124:127], v[218:221], v[202:205], v[96:99]
	v_mfma_f32_16x16x32_bf16 v[96:99], v[222:225], v[198:201], v[116:119]
	v_mfma_f32_16x16x32_bf16 v[68:71], v[214:217], v[206:209], v[68:71]
	v_mfma_f32_16x16x32_bf16 v[64:67], v[222:225], v[206:209], v[64:67]
	v_mfma_f32_16x16x32_bf16 v[116:119], v[230:233], v[202:205], v[96:99]
	v_mfma_f32_16x16x32_bf16 v[68:71], v[218:221], v[210:213], v[68:71]
	v_mfma_f32_16x16x32_bf16 v[64:67], v[230:233], v[210:213], v[64:67]
	s_setprio 0
	s_mov_b32 m0, s63
	v_lshl_add_u64 v[184:185], v[226:227], 0, s[14:15]
	s_barrier
; #define PG8_STAGE(bufoff, gbase, voff) do { _Pragma("unroll") for (int _i = 0; _i < 2; ++_i) \
;         __builtin_amdgcn_global_load_lds((const unsigned*)((const char*)(gbase) + (voff)[_i]), (LAS unsigned*)(lds + (bufoff) + ldsw + _i * 8192), 16, 0, 0); } while (0)
; #define PG8_LDA(dst, b, h) do { _Pragma("unroll") for (int m = 0; m < 4; ++m) _Pragma("unroll") for (int k = 0; k < 2; ++k) dst[m][k] = *(const LAS bf16x8*)(lds + PG8_SA(b, h) + aoff + m * 2048 + k * 1024); } while (0)
; #define PG8_MMA(ai, bj, At, Bt) do { __builtin_amdgcn_s_setprio(1); _Pragma("unroll") for (int m = 0; m < 4; ++m) _Pragma("unroll") for (int n = 0; n < 2; ++n) _Pragma("unroll") for (int k = 0; k < 2; ++k) \
;         acc[ai][bj][m][n] = __builtin_amdgcn_mfma_f32_16x16x32_bf16(Bt[n][k], At[m][k], acc[ai][bj][m][n], 0, 0, 0); __builtin_amdgcn_s_setprio(0); } while (0)
; #define PG8_WAIT_V(n) asm volatile("s_waitcnt vmcnt(" #n ")" ::: "memory")
; #define PG8_WAIT_L(n) asm volatile("s_waitcnt lgkmcnt(" #n ")" ::: "memory")
; #define PG8_BAR __builtin_amdgcn_s_barrier()
; #define PG8_SCHED __builtin_amdgcn_sched_barrier(0)
; template <class Map, class Epi>
; DI void gemm_phase(LAS unsigned char* lds, const Map& MP, const Epi& E, const int nM, const int nN, const int K, const int lda, const int ldb) {
;     ...
;             PG8_LDA(At, 1, 1); PG8_STAGE(PG8_SA(1, 0), a3, voffA);
;             PG8_BAR; PG8_WAIT_L(0); PG8_MMA(1, 0, At, B0); PG8_BAR; PG8_SCHED;
;             PG8_STAGE(PG8_SB(1, 1), b3 + hstepB, voffB);
;             PG8_WAIT_V(6); PG8_BAR; PG8_MMA(1, 1, At, B1); PG8_BAR;
	ds_read_b128 v[96:99], v190 offset:49152
	ds_read_b128 v[100:103], v190 offset:50176
	ds_read_b128 v[108:111], v190 offset:51200
	ds_read_b128 v[112:115], v190 offset:52224
	ds_read_b128 v[160:163], v190 offset:53248
	ds_read_b128 v[164:167], v190 offset:54272
	ds_read_b128 v[198:201], v190 offset:55296
	ds_read_b128 v[202:205], v190 offset:56320
	global_load_lds_dwordx4 v[184:185], off
	v_lshl_add_u64 v[184:185], v[234:235], 0, s[14:15]
	s_mov_b32 m0, s4
	s_nop 0
	global_load_lds_dwordx4 v[184:185], off
	s_barrier
	s_setprio 1
	s_waitcnt lgkmcnt(7)
	v_mfma_f32_16x16x32_bf16 v[60:63], v[80:83], v[96:99], v[60:63]
	v_mfma_f32_16x16x32_bf16 v[48:51], v[88:91], v[96:99], v[48:51]
	s_waitcnt lgkmcnt(5)
	v_mfma_f32_16x16x32_bf16 v[40:43], v[80:83], v[108:111], v[40:43]
	v_mfma_f32_16x16x32_bf16 v[32:35], v[88:91], v[108:111], v[32:35]
	s_waitcnt lgkmcnt(3)
	v_mfma_f32_16x16x32_bf16 v[24:27], v[80:83], v[160:163], v[24:27]
	v_mfma_f32_16x16x32_bf16 v[16:19], v[88:91], v[160:163], v[16:19]
	s_waitcnt lgkmcnt(1)
	v_mfma_f32_16x16x32_bf16 v[12:15], v[80:83], v[198:201], v[12:15]
	v_mfma_f32_16x16x32_bf16 v[8:11], v[88:91], v[198:201], v[8:11]
	v_mfma_f32_16x16x32_bf16 v[60:63], v[84:87], v[100:103], v[60:63]
	v_mfma_f32_16x16x32_bf16 v[48:51], v[92:95], v[100:103], v[48:51]
	v_mfma_f32_16x16x32_bf16 v[40:43], v[84:87], v[112:115], v[40:43]
	v_mfma_f32_16x16x32_bf16 v[32:35], v[92:95], v[112:115], v[32:35]
	v_mfma_f32_16x16x32_bf16 v[24:27], v[84:87], v[164:167], v[24:27]
	v_mfma_f32_16x16x32_bf16 v[16:19], v[92:95], v[164:167], v[16:19]
	s_waitcnt lgkmcnt(0)
	v_mfma_f32_16x16x32_bf16 v[12:15], v[84:87], v[202:205], v[12:15]
	v_mfma_f32_16x16x32_bf16 v[8:11], v[92:95], v[202:205], v[8:11]
	s_setprio 0
	s_barrier
	s_add_u32 s24, s24, 0x80080
	s_addc_u32 s25, s25, 0
	s_add_i32 s46, s46, s66
	v_lshl_add_u64 v[80:81], s[24:25], 0, v[172:173]
	s_mov_b32 m0, s46
	s_nop 0
	global_load_lds_dwordx4 v[80:81], off
	v_lshl_add_u64 v[80:81], s[24:25], 0, v[168:169]
	s_add_i32 m0, s46, 0x2000
	s_nop 0
	global_load_lds_dwordx4 v[80:81], off
	s_waitcnt vmcnt(6)
	s_barrier
	s_setprio 1
	v_mfma_f32_16x16x32_bf16 v[56:59], v[214:217], v[96:99], v[56:59]
	v_mfma_f32_16x16x32_bf16 v[52:55], v[222:225], v[96:99], v[52:55]
	v_mfma_f32_16x16x32_bf16 v[44:47], v[214:217], v[108:111], v[44:47]
	v_mfma_f32_16x16x32_bf16 v[36:39], v[222:225], v[108:111], v[36:39]
	v_mfma_f32_16x16x32_bf16 v[28:31], v[214:217], v[160:163], v[28:31]
	v_mfma_f32_16x16x32_bf16 v[20:23], v[222:225], v[160:163], v[20:23]
	v_mfma_f32_16x16x32_bf16 v[4:7], v[214:217], v[198:201], v[4:7]
	v_mfma_f32_16x16x32_bf16 v[0:3], v[222:225], v[198:201], v[0:3]
	v_mfma_f32_16x16x32_bf16 v[56:59], v[218:221], v[100:103], v[56:59]
	v_mfma_f32_16x16x32_bf16 v[52:55], v[230:233], v[100:103], v[52:55]
	v_mfma_f32_16x16x32_bf16 v[44:47], v[218:221], v[112:115], v[44:47]
	v_mfma_f32_16x16x32_bf16 v[36:39], v[230:233], v[112:115], v[36:39]
	v_mfma_f32_16x16x32_bf16 v[28:31], v[218:221], v[164:167], v[28:31]
	v_mfma_f32_16x16x32_bf16 v[20:23], v[230:233], v[164:167], v[20:23]
	v_mfma_f32_16x16x32_bf16 v[4:7], v[218:221], v[202:205], v[4:7]
	v_mfma_f32_16x16x32_bf16 v[0:3], v[230:233], v[202:205], v[0:3]
	s_setprio 0
	s_add_i32 s3, s3, 2
	s_add_u32 vcc_lo, vcc_lo, 0x100
	s_addc_u32 vcc_hi, vcc_hi, 0
	s_add_u32 s42, s42, 0x100
	s_addc_u32 s43, s43, 0
	s_cmp_gt_u32 s3, 29
	s_barrier
	s_cbranch_scc0 .LBB1_1069
; DI float silu_mul(float g, float v) { return g * v * __builtin_amdgcn_rcpf(1.0f + __builtin_amdgcn_exp2f(-LOG2E * g)); }
;     DI void operator()(const f32x4 (&acc)[2][2][4][2], const Unit& u, int wr, int wc, int fr, int fq) const {
;         const int row0 = u.pm * BM + wr * 64 + fr, ch0 = u.pn * 128 + wc * 32 + 8 * fq;
;         f32x4 w0[2], w1[2], w2[2], bb[2];
; #pragma unroll
;         for (int n = 0; n < 2; ++n) { w0[n] = *(const f32x4*)(cw + ch0 + 4 * n); w1[n] = *(const f32x4*)(cw + DFF + ch0 + 4 * n); w2[n] = *(const f32x4*)(cw + 2 * DFF + ch0 + 4 * n); bb[n] = *(const f32x4*)(cb + ch0 + 4 * n); }
; #pragma unroll
;         for (int ai = 0; ai < 2; ++ai)
; #pragma unroll
;             for (int m = 0; m < 4; ++m) {
;                 const bool efirst = (m == 0) && (fr == 0), elast = (m == 3) && (fr == 15);
;                 const int row = row0 + ai * HALF + m * 16;
;                 f32x4 gc[2];
; #pragma unroll
;                 for (int n = 0; n < 2; ++n) {
;                     const f32x4 g = acc[ai][0][m][n];
;                     const f32x4 gprev = acc[ai][0][m > 0 ? m - 1 : 0][n], gnext = acc[ai][0][m < 3 ? m + 1 : 3][n];
;                     f32x4 up, dn;
; #pragma unroll
;                     for (int e = 0; e < 4; ++e) {
;                         const float pu = (m > 0 && fr == 15) ? gprev[e] : g[e];
;                         const float pd = (m < 3 && fr == 0) ? gnext[e] : g[e];
;                         up[e] = dpp_ror1(pu); dn[e] = dpp_ror15(pd);
;                     }
;                     if (efirst) up = (f32x4){0.f, 0.f, 0.f, 0.f};
;                     if (elast) dn = (f32x4){0.f, 0.f, 0.f, 0.f};
;                     gc[n] = w0[n] * up + w1[n] * g + w2[n] * dn + bb[n];
;                 }
;                 if (efirst || elast) {
;                     const size_t eo = (size_t)((row >> 6) * 2 + (elast ? 1 : 0)) * DFF + ch0;
; #pragma unroll
;                     for (int n = 0; n < 2; ++n) { *(f32x4*)(EP + eo + 4 * n) = gc[n]; *(f32x4*)(ER + eo + 4 * n) = acc[ai][0][m][n]; *(f32x4*)(EV + eo + 4 * n) = acc[ai][1][m][n]; }
;                 } else {
;                     const f32x4 v0 = acc[ai][1][m][0], v1 = acc[ai][1][m][1];
;                     u32x4 o;
;                     o[0] = pack2(silu_mul(gc[0][0], v0[0]), silu_mul(gc[0][1], v0[1])); o[1] = pack2(silu_mul(gc[0][2], v0[2]), silu_mul(gc[0][3], v0[3]));
	s_lshl_b32 s21, s45, 7
	v_mov_b32_e32 v194, v186
	v_mov_b32_e32 v80, v187
	s_or_b32 s21, s21, s62
	v_mov_b32_e32 v160, 0
	v_lshl_add_u32 v184, v80, 3, s21
	v_ashrrev_i32_e32 v185, 31, v184
	v_lshlrev_b64 v[80:81], 2, v[184:185]
	v_lshl_add_u64 v[84:85], s[6:7], 0, v[80:81]
	v_lshl_add_u64 v[88:89], s[16:17], 0, v[80:81]
	v_lshl_add_u64 v[92:93], s[18:19], 0, v[80:81]
	v_lshl_add_u64 v[112:113], s[52:53], 0, v[80:81]
	global_load_dwordx4 v[80:83], v[84:85], off offset:16
	global_load_dwordx4 v[96:99], v[84:85], off
	s_nop 0
	global_load_dwordx4 v[84:87], v[88:89], off offset:16
	global_load_dwordx4 v[100:103], v[88:89], off
	s_nop 0
	global_load_dwordx4 v[88:91], v[92:93], off offset:16
	global_load_dwordx4 v[108:111], v[92:93], off
	s_nop 0
	global_load_dwordx4 v[92:95], v[112:113], off offset:16
	s_nop 0
	global_load_dwordx4 v[112:115], v[112:113], off
	v_cmp_eq_u32_e32 vcc, 0, v194
	v_mov_b32_e32 v164, 0
	v_mov_b32_e32 v195, 0
	v_cndmask_b32_e32 v161, v148, v136, vcc
	v_cndmask_b32_e32 v162, v149, v137, vcc
	v_cndmask_b32_e32 v163, v150, v138, vcc
	v_mov_b32_dpp v160, v161 row_ror:15 row_mask:0xf bank_mask:0xf
	v_mov_b32_e32 v161, 0
	v_mov_b32_e32 v166, 0
	v_mov_b32_e32 v167, 0
	v_mov_b32_dpp v161, v162 row_ror:15 row_mask:0xf bank_mask:0xf
	v_mov_b32_e32 v162, 0
	v_mov_b32_dpp v164, v150 row_ror:1 row_mask:0xf bank_mask:0xf
	v_cndmask_b32_e32 v165, v151, v139, vcc
	v_mov_b32_dpp v162, v163 row_ror:15 row_mask:0xf bank_mask:0xf
	v_mov_b32_dpp v195, v151 row_ror:1 row_mask:0xf bank_mask:0xf
	v_mov_b32_e32 v163, 0
	v_mov_b32_dpp v166, v148 row_ror:1 row_mask:0xf bank_mask:0xf
	v_mov_b32_dpp v167, v149 row_ror:1 row_mask:0xf bank_mask:0xf
	v_mov_b32_dpp v163, v165 row_ror:15 row_mask:0xf bank_mask:0xf
	v_cndmask_b32_e64 v165, v195, 0, vcc
	v_cndmask_b32_e64 v164, v164, 0, vcc
	v_cndmask_b32_e64 v167, v167, 0, vcc
	v_cndmask_b32_e64 v166, v166, 0, vcc
	v_mov_b32_e32 v195, 0
	v_mov_b32_e32 v196, 0
	v_mov_b32_e32 v198, 0
	v_mov_b32_e32 v200, 0
	v_mov_b32_dpp v195, v144 row_ror:1 row_mask:0xf bank_mask:0xf
	v_mov_b32_dpp v196, v145 row_ror:1 row_mask:0xf bank_mask:0xf
	v_mov_b32_dpp v198, v146 row_ror:1 row_mask:0xf bank_mask:0xf
	v_cndmask_b32_e32 v199, v147, v131, vcc
	v_mov_b32_dpp v200, v147 row_ror:1 row_mask:0xf bank_mask:0xf
	v_cndmask_b32_e64 v198, v198, 0, vcc
	v_cndmask_b32_e64 v201, v196, 0, vcc
	s_lshl_b32 s3, s44, 8
	s_add_i32 s3, s3, s49
	v_add_u32_e32 v193, s3, v194
	v_cmp_ne_u32_e64 s[46:47], 0, v194
	s_waitcnt vmcnt(0)
	v_pk_mul_f32 v[164:165], v[98:99], v[164:165]
	v_pk_mul_f32 v[166:167], v[96:97], v[166:167]
	v_pk_fma_f32 v[164:165], v[150:151], v[102:103], v[164:165]
	v_pk_fma_f32 v[166:167], v[148:149], v[100:101], v[166:167]
	v_pk_fma_f32 v[162:163], v[110:111], v[162:163], v[164:165]
	v_cndmask_b32_e32 v165, v144, v128, vcc
	v_mov_b32_e32 v164, 0
	v_pk_fma_f32 v[160:161], v[108:109], v[160:161], v[166:167]
	v_cndmask_b32_e32 v166, v145, v129, vcc
	v_mov_b32_dpp v164, v165 row_ror:15 row_mask:0xf bank_mask:0xf
	v_mov_b32_e32 v165, 0
	v_cndmask_b32_e32 v167, v146, v130, vcc
	v_pk_add_f32 v[162:163], v[114:115], v[162:163]
	v_mov_b32_dpp v165, v166 row_ror:15 row_mask:0xf bank_mask:0xf
	v_mov_b32_e32 v166, 0
	v_pk_add_f32 v[160:161], v[112:113], v[160:161]
	s_nop 0
	v_mov_b32_dpp v166, v167 row_ror:15 row_mask:0xf bank_mask:0xf
	v_mov_b32_e32 v167, 0
	s_nop 1
	v_mov_b32_dpp v167, v199 row_ror:15 row_mask:0xf bank_mask:0xf
	v_cndmask_b32_e64 v199, v200, 0, vcc
	v_cndmask_b32_e64 v200, v195, 0, vcc
	v_pk_mul_f32 v[200:201], v[80:81], v[200:201]
	v_pk_mul_f32 v[198:199], v[82:83], v[198:199]
	v_pk_fma_f32 v[200:201], v[144:145], v[84:85], v[200:201]
	v_pk_fma_f32 v[198:199], v[146:147], v[86:87], v[198:199]
	v_pk_fma_f32 v[164:165], v[88:89], v[164:165], v[200:201]
	v_pk_fma_f32 v[166:167], v[90:91], v[166:167], v[198:199]
	v_pk_add_f32 v[164:165], v[92:93], v[164:165]
	v_pk_add_f32 v[166:167], v[94:95], v[166:167]
	s_and_saveexec_b64 s[24:25], s[46:47]
	s_xor_b64 s[24:25], exec, s[24:25]
	s_cbranch_execz .LBB1_1072
	v_mul_f32_e32 v195, 0xbfb8aa3b, v160
	v_exp_f32_e32 v195, v195
	v_mul_f32_e32 v196, 0xbfb8aa3b, v161
	v_exp_f32_e32 v196, v196
	v_pk_mul_f32 v[160:161], v[156:157], v[160:161]
	v_add_f32_e32 v195, 1.0, v195
	v_rcp_f32_e32 v198, v195
	v_add_f32_e32 v196, 1.0, v196
	v_mul_f32_e32 v195, 0xbfb8aa3b, v162
	v_rcp_f32_e32 v199, v196
	v_exp_f32_e32 v195, v195
	v_mul_f32_e32 v196, 0xbfb8aa3b, v163
	v_exp_f32_e32 v196, v196
	v_pk_mul_f32 v[160:161], v[160:161], v[198:199]
	v_add_f32_e32 v195, 1.0, v195
	v_rcp_f32_e32 v200, v195
	v_add_f32_e32 v195, 1.0, v196
	v_rcp_f32_e32 v201, v195
	v_cvt_pk_bf16_f32 v160, v160, v161
	v_mul_f32_e32 v161, 0xbfb8aa3b, v164
	v_exp_f32_e32 v195, v161
	v_mul_f32_e32 v161, 0xbfb8aa3b, v165
	v_exp_f32_e32 v196, v161
	v_pk_mul_f32 v[162:163], v[158:159], v[162:163]
	v_pk_mul_f32 v[164:165], v[152:153], v[164:165]
	v_pk_mul_f32 v[162:163], v[162:163], v[200:201]
	s_nop 0
	v_cvt_pk_bf16_f32 v161, v162, v163
	v_add_f32_e32 v162, 1.0, v195
	v_mul_f32_e32 v195, 0xbfb8aa3b, v166
	v_add_f32_e32 v163, 1.0, v196
	v_exp_f32_e32 v195, v195
	v_mul_f32_e32 v196, 0xbfb8aa3b, v167
	v_exp_f32_e32 v196, v196
	v_rcp_f32_e32 v162, v162
	v_add_f32_e32 v195, 1.0, v195
	v_rcp_f32_e32 v198, v195
	v_add_f32_e32 v195, 1.0, v196
	v_rcp_f32_e32 v163, v163
	v_rcp_f32_e32 v199, v195
	v_pk_mul_f32 v[166:167], v[154:155], v[166:167]
	v_pk_mul_f32 v[162:163], v[164:165], v[162:163]
	v_pk_mul_f32 v[164:165], v[166:167], v[198:199]
	v_cvt_pk_bf16_f32 v162, v162, v163
	v_cvt_pk_bf16_f32 v163, v164, v165
	v_mov_b64_e32 v[164:165], s[54:55]
	v_mad_i64_i32 v[164:165], s[42:43], v193, s60, v[164:165]
	v_lshl_add_u64 v[164:165], v[184:185], 1, v[164:165]
	flat_store_dwordx4 v[164:165], v[160:163]

; #define PG8_STAGE(bufoff, gbase, voff) do { _Pragma("unroll") for (int _i = 0; _i < 2; ++_i) \
;         __builtin_amdgcn_global_load_lds((const unsigned*)((const char*)(gbase) + (voff)[_i]), (LAS unsigned*)(lds + (bufoff) + ldsw + _i * 8192), 16, 0, 0); } while (0)
; #define PG8_LDA(dst, b, h) do { _Pragma("unroll") for (int m = 0; m < 4; ++m) _Pragma("unroll") for (int k = 0; k < 2; ++k) dst[m][k] = *(const LAS bf16x8*)(lds + PG8_SA(b, h) + aoff + m * 2048 + k * 1024); } while (0)
; #define PG8_LDB(dst, b, h) do { _Pragma("unroll") for (int n = 0; n < 2; ++n) _Pragma("unroll") for (int k = 0; k < 2; ++k) dst[n][k] = *(const LAS bf16x8*)(lds + PG8_SB(b, h) + boff + n * 2048 + k * 1024); } while (0)
; #define PG8_MMA(ai, bj, At, Bt) do { __builtin_amdgcn_s_setprio(1); _Pragma("unroll") for (int m = 0; m < 4; ++m) _Pragma("unroll") for (int n = 0; n < 2; ++n) _Pragma("unroll") for (int k = 0; k < 2; ++k) \
;         acc[ai][bj][m][n] = __builtin_amdgcn_mfma_f32_16x16x32_bf16(Bt[n][k], At[m][k], acc[ai][bj][m][n], 0, 0, 0); __builtin_amdgcn_s_setprio(0); } while (0)
; #define PG8_WAIT_L(n) asm volatile("s_waitcnt lgkmcnt(" #n ")" ::: "memory")
; #define PG8_BAR __builtin_amdgcn_s_barrier()
; #define PG8_SCHED __builtin_amdgcn_sched_barrier(0)
; template <class Map, class Epi>
; DI void gemm_phase(LAS unsigned char* lds, const Map& MP, const Epi& E, const int nM, const int nN, const int K, const int lda, const int ldb) {
;     ...
;             const bool last = (t == nt - 2);
;             const char* a1 = cA + (size_t)(t + 1) * kstep;
;             const char* a2 = last ? nA : cA + (size_t)(t + 2) * kstep; const char* b2 = last ? nB : cB + (size_t)(t + 2) * kstep;
;             const char* a3 = a2 + kstep; const char* b3 = b2 + kstep;
;             PG8_LDB(B0, 0, 0); PG8_SCHED; PG8_LDA(At, 0, 0); PG8_STAGE(PG8_SA(1, 1), a1 + hstepA, voffA);
;             PG8_WAIT_L(8); PG8_BAR; PG8_WAIT_L(0); PG8_MMA(0, 0, At, B0); PG8_BAR; PG8_SCHED;
;             PG8_LDB(B1, 0, 1); PG8_STAGE(PG8_SB(0, 0), b2, voffB);
;             PG8_BAR; PG8_WAIT_L(0); PG8_MMA(0, 1, At, B1); PG8_BAR;
;             PG8_LDA(At, 0, 1); PG8_STAGE(PG8_SA(0, 0), a2, voffA);
;             PG8_BAR; PG8_WAIT_L(0); PG8_MMA(1, 0, At, B0); PG8_BAR; PG8_SCHED;
.LBB1_1239:
	ds_read_b128 v[152:155], v149
	ds_read_b128 v[156:159], v149 offset:1024
	ds_read_b128 v[160:163], v149 offset:2048
	ds_read_b128 v[164:167], v149 offset:3072
	s_add_u32 s10, s8, 0x100
	s_addc_u32 s11, s9, 0
	s_cmpk_eq_i32 s3, 0x54
	s_cselect_b32 s15, s43, s11
	s_cselect_b32 s14, s42, s10
	s_cselect_b32 s13, s7, s38
	s_cselect_b32 s12, s6, s5
	v_lshl_add_u64 v[144:145], s[8:9], 0, v[138:139]
	s_add_i32 m0, s24, 0xc000
	ds_read_b128 v[168:171], v150
	ds_read_b128 v[172:175], v150 offset:1024
	ds_read_b128 v[176:179], v150 offset:2048
	ds_read_b128 v[180:183], v150 offset:3072
	ds_read_b128 v[184:187], v150 offset:4096
	ds_read_b128 v[188:191], v150 offset:5120
	ds_read_b128 v[192:195], v150 offset:6144
	ds_read_b128 v[198:201], v150 offset:7168
	global_load_lds_dwordx4 v[144:145], off
	v_lshl_add_u64 v[144:145], s[8:9], 0, v[136:137]
	s_add_i32 m0, s24, 0xe000
	s_nop 0
	global_load_lds_dwordx4 v[144:145], off
	s_waitcnt lgkmcnt(8)
	s_barrier
	s_setprio 1
	s_waitcnt lgkmcnt(7)
	v_mfma_f32_16x16x32_bf16 v[124:127], v[152:155], v[168:171], v[124:127]
	v_mfma_f32_16x16x32_bf16 v[120:123], v[160:163], v[168:171], v[120:123]
	s_waitcnt lgkmcnt(5)
	v_mfma_f32_16x16x32_bf16 v[108:111], v[152:155], v[176:179], v[108:111]
	v_mfma_f32_16x16x32_bf16 v[104:107], v[160:163], v[176:179], v[104:107]
	s_waitcnt lgkmcnt(3)
	v_mfma_f32_16x16x32_bf16 v[92:95], v[152:155], v[184:187], v[92:95]
	v_mfma_f32_16x16x32_bf16 v[88:91], v[160:163], v[184:187], v[88:91]
	s_waitcnt lgkmcnt(1)
	v_mfma_f32_16x16x32_bf16 v[76:79], v[152:155], v[192:195], v[76:79]
	v_mfma_f32_16x16x32_bf16 v[72:75], v[160:163], v[192:195], v[72:75]
	v_mfma_f32_16x16x32_bf16 v[124:127], v[156:159], v[172:175], v[124:127]
	v_mfma_f32_16x16x32_bf16 v[120:123], v[164:167], v[172:175], v[120:123]
	v_mfma_f32_16x16x32_bf16 v[108:111], v[156:159], v[180:183], v[108:111]
	v_mfma_f32_16x16x32_bf16 v[104:107], v[164:167], v[180:183], v[104:107]
	v_mfma_f32_16x16x32_bf16 v[92:95], v[156:159], v[188:191], v[92:95]
	v_mfma_f32_16x16x32_bf16 v[88:91], v[164:167], v[188:191], v[88:91]
	s_waitcnt lgkmcnt(0)
	v_mfma_f32_16x16x32_bf16 v[76:79], v[156:159], v[198:201], v[76:79]
	v_mfma_f32_16x16x32_bf16 v[72:75], v[164:167], v[198:201], v[72:75]
	s_setprio 0
	s_barrier
	s_add_i32 s8, s35, s22
	v_lshl_add_u64 v[144:145], s[12:13], 0, v[132:133]
	s_mov_b32 m0, s8
	ds_read_b128 v[202:205], v151
	ds_read_b128 v[206:209], v151 offset:1024
	ds_read_b128 v[210:213], v151 offset:2048
	ds_read_b128 v[214:217], v151 offset:3072
	global_load_lds_dwordx4 v[144:145], off
	v_lshl_add_u64 v[218:219], s[12:13], 0, v[128:129]
	s_add_i32 m0, s8, 0x2000
	s_nop 0
	global_load_lds_dwordx4 v[218:219], off
	s_barrier
	s_setprio 1
	s_waitcnt lgkmcnt(3)
	v_mfma_f32_16x16x32_bf16 v[116:119], v[202:205], v[168:171], v[116:119]
	s_waitcnt lgkmcnt(1)
	v_mfma_f32_16x16x32_bf16 v[112:115], v[210:213], v[168:171], v[112:115]
	v_mfma_f32_16x16x32_bf16 v[100:103], v[202:205], v[176:179], v[100:103]
	v_mfma_f32_16x16x32_bf16 v[96:99], v[210:213], v[176:179], v[96:99]
	v_mfma_f32_16x16x32_bf16 v[84:87], v[202:205], v[184:187], v[84:87]
	v_mfma_f32_16x16x32_bf16 v[80:83], v[210:213], v[184:187], v[80:83]
	v_mfma_f32_16x16x32_bf16 v[68:71], v[202:205], v[192:195], v[68:71]
	v_mfma_f32_16x16x32_bf16 v[64:67], v[210:213], v[192:195], v[64:67]
	v_mfma_f32_16x16x32_bf16 v[116:119], v[206:209], v[172:175], v[116:119]
	s_waitcnt lgkmcnt(0)
	v_mfma_f32_16x16x32_bf16 v[112:115], v[214:217], v[172:175], v[112:115]
	v_mfma_f32_16x16x32_bf16 v[100:103], v[206:209], v[180:183], v[100:103]
	v_mfma_f32_16x16x32_bf16 v[96:99], v[214:217], v[180:183], v[96:99]
	v_mfma_f32_16x16x32_bf16 v[84:87], v[206:209], v[188:191], v[84:87]
	v_mfma_f32_16x16x32_bf16 v[80:83], v[214:217], v[188:191], v[80:83]
	v_mfma_f32_16x16x32_bf16 v[68:71], v[206:209], v[198:201], v[68:71]
	v_mfma_f32_16x16x32_bf16 v[64:67], v[214:217], v[198:201], v[64:67]
	s_setprio 0
	s_mov_b32 m0, s24
	v_lshl_add_u64 v[220:221], s[14:15], 0, v[134:135]
	s_barrier
	ds_read_b128 v[168:171], v150 offset:16384
	ds_read_b128 v[172:175], v150 offset:17408
	ds_read_b128 v[176:179], v150 offset:18432
	ds_read_b128 v[180:183], v150 offset:19456
	ds_read_b128 v[184:187], v150 offset:20480
	ds_read_b128 v[188:191], v150 offset:21504
	ds_read_b128 v[192:195], v150 offset:22528
	ds_read_b128 v[198:201], v150 offset:23552
	global_load_lds_dwordx4 v[220:221], off
	v_lshl_add_u64 v[222:223], s[14:15], 0, v[130:131]
	s_mov_b32 m0, s25
	s_nop 0
	global_load_lds_dwordx4 v[222:223], off
	s_barrier
	s_setprio 1
	s_waitcnt lgkmcnt(7)
	v_mfma_f32_16x16x32_bf16 v[60:63], v[152:155], v[168:171], v[60:63]
	v_mfma_f32_16x16x32_bf16 v[56:59], v[160:163], v[168:171], v[56:59]
	s_waitcnt lgkmcnt(5)
	v_mfma_f32_16x16x32_bf16 v[44:47], v[152:155], v[176:179], v[44:47]
	v_mfma_f32_16x16x32_bf16 v[40:43], v[160:163], v[176:179], v[40:43]
	s_waitcnt lgkmcnt(3)
	v_mfma_f32_16x16x32_bf16 v[28:31], v[152:155], v[184:187], v[28:31]
	v_mfma_f32_16x16x32_bf16 v[24:27], v[160:163], v[184:187], v[24:27]
	s_waitcnt lgkmcnt(1)
	v_mfma_f32_16x16x32_bf16 v[12:15], v[152:155], v[192:195], v[12:15]
	v_mfma_f32_16x16x32_bf16 v[8:11], v[160:163], v[192:195], v[8:11]
	v_mfma_f32_16x16x32_bf16 v[60:63], v[156:159], v[172:175], v[60:63]
	v_mfma_f32_16x16x32_bf16 v[56:59], v[164:167], v[172:175], v[56:59]
	v_mfma_f32_16x16x32_bf16 v[44:47], v[156:159], v[180:183], v[44:47]
	v_mfma_f32_16x16x32_bf16 v[40:43], v[164:167], v[180:183], v[40:43]
	v_mfma_f32_16x16x32_bf16 v[28:31], v[156:159], v[188:191], v[28:31]
	v_mfma_f32_16x16x32_bf16 v[24:27], v[164:167], v[188:191], v[24:27]
	s_waitcnt lgkmcnt(0)
	v_mfma_f32_16x16x32_bf16 v[12:15], v[156:159], v[198:201], v[12:15]
	v_mfma_f32_16x16x32_bf16 v[8:11], v[164:167], v[198:201], v[8:11]
	s_setprio 0
	s_barrier
; #define PG8_STAGE(bufoff, gbase, voff) do { _Pragma("unroll") for (int _i = 0; _i < 2; ++_i) \
;         __builtin_amdgcn_global_load_lds((const unsigned*)((const char*)(gbase) + (voff)[_i]), (LAS unsigned*)(lds + (bufoff) + ldsw + _i * 8192), 16, 0, 0); } while (0)
; #define PG8_LDA(dst, b, h) do { _Pragma("unroll") for (int m = 0; m < 4; ++m) _Pragma("unroll") for (int k = 0; k < 2; ++k) dst[m][k] = *(const LAS bf16x8*)(lds + PG8_SA(b, h) + aoff + m * 2048 + k * 1024); } while (0)
; #define PG8_LDB(dst, b, h) do { _Pragma("unroll") for (int n = 0; n < 2; ++n) _Pragma("unroll") for (int k = 0; k < 2; ++k) dst[n][k] = *(const LAS bf16x8*)(lds + PG8_SB(b, h) + boff + n * 2048 + k * 1024); } while (0)
; #define PG8_MMA(ai, bj, At, Bt) do { __builtin_amdgcn_s_setprio(1); _Pragma("unroll") for (int m = 0; m < 4; ++m) _Pragma("unroll") for (int n = 0; n < 2; ++n) _Pragma("unroll") for (int k = 0; k < 2; ++k) \
;         acc[ai][bj][m][n] = __builtin_amdgcn_mfma_f32_16x16x32_bf16(Bt[n][k], At[m][k], acc[ai][bj][m][n], 0, 0, 0); __builtin_amdgcn_s_setprio(0); } while (0)
; #define PG8_WAIT_V(n) asm volatile("s_waitcnt vmcnt(" #n ")" ::: "memory")
; #define PG8_WAIT_L(n) asm volatile("s_waitcnt lgkmcnt(" #n ")" ::: "memory")
; #define PG8_BAR __builtin_amdgcn_s_barrier()
; #define PG8_SCHED __builtin_amdgcn_sched_barrier(0)
; template <class Map, class Epi>
; DI void gemm_phase(LAS unsigned char* lds, const Map& MP, const Epi& E, const int nM, const int nN, const int K, const int lda, const int ldb) {
;     ...
;             PG8_STAGE(PG8_SB(0, 1), b2 + hstepB, voffB);
;             PG8_WAIT_V(6); PG8_BAR; PG8_MMA(1, 1, At, B1); PG8_BAR;
;             PG8_LDB(B0, 1, 0); PG8_SCHED; PG8_LDA(At, 1, 0); PG8_STAGE(PG8_SA(0, 1), a2 + hstepA, voffA);
;             PG8_WAIT_L(8); PG8_BAR; PG8_WAIT_L(0); PG8_MMA(0, 0, At, B0); PG8_BAR; PG8_SCHED;
;             PG8_LDB(B1, 1, 1); PG8_STAGE(PG8_SB(1, 0), b3, voffB);
;             PG8_BAR; PG8_WAIT_L(0); PG8_MMA(0, 1, At, B1); PG8_BAR;
	s_add_u32 s8, s12, 0x160000
	s_addc_u32 s9, s13, 0
	s_add_i32 s39, s36, s22
	v_lshl_add_u64 v[152:153], s[8:9], 0, v[132:133]
	s_mov_b32 m0, s39
	s_nop 0
	global_load_lds_dwordx4 v[152:153], off
	v_lshl_add_u64 v[152:153], s[8:9], 0, v[128:129]
	s_add_i32 m0, s39, 0x2000
	s_nop 0
	global_load_lds_dwordx4 v[152:153], off
	s_waitcnt vmcnt(6)
	s_barrier
	s_setprio 1
	v_mfma_f32_16x16x32_bf16 v[52:55], v[202:205], v[168:171], v[52:55]
	v_mfma_f32_16x16x32_bf16 v[48:51], v[210:213], v[168:171], v[48:51]
	v_mfma_f32_16x16x32_bf16 v[36:39], v[202:205], v[176:179], v[36:39]
	v_mfma_f32_16x16x32_bf16 v[32:35], v[210:213], v[176:179], v[32:35]
	v_mfma_f32_16x16x32_bf16 v[20:23], v[202:205], v[184:187], v[20:23]
	v_mfma_f32_16x16x32_bf16 v[16:19], v[210:213], v[184:187], v[16:19]
	v_mfma_f32_16x16x32_bf16 v[4:7], v[202:205], v[192:195], v[4:7]
	v_mfma_f32_16x16x32_bf16 v[0:3], v[210:213], v[192:195], v[0:3]
	v_mfma_f32_16x16x32_bf16 v[52:55], v[206:209], v[172:175], v[52:55]
	v_mfma_f32_16x16x32_bf16 v[48:51], v[214:217], v[172:175], v[48:51]
	v_mfma_f32_16x16x32_bf16 v[36:39], v[206:209], v[180:183], v[36:39]
	v_mfma_f32_16x16x32_bf16 v[32:35], v[214:217], v[180:183], v[32:35]
	v_mfma_f32_16x16x32_bf16 v[20:23], v[206:209], v[188:191], v[20:23]
	v_mfma_f32_16x16x32_bf16 v[16:19], v[214:217], v[188:191], v[16:19]
	v_mfma_f32_16x16x32_bf16 v[4:7], v[206:209], v[198:201], v[4:7]
	v_mfma_f32_16x16x32_bf16 v[0:3], v[214:217], v[198:201], v[0:3]
	s_setprio 0
	s_add_i32 s39, 0, 0x18000
	v_add_u32_e32 v164, s39, v148
	s_barrier
	ds_read_b128 v[152:155], v164
	ds_read_b128 v[156:159], v164 offset:1024
	ds_read_b128 v[160:163], v164 offset:2048
	ds_read_b128 v[164:167], v164 offset:3072
	s_add_u32 s8, s14, 0x160000
	s_addc_u32 s9, s15, 0
	s_mov_b32 m0, s26
	v_lshl_add_u64 v[202:203], s[8:9], 0, v[134:135]
	ds_read_b128 v[168:171], v150 offset:32768
	ds_read_b128 v[172:175], v150 offset:33792
	ds_read_b128 v[176:179], v150 offset:34816
	ds_read_b128 v[180:183], v150 offset:35840
	ds_read_b128 v[184:187], v150 offset:36864
	ds_read_b128 v[188:191], v150 offset:37888
	ds_read_b128 v[192:195], v150 offset:38912
	ds_read_b128 v[198:201], v150 offset:39936
	global_load_lds_dwordx4 v[202:203], off
	v_lshl_add_u64 v[202:203], s[8:9], 0, v[130:131]
	s_mov_b32 m0, s27
	s_nop 0
	global_load_lds_dwordx4 v[202:203], off
	s_waitcnt lgkmcnt(8)
	s_barrier
	s_setprio 1
	s_waitcnt lgkmcnt(7)
	v_mfma_f32_16x16x32_bf16 v[124:127], v[152:155], v[168:171], v[124:127]
	v_mfma_f32_16x16x32_bf16 v[120:123], v[160:163], v[168:171], v[120:123]
	s_waitcnt lgkmcnt(5)
	v_mfma_f32_16x16x32_bf16 v[108:111], v[152:155], v[176:179], v[108:111]
	v_mfma_f32_16x16x32_bf16 v[104:107], v[160:163], v[176:179], v[104:107]
	s_waitcnt lgkmcnt(3)
	v_mfma_f32_16x16x32_bf16 v[92:95], v[152:155], v[184:187], v[92:95]
	v_mfma_f32_16x16x32_bf16 v[88:91], v[160:163], v[184:187], v[88:91]
	s_waitcnt lgkmcnt(1)
	v_mfma_f32_16x16x32_bf16 v[76:79], v[152:155], v[192:195], v[76:79]
	v_mfma_f32_16x16x32_bf16 v[72:75], v[160:163], v[192:195], v[72:75]
	v_mfma_f32_16x16x32_bf16 v[124:127], v[156:159], v[172:175], v[124:127]
	v_mfma_f32_16x16x32_bf16 v[120:123], v[164:167], v[172:175], v[120:123]
	v_mfma_f32_16x16x32_bf16 v[108:111], v[156:159], v[180:183], v[108:111]
	v_mfma_f32_16x16x32_bf16 v[104:107], v[164:167], v[180:183], v[104:107]
	v_mfma_f32_16x16x32_bf16 v[92:95], v[156:159], v[188:191], v[92:95]
	v_mfma_f32_16x16x32_bf16 v[88:91], v[164:167], v[188:191], v[88:91]
	s_waitcnt lgkmcnt(0)
	v_mfma_f32_16x16x32_bf16 v[76:79], v[156:159], v[198:201], v[76:79]
	v_mfma_f32_16x16x32_bf16 v[72:75], v[164:167], v[198:201], v[72:75]
	s_setprio 0
	s_barrier
	s_add_i32 s14, 0, 0x1c000
	s_add_i32 s8, s39, s22
	v_add_u32_e32 v196, s14, v148
	v_lshl_add_u64 v[144:145], v[144:145], 0, s[52:53]
	s_mov_b32 m0, s8
	ds_read_b128 v[202:205], v196
	ds_read_b128 v[206:209], v196 offset:1024
	ds_read_b128 v[210:213], v196 offset:2048
	ds_read_b128 v[214:217], v196 offset:3072
	global_load_lds_dwordx4 v[144:145], off
	v_lshl_add_u64 v[144:145], v[218:219], 0, s[52:53]
	s_add_i32 m0, s8, 0x2000
	s_nop 0
	global_load_lds_dwordx4 v[144:145], off
	s_barrier
	s_setprio 1
	s_waitcnt lgkmcnt(3)
	v_mfma_f32_16x16x32_bf16 v[116:119], v[202:205], v[168:171], v[116:119]
	s_waitcnt lgkmcnt(1)
	v_mfma_f32_16x16x32_bf16 v[112:115], v[210:213], v[168:171], v[112:115]
	v_mfma_f32_16x16x32_bf16 v[100:103], v[202:205], v[176:179], v[100:103]
	v_mfma_f32_16x16x32_bf16 v[96:99], v[210:213], v[176:179], v[96:99]
	v_mfma_f32_16x16x32_bf16 v[84:87], v[202:205], v[184:187], v[84:87]
	v_mfma_f32_16x16x32_bf16 v[80:83], v[210:213], v[184:187], v[80:83]
	v_mfma_f32_16x16x32_bf16 v[68:71], v[202:205], v[192:195], v[68:71]
	v_mfma_f32_16x16x32_bf16 v[64:67], v[210:213], v[192:195], v[64:67]
	v_mfma_f32_16x16x32_bf16 v[116:119], v[206:209], v[172:175], v[116:119]
	s_waitcnt lgkmcnt(0)
	v_mfma_f32_16x16x32_bf16 v[112:115], v[214:217], v[172:175], v[112:115]
	v_mfma_f32_16x16x32_bf16 v[100:103], v[206:209], v[180:183], v[100:103]
	v_mfma_f32_16x16x32_bf16 v[96:99], v[214:217], v[180:183], v[96:99]
	v_mfma_f32_16x16x32_bf16 v[84:87], v[206:209], v[188:191], v[84:87]
	v_mfma_f32_16x16x32_bf16 v[80:83], v[214:217], v[188:191], v[80:83]
	v_mfma_f32_16x16x32_bf16 v[68:71], v[206:209], v[198:201], v[68:71]
	v_mfma_f32_16x16x32_bf16 v[64:67], v[214:217], v[198:201], v[64:67]
	s_setprio 0
	s_mov_b32 m0, s30
	v_lshl_add_u64 v[144:145], v[220:221], 0, s[52:53]
	s_barrier
; DI unsigned pack2(float a, float b) { f32x2 v = {a, b}; hwbf16x2 r = __builtin_convertvector(v, hwbf16x2); return __builtin_bit_cast(unsigned, r); }
; DI float bflo(unsigned w) { return __uint_as_float(w << 16); }
; DI float bfhi(unsigned w) { return __uint_as_float(w & 0xffff0000u); }
; #define PG8_STAGE(bufoff, gbase, voff) do { _Pragma("unroll") for (int _i = 0; _i < 2; ++_i) \
;         __builtin_amdgcn_global_load_lds((const unsigned*)((const char*)(gbase) + (voff)[_i]), (LAS unsigned*)(lds + (bufoff) + ldsw + _i * 8192), 16, 0, 0); } while (0)
; #define PG8_WAIT_V(n) asm volatile("s_waitcnt vmcnt(" #n ")" ::: "memory")
; #define PG8_WAIT_L(n) asm volatile("s_waitcnt lgkmcnt(" #n ")" ::: "memory")
;     DI void operator()(const f32x4 (&acc)[2][2][4][2], const Unit& u, int wr, int wc, int fr, int fq) const {
;     ...
;             for (int m = 0; m < 4; ++m) { const size_t ro = (size_t)(row0 + ai * HALF + m * 16) * D + col0;
; #pragma unroll
;                 for (int bj = 0; bj < 2; ++bj) {
;                     f32x4 x0, x1;
;                     if constexpr (IB) { const u32x4 w = *(const u32x4*)((const bf16_t*)Xin + ro + bj * HALF);
;                         x0 = (f32x4){bflo(w[0]), bfhi(w[0]), bflo(w[1]), bfhi(w[1])}; x1 = (f32x4){bflo(w[2]), bfhi(w[2]), bflo(w[3]), bfhi(w[3])}; }
;                     else { x0 = *(const f32x4*)((const float*)Xin + ro + bj * HALF); x1 = *(const f32x4*)((const float*)Xin + ro + bj * HALF + 4); }
;                     x0 += acc[ai][bj][m][0] * sc[bj][0]; x1 += acc[ai][bj][m][1] * sc[bj][1];
;                     if constexpr (OB) { u32x4 o; o[0] = pack2(x0[0], x0[1]); o[1] = pack2(x0[2], x0[3]); o[2] = pack2(x1[0], x1[1]); o[3] = pack2(x1[2], x1[3]);
;                         *(u32x4*)((bf16_t*)Xout + ro + bj * HALF) = o; }
;                     else { *(f32x4*)((float*)Xout + ro + bj * HALF) = x0; *(f32x4*)((float*)Xout + ro + bj * HALF + 4) = x1; } } }
; template <class Map, class Epi>
; DI void gemm_phase(LAS unsigned char* lds, const Map& MP, const Epi& E, const int nM, const int nN, const int K, const int lda, const int ldb) {
;     ...
;             PG8_LDA(At, 1, 1); PG8_STAGE(PG8_SA(1, 0), a3, voffA);
;             PG8_BAR; PG8_WAIT_L(0); PG8_MMA(1, 0, At, B0); PG8_BAR; PG8_SCHED;
;             PG8_STAGE(PG8_SB(1, 1), b3 + hstepB, voffB);
;             PG8_WAIT_V(6); PG8_BAR; PG8_MMA(1, 1, At, B1); PG8_BAR;
	ds_read_b128 v[168:171], v150 offset:49152
	ds_read_b128 v[172:175], v150 offset:50176
	ds_read_b128 v[176:179], v150 offset:51200
	ds_read_b128 v[180:183], v150 offset:52224
	ds_read_b128 v[184:187], v150 offset:53248
	ds_read_b128 v[188:191], v150 offset:54272
	ds_read_b128 v[192:195], v150 offset:55296
	ds_read_b128 v[198:201], v150 offset:56320
	global_load_lds_dwordx4 v[144:145], off
	v_lshl_add_u64 v[144:145], v[222:223], 0, s[52:53]
	s_mov_b32 m0, s31
	s_nop 0
	global_load_lds_dwordx4 v[144:145], off
	s_barrier
	s_setprio 1
	s_waitcnt lgkmcnt(7)
	v_mfma_f32_16x16x32_bf16 v[60:63], v[152:155], v[168:171], v[60:63]
	v_mfma_f32_16x16x32_bf16 v[56:59], v[160:163], v[168:171], v[56:59]
	s_waitcnt lgkmcnt(5)
	v_mfma_f32_16x16x32_bf16 v[44:47], v[152:155], v[176:179], v[44:47]
	v_mfma_f32_16x16x32_bf16 v[40:43], v[160:163], v[176:179], v[40:43]
	s_waitcnt lgkmcnt(3)
	v_mfma_f32_16x16x32_bf16 v[28:31], v[152:155], v[184:187], v[28:31]
	v_mfma_f32_16x16x32_bf16 v[24:27], v[160:163], v[184:187], v[24:27]
	s_waitcnt lgkmcnt(1)
	v_mfma_f32_16x16x32_bf16 v[12:15], v[152:155], v[192:195], v[12:15]
	v_mfma_f32_16x16x32_bf16 v[8:11], v[160:163], v[192:195], v[8:11]
	v_mfma_f32_16x16x32_bf16 v[60:63], v[156:159], v[172:175], v[60:63]
	v_mfma_f32_16x16x32_bf16 v[56:59], v[164:167], v[172:175], v[56:59]
	v_mfma_f32_16x16x32_bf16 v[44:47], v[156:159], v[180:183], v[44:47]
	v_mfma_f32_16x16x32_bf16 v[40:43], v[164:167], v[180:183], v[40:43]
	v_mfma_f32_16x16x32_bf16 v[28:31], v[156:159], v[188:191], v[28:31]
	v_mfma_f32_16x16x32_bf16 v[24:27], v[164:167], v[188:191], v[24:27]
	s_waitcnt lgkmcnt(0)
	v_mfma_f32_16x16x32_bf16 v[12:15], v[156:159], v[198:201], v[12:15]
	v_mfma_f32_16x16x32_bf16 v[8:11], v[164:167], v[198:201], v[8:11]
	s_setprio 0
	s_barrier
	s_add_u32 s8, s12, 0x160080
	s_addc_u32 s9, s13, 0
	s_add_i32 s12, s14, s22
	v_lshl_add_u64 v[144:145], s[8:9], 0, v[132:133]
	s_mov_b32 m0, s12
	s_nop 0
	global_load_lds_dwordx4 v[144:145], off
	v_lshl_add_u64 v[144:145], s[8:9], 0, v[128:129]
	s_add_i32 m0, s12, 0x2000
	s_nop 0
	global_load_lds_dwordx4 v[144:145], off
	s_waitcnt vmcnt(6)
	s_barrier
	s_setprio 1
	v_mfma_f32_16x16x32_bf16 v[52:55], v[202:205], v[168:171], v[52:55]
	v_mfma_f32_16x16x32_bf16 v[48:51], v[210:213], v[168:171], v[48:51]
	v_mfma_f32_16x16x32_bf16 v[36:39], v[202:205], v[176:179], v[36:39]
	v_mfma_f32_16x16x32_bf16 v[32:35], v[210:213], v[176:179], v[32:35]
	v_mfma_f32_16x16x32_bf16 v[20:23], v[202:205], v[184:187], v[20:23]
	v_mfma_f32_16x16x32_bf16 v[16:19], v[210:213], v[184:187], v[16:19]
	v_mfma_f32_16x16x32_bf16 v[4:7], v[202:205], v[192:195], v[4:7]
	v_mfma_f32_16x16x32_bf16 v[0:3], v[210:213], v[192:195], v[0:3]
	v_mfma_f32_16x16x32_bf16 v[52:55], v[206:209], v[172:175], v[52:55]
	v_mfma_f32_16x16x32_bf16 v[48:51], v[214:217], v[172:175], v[48:51]
	v_mfma_f32_16x16x32_bf16 v[36:39], v[206:209], v[180:183], v[36:39]
	v_mfma_f32_16x16x32_bf16 v[32:35], v[214:217], v[180:183], v[32:35]
	v_mfma_f32_16x16x32_bf16 v[20:23], v[206:209], v[188:191], v[20:23]
	v_mfma_f32_16x16x32_bf16 v[16:19], v[214:217], v[188:191], v[16:19]
	v_mfma_f32_16x16x32_bf16 v[4:7], v[206:209], v[198:201], v[4:7]
	v_mfma_f32_16x16x32_bf16 v[0:3], v[214:217], v[198:201], v[0:3]
	s_setprio 0
	s_add_i32 s3, s3, 2
	s_add_u32 s5, s5, 0x100
	s_addc_u32 s38, s38, 0
	s_cmpk_gt_u32 s3, 0x55
	s_mov_b64 s[8:9], s[10:11]
	s_barrier
	s_cbranch_scc0 .LBB1_1239
	v_mov_b32_e32 v152, v147
	v_mov_b32_e32 v144, v146
	s_lshl_b32 s2, s2, 8
	s_add_i32 s2, s2, s29
	s_lshl_b32 s3, s4, 8
	v_add_u32_e32 v152, s2, v152
	s_or_b32 s3, s3, s54
	v_ashrrev_i32_e32 v153, 31, v152
	v_lshl_add_u32 v144, v144, 3, s3
	v_lshlrev_b64 v[152:153], 12, v[152:153]
	v_ashrrev_i32_e32 v145, 31, v144
	v_lshl_add_u64 v[152:153], s[46:47], 0, v[152:153]
	v_lshl_add_u64 v[144:145], v[144:145], 1, v[152:153]
	flat_load_dwordx4 v[152:155], v[144:145]
	s_mov_b64 s[2:3], 0x10000
	s_mov_b32 s4, s37
	s_mov_b64 s[10:11], s[6:7]
	s_mov_b64 s[8:9], s[42:43]
	s_waitcnt vmcnt(0) lgkmcnt(0)
	v_lshlrev_b32_e32 v156, 16, v152
	v_and_b32_e32 v157, 0xffff0000, v152
	v_lshlrev_b32_e32 v152, 16, v153
	v_and_b32_e32 v153, 0xffff0000, v153
	v_lshlrev_b32_e32 v158, 16, v154
	v_and_b32_e32 v159, 0xffff0000, v154
	v_lshlrev_b32_e32 v154, 16, v155
	v_and_b32_e32 v155, 0xffff0000, v155
	v_pk_add_f32 v[126:127], v[126:127], v[152:153]
	v_pk_add_f32 v[124:125], v[124:125], v[156:157]
	v_pk_add_f32 v[152:153], v[122:123], v[154:155]
	v_pk_add_f32 v[122:123], v[120:121], v[158:159]
	v_cvt_pk_bf16_f32 v120, v124, v125
	v_cvt_pk_bf16_f32 v121, v126, v127
	v_cvt_pk_bf16_f32 v122, v122, v123
	v_cvt_pk_bf16_f32 v123, v152, v153
	flat_store_dwordx4 v[144:145], v[120:123]
	flat_load_dwordx4 v[120:123], v[144:145] offset:256
	s_waitcnt vmcnt(0) lgkmcnt(0)
	v_lshlrev_b32_e32 v124, 16, v120
	v_and_b32_e32 v125, 0xffff0000, v120
	v_lshlrev_b32_e32 v120, 16, v121
	v_and_b32_e32 v121, 0xffff0000, v121
	v_lshlrev_b32_e32 v126, 16, v122
	v_and_b32_e32 v127, 0xffff0000, v122
	v_lshlrev_b32_e32 v122, 16, v123
	v_and_b32_e32 v123, 0xffff0000, v123
	v_pk_add_f32 v[116:117], v[116:117], v[124:125]
	v_pk_add_f32 v[118:119], v[118:119], v[120:121]
	v_pk_add_f32 v[120:121], v[114:115], v[122:123]
	v_pk_add_f32 v[114:115], v[112:113], v[126:127]
	v_cvt_pk_bf16_f32 v112, v116, v117
	v_lshl_add_u64 v[116:117], v[144:145], 0, s[2:3]
	s_mov_b32 s2, 0x10000
	v_cvt_pk_bf16_f32 v113, v118, v119
	v_add_co_u32_e32 v118, vcc, s2, v144
	v_cvt_pk_bf16_f32 v114, v114, v115
	v_cvt_pk_bf16_f32 v115, v120, v121
	v_addc_co_u32_e32 v119, vcc, 0, v145, vcc
	flat_store_dwordx4 v[144:145], v[112:115] offset:256
	flat_load_dwordx4 v[112:115], v[118:119]
	s_mov_b64 s[2:3], 0x20000
	s_waitcnt vmcnt(0) lgkmcnt(0)
; DI unsigned pack2(float a, float b) { f32x2 v = {a, b}; hwbf16x2 r = __builtin_convertvector(v, hwbf16x2); return __builtin_bit_cast(unsigned, r); }
; DI float bflo(unsigned w) { return __uint_as_float(w << 16); }
; DI float bfhi(unsigned w) { return __uint_as_float(w & 0xffff0000u); }
;     DI void operator()(const f32x4 (&acc)[2][2][4][2], const Unit& u, int wr, int wc, int fr, int fq) const {
;     ...
;             for (int m = 0; m < 4; ++m) { const size_t ro = (size_t)(row0 + ai * HALF + m * 16) * D + col0;
; #pragma unroll
;                 for (int bj = 0; bj < 2; ++bj) {
;                     f32x4 x0, x1;
;                     if constexpr (IB) { const u32x4 w = *(const u32x4*)((const bf16_t*)Xin + ro + bj * HALF);
;                         x0 = (f32x4){bflo(w[0]), bfhi(w[0]), bflo(w[1]), bfhi(w[1])}; x1 = (f32x4){bflo(w[2]), bfhi(w[2]), bflo(w[3]), bfhi(w[3])}; }
;                     else { x0 = *(const f32x4*)((const float*)Xin + ro + bj * HALF); x1 = *(const f32x4*)((const float*)Xin + ro + bj * HALF + 4); }
;                     x0 += acc[ai][bj][m][0] * sc[bj][0]; x1 += acc[ai][bj][m][1] * sc[bj][1];
;                     if constexpr (OB) { u32x4 o; o[0] = pack2(x0[0], x0[1]); o[1] = pack2(x0[2], x0[3]); o[2] = pack2(x1[0], x1[1]); o[3] = pack2(x1[2], x1[3]);
;                         *(u32x4*)((bf16_t*)Xout + ro + bj * HALF) = o; }
;                     else { *(f32x4*)((float*)Xout + ro + bj * HALF) = x0; *(f32x4*)((float*)Xout + ro + bj * HALF + 4) = x1; } } }
	v_lshlrev_b32_e32 v120, 16, v112
	v_and_b32_e32 v121, 0xffff0000, v112
	v_lshlrev_b32_e32 v112, 16, v113
	v_and_b32_e32 v113, 0xffff0000, v113
	v_lshlrev_b32_e32 v122, 16, v114
	v_and_b32_e32 v123, 0xffff0000, v114
	v_lshlrev_b32_e32 v114, 16, v115
	v_and_b32_e32 v115, 0xffff0000, v115
	v_pk_add_f32 v[110:111], v[110:111], v[112:113]
	v_pk_add_f32 v[108:109], v[108:109], v[120:121]
	v_pk_add_f32 v[112:113], v[106:107], v[114:115]
	v_pk_add_f32 v[106:107], v[104:105], v[122:123]
	v_cvt_pk_bf16_f32 v104, v108, v109
	v_cvt_pk_bf16_f32 v105, v110, v111
	v_cvt_pk_bf16_f32 v106, v106, v107
	v_cvt_pk_bf16_f32 v107, v112, v113
	flat_store_dwordx4 v[118:119], v[104:107]
	flat_load_dwordx4 v[104:107], v[116:117] offset:256
	s_waitcnt vmcnt(0) lgkmcnt(0)
	v_lshlrev_b32_e32 v108, 16, v104
	v_and_b32_e32 v109, 0xffff0000, v104
	v_lshlrev_b32_e32 v104, 16, v105
	v_and_b32_e32 v105, 0xffff0000, v105
	v_lshlrev_b32_e32 v110, 16, v106
	v_and_b32_e32 v111, 0xffff0000, v106
	v_lshlrev_b32_e32 v106, 16, v107
	v_and_b32_e32 v107, 0xffff0000, v107
	v_pk_add_f32 v[100:101], v[100:101], v[108:109]
	v_pk_add_f32 v[102:103], v[102:103], v[104:105]
	v_pk_add_f32 v[104:105], v[98:99], v[106:107]
	v_pk_add_f32 v[98:99], v[96:97], v[110:111]
	v_cvt_pk_bf16_f32 v96, v100, v101
	v_lshl_add_u64 v[100:101], v[144:145], 0, s[2:3]
	s_mov_b32 s2, 0x20000
	v_cvt_pk_bf16_f32 v97, v102, v103
	v_add_co_u32_e32 v102, vcc, s2, v144
	v_cvt_pk_bf16_f32 v98, v98, v99
	v_cvt_pk_bf16_f32 v99, v104, v105
	v_addc_co_u32_e32 v103, vcc, 0, v145, vcc
	flat_store_dwordx4 v[116:117], v[96:99] offset:256
	flat_load_dwordx4 v[96:99], v[102:103]
	s_mov_b64 s[2:3], 0x30000
	s_waitcnt vmcnt(0) lgkmcnt(0)
	v_lshlrev_b32_e32 v104, 16, v96
	v_and_b32_e32 v105, 0xffff0000, v96
	v_lshlrev_b32_e32 v96, 16, v97
	v_and_b32_e32 v97, 0xffff0000, v97
	v_lshlrev_b32_e32 v106, 16, v98
	v_and_b32_e32 v107, 0xffff0000, v98
	v_lshlrev_b32_e32 v98, 16, v99
	v_and_b32_e32 v99, 0xffff0000, v99
	v_pk_add_f32 v[94:95], v[94:95], v[96:97]
	v_pk_add_f32 v[92:93], v[92:93], v[104:105]
	v_pk_add_f32 v[96:97], v[90:91], v[98:99]
	v_pk_add_f32 v[90:91], v[88:89], v[106:107]
	v_cvt_pk_bf16_f32 v88, v92, v93
	v_cvt_pk_bf16_f32 v89, v94, v95
	v_cvt_pk_bf16_f32 v90, v90, v91
	v_cvt_pk_bf16_f32 v91, v96, v97
	flat_store_dwordx4 v[102:103], v[88:91]
	flat_load_dwordx4 v[88:91], v[100:101] offset:256
	s_waitcnt vmcnt(0) lgkmcnt(0)
	v_lshlrev_b32_e32 v92, 16, v88
	v_and_b32_e32 v93, 0xffff0000, v88
	v_lshlrev_b32_e32 v88, 16, v89
	v_and_b32_e32 v89, 0xffff0000, v89
	v_lshlrev_b32_e32 v94, 16, v90
	v_and_b32_e32 v95, 0xffff0000, v90
	v_lshlrev_b32_e32 v90, 16, v91
	v_and_b32_e32 v91, 0xffff0000, v91
	v_pk_add_f32 v[86:87], v[86:87], v[88:89]
	v_pk_add_f32 v[84:85], v[84:85], v[92:93]
	v_pk_add_f32 v[88:89], v[82:83], v[90:91]
	v_pk_add_f32 v[82:83], v[80:81], v[94:95]
	v_cvt_pk_bf16_f32 v80, v84, v85
	v_cvt_pk_bf16_f32 v81, v86, v87
	v_cvt_pk_bf16_f32 v82, v82, v83
	v_cvt_pk_bf16_f32 v83, v88, v89
	flat_store_dwordx4 v[100:101], v[80:83] offset:256
	s_nop 1
	v_lshl_add_u64 v[80:81], v[144:145], 0, s[2:3]
	s_mov_b32 s2, 0x30000
	v_add_co_u32_e32 v86, vcc, s2, v144
	s_mov_b64 s[2:3], 0x80000
	s_nop 0
	v_addc_co_u32_e32 v87, vcc, 0, v145, vcc
	flat_load_dwordx4 v[82:85], v[86:87]
	s_waitcnt vmcnt(0) lgkmcnt(0)
	v_lshlrev_b32_e32 v88, 16, v82
	v_and_b32_e32 v89, 0xffff0000, v82
	v_lshlrev_b32_e32 v82, 16, v83
	v_and_b32_e32 v83, 0xffff0000, v83
	v_lshlrev_b32_e32 v90, 16, v84
	v_and_b32_e32 v91, 0xffff0000, v84
	v_lshlrev_b32_e32 v84, 16, v85
	v_and_b32_e32 v85, 0xffff0000, v85
	v_pk_add_f32 v[78:79], v[78:79], v[82:83]
	v_pk_add_f32 v[76:77], v[76:77], v[88:89]
	v_pk_add_f32 v[82:83], v[74:75], v[84:85]
	v_pk_add_f32 v[74:75], v[72:73], v[90:91]
	v_cvt_pk_bf16_f32 v72, v76, v77
	v_cvt_pk_bf16_f32 v73, v78, v79
	v_cvt_pk_bf16_f32 v74, v74, v75
	v_cvt_pk_bf16_f32 v75, v82, v83
	flat_store_dwordx4 v[86:87], v[72:75]
	flat_load_dwordx4 v[72:75], v[80:81] offset:256
	s_waitcnt vmcnt(0) lgkmcnt(0)
	v_lshlrev_b32_e32 v76, 16, v72
	v_and_b32_e32 v77, 0xffff0000, v72
	v_lshlrev_b32_e32 v72, 16, v73
	v_and_b32_e32 v73, 0xffff0000, v73
	v_lshlrev_b32_e32 v78, 16, v74
	v_and_b32_e32 v79, 0xffff0000, v74
	v_lshlrev_b32_e32 v74, 16, v75
	v_and_b32_e32 v75, 0xffff0000, v75
	v_pk_add_f32 v[70:71], v[70:71], v[72:73]
	v_pk_add_f32 v[68:69], v[68:69], v[76:77]
	v_pk_add_f32 v[72:73], v[66:67], v[74:75]
	v_pk_add_f32 v[66:67], v[64:65], v[78:79]
	v_cvt_pk_bf16_f32 v64, v68, v69
	v_cvt_pk_bf16_f32 v65, v70, v71
	v_cvt_pk_bf16_f32 v66, v66, v67
	v_cvt_pk_bf16_f32 v67, v72, v73
	flat_store_dwordx4 v[80:81], v[64:67] offset:256
	s_nop 1
	v_lshl_add_u64 v[64:65], v[144:145], 0, s[2:3]
	s_mov_b32 s2, 0x80000
	v_add_co_u32_e32 v70, vcc, s2, v144
	s_mov_b64 s[2:3], 0x90000
	s_nop 0
	v_addc_co_u32_e32 v71, vcc, 0, v145, vcc
	flat_load_dwordx4 v[66:69], v[70:71]
	s_waitcnt vmcnt(0) lgkmcnt(0)
	v_lshlrev_b32_e32 v72, 16, v66
	v_and_b32_e32 v73, 0xffff0000, v66
	v_lshlrev_b32_e32 v66, 16, v67
	v_and_b32_e32 v67, 0xffff0000, v67
	v_lshlrev_b32_e32 v74, 16, v68
	v_and_b32_e32 v75, 0xffff0000, v68
	v_lshlrev_b32_e32 v68, 16, v69
	v_and_b32_e32 v69, 0xffff0000, v69
	v_pk_add_f32 v[62:63], v[62:63], v[66:67]
	v_pk_add_f32 v[60:61], v[60:61], v[72:73]
	v_pk_add_f32 v[66:67], v[58:59], v[68:69]
	v_pk_add_f32 v[58:59], v[56:57], v[74:75]
	v_cvt_pk_bf16_f32 v56, v60, v61
	v_cvt_pk_bf16_f32 v57, v62, v63
	v_cvt_pk_bf16_f32 v58, v58, v59
	v_cvt_pk_bf16_f32 v59, v66, v67
	flat_store_dwordx4 v[70:71], v[56:59]
	flat_load_dwordx4 v[56:59], v[64:65] offset:256
	s_waitcnt vmcnt(0) lgkmcnt(0)
; DI unsigned pack2(float a, float b) { f32x2 v = {a, b}; hwbf16x2 r = __builtin_convertvector(v, hwbf16x2); return __builtin_bit_cast(unsigned, r); }
; DI float bflo(unsigned w) { return __uint_as_float(w << 16); }
; DI float bfhi(unsigned w) { return __uint_as_float(w & 0xffff0000u); }
; #define PG8_WAIT_V(n) asm volatile("s_waitcnt vmcnt(" #n ")" ::: "memory")
; #define PG8_BAR __builtin_amdgcn_s_barrier()
;     DI void operator()(const f32x4 (&acc)[2][2][4][2], const Unit& u, int wr, int wc, int fr, int fq) const {
;     ...
;             for (int m = 0; m < 4; ++m) { const size_t ro = (size_t)(row0 + ai * HALF + m * 16) * D + col0;
; #pragma unroll
;                 for (int bj = 0; bj < 2; ++bj) {
;                     f32x4 x0, x1;
;                     if constexpr (IB) { const u32x4 w = *(const u32x4*)((const bf16_t*)Xin + ro + bj * HALF);
;                         x0 = (f32x4){bflo(w[0]), bfhi(w[0]), bflo(w[1]), bfhi(w[1])}; x1 = (f32x4){bflo(w[2]), bfhi(w[2]), bflo(w[3]), bfhi(w[3])}; }
;                     else { x0 = *(const f32x4*)((const float*)Xin + ro + bj * HALF); x1 = *(const f32x4*)((const float*)Xin + ro + bj * HALF + 4); }
;                     x0 += acc[ai][bj][m][0] * sc[bj][0]; x1 += acc[ai][bj][m][1] * sc[bj][1];
;                     if constexpr (OB) { u32x4 o; o[0] = pack2(x0[0], x0[1]); o[1] = pack2(x0[2], x0[3]); o[2] = pack2(x1[0], x1[1]); o[3] = pack2(x1[2], x1[3]);
;                         *(u32x4*)((bf16_t*)Xout + ro + bj * HALF) = o; }
;                     else { *(f32x4*)((float*)Xout + ro + bj * HALF) = x0; *(f32x4*)((float*)Xout + ro + bj * HALF + 4) = x1; } } }
; template <class Map, class Epi>
; DI void gemm_phase(LAS unsigned char* lds, const Map& MP, const Epi& E, const int nM, const int nN, const int K, const int lda, const int ldb) {
;     ...
;         cur = nxt; cA = nA; cB = nB; ++ui;
;     }
;     PG8_WAIT_V(0);
;     if (wr == 0) PG8_BAR;
;     PG8_BAR;
	v_lshlrev_b32_e32 v60, 16, v56
	v_and_b32_e32 v61, 0xffff0000, v56
	v_lshlrev_b32_e32 v56, 16, v57
	v_and_b32_e32 v57, 0xffff0000, v57
	v_lshlrev_b32_e32 v62, 16, v58
	v_and_b32_e32 v63, 0xffff0000, v58
	v_lshlrev_b32_e32 v58, 16, v59
	v_and_b32_e32 v59, 0xffff0000, v59
	v_pk_add_f32 v[54:55], v[54:55], v[56:57]
	v_pk_add_f32 v[52:53], v[52:53], v[60:61]
	v_pk_add_f32 v[56:57], v[50:51], v[58:59]
	v_pk_add_f32 v[50:51], v[48:49], v[62:63]
	v_cvt_pk_bf16_f32 v48, v52, v53
	v_cvt_pk_bf16_f32 v49, v54, v55
	v_cvt_pk_bf16_f32 v50, v50, v51
	v_cvt_pk_bf16_f32 v51, v56, v57
	flat_store_dwordx4 v[64:65], v[48:51] offset:256
	s_nop 1
	v_lshl_add_u64 v[48:49], v[144:145], 0, s[2:3]
	s_mov_b32 s2, 0x90000
	v_add_co_u32_e32 v54, vcc, s2, v144
	s_mov_b64 s[2:3], 0xa0000
	s_nop 0
	v_addc_co_u32_e32 v55, vcc, 0, v145, vcc
	flat_load_dwordx4 v[50:53], v[54:55]
	s_waitcnt vmcnt(0) lgkmcnt(0)
	v_lshlrev_b32_e32 v56, 16, v50
	v_and_b32_e32 v57, 0xffff0000, v50
	v_lshlrev_b32_e32 v50, 16, v51
	v_and_b32_e32 v51, 0xffff0000, v51
	v_lshlrev_b32_e32 v58, 16, v52
	v_and_b32_e32 v59, 0xffff0000, v52
	v_lshlrev_b32_e32 v52, 16, v53
	v_and_b32_e32 v53, 0xffff0000, v53
	v_pk_add_f32 v[46:47], v[46:47], v[50:51]
	v_pk_add_f32 v[44:45], v[44:45], v[56:57]
	v_pk_add_f32 v[50:51], v[42:43], v[52:53]
	v_pk_add_f32 v[42:43], v[40:41], v[58:59]
	v_cvt_pk_bf16_f32 v40, v44, v45
	v_cvt_pk_bf16_f32 v41, v46, v47
	v_cvt_pk_bf16_f32 v42, v42, v43
	v_cvt_pk_bf16_f32 v43, v50, v51
	flat_store_dwordx4 v[54:55], v[40:43]
	flat_load_dwordx4 v[40:43], v[48:49] offset:256
	s_waitcnt vmcnt(0) lgkmcnt(0)
	v_lshlrev_b32_e32 v44, 16, v40
	v_and_b32_e32 v45, 0xffff0000, v40
	v_lshlrev_b32_e32 v40, 16, v41
	v_and_b32_e32 v41, 0xffff0000, v41
	v_lshlrev_b32_e32 v46, 16, v42
	v_and_b32_e32 v47, 0xffff0000, v42
	v_lshlrev_b32_e32 v42, 16, v43
	v_and_b32_e32 v43, 0xffff0000, v43
	v_pk_add_f32 v[38:39], v[38:39], v[40:41]
	v_pk_add_f32 v[36:37], v[36:37], v[44:45]
	v_pk_add_f32 v[40:41], v[34:35], v[42:43]
	v_pk_add_f32 v[34:35], v[32:33], v[46:47]
	v_cvt_pk_bf16_f32 v32, v36, v37
	v_cvt_pk_bf16_f32 v33, v38, v39
	v_cvt_pk_bf16_f32 v34, v34, v35
	v_cvt_pk_bf16_f32 v35, v40, v41
	flat_store_dwordx4 v[48:49], v[32:35] offset:256
	s_nop 1
	v_lshl_add_u64 v[32:33], v[144:145], 0, s[2:3]
	s_mov_b32 s2, 0xa0000
	v_add_co_u32_e32 v38, vcc, s2, v144
	s_mov_b64 s[2:3], 0xb0000
	s_nop 0
	v_addc_co_u32_e32 v39, vcc, 0, v145, vcc
	flat_load_dwordx4 v[34:37], v[38:39]
	s_waitcnt vmcnt(0) lgkmcnt(0)
	v_lshlrev_b32_e32 v40, 16, v34
	v_and_b32_e32 v41, 0xffff0000, v34
	v_lshlrev_b32_e32 v34, 16, v35
	v_and_b32_e32 v35, 0xffff0000, v35
	v_lshlrev_b32_e32 v42, 16, v36
	v_and_b32_e32 v43, 0xffff0000, v36
	v_lshlrev_b32_e32 v36, 16, v37
	v_and_b32_e32 v37, 0xffff0000, v37
	v_pk_add_f32 v[30:31], v[30:31], v[34:35]
	v_pk_add_f32 v[28:29], v[28:29], v[40:41]
	v_pk_add_f32 v[34:35], v[26:27], v[36:37]
	v_pk_add_f32 v[26:27], v[24:25], v[42:43]
	v_cvt_pk_bf16_f32 v24, v28, v29
	v_cvt_pk_bf16_f32 v25, v30, v31
	v_cvt_pk_bf16_f32 v26, v26, v27
	v_cvt_pk_bf16_f32 v27, v34, v35
	flat_store_dwordx4 v[38:39], v[24:27]
	flat_load_dwordx4 v[24:27], v[32:33] offset:256
	s_waitcnt vmcnt(0) lgkmcnt(0)
	v_lshlrev_b32_e32 v28, 16, v24
	v_and_b32_e32 v29, 0xffff0000, v24
	v_lshlrev_b32_e32 v24, 16, v25
	v_and_b32_e32 v25, 0xffff0000, v25
	v_lshlrev_b32_e32 v30, 16, v26
	v_and_b32_e32 v31, 0xffff0000, v26
	v_lshlrev_b32_e32 v26, 16, v27
	v_and_b32_e32 v27, 0xffff0000, v27
	v_pk_add_f32 v[22:23], v[22:23], v[24:25]
	v_pk_add_f32 v[20:21], v[20:21], v[28:29]
	v_pk_add_f32 v[24:25], v[18:19], v[26:27]
	v_pk_add_f32 v[18:19], v[16:17], v[30:31]
	v_cvt_pk_bf16_f32 v16, v20, v21
	v_cvt_pk_bf16_f32 v17, v22, v23
	v_cvt_pk_bf16_f32 v18, v18, v19
	v_cvt_pk_bf16_f32 v19, v24, v25
	flat_store_dwordx4 v[32:33], v[16:19] offset:256
	s_nop 1
	v_lshl_add_u64 v[16:17], v[144:145], 0, s[2:3]
	s_mov_b32 s2, 0xb0000
	v_add_co_u32_e32 v22, vcc, s2, v144
	s_mov_b32 s2, s55
	s_nop 0
	v_addc_co_u32_e32 v23, vcc, 0, v145, vcc
	flat_load_dwordx4 v[18:21], v[22:23]
	s_and_b64 vcc, exec, s[40:41]
	s_waitcnt vmcnt(0) lgkmcnt(0)
	v_lshlrev_b32_e32 v24, 16, v18
	v_and_b32_e32 v25, 0xffff0000, v18
	v_lshlrev_b32_e32 v18, 16, v19
	v_and_b32_e32 v19, 0xffff0000, v19
	v_lshlrev_b32_e32 v26, 16, v20
	v_and_b32_e32 v27, 0xffff0000, v20
	v_lshlrev_b32_e32 v20, 16, v21
	v_and_b32_e32 v21, 0xffff0000, v21
	v_pk_add_f32 v[14:15], v[14:15], v[18:19]
	v_pk_add_f32 v[12:13], v[12:13], v[24:25]
	v_pk_add_f32 v[18:19], v[10:11], v[20:21]
	v_pk_add_f32 v[10:11], v[8:9], v[26:27]
	v_cvt_pk_bf16_f32 v8, v12, v13
	v_cvt_pk_bf16_f32 v9, v14, v15
	v_cvt_pk_bf16_f32 v10, v10, v11
	v_cvt_pk_bf16_f32 v11, v18, v19
	flat_store_dwordx4 v[22:23], v[8:11]
	flat_load_dwordx4 v[8:11], v[16:17] offset:256
	s_waitcnt vmcnt(0) lgkmcnt(0)
	v_lshlrev_b32_e32 v12, 16, v8
	v_and_b32_e32 v13, 0xffff0000, v8
	v_lshlrev_b32_e32 v8, 16, v9
	v_and_b32_e32 v9, 0xffff0000, v9
	v_lshlrev_b32_e32 v14, 16, v10
	v_and_b32_e32 v15, 0xffff0000, v10
	v_lshlrev_b32_e32 v10, 16, v11
	v_and_b32_e32 v11, 0xffff0000, v11
	v_pk_add_f32 v[6:7], v[6:7], v[8:9]
	v_pk_add_f32 v[4:5], v[4:5], v[12:13]
	v_pk_add_f32 v[8:9], v[2:3], v[10:11]
	v_pk_add_f32 v[2:3], v[0:1], v[14:15]
	v_cvt_pk_bf16_f32 v0, v4, v5
	v_cvt_pk_bf16_f32 v1, v6, v7
	v_cvt_pk_bf16_f32 v2, v2, v3
	v_cvt_pk_bf16_f32 v3, v8, v9
	flat_store_dwordx4 v[16:17], v[0:3] offset:256
	s_cbranch_vccz .LBB1_1232
	s_waitcnt vmcnt(0)
	s_cmpk_gt_u32 s17, 0xff
	s_cbranch_scc1 .LBB1_1243
	s_barrier

; #define PG8_STAGE(bufoff, gbase, voff) do { _Pragma("unroll") for (int _i = 0; _i < 2; ++_i) \
;         __builtin_amdgcn_global_load_lds((const unsigned*)((const char*)(gbase) + (voff)[_i]), (LAS unsigned*)(lds + (bufoff) + ldsw + _i * 8192), 16, 0, 0); } while (0)
; #define PG8_LDA(dst, b, h) do { _Pragma("unroll") for (int m = 0; m < 4; ++m) _Pragma("unroll") for (int k = 0; k < 2; ++k) dst[m][k] = *(const LAS bf16x8*)(lds + PG8_SA(b, h) + aoff + m * 2048 + k * 1024); } while (0)
; #define PG8_LDB(dst, b, h) do { _Pragma("unroll") for (int n = 0; n < 2; ++n) _Pragma("unroll") for (int k = 0; k < 2; ++k) dst[n][k] = *(const LAS bf16x8*)(lds + PG8_SB(b, h) + boff + n * 2048 + k * 1024); } while (0)
; #define PG8_MMA(ai, bj, At, Bt) do { __builtin_amdgcn_s_setprio(1); _Pragma("unroll") for (int m = 0; m < 4; ++m) _Pragma("unroll") for (int n = 0; n < 2; ++n) _Pragma("unroll") for (int k = 0; k < 2; ++k) \
;         acc[ai][bj][m][n] = __builtin_amdgcn_mfma_f32_16x16x32_bf16(Bt[n][k], At[m][k], acc[ai][bj][m][n], 0, 0, 0); __builtin_amdgcn_s_setprio(0); } while (0)
; #define PG8_WAIT_L(n) asm volatile("s_waitcnt lgkmcnt(" #n ")" ::: "memory")
; #define PG8_BAR __builtin_amdgcn_s_barrier()
; #define PG8_SCHED __builtin_amdgcn_sched_barrier(0)
; template <class Map, class Epi>
; DI void gemm_phase(LAS unsigned char* lds, const Map& MP, const Epi& E, const int nM, const int nN, const int K, const int lda, const int ldb) {
;     ...
;             const bool last = (t == nt - 2);
;             const char* a1 = cA + (size_t)(t + 1) * kstep;
;             const char* a2 = last ? nA : cA + (size_t)(t + 2) * kstep; const char* b2 = last ? nB : cB + (size_t)(t + 2) * kstep;
;             const char* a3 = a2 + kstep; const char* b3 = b2 + kstep;
;             PG8_LDB(B0, 0, 0); PG8_SCHED; PG8_LDA(At, 0, 0); PG8_STAGE(PG8_SA(1, 1), a1 + hstepA, voffA);
;             PG8_WAIT_L(8); PG8_BAR; PG8_WAIT_L(0); PG8_MMA(0, 0, At, B0); PG8_BAR; PG8_SCHED;
;             PG8_LDB(B1, 0, 1); PG8_STAGE(PG8_SB(0, 0), b2, voffB);
;             PG8_BAR; PG8_WAIT_L(0); PG8_MMA(0, 1, At, B1); PG8_BAR;
;             PG8_LDA(At, 0, 1); PG8_STAGE(PG8_SA(0, 0), a2, voffA);
;             PG8_BAR; PG8_WAIT_L(0); PG8_MMA(1, 0, At, B0); PG8_BAR; PG8_SCHED;
.LBB1_1382:
	ds_read_b128 v[150:153], v147
	ds_read_b128 v[154:157], v147 offset:1024
	ds_read_b128 v[158:161], v147 offset:2048
	ds_read_b128 v[162:165], v147 offset:3072
	s_add_u32 s22, s20, 0xfff80080
	s_addc_u32 s23, s21, -1
	s_cmp_eq_u32 s3, 28
	s_cselect_b32 s25, s15, s23
	s_cselect_b32 s24, s48, s22
	s_cselect_b32 s23, s13, s53
	s_cselect_b32 s22, s49, s52
	v_lshl_add_u64 v[194:195], s[20:21], 0, v[138:139]
	s_add_i32 m0, s31, 0xc000
	ds_read_b128 v[166:169], v148
	ds_read_b128 v[170:173], v148 offset:1024
	ds_read_b128 v[174:177], v148 offset:2048
	ds_read_b128 v[178:181], v148 offset:3072
	ds_read_b128 v[182:185], v148 offset:4096
	ds_read_b128 v[186:189], v148 offset:5120
	ds_read_b128 v[190:193], v148 offset:6144
	ds_read_b128 v[198:201], v148 offset:7168
	global_load_lds_dwordx4 v[194:195], off
	v_lshl_add_u64 v[194:195], s[20:21], 0, v[136:137]
	s_add_i32 m0, s31, 0xe000
	s_nop 0
	global_load_lds_dwordx4 v[194:195], off
	s_waitcnt lgkmcnt(8)
	s_barrier
	s_setprio 1
	s_waitcnt lgkmcnt(7)
	v_mfma_f32_16x16x32_bf16 v[124:127], v[150:153], v[166:169], v[124:127]
	v_mfma_f32_16x16x32_bf16 v[120:123], v[158:161], v[166:169], v[120:123]
	s_waitcnt lgkmcnt(5)
	v_mfma_f32_16x16x32_bf16 v[116:119], v[150:153], v[174:177], v[116:119]
	v_mfma_f32_16x16x32_bf16 v[112:115], v[158:161], v[174:177], v[112:115]
	s_waitcnt lgkmcnt(3)
	v_mfma_f32_16x16x32_bf16 v[100:103], v[150:153], v[182:185], v[100:103]
	v_mfma_f32_16x16x32_bf16 v[96:99], v[158:161], v[182:185], v[96:99]
	s_waitcnt lgkmcnt(1)
	v_mfma_f32_16x16x32_bf16 v[84:87], v[150:153], v[190:193], v[84:87]
	v_mfma_f32_16x16x32_bf16 v[80:83], v[158:161], v[190:193], v[80:83]
	v_mfma_f32_16x16x32_bf16 v[124:127], v[154:157], v[170:173], v[124:127]
	v_mfma_f32_16x16x32_bf16 v[120:123], v[162:165], v[170:173], v[120:123]
	v_mfma_f32_16x16x32_bf16 v[116:119], v[154:157], v[178:181], v[116:119]
	v_mfma_f32_16x16x32_bf16 v[112:115], v[162:165], v[178:181], v[112:115]
	v_mfma_f32_16x16x32_bf16 v[100:103], v[154:157], v[186:189], v[100:103]
	v_mfma_f32_16x16x32_bf16 v[96:99], v[162:165], v[186:189], v[96:99]
	s_waitcnt lgkmcnt(0)
	v_mfma_f32_16x16x32_bf16 v[84:87], v[154:157], v[198:201], v[84:87]
	v_mfma_f32_16x16x32_bf16 v[80:83], v[162:165], v[198:201], v[80:83]
	s_setprio 0
	s_barrier
	s_add_i32 s54, s44, s29
	v_lshl_add_u64 v[194:195], s[22:23], 0, v[132:133]
	s_mov_b32 m0, s54
	ds_read_b128 v[202:205], v149
	ds_read_b128 v[206:209], v149 offset:1024
	ds_read_b128 v[210:213], v149 offset:2048
	ds_read_b128 v[214:217], v149 offset:3072
	global_load_lds_dwordx4 v[194:195], off
	v_lshl_add_u64 v[218:219], s[22:23], 0, v[128:129]
	s_add_i32 m0, s54, 0x2000
	s_nop 0
	global_load_lds_dwordx4 v[218:219], off
	s_barrier
	s_setprio 1
	s_waitcnt lgkmcnt(3)
	v_mfma_f32_16x16x32_bf16 v[108:111], v[202:205], v[166:169], v[108:111]
	s_waitcnt lgkmcnt(1)
	v_mfma_f32_16x16x32_bf16 v[104:107], v[210:213], v[166:169], v[104:107]
	v_mfma_f32_16x16x32_bf16 v[92:95], v[202:205], v[174:177], v[92:95]
	v_mfma_f32_16x16x32_bf16 v[88:91], v[210:213], v[174:177], v[88:91]
	v_mfma_f32_16x16x32_bf16 v[76:79], v[202:205], v[182:185], v[76:79]
	v_mfma_f32_16x16x32_bf16 v[72:75], v[210:213], v[182:185], v[72:75]
	v_mfma_f32_16x16x32_bf16 v[68:71], v[202:205], v[190:193], v[68:71]
	v_mfma_f32_16x16x32_bf16 v[64:67], v[210:213], v[190:193], v[64:67]
	v_mfma_f32_16x16x32_bf16 v[108:111], v[206:209], v[170:173], v[108:111]
	s_waitcnt lgkmcnt(0)
	v_mfma_f32_16x16x32_bf16 v[104:107], v[214:217], v[170:173], v[104:107]
	v_mfma_f32_16x16x32_bf16 v[92:95], v[206:209], v[178:181], v[92:95]
	v_mfma_f32_16x16x32_bf16 v[88:91], v[214:217], v[178:181], v[88:91]
	v_mfma_f32_16x16x32_bf16 v[76:79], v[206:209], v[186:189], v[76:79]
	v_mfma_f32_16x16x32_bf16 v[72:75], v[214:217], v[186:189], v[72:75]
	v_mfma_f32_16x16x32_bf16 v[68:71], v[206:209], v[198:201], v[68:71]
	v_mfma_f32_16x16x32_bf16 v[64:67], v[214:217], v[198:201], v[64:67]
	s_setprio 0
	s_mov_b32 m0, s31
	v_lshl_add_u64 v[220:221], s[24:25], 0, v[134:135]
	s_barrier
	ds_read_b128 v[166:169], v148 offset:16384
	ds_read_b128 v[170:173], v148 offset:17408
	ds_read_b128 v[174:177], v148 offset:18432
	ds_read_b128 v[178:181], v148 offset:19456
	ds_read_b128 v[182:185], v148 offset:20480
	ds_read_b128 v[186:189], v148 offset:21504
	ds_read_b128 v[190:193], v148 offset:22528
	ds_read_b128 v[198:201], v148 offset:23552
	global_load_lds_dwordx4 v[220:221], off
	v_lshl_add_u64 v[222:223], s[24:25], 0, v[130:131]
	s_mov_b32 m0, s11
	s_nop 0
	global_load_lds_dwordx4 v[222:223], off
	s_barrier
	s_setprio 1
	s_waitcnt lgkmcnt(7)
	v_mfma_f32_16x16x32_bf16 v[60:63], v[150:153], v[166:169], v[60:63]
	v_mfma_f32_16x16x32_bf16 v[56:59], v[158:161], v[166:169], v[56:59]
	s_waitcnt lgkmcnt(5)
	v_mfma_f32_16x16x32_bf16 v[52:55], v[150:153], v[174:177], v[52:55]
	v_mfma_f32_16x16x32_bf16 v[48:51], v[158:161], v[174:177], v[48:51]
	s_waitcnt lgkmcnt(3)
	v_mfma_f32_16x16x32_bf16 v[36:39], v[150:153], v[182:185], v[36:39]
	v_mfma_f32_16x16x32_bf16 v[32:35], v[158:161], v[182:185], v[32:35]
	s_waitcnt lgkmcnt(1)
	v_mfma_f32_16x16x32_bf16 v[20:23], v[150:153], v[190:193], v[20:23]
	v_mfma_f32_16x16x32_bf16 v[16:19], v[158:161], v[190:193], v[16:19]
	v_mfma_f32_16x16x32_bf16 v[60:63], v[154:157], v[170:173], v[60:63]
	v_mfma_f32_16x16x32_bf16 v[56:59], v[162:165], v[170:173], v[56:59]
	v_mfma_f32_16x16x32_bf16 v[52:55], v[154:157], v[178:181], v[52:55]
	v_mfma_f32_16x16x32_bf16 v[48:51], v[162:165], v[178:181], v[48:51]
	v_mfma_f32_16x16x32_bf16 v[36:39], v[154:157], v[186:189], v[36:39]
	v_mfma_f32_16x16x32_bf16 v[32:35], v[162:165], v[186:189], v[32:35]
	s_waitcnt lgkmcnt(0)
	v_mfma_f32_16x16x32_bf16 v[20:23], v[154:157], v[198:201], v[20:23]
	v_mfma_f32_16x16x32_bf16 v[16:19], v[162:165], v[198:201], v[16:19]
	s_setprio 0
	s_barrier
; #define PG8_STAGE(bufoff, gbase, voff) do { _Pragma("unroll") for (int _i = 0; _i < 2; ++_i) \
;         __builtin_amdgcn_global_load_lds((const unsigned*)((const char*)(gbase) + (voff)[_i]), (LAS unsigned*)(lds + (bufoff) + ldsw + _i * 8192), 16, 0, 0); } while (0)
; #define PG8_LDA(dst, b, h) do { _Pragma("unroll") for (int m = 0; m < 4; ++m) _Pragma("unroll") for (int k = 0; k < 2; ++k) dst[m][k] = *(const LAS bf16x8*)(lds + PG8_SA(b, h) + aoff + m * 2048 + k * 1024); } while (0)
; #define PG8_LDB(dst, b, h) do { _Pragma("unroll") for (int n = 0; n < 2; ++n) _Pragma("unroll") for (int k = 0; k < 2; ++k) dst[n][k] = *(const LAS bf16x8*)(lds + PG8_SB(b, h) + boff + n * 2048 + k * 1024); } while (0)
; #define PG8_MMA(ai, bj, At, Bt) do { __builtin_amdgcn_s_setprio(1); _Pragma("unroll") for (int m = 0; m < 4; ++m) _Pragma("unroll") for (int n = 0; n < 2; ++n) _Pragma("unroll") for (int k = 0; k < 2; ++k) \
;         acc[ai][bj][m][n] = __builtin_amdgcn_mfma_f32_16x16x32_bf16(Bt[n][k], At[m][k], acc[ai][bj][m][n], 0, 0, 0); __builtin_amdgcn_s_setprio(0); } while (0)
; #define PG8_WAIT_V(n) asm volatile("s_waitcnt vmcnt(" #n ")" ::: "memory")
; #define PG8_WAIT_L(n) asm volatile("s_waitcnt lgkmcnt(" #n ")" ::: "memory")
; #define PG8_BAR __builtin_amdgcn_s_barrier()
; #define PG8_SCHED __builtin_amdgcn_sched_barrier(0)
; template <class Map, class Epi>
; DI void gemm_phase(LAS unsigned char* lds, const Map& MP, const Epi& E, const int nM, const int nN, const int K, const int lda, const int ldb) {
;     ...
;             PG8_STAGE(PG8_SB(0, 1), b2 + hstepB, voffB);
;             PG8_WAIT_V(6); PG8_BAR; PG8_MMA(1, 1, At, B1); PG8_BAR;
;             PG8_LDB(B0, 1, 0); PG8_SCHED; PG8_LDA(At, 1, 0); PG8_STAGE(PG8_SA(0, 1), a2 + hstepA, voffA);
;             PG8_WAIT_L(8); PG8_BAR; PG8_WAIT_L(0); PG8_MMA(0, 0, At, B0); PG8_BAR; PG8_SCHED;
;             PG8_LDB(B1, 1, 1); PG8_STAGE(PG8_SB(1, 0), b3, voffB);
;             PG8_BAR; PG8_WAIT_L(0); PG8_MMA(0, 1, At, B1); PG8_BAR;
	s_add_u32 s54, s22, 0x80000
	s_addc_u32 s55, s23, 0
	s_add_i32 s56, s45, s29
	v_lshl_add_u64 v[150:151], s[54:55], 0, v[132:133]
	s_mov_b32 m0, s56
	s_nop 0
	global_load_lds_dwordx4 v[150:151], off
	v_lshl_add_u64 v[150:151], s[54:55], 0, v[128:129]
	s_add_i32 m0, s56, 0x2000
	s_nop 0
	global_load_lds_dwordx4 v[150:151], off
	s_waitcnt vmcnt(6)
	s_barrier
	s_setprio 1
	v_mfma_f32_16x16x32_bf16 v[44:47], v[202:205], v[166:169], v[44:47]
	v_mfma_f32_16x16x32_bf16 v[40:43], v[210:213], v[166:169], v[40:43]
	v_mfma_f32_16x16x32_bf16 v[28:31], v[202:205], v[174:177], v[28:31]
	v_mfma_f32_16x16x32_bf16 v[24:27], v[210:213], v[174:177], v[24:27]
	v_mfma_f32_16x16x32_bf16 v[12:15], v[202:205], v[182:185], v[12:15]
	v_mfma_f32_16x16x32_bf16 v[8:11], v[210:213], v[182:185], v[8:11]
	v_mfma_f32_16x16x32_bf16 v[4:7], v[202:205], v[190:193], v[4:7]
	v_mfma_f32_16x16x32_bf16 v[0:3], v[210:213], v[190:193], v[0:3]
	v_mfma_f32_16x16x32_bf16 v[44:47], v[206:209], v[170:173], v[44:47]
	v_mfma_f32_16x16x32_bf16 v[40:43], v[214:217], v[170:173], v[40:43]
	v_mfma_f32_16x16x32_bf16 v[28:31], v[206:209], v[178:181], v[28:31]
	v_mfma_f32_16x16x32_bf16 v[24:27], v[214:217], v[178:181], v[24:27]
	v_mfma_f32_16x16x32_bf16 v[12:15], v[206:209], v[186:189], v[12:15]
	v_mfma_f32_16x16x32_bf16 v[8:11], v[214:217], v[186:189], v[8:11]
	v_mfma_f32_16x16x32_bf16 v[4:7], v[206:209], v[198:201], v[4:7]
	v_mfma_f32_16x16x32_bf16 v[0:3], v[214:217], v[198:201], v[0:3]
	s_setprio 0
	s_add_i32 s54, 0, 0x18000
	v_add_u32_e32 v162, s54, v146
	s_barrier
	ds_read_b128 v[150:153], v162
	ds_read_b128 v[154:157], v162 offset:1024
	ds_read_b128 v[158:161], v162 offset:2048
	ds_read_b128 v[162:165], v162 offset:3072
	s_add_u32 s24, s24, 0x80000
	s_addc_u32 s25, s25, 0
	s_mov_b32 m0, s34
	v_lshl_add_u64 v[202:203], s[24:25], 0, v[134:135]
	ds_read_b128 v[166:169], v148 offset:32768
	ds_read_b128 v[170:173], v148 offset:33792
	ds_read_b128 v[174:177], v148 offset:34816
	ds_read_b128 v[178:181], v148 offset:35840
	ds_read_b128 v[182:185], v148 offset:36864
	ds_read_b128 v[186:189], v148 offset:37888
	ds_read_b128 v[190:193], v148 offset:38912
	ds_read_b128 v[198:201], v148 offset:39936
	global_load_lds_dwordx4 v[202:203], off
	v_lshl_add_u64 v[202:203], s[24:25], 0, v[130:131]
	s_mov_b32 m0, s35
	s_nop 0
	global_load_lds_dwordx4 v[202:203], off
	s_waitcnt lgkmcnt(8)
	s_barrier
	s_setprio 1
	s_waitcnt lgkmcnt(7)
	v_mfma_f32_16x16x32_bf16 v[124:127], v[150:153], v[166:169], v[124:127]
	v_mfma_f32_16x16x32_bf16 v[120:123], v[158:161], v[166:169], v[120:123]
	s_waitcnt lgkmcnt(5)
	v_mfma_f32_16x16x32_bf16 v[116:119], v[150:153], v[174:177], v[116:119]
	v_mfma_f32_16x16x32_bf16 v[112:115], v[158:161], v[174:177], v[112:115]
	s_waitcnt lgkmcnt(3)
	v_mfma_f32_16x16x32_bf16 v[100:103], v[150:153], v[182:185], v[100:103]
	v_mfma_f32_16x16x32_bf16 v[96:99], v[158:161], v[182:185], v[96:99]
	s_waitcnt lgkmcnt(1)
	v_mfma_f32_16x16x32_bf16 v[84:87], v[150:153], v[190:193], v[84:87]
	v_mfma_f32_16x16x32_bf16 v[80:83], v[158:161], v[190:193], v[80:83]
	v_mfma_f32_16x16x32_bf16 v[124:127], v[154:157], v[170:173], v[124:127]
	v_mfma_f32_16x16x32_bf16 v[120:123], v[162:165], v[170:173], v[120:123]
	v_mfma_f32_16x16x32_bf16 v[116:119], v[154:157], v[178:181], v[116:119]
	v_mfma_f32_16x16x32_bf16 v[112:115], v[162:165], v[178:181], v[112:115]
	v_mfma_f32_16x16x32_bf16 v[100:103], v[154:157], v[186:189], v[100:103]
	v_mfma_f32_16x16x32_bf16 v[96:99], v[162:165], v[186:189], v[96:99]
	s_waitcnt lgkmcnt(0)
	v_mfma_f32_16x16x32_bf16 v[84:87], v[154:157], v[198:201], v[84:87]
	v_mfma_f32_16x16x32_bf16 v[80:83], v[162:165], v[198:201], v[80:83]
	s_setprio 0
	s_barrier
	s_add_i32 s24, 0, 0x1c000
	s_add_i32 s25, s54, s29
	v_add_u32_e32 v196, s24, v146
	v_lshl_add_u64 v[194:195], v[194:195], 0, s[8:9]
	s_mov_b32 m0, s25
	ds_read_b128 v[202:205], v196
	ds_read_b128 v[206:209], v196 offset:1024
	ds_read_b128 v[210:213], v196 offset:2048
	ds_read_b128 v[214:217], v196 offset:3072
	global_load_lds_dwordx4 v[194:195], off
	v_lshl_add_u64 v[194:195], v[218:219], 0, s[8:9]
	s_add_i32 m0, s25, 0x2000
	s_nop 0
	global_load_lds_dwordx4 v[194:195], off
	s_barrier
	s_setprio 1
	s_waitcnt lgkmcnt(3)
	v_mfma_f32_16x16x32_bf16 v[108:111], v[202:205], v[166:169], v[108:111]
	s_waitcnt lgkmcnt(1)
	v_mfma_f32_16x16x32_bf16 v[104:107], v[210:213], v[166:169], v[104:107]
	v_mfma_f32_16x16x32_bf16 v[92:95], v[202:205], v[174:177], v[92:95]
	v_mfma_f32_16x16x32_bf16 v[88:91], v[210:213], v[174:177], v[88:91]
	v_mfma_f32_16x16x32_bf16 v[76:79], v[202:205], v[182:185], v[76:79]
	v_mfma_f32_16x16x32_bf16 v[72:75], v[210:213], v[182:185], v[72:75]
	v_mfma_f32_16x16x32_bf16 v[68:71], v[202:205], v[190:193], v[68:71]
	v_mfma_f32_16x16x32_bf16 v[64:67], v[210:213], v[190:193], v[64:67]
	v_mfma_f32_16x16x32_bf16 v[108:111], v[206:209], v[170:173], v[108:111]
	s_waitcnt lgkmcnt(0)
	v_mfma_f32_16x16x32_bf16 v[104:107], v[214:217], v[170:173], v[104:107]
	v_mfma_f32_16x16x32_bf16 v[92:95], v[206:209], v[178:181], v[92:95]
	v_mfma_f32_16x16x32_bf16 v[88:91], v[214:217], v[178:181], v[88:91]
	v_mfma_f32_16x16x32_bf16 v[76:79], v[206:209], v[186:189], v[76:79]
	v_mfma_f32_16x16x32_bf16 v[72:75], v[214:217], v[186:189], v[72:75]
	v_mfma_f32_16x16x32_bf16 v[68:71], v[206:209], v[198:201], v[68:71]
	v_mfma_f32_16x16x32_bf16 v[64:67], v[214:217], v[198:201], v[64:67]
	s_setprio 0
	s_mov_b32 m0, s39
	v_lshl_add_u64 v[194:195], v[220:221], 0, s[8:9]
	s_barrier
; #define PG8_STAGE(bufoff, gbase, voff) do { _Pragma("unroll") for (int _i = 0; _i < 2; ++_i) \
;         __builtin_amdgcn_global_load_lds((const unsigned*)((const char*)(gbase) + (voff)[_i]), (LAS unsigned*)(lds + (bufoff) + ldsw + _i * 8192), 16, 0, 0); } while (0)
; #define PG8_LDA(dst, b, h) do { _Pragma("unroll") for (int m = 0; m < 4; ++m) _Pragma("unroll") for (int k = 0; k < 2; ++k) dst[m][k] = *(const LAS bf16x8*)(lds + PG8_SA(b, h) + aoff + m * 2048 + k * 1024); } while (0)
; #define PG8_MMA(ai, bj, At, Bt) do { __builtin_amdgcn_s_setprio(1); _Pragma("unroll") for (int m = 0; m < 4; ++m) _Pragma("unroll") for (int n = 0; n < 2; ++n) _Pragma("unroll") for (int k = 0; k < 2; ++k) \
;         acc[ai][bj][m][n] = __builtin_amdgcn_mfma_f32_16x16x32_bf16(Bt[n][k], At[m][k], acc[ai][bj][m][n], 0, 0, 0); __builtin_amdgcn_s_setprio(0); } while (0)
; #define PG8_WAIT_V(n) asm volatile("s_waitcnt vmcnt(" #n ")" ::: "memory")
; #define PG8_WAIT_L(n) asm volatile("s_waitcnt lgkmcnt(" #n ")" ::: "memory")
; #define PG8_BAR __builtin_amdgcn_s_barrier()
; #define PG8_SCHED __builtin_amdgcn_sched_barrier(0)
; template <class Map, class Epi>
; DI void gemm_phase(LAS unsigned char* lds, const Map& MP, const Epi& E, const int nM, const int nN, const int K, const int lda, const int ldb) {
;     ...
;             PG8_LDA(At, 1, 1); PG8_STAGE(PG8_SA(1, 0), a3, voffA);
;             PG8_BAR; PG8_WAIT_L(0); PG8_MMA(1, 0, At, B0); PG8_BAR; PG8_SCHED;
;             PG8_STAGE(PG8_SB(1, 1), b3 + hstepB, voffB);
;             PG8_WAIT_V(6); PG8_BAR; PG8_MMA(1, 1, At, B1); PG8_BAR;
	ds_read_b128 v[166:169], v148 offset:49152
	ds_read_b128 v[170:173], v148 offset:50176
	ds_read_b128 v[174:177], v148 offset:51200
	ds_read_b128 v[178:181], v148 offset:52224
	ds_read_b128 v[182:185], v148 offset:53248
	ds_read_b128 v[186:189], v148 offset:54272
	ds_read_b128 v[190:193], v148 offset:55296
	ds_read_b128 v[198:201], v148 offset:56320
	global_load_lds_dwordx4 v[194:195], off
	v_lshl_add_u64 v[194:195], v[222:223], 0, s[8:9]
	s_mov_b32 m0, s42
	s_nop 0
	global_load_lds_dwordx4 v[194:195], off
	s_barrier
	s_setprio 1
	s_waitcnt lgkmcnt(7)
	v_mfma_f32_16x16x32_bf16 v[60:63], v[150:153], v[166:169], v[60:63]
	v_mfma_f32_16x16x32_bf16 v[56:59], v[158:161], v[166:169], v[56:59]
	s_waitcnt lgkmcnt(5)
	v_mfma_f32_16x16x32_bf16 v[52:55], v[150:153], v[174:177], v[52:55]
	v_mfma_f32_16x16x32_bf16 v[48:51], v[158:161], v[174:177], v[48:51]
	s_waitcnt lgkmcnt(3)
	v_mfma_f32_16x16x32_bf16 v[36:39], v[150:153], v[182:185], v[36:39]
	v_mfma_f32_16x16x32_bf16 v[32:35], v[158:161], v[182:185], v[32:35]
	s_waitcnt lgkmcnt(1)
	v_mfma_f32_16x16x32_bf16 v[20:23], v[150:153], v[190:193], v[20:23]
	v_mfma_f32_16x16x32_bf16 v[16:19], v[158:161], v[190:193], v[16:19]
	v_mfma_f32_16x16x32_bf16 v[60:63], v[154:157], v[170:173], v[60:63]
	v_mfma_f32_16x16x32_bf16 v[56:59], v[162:165], v[170:173], v[56:59]
	v_mfma_f32_16x16x32_bf16 v[52:55], v[154:157], v[178:181], v[52:55]
	v_mfma_f32_16x16x32_bf16 v[48:51], v[162:165], v[178:181], v[48:51]
	v_mfma_f32_16x16x32_bf16 v[36:39], v[154:157], v[186:189], v[36:39]
	v_mfma_f32_16x16x32_bf16 v[32:35], v[162:165], v[186:189], v[32:35]
	s_waitcnt lgkmcnt(0)
	v_mfma_f32_16x16x32_bf16 v[20:23], v[154:157], v[198:201], v[20:23]
	v_mfma_f32_16x16x32_bf16 v[16:19], v[162:165], v[198:201], v[16:19]
	s_setprio 0
	s_barrier
	s_add_u32 s22, s22, 0x80080
	s_addc_u32 s23, s23, 0
	s_add_i32 s24, s24, s29
	v_lshl_add_u64 v[150:151], s[22:23], 0, v[132:133]
	s_mov_b32 m0, s24
	s_nop 0
	global_load_lds_dwordx4 v[150:151], off
	v_lshl_add_u64 v[150:151], s[22:23], 0, v[128:129]
	s_add_i32 m0, s24, 0x2000
	s_nop 0
	global_load_lds_dwordx4 v[150:151], off
	s_waitcnt vmcnt(6)
	s_barrier
	s_setprio 1
	v_mfma_f32_16x16x32_bf16 v[44:47], v[202:205], v[166:169], v[44:47]
	v_mfma_f32_16x16x32_bf16 v[40:43], v[210:213], v[166:169], v[40:43]
	v_mfma_f32_16x16x32_bf16 v[28:31], v[202:205], v[174:177], v[28:31]
	v_mfma_f32_16x16x32_bf16 v[24:27], v[210:213], v[174:177], v[24:27]
	v_mfma_f32_16x16x32_bf16 v[12:15], v[202:205], v[182:185], v[12:15]
	v_mfma_f32_16x16x32_bf16 v[8:11], v[210:213], v[182:185], v[8:11]
	v_mfma_f32_16x16x32_bf16 v[4:7], v[202:205], v[190:193], v[4:7]
	v_mfma_f32_16x16x32_bf16 v[0:3], v[210:213], v[190:193], v[0:3]
	v_mfma_f32_16x16x32_bf16 v[44:47], v[206:209], v[170:173], v[44:47]
	v_mfma_f32_16x16x32_bf16 v[40:43], v[214:217], v[170:173], v[40:43]
	v_mfma_f32_16x16x32_bf16 v[28:31], v[206:209], v[178:181], v[28:31]
	v_mfma_f32_16x16x32_bf16 v[24:27], v[214:217], v[178:181], v[24:27]
	v_mfma_f32_16x16x32_bf16 v[12:15], v[206:209], v[186:189], v[12:15]
	v_mfma_f32_16x16x32_bf16 v[8:11], v[214:217], v[186:189], v[8:11]
	v_mfma_f32_16x16x32_bf16 v[4:7], v[206:209], v[198:201], v[4:7]
	v_mfma_f32_16x16x32_bf16 v[0:3], v[214:217], v[198:201], v[0:3]
	s_setprio 0
	s_add_i32 s3, s3, 2
	s_add_u32 s52, s52, 0x100
	s_addc_u32 s53, s53, 0
	s_add_u32 s20, s20, 0x100
	s_addc_u32 s21, s21, 0
	s_cmp_gt_u32 s3, 29
	s_barrier
	s_cbranch_scc0 .LBB1_1382
; DI unsigned pack2(float a, float b) { f32x2 v = {a, b}; hwbf16x2 r = __builtin_convertvector(v, hwbf16x2); return __builtin_bit_cast(unsigned, r); }
;     DI const char* a(const Unit& u) const { return (const char*)(A + (size_t)u.pm * BM * lda); }
;     DI const char* a(const Unit& u) const { return (const char*)(A + (size_t)u.pm * BM * 2048 + (u.pn >> 1) * 512); }
;     DI const char* a(const Unit& u) const { return (const char*)((u.pn < 12 ? A1 : A2) + (size_t)u.pm * BM * 512); }
; #define PG8_WAIT_V(n) asm volatile("s_waitcnt vmcnt(" #n ")" ::: "memory")
; #define PG8_BAR __builtin_amdgcn_s_barrier()
;     DI void operator()(const f32x4 (&acc)[2][2][4][2], const Unit& u, int wr, int wc, int fr, int fq) const {
;         bf16_t* O = O1; int ldc = ldc1, pn = u.pn; if (pn >= split) { O = O2; ldc = ldc2; pn -= split; }
;         const int row0 = u.pm * BM + wr * 64 + fr, col0 = pn * BM + wc * 32 + 8 * fq;
; #pragma unroll
;         for (int ai = 0; ai < 2; ++ai)
; #pragma unroll
;             for (int m = 0; m < 4; ++m) { bf16_t* rowp = O + (size_t)(row0 + ai * HALF + m * 16) * ldc + col0;
; #pragma unroll
;                 for (int bj = 0; bj < 2; ++bj) { const f32x4 v0 = acc[ai][bj][m][0], v1 = acc[ai][bj][m][1];
;                     u32x4 o; o[0] = pack2(v0[0], v0[1]); o[1] = pack2(v0[2], v0[3]); o[2] = pack2(v1[0], v1[1]); o[3] = pack2(v1[2], v1[3]);
;                     *(u32x4*)(rowp + bj * HALF) = o; } }
; template <class Map, class Epi>
; DI void gemm_phase(LAS unsigned char* lds, const Map& MP, const Epi& E, const int nM, const int nN, const int K, const int lda, const int ldb) {
;     ...
;         if (!has_next) break;
; #pragma unroll
;         for (int a = 0; a < 2; ++a)
; #pragma unroll
;             for (int b = 0; b < 2; ++b)
; #pragma unroll
;                 for (int m = 0; m < 4; ++m)
; #pragma unroll
;                     for (int n = 0; n < 2; ++n) acc[a][b][m][n] = (f32x4){0.f, 0.f, 0.f, 0.f};
;         cur = nxt; cA = nA; cB = nB; ++ui;
;     }
;     PG8_WAIT_V(0);
;     if (wr == 0) PG8_BAR;
	s_lshl_b32 s3, s10, 8
	v_mov_b32_e32 v150, v144
	v_mov_b32_e32 v151, v145
	s_add_i32 s3, s3, s37
	v_cvt_pk_bf16_f32 v68, v68, v69
	v_add_u32_e32 v154, s3, v150
	s_lshl_b32 s3, s47, 8
	s_or_b32 s3, s3, s38
	v_lshl_add_u32 v150, v151, 3, s3
	v_ashrrev_i32_e32 v151, 31, v150
	v_lshl_add_u64 v[150:151], v[150:151], 1, s[6:7]
	v_cvt_pk_bf16_f32 v69, v70, v71
	v_cvt_pk_bf16_f32 v70, v64, v65
	v_add_u32_e32 v64, 0x80, v154
	v_mad_i64_i32 v[152:153], s[20:21], v154, s46, v[150:151]
	v_cvt_pk_bf16_f32 v108, v108, v109
	v_cvt_pk_bf16_f32 v109, v110, v111
	v_cvt_pk_bf16_f32 v110, v104, v105
	v_cvt_pk_bf16_f32 v111, v106, v107
	v_add_u32_e32 v104, 16, v154
	v_mad_i64_i32 v[64:65], s[20:21], v64, s46, v[150:151]
	v_cvt_pk_bf16_f32 v44, v44, v45
	v_cvt_pk_bf16_f32 v45, v46, v47
	v_cvt_pk_bf16_f32 v46, v40, v41
	v_cvt_pk_bf16_f32 v47, v42, v43
	v_add_u32_e32 v40, 0x90, v154
	flat_store_dwordx4 v[152:153], v[108:111] offset:256
	v_cvt_pk_bf16_f32 v92, v92, v93
	v_cvt_pk_bf16_f32 v93, v94, v95
	v_mad_i64_i32 v[108:109], s[20:21], v104, s46, v[150:151]
	v_cvt_pk_bf16_f32 v94, v88, v89
	v_cvt_pk_bf16_f32 v95, v90, v91
	v_add_u32_e32 v88, 32, v154
	flat_store_dwordx4 v[64:65], v[44:47] offset:256
	v_cvt_pk_bf16_f32 v28, v28, v29
	v_cvt_pk_bf16_f32 v29, v30, v31
	v_mad_i64_i32 v[44:45], s[20:21], v40, s46, v[150:151]
	v_cvt_pk_bf16_f32 v30, v24, v25
	v_cvt_pk_bf16_f32 v31, v26, v27
	v_add_u32_e32 v24, 0xa0, v154
	flat_store_dwordx4 v[108:109], v[92:95] offset:256
	v_cvt_pk_bf16_f32 v76, v76, v77
	v_cvt_pk_bf16_f32 v77, v78, v79
	v_mad_i64_i32 v[92:93], s[20:21], v88, s46, v[150:151]
	v_cvt_pk_bf16_f32 v78, v72, v73
	v_cvt_pk_bf16_f32 v79, v74, v75
	v_add_u32_e32 v72, 48, v154
	flat_store_dwordx4 v[44:45], v[28:31] offset:256
	v_cvt_pk_bf16_f32 v12, v12, v13
	v_cvt_pk_bf16_f32 v13, v14, v15
	v_mad_i64_i32 v[28:29], s[20:21], v24, s46, v[150:151]
	v_cvt_pk_bf16_f32 v14, v8, v9
	v_cvt_pk_bf16_f32 v15, v10, v11
	v_add_u32_e32 v8, 0xb0, v154
	flat_store_dwordx4 v[92:93], v[76:79] offset:256
	flat_store_dwordx4 v[28:29], v[12:15] offset:256
	v_cvt_pk_bf16_f32 v124, v124, v125
	v_mad_i64_i32 v[76:77], s[20:21], v72, s46, v[150:151]
	v_mad_i64_i32 v[12:13], s[20:21], v8, s46, v[150:151]
	v_cvt_pk_bf16_f32 v125, v126, v127
	v_cvt_pk_bf16_f32 v126, v120, v121
	v_cvt_pk_bf16_f32 v127, v122, v123
	v_cvt_pk_bf16_f32 v104, v116, v117
	v_cvt_pk_bf16_f32 v105, v118, v119
	v_cvt_pk_bf16_f32 v106, v112, v113
	v_cvt_pk_bf16_f32 v107, v114, v115
	v_cvt_pk_bf16_f32 v88, v100, v101
	v_cvt_pk_bf16_f32 v89, v102, v103
	v_cvt_pk_bf16_f32 v90, v96, v97
	v_cvt_pk_bf16_f32 v91, v98, v99
	v_cvt_pk_bf16_f32 v72, v84, v85
	v_cvt_pk_bf16_f32 v73, v86, v87
	v_cvt_pk_bf16_f32 v74, v80, v81
	v_cvt_pk_bf16_f32 v75, v82, v83
	v_cvt_pk_bf16_f32 v71, v66, v67
	v_cvt_pk_bf16_f32 v60, v60, v61
	v_cvt_pk_bf16_f32 v61, v62, v63
	v_cvt_pk_bf16_f32 v62, v56, v57
	v_cvt_pk_bf16_f32 v63, v58, v59
	v_cvt_pk_bf16_f32 v40, v52, v53
	v_cvt_pk_bf16_f32 v41, v54, v55
	v_cvt_pk_bf16_f32 v42, v48, v49
	v_cvt_pk_bf16_f32 v43, v50, v51
	v_cvt_pk_bf16_f32 v24, v36, v37
	v_cvt_pk_bf16_f32 v25, v38, v39
	v_cvt_pk_bf16_f32 v26, v32, v33
	v_cvt_pk_bf16_f32 v27, v34, v35
	v_cvt_pk_bf16_f32 v8, v20, v21
	v_cvt_pk_bf16_f32 v9, v22, v23
	v_cvt_pk_bf16_f32 v10, v16, v17
	v_cvt_pk_bf16_f32 v11, v18, v19
	v_cvt_pk_bf16_f32 v4, v4, v5
	v_cvt_pk_bf16_f32 v5, v6, v7
	v_cvt_pk_bf16_f32 v6, v0, v1
	v_cvt_pk_bf16_f32 v7, v2, v3
	s_and_b64 vcc, exec, s[40:41]
	s_mov_b32 s47, s12
	s_mov_b32 s10, s14
	s_mov_b64 s[20:21], s[18:19]
	s_mov_b64 s[22:23], s[16:17]
	flat_store_dwordx4 v[152:153], v[124:127]
	flat_store_dwordx4 v[108:109], v[104:107]
	flat_store_dwordx4 v[92:93], v[88:91]
	flat_store_dwordx4 v[76:77], v[72:75]
	flat_store_dwordx4 v[76:77], v[68:71] offset:256
	flat_store_dwordx4 v[64:65], v[60:63]
	flat_store_dwordx4 v[44:45], v[40:43]
	flat_store_dwordx4 v[28:29], v[24:27]
	flat_store_dwordx4 v[12:13], v[8:11]
	flat_store_dwordx4 v[12:13], v[4:7] offset:256
	s_cbranch_vccz .LBB1_1379
	s_waitcnt vmcnt(0)
	s_cmpk_gt_u32 s4, 0xff
	s_cbranch_scc1 .LBB1_1386
	s_barrier

; #define PG8_STAGE(bufoff, gbase, voff) do { _Pragma("unroll") for (int _i = 0; _i < 2; ++_i) \
;         __builtin_amdgcn_global_load_lds((const unsigned*)((const char*)(gbase) + (voff)[_i]), (LAS unsigned*)(lds + (bufoff) + ldsw + _i * 8192), 16, 0, 0); } while (0)
; #define PG8_LDA(dst, b, h) do { _Pragma("unroll") for (int m = 0; m < 4; ++m) _Pragma("unroll") for (int k = 0; k < 2; ++k) dst[m][k] = *(const LAS bf16x8*)(lds + PG8_SA(b, h) + aoff + m * 2048 + k * 1024); } while (0)
; #define PG8_LDB(dst, b, h) do { _Pragma("unroll") for (int n = 0; n < 2; ++n) _Pragma("unroll") for (int k = 0; k < 2; ++k) dst[n][k] = *(const LAS bf16x8*)(lds + PG8_SB(b, h) + boff + n * 2048 + k * 1024); } while (0)
; #define PG8_MMA(ai, bj, At, Bt) do { __builtin_amdgcn_s_setprio(1); _Pragma("unroll") for (int m = 0; m < 4; ++m) _Pragma("unroll") for (int n = 0; n < 2; ++n) _Pragma("unroll") for (int k = 0; k < 2; ++k) \
;         acc[ai][bj][m][n] = __builtin_amdgcn_mfma_f32_16x16x32_bf16(Bt[n][k], At[m][k], acc[ai][bj][m][n], 0, 0, 0); __builtin_amdgcn_s_setprio(0); } while (0)
; #define PG8_WAIT_L(n) asm volatile("s_waitcnt lgkmcnt(" #n ")" ::: "memory")
; #define PG8_BAR __builtin_amdgcn_s_barrier()
; #define PG8_SCHED __builtin_amdgcn_sched_barrier(0)
; template <class Map, class Epi>
; DI void gemm_phase(LAS unsigned char* lds, const Map& MP, const Epi& E, const int nM, const int nN, const int K, const int lda, const int ldb) {
;     ...
;             const bool last = (t == nt - 2);
;             const char* a1 = cA + (size_t)(t + 1) * kstep;
;             const char* a2 = last ? nA : cA + (size_t)(t + 2) * kstep; const char* b2 = last ? nB : cB + (size_t)(t + 2) * kstep;
;             const char* a3 = a2 + kstep; const char* b3 = b2 + kstep;
;             PG8_LDB(B0, 0, 0); PG8_SCHED; PG8_LDA(At, 0, 0); PG8_STAGE(PG8_SA(1, 1), a1 + hstepA, voffA);
;             PG8_WAIT_L(8); PG8_BAR; PG8_WAIT_L(0); PG8_MMA(0, 0, At, B0); PG8_BAR; PG8_SCHED;
;             PG8_LDB(B1, 0, 1); PG8_STAGE(PG8_SB(0, 0), b2, voffB);
;             PG8_BAR; PG8_WAIT_L(0); PG8_MMA(0, 1, At, B1); PG8_BAR;
;             PG8_LDA(At, 0, 1); PG8_STAGE(PG8_SA(0, 0), a2, voffA);
;             PG8_BAR; PG8_WAIT_L(0); PG8_MMA(1, 0, At, B0); PG8_BAR; PG8_SCHED;
.LBB1_1529:
	ds_read_b128 v[150:153], v147
	ds_read_b128 v[154:157], v147 offset:1024
	ds_read_b128 v[158:161], v147 offset:2048
	ds_read_b128 v[162:165], v147 offset:3072
	s_add_u32 s20, s18, 0xfffe0080
	s_addc_u32 s21, s19, -1
	s_cmp_eq_u32 s3, 4
	s_cselect_b32 s23, s13, s21
	s_cselect_b32 s22, s52, s20
	s_cselect_b32 s21, s53, s56
	s_cselect_b32 s20, s54, s55
	v_lshl_add_u64 v[194:195], s[18:19], 0, v[138:139]
	s_add_i32 m0, s11, 0xc000
	ds_read_b128 v[166:169], v148
	ds_read_b128 v[170:173], v148 offset:1024
	ds_read_b128 v[174:177], v148 offset:2048
	ds_read_b128 v[178:181], v148 offset:3072
	ds_read_b128 v[182:185], v148 offset:4096
	ds_read_b128 v[186:189], v148 offset:5120
	ds_read_b128 v[190:193], v148 offset:6144
	ds_read_b128 v[198:201], v148 offset:7168
	global_load_lds_dwordx4 v[194:195], off
	v_lshl_add_u64 v[194:195], s[18:19], 0, v[136:137]
	s_add_i32 m0, s11, 0xe000
	s_nop 0
	global_load_lds_dwordx4 v[194:195], off
	s_waitcnt lgkmcnt(8)
	s_barrier
	s_setprio 1
	s_waitcnt lgkmcnt(7)
	v_mfma_f32_16x16x32_bf16 v[124:127], v[150:153], v[166:169], v[124:127]
	v_mfma_f32_16x16x32_bf16 v[120:123], v[158:161], v[166:169], v[120:123]
	s_waitcnt lgkmcnt(5)
	v_mfma_f32_16x16x32_bf16 v[116:119], v[150:153], v[174:177], v[116:119]
	v_mfma_f32_16x16x32_bf16 v[112:115], v[158:161], v[174:177], v[112:115]
	s_waitcnt lgkmcnt(3)
	v_mfma_f32_16x16x32_bf16 v[100:103], v[150:153], v[182:185], v[100:103]
	v_mfma_f32_16x16x32_bf16 v[96:99], v[158:161], v[182:185], v[96:99]
	s_waitcnt lgkmcnt(1)
	v_mfma_f32_16x16x32_bf16 v[84:87], v[150:153], v[190:193], v[84:87]
	v_mfma_f32_16x16x32_bf16 v[80:83], v[158:161], v[190:193], v[80:83]
	v_mfma_f32_16x16x32_bf16 v[124:127], v[154:157], v[170:173], v[124:127]
	v_mfma_f32_16x16x32_bf16 v[120:123], v[162:165], v[170:173], v[120:123]
	v_mfma_f32_16x16x32_bf16 v[116:119], v[154:157], v[178:181], v[116:119]
	v_mfma_f32_16x16x32_bf16 v[112:115], v[162:165], v[178:181], v[112:115]
	v_mfma_f32_16x16x32_bf16 v[100:103], v[154:157], v[186:189], v[100:103]
	v_mfma_f32_16x16x32_bf16 v[96:99], v[162:165], v[186:189], v[96:99]
	s_waitcnt lgkmcnt(0)
	v_mfma_f32_16x16x32_bf16 v[84:87], v[154:157], v[198:201], v[84:87]
	v_mfma_f32_16x16x32_bf16 v[80:83], v[162:165], v[198:201], v[80:83]
	s_setprio 0
	s_barrier
	s_add_i32 s57, s47, s31
	v_lshl_add_u64 v[194:195], s[20:21], 0, v[132:133]
	s_mov_b32 m0, s57
	ds_read_b128 v[202:205], v149
	ds_read_b128 v[206:209], v149 offset:1024
	ds_read_b128 v[210:213], v149 offset:2048
	ds_read_b128 v[214:217], v149 offset:3072
	global_load_lds_dwordx4 v[194:195], off
	v_lshl_add_u64 v[218:219], s[20:21], 0, v[128:129]
	s_add_i32 m0, s57, 0x2000
	s_nop 0
	global_load_lds_dwordx4 v[218:219], off
	s_barrier
	s_setprio 1
	s_waitcnt lgkmcnt(3)
	v_mfma_f32_16x16x32_bf16 v[108:111], v[202:205], v[166:169], v[108:111]
	s_waitcnt lgkmcnt(1)
	v_mfma_f32_16x16x32_bf16 v[104:107], v[210:213], v[166:169], v[104:107]
	v_mfma_f32_16x16x32_bf16 v[92:95], v[202:205], v[174:177], v[92:95]
	v_mfma_f32_16x16x32_bf16 v[88:91], v[210:213], v[174:177], v[88:91]
	v_mfma_f32_16x16x32_bf16 v[76:79], v[202:205], v[182:185], v[76:79]
	v_mfma_f32_16x16x32_bf16 v[72:75], v[210:213], v[182:185], v[72:75]
	v_mfma_f32_16x16x32_bf16 v[68:71], v[202:205], v[190:193], v[68:71]
	v_mfma_f32_16x16x32_bf16 v[64:67], v[210:213], v[190:193], v[64:67]
	v_mfma_f32_16x16x32_bf16 v[108:111], v[206:209], v[170:173], v[108:111]
	s_waitcnt lgkmcnt(0)
	v_mfma_f32_16x16x32_bf16 v[104:107], v[214:217], v[170:173], v[104:107]
	v_mfma_f32_16x16x32_bf16 v[92:95], v[206:209], v[178:181], v[92:95]
	v_mfma_f32_16x16x32_bf16 v[88:91], v[214:217], v[178:181], v[88:91]
	v_mfma_f32_16x16x32_bf16 v[76:79], v[206:209], v[186:189], v[76:79]
	v_mfma_f32_16x16x32_bf16 v[72:75], v[214:217], v[186:189], v[72:75]
	v_mfma_f32_16x16x32_bf16 v[68:71], v[206:209], v[198:201], v[68:71]
	v_mfma_f32_16x16x32_bf16 v[64:67], v[214:217], v[198:201], v[64:67]
	s_setprio 0
	s_mov_b32 m0, s11
	v_lshl_add_u64 v[220:221], s[22:23], 0, v[134:135]
	s_barrier
	ds_read_b128 v[166:169], v148 offset:16384
	ds_read_b128 v[170:173], v148 offset:17408
	ds_read_b128 v[174:177], v148 offset:18432
	ds_read_b128 v[178:181], v148 offset:19456
	ds_read_b128 v[182:185], v148 offset:20480
	ds_read_b128 v[186:189], v148 offset:21504
	ds_read_b128 v[190:193], v148 offset:22528
	ds_read_b128 v[198:201], v148 offset:23552
	global_load_lds_dwordx4 v[220:221], off
	v_lshl_add_u64 v[222:223], s[22:23], 0, v[130:131]
	s_mov_b32 m0, s35
	s_nop 0
	global_load_lds_dwordx4 v[222:223], off
	s_barrier
	s_setprio 1
	s_waitcnt lgkmcnt(7)
	v_mfma_f32_16x16x32_bf16 v[60:63], v[150:153], v[166:169], v[60:63]
	v_mfma_f32_16x16x32_bf16 v[56:59], v[158:161], v[166:169], v[56:59]
	s_waitcnt lgkmcnt(5)
	v_mfma_f32_16x16x32_bf16 v[52:55], v[150:153], v[174:177], v[52:55]
	v_mfma_f32_16x16x32_bf16 v[48:51], v[158:161], v[174:177], v[48:51]
	s_waitcnt lgkmcnt(3)
	v_mfma_f32_16x16x32_bf16 v[36:39], v[150:153], v[182:185], v[36:39]
	v_mfma_f32_16x16x32_bf16 v[32:35], v[158:161], v[182:185], v[32:35]
	s_waitcnt lgkmcnt(1)
	v_mfma_f32_16x16x32_bf16 v[20:23], v[150:153], v[190:193], v[20:23]
	v_mfma_f32_16x16x32_bf16 v[16:19], v[158:161], v[190:193], v[16:19]
	v_mfma_f32_16x16x32_bf16 v[60:63], v[154:157], v[170:173], v[60:63]
	v_mfma_f32_16x16x32_bf16 v[56:59], v[162:165], v[170:173], v[56:59]
	v_mfma_f32_16x16x32_bf16 v[52:55], v[154:157], v[178:181], v[52:55]
	v_mfma_f32_16x16x32_bf16 v[48:51], v[162:165], v[178:181], v[48:51]
	v_mfma_f32_16x16x32_bf16 v[36:39], v[154:157], v[186:189], v[36:39]
	v_mfma_f32_16x16x32_bf16 v[32:35], v[162:165], v[186:189], v[32:35]
	s_waitcnt lgkmcnt(0)
	v_mfma_f32_16x16x32_bf16 v[20:23], v[154:157], v[198:201], v[20:23]
	v_mfma_f32_16x16x32_bf16 v[16:19], v[162:165], v[198:201], v[16:19]
	s_setprio 0
	s_barrier
; #define PG8_STAGE(bufoff, gbase, voff) do { _Pragma("unroll") for (int _i = 0; _i < 2; ++_i) \
;         __builtin_amdgcn_global_load_lds((const unsigned*)((const char*)(gbase) + (voff)[_i]), (LAS unsigned*)(lds + (bufoff) + ldsw + _i * 8192), 16, 0, 0); } while (0)
; #define PG8_LDA(dst, b, h) do { _Pragma("unroll") for (int m = 0; m < 4; ++m) _Pragma("unroll") for (int k = 0; k < 2; ++k) dst[m][k] = *(const LAS bf16x8*)(lds + PG8_SA(b, h) + aoff + m * 2048 + k * 1024); } while (0)
; #define PG8_LDB(dst, b, h) do { _Pragma("unroll") for (int n = 0; n < 2; ++n) _Pragma("unroll") for (int k = 0; k < 2; ++k) dst[n][k] = *(const LAS bf16x8*)(lds + PG8_SB(b, h) + boff + n * 2048 + k * 1024); } while (0)
; #define PG8_MMA(ai, bj, At, Bt) do { __builtin_amdgcn_s_setprio(1); _Pragma("unroll") for (int m = 0; m < 4; ++m) _Pragma("unroll") for (int n = 0; n < 2; ++n) _Pragma("unroll") for (int k = 0; k < 2; ++k) \
;         acc[ai][bj][m][n] = __builtin_amdgcn_mfma_f32_16x16x32_bf16(Bt[n][k], At[m][k], acc[ai][bj][m][n], 0, 0, 0); __builtin_amdgcn_s_setprio(0); } while (0)
; #define PG8_WAIT_V(n) asm volatile("s_waitcnt vmcnt(" #n ")" ::: "memory")
; #define PG8_WAIT_L(n) asm volatile("s_waitcnt lgkmcnt(" #n ")" ::: "memory")
; #define PG8_BAR __builtin_amdgcn_s_barrier()
; #define PG8_SCHED __builtin_amdgcn_sched_barrier(0)
; template <class Map, class Epi>
; DI void gemm_phase(LAS unsigned char* lds, const Map& MP, const Epi& E, const int nM, const int nN, const int K, const int lda, const int ldb) {
;     ...
;             PG8_STAGE(PG8_SB(0, 1), b2 + hstepB, voffB);
;             PG8_WAIT_V(6); PG8_BAR; PG8_MMA(1, 1, At, B1); PG8_BAR;
;             PG8_LDB(B0, 1, 0); PG8_SCHED; PG8_LDA(At, 1, 0); PG8_STAGE(PG8_SA(0, 1), a2 + hstepA, voffA);
;             PG8_WAIT_L(8); PG8_BAR; PG8_WAIT_L(0); PG8_MMA(0, 0, At, B0); PG8_BAR; PG8_SCHED;
;             PG8_LDB(B1, 1, 1); PG8_STAGE(PG8_SB(1, 0), b3, voffB);
;             PG8_BAR; PG8_WAIT_L(0); PG8_MMA(0, 1, At, B1); PG8_BAR;
	s_add_u32 s58, s20, 0x20000
	s_addc_u32 s59, s21, 0
	s_add_i32 s57, s48, s31
	v_lshl_add_u64 v[150:151], s[58:59], 0, v[132:133]
	s_mov_b32 m0, s57
	s_nop 0
	global_load_lds_dwordx4 v[150:151], off
	v_lshl_add_u64 v[150:151], s[58:59], 0, v[128:129]
	s_add_i32 m0, s57, 0x2000
	s_nop 0
	global_load_lds_dwordx4 v[150:151], off
	s_waitcnt vmcnt(6)
	s_barrier
	s_setprio 1
	v_mfma_f32_16x16x32_bf16 v[44:47], v[202:205], v[166:169], v[44:47]
	v_mfma_f32_16x16x32_bf16 v[40:43], v[210:213], v[166:169], v[40:43]
	v_mfma_f32_16x16x32_bf16 v[28:31], v[202:205], v[174:177], v[28:31]
	v_mfma_f32_16x16x32_bf16 v[24:27], v[210:213], v[174:177], v[24:27]
	v_mfma_f32_16x16x32_bf16 v[12:15], v[202:205], v[182:185], v[12:15]
	v_mfma_f32_16x16x32_bf16 v[8:11], v[210:213], v[182:185], v[8:11]
	v_mfma_f32_16x16x32_bf16 v[4:7], v[202:205], v[190:193], v[4:7]
	v_mfma_f32_16x16x32_bf16 v[0:3], v[210:213], v[190:193], v[0:3]
	v_mfma_f32_16x16x32_bf16 v[44:47], v[206:209], v[170:173], v[44:47]
	v_mfma_f32_16x16x32_bf16 v[40:43], v[214:217], v[170:173], v[40:43]
	v_mfma_f32_16x16x32_bf16 v[28:31], v[206:209], v[178:181], v[28:31]
	v_mfma_f32_16x16x32_bf16 v[24:27], v[214:217], v[178:181], v[24:27]
	v_mfma_f32_16x16x32_bf16 v[12:15], v[206:209], v[186:189], v[12:15]
	v_mfma_f32_16x16x32_bf16 v[8:11], v[214:217], v[186:189], v[8:11]
	v_mfma_f32_16x16x32_bf16 v[4:7], v[206:209], v[198:201], v[4:7]
	v_mfma_f32_16x16x32_bf16 v[0:3], v[214:217], v[198:201], v[0:3]
	s_setprio 0
	s_add_i32 s57, 0, 0x18000
	v_add_u32_e32 v162, s57, v146
	s_barrier
	ds_read_b128 v[150:153], v162
	ds_read_b128 v[154:157], v162 offset:1024
	ds_read_b128 v[158:161], v162 offset:2048
	ds_read_b128 v[162:165], v162 offset:3072
	s_add_u32 s22, s22, 0x20000
	s_addc_u32 s23, s23, 0
	s_mov_b32 m0, s36
	v_lshl_add_u64 v[202:203], s[22:23], 0, v[134:135]
	ds_read_b128 v[166:169], v148 offset:32768
	ds_read_b128 v[170:173], v148 offset:33792
	ds_read_b128 v[174:177], v148 offset:34816
	ds_read_b128 v[178:181], v148 offset:35840
	ds_read_b128 v[182:185], v148 offset:36864
	ds_read_b128 v[186:189], v148 offset:37888
	ds_read_b128 v[190:193], v148 offset:38912
	ds_read_b128 v[198:201], v148 offset:39936
	global_load_lds_dwordx4 v[202:203], off
	v_lshl_add_u64 v[202:203], s[22:23], 0, v[130:131]
	s_mov_b32 m0, s37
	s_nop 0
	global_load_lds_dwordx4 v[202:203], off
	s_waitcnt lgkmcnt(8)
	s_barrier
	s_setprio 1
	s_waitcnt lgkmcnt(7)
	v_mfma_f32_16x16x32_bf16 v[124:127], v[150:153], v[166:169], v[124:127]
	v_mfma_f32_16x16x32_bf16 v[120:123], v[158:161], v[166:169], v[120:123]
	s_waitcnt lgkmcnt(5)
	v_mfma_f32_16x16x32_bf16 v[116:119], v[150:153], v[174:177], v[116:119]
	v_mfma_f32_16x16x32_bf16 v[112:115], v[158:161], v[174:177], v[112:115]
	s_waitcnt lgkmcnt(3)
	v_mfma_f32_16x16x32_bf16 v[100:103], v[150:153], v[182:185], v[100:103]
	v_mfma_f32_16x16x32_bf16 v[96:99], v[158:161], v[182:185], v[96:99]
	s_waitcnt lgkmcnt(1)
	v_mfma_f32_16x16x32_bf16 v[84:87], v[150:153], v[190:193], v[84:87]
	v_mfma_f32_16x16x32_bf16 v[80:83], v[158:161], v[190:193], v[80:83]
	v_mfma_f32_16x16x32_bf16 v[124:127], v[154:157], v[170:173], v[124:127]
	v_mfma_f32_16x16x32_bf16 v[120:123], v[162:165], v[170:173], v[120:123]
	v_mfma_f32_16x16x32_bf16 v[116:119], v[154:157], v[178:181], v[116:119]
	v_mfma_f32_16x16x32_bf16 v[112:115], v[162:165], v[178:181], v[112:115]
	v_mfma_f32_16x16x32_bf16 v[100:103], v[154:157], v[186:189], v[100:103]
	v_mfma_f32_16x16x32_bf16 v[96:99], v[162:165], v[186:189], v[96:99]
	s_waitcnt lgkmcnt(0)
	v_mfma_f32_16x16x32_bf16 v[84:87], v[154:157], v[198:201], v[84:87]
	v_mfma_f32_16x16x32_bf16 v[80:83], v[162:165], v[198:201], v[80:83]
	s_setprio 0
	s_barrier
	s_add_i32 s22, 0, 0x1c000
	s_add_i32 s23, s57, s31
	v_add_u32_e32 v196, s22, v146
	v_lshl_add_u64 v[194:195], v[194:195], 0, s[8:9]
	s_mov_b32 m0, s23
	ds_read_b128 v[202:205], v196
	ds_read_b128 v[206:209], v196 offset:1024
	ds_read_b128 v[210:213], v196 offset:2048
	ds_read_b128 v[214:217], v196 offset:3072
	global_load_lds_dwordx4 v[194:195], off
	v_lshl_add_u64 v[194:195], v[218:219], 0, s[8:9]
	s_add_i32 m0, s23, 0x2000
	s_nop 0
	global_load_lds_dwordx4 v[194:195], off
	s_barrier
	s_setprio 1
	s_waitcnt lgkmcnt(3)
	v_mfma_f32_16x16x32_bf16 v[108:111], v[202:205], v[166:169], v[108:111]
	s_waitcnt lgkmcnt(1)
	v_mfma_f32_16x16x32_bf16 v[104:107], v[210:213], v[166:169], v[104:107]
	v_mfma_f32_16x16x32_bf16 v[92:95], v[202:205], v[174:177], v[92:95]
	v_mfma_f32_16x16x32_bf16 v[88:91], v[210:213], v[174:177], v[88:91]
	v_mfma_f32_16x16x32_bf16 v[76:79], v[202:205], v[182:185], v[76:79]
	v_mfma_f32_16x16x32_bf16 v[72:75], v[210:213], v[182:185], v[72:75]
	v_mfma_f32_16x16x32_bf16 v[68:71], v[202:205], v[190:193], v[68:71]
	v_mfma_f32_16x16x32_bf16 v[64:67], v[210:213], v[190:193], v[64:67]
	v_mfma_f32_16x16x32_bf16 v[108:111], v[206:209], v[170:173], v[108:111]
	s_waitcnt lgkmcnt(0)
	v_mfma_f32_16x16x32_bf16 v[104:107], v[214:217], v[170:173], v[104:107]
	v_mfma_f32_16x16x32_bf16 v[92:95], v[206:209], v[178:181], v[92:95]
	v_mfma_f32_16x16x32_bf16 v[88:91], v[214:217], v[178:181], v[88:91]
	v_mfma_f32_16x16x32_bf16 v[76:79], v[206:209], v[186:189], v[76:79]
	v_mfma_f32_16x16x32_bf16 v[72:75], v[214:217], v[186:189], v[72:75]
	v_mfma_f32_16x16x32_bf16 v[68:71], v[206:209], v[198:201], v[68:71]
	v_mfma_f32_16x16x32_bf16 v[64:67], v[214:217], v[198:201], v[64:67]
	s_setprio 0
	s_mov_b32 m0, s43
	v_lshl_add_u64 v[194:195], v[220:221], 0, s[8:9]
	s_barrier
; #define PG8_STAGE(bufoff, gbase, voff) do { _Pragma("unroll") for (int _i = 0; _i < 2; ++_i) \
;         __builtin_amdgcn_global_load_lds((const unsigned*)((const char*)(gbase) + (voff)[_i]), (LAS unsigned*)(lds + (bufoff) + ldsw + _i * 8192), 16, 0, 0); } while (0)
; #define PG8_LDA(dst, b, h) do { _Pragma("unroll") for (int m = 0; m < 4; ++m) _Pragma("unroll") for (int k = 0; k < 2; ++k) dst[m][k] = *(const LAS bf16x8*)(lds + PG8_SA(b, h) + aoff + m * 2048 + k * 1024); } while (0)
; #define PG8_MMA(ai, bj, At, Bt) do { __builtin_amdgcn_s_setprio(1); _Pragma("unroll") for (int m = 0; m < 4; ++m) _Pragma("unroll") for (int n = 0; n < 2; ++n) _Pragma("unroll") for (int k = 0; k < 2; ++k) \
;         acc[ai][bj][m][n] = __builtin_amdgcn_mfma_f32_16x16x32_bf16(Bt[n][k], At[m][k], acc[ai][bj][m][n], 0, 0, 0); __builtin_amdgcn_s_setprio(0); } while (0)
; #define PG8_WAIT_V(n) asm volatile("s_waitcnt vmcnt(" #n ")" ::: "memory")
; #define PG8_WAIT_L(n) asm volatile("s_waitcnt lgkmcnt(" #n ")" ::: "memory")
; #define PG8_BAR __builtin_amdgcn_s_barrier()
; #define PG8_SCHED __builtin_amdgcn_sched_barrier(0)
; template <class Map, class Epi>
; DI void gemm_phase(LAS unsigned char* lds, const Map& MP, const Epi& E, const int nM, const int nN, const int K, const int lda, const int ldb) {
;     ...
;             PG8_LDA(At, 1, 1); PG8_STAGE(PG8_SA(1, 0), a3, voffA);
;             PG8_BAR; PG8_WAIT_L(0); PG8_MMA(1, 0, At, B0); PG8_BAR; PG8_SCHED;
;             PG8_STAGE(PG8_SB(1, 1), b3 + hstepB, voffB);
;             PG8_WAIT_V(6); PG8_BAR; PG8_MMA(1, 1, At, B1); PG8_BAR;
	ds_read_b128 v[166:169], v148 offset:49152
	ds_read_b128 v[170:173], v148 offset:50176
	ds_read_b128 v[174:177], v148 offset:51200
	ds_read_b128 v[178:181], v148 offset:52224
	ds_read_b128 v[182:185], v148 offset:53248
	ds_read_b128 v[186:189], v148 offset:54272
	ds_read_b128 v[190:193], v148 offset:55296
	ds_read_b128 v[198:201], v148 offset:56320
	global_load_lds_dwordx4 v[194:195], off
	v_lshl_add_u64 v[194:195], v[222:223], 0, s[8:9]
	s_mov_b32 m0, s44
	s_nop 0
	global_load_lds_dwordx4 v[194:195], off
	s_barrier
	s_setprio 1
	s_waitcnt lgkmcnt(7)
	v_mfma_f32_16x16x32_bf16 v[60:63], v[150:153], v[166:169], v[60:63]
	v_mfma_f32_16x16x32_bf16 v[56:59], v[158:161], v[166:169], v[56:59]
	s_waitcnt lgkmcnt(5)
	v_mfma_f32_16x16x32_bf16 v[52:55], v[150:153], v[174:177], v[52:55]
	v_mfma_f32_16x16x32_bf16 v[48:51], v[158:161], v[174:177], v[48:51]
	s_waitcnt lgkmcnt(3)
	v_mfma_f32_16x16x32_bf16 v[36:39], v[150:153], v[182:185], v[36:39]
	v_mfma_f32_16x16x32_bf16 v[32:35], v[158:161], v[182:185], v[32:35]
	s_waitcnt lgkmcnt(1)
	v_mfma_f32_16x16x32_bf16 v[20:23], v[150:153], v[190:193], v[20:23]
	v_mfma_f32_16x16x32_bf16 v[16:19], v[158:161], v[190:193], v[16:19]
	v_mfma_f32_16x16x32_bf16 v[60:63], v[154:157], v[170:173], v[60:63]
	v_mfma_f32_16x16x32_bf16 v[56:59], v[162:165], v[170:173], v[56:59]
	v_mfma_f32_16x16x32_bf16 v[52:55], v[154:157], v[178:181], v[52:55]
	v_mfma_f32_16x16x32_bf16 v[48:51], v[162:165], v[178:181], v[48:51]
	v_mfma_f32_16x16x32_bf16 v[36:39], v[154:157], v[186:189], v[36:39]
	v_mfma_f32_16x16x32_bf16 v[32:35], v[162:165], v[186:189], v[32:35]
	s_waitcnt lgkmcnt(0)
	v_mfma_f32_16x16x32_bf16 v[20:23], v[154:157], v[198:201], v[20:23]
	v_mfma_f32_16x16x32_bf16 v[16:19], v[162:165], v[198:201], v[16:19]
	s_setprio 0
	s_barrier
	s_add_u32 s20, s20, 0x20080
	s_addc_u32 s21, s21, 0
	s_add_i32 s22, s22, s31
	v_lshl_add_u64 v[150:151], s[20:21], 0, v[132:133]
	s_mov_b32 m0, s22
	s_nop 0
	global_load_lds_dwordx4 v[150:151], off
	v_lshl_add_u64 v[150:151], s[20:21], 0, v[128:129]
	s_add_i32 m0, s22, 0x2000
	s_nop 0
	global_load_lds_dwordx4 v[150:151], off
	s_waitcnt vmcnt(6)
	s_barrier
	s_setprio 1
	v_mfma_f32_16x16x32_bf16 v[44:47], v[202:205], v[166:169], v[44:47]
	v_mfma_f32_16x16x32_bf16 v[40:43], v[210:213], v[166:169], v[40:43]
	v_mfma_f32_16x16x32_bf16 v[28:31], v[202:205], v[174:177], v[28:31]
	v_mfma_f32_16x16x32_bf16 v[24:27], v[210:213], v[174:177], v[24:27]
	v_mfma_f32_16x16x32_bf16 v[12:15], v[202:205], v[182:185], v[12:15]
	v_mfma_f32_16x16x32_bf16 v[8:11], v[210:213], v[182:185], v[8:11]
	v_mfma_f32_16x16x32_bf16 v[4:7], v[202:205], v[190:193], v[4:7]
	v_mfma_f32_16x16x32_bf16 v[0:3], v[210:213], v[190:193], v[0:3]
	v_mfma_f32_16x16x32_bf16 v[44:47], v[206:209], v[170:173], v[44:47]
	v_mfma_f32_16x16x32_bf16 v[40:43], v[214:217], v[170:173], v[40:43]
	v_mfma_f32_16x16x32_bf16 v[28:31], v[206:209], v[178:181], v[28:31]
	v_mfma_f32_16x16x32_bf16 v[24:27], v[214:217], v[178:181], v[24:27]
	v_mfma_f32_16x16x32_bf16 v[12:15], v[206:209], v[186:189], v[12:15]
	v_mfma_f32_16x16x32_bf16 v[8:11], v[214:217], v[186:189], v[8:11]
	v_mfma_f32_16x16x32_bf16 v[4:7], v[206:209], v[198:201], v[4:7]
	v_mfma_f32_16x16x32_bf16 v[0:3], v[214:217], v[198:201], v[0:3]
	s_setprio 0
	s_add_i32 s3, s3, 2
	s_add_u32 s55, s55, 0x100
	s_addc_u32 s56, s56, 0
	s_add_u32 s18, s18, 0x100
	s_addc_u32 s19, s19, 0
	s_cmp_gt_u32 s3, 5
	s_barrier
	s_cbranch_scc0 .LBB1_1529
; DI unsigned pack2(float a, float b) { f32x2 v = {a, b}; hwbf16x2 r = __builtin_convertvector(v, hwbf16x2); return __builtin_bit_cast(unsigned, r); }
;     DI void operator()(const f32x4 (&acc)[2][2][4][2], const Unit& u, int wr, int wc, int fr, int fq) const {
;         bf16_t* O = O1; int ldc = ldc1, pn = u.pn; if (pn >= split) { O = O2; ldc = ldc2; pn -= split; }
;         const int row0 = u.pm * BM + wr * 64 + fr, col0 = pn * BM + wc * 32 + 8 * fq;
; #pragma unroll
;         for (int ai = 0; ai < 2; ++ai)
; #pragma unroll
;             for (int m = 0; m < 4; ++m) { bf16_t* rowp = O + (size_t)(row0 + ai * HALF + m * 16) * ldc + col0;
; #pragma unroll
;                 for (int bj = 0; bj < 2; ++bj) { const f32x4 v0 = acc[ai][bj][m][0], v1 = acc[ai][bj][m][1];
;                     u32x4 o; o[0] = pack2(v0[0], v0[1]); o[1] = pack2(v0[2], v0[3]); o[2] = pack2(v1[0], v1[1]); o[3] = pack2(v1[2], v1[3]);
;                     *(u32x4*)(rowp + bj * HALF) = o; } }
	s_cmp_lt_i32 s45, 12
	s_cselect_b32 s3, 0, -12
	s_mov_b32 s13, 0x1e510000
	s_movk_i32 s18, 0xc00
	s_cselect_b32 s13, s13, 0x2a510000
	s_cselect_b32 s20, s18, 0x1000
	s_add_i32 s3, s3, s45
	s_add_u32 s18, s6, s13
	v_mov_b32_e32 v150, v144
	v_mov_b32_e32 v151, v145
	s_addc_u32 s19, s7, 0
	s_lshl_b32 s10, s10, 8
	s_lshl_b32 s3, s3, 8
	s_add_i32 s10, s10, s39
	s_or_b32 s3, s3, s42
	v_add_u32_e32 v154, s10, v150
	v_lshl_add_u32 v150, v151, 3, s3
	v_ashrrev_i32_e32 v151, 31, v150
	v_lshl_add_u64 v[150:151], v[150:151], 1, s[18:19]
	v_mad_i64_i32 v[152:153], s[18:19], s20, v154, 0
	v_cvt_pk_bf16_f32 v108, v108, v109
	v_cvt_pk_bf16_f32 v109, v110, v111
	v_cvt_pk_bf16_f32 v110, v104, v105
	v_add_u32_e32 v104, 16, v154
	v_lshl_add_u64 v[152:153], v[152:153], 1, v[150:151]
	v_cvt_pk_bf16_f32 v111, v106, v107
	v_mad_i64_i32 v[104:105], s[18:19], s20, v104, 0
	v_cvt_pk_bf16_f32 v92, v92, v93
	v_cvt_pk_bf16_f32 v93, v94, v95
	v_cvt_pk_bf16_f32 v94, v88, v89
	v_add_u32_e32 v88, 32, v154
	v_cvt_pk_bf16_f32 v124, v124, v125
	v_cvt_pk_bf16_f32 v125, v126, v127
	v_cvt_pk_bf16_f32 v126, v120, v121
	v_cvt_pk_bf16_f32 v127, v122, v123
	flat_store_dwordx4 v[152:153], v[108:111] offset:256
	v_cvt_pk_bf16_f32 v95, v90, v91
	v_mad_i64_i32 v[88:89], s[18:19], s20, v88, 0
	v_lshl_add_u64 v[108:109], v[104:105], 1, v[150:151]
	v_cvt_pk_bf16_f32 v76, v76, v77
	v_cvt_pk_bf16_f32 v77, v78, v79
	v_cvt_pk_bf16_f32 v78, v72, v73
	v_add_u32_e32 v72, 48, v154
	v_cvt_pk_bf16_f32 v68, v68, v69
	v_cvt_pk_bf16_f32 v69, v70, v71
	v_cvt_pk_bf16_f32 v70, v64, v65
	v_add_u32_e32 v64, 0x80, v154
	flat_store_dwordx4 v[152:153], v[124:127]
	v_cvt_pk_bf16_f32 v104, v116, v117
	v_cvt_pk_bf16_f32 v105, v118, v119
	v_cvt_pk_bf16_f32 v106, v112, v113
	v_cvt_pk_bf16_f32 v107, v114, v115
	flat_store_dwordx4 v[108:109], v[92:95] offset:256
	v_cvt_pk_bf16_f32 v79, v74, v75
	v_mad_i64_i32 v[72:73], s[18:19], s20, v72, 0
	v_lshl_add_u64 v[92:93], v[88:89], 1, v[150:151]
	v_mad_i64_i32 v[64:65], s[18:19], s20, v64, 0
	v_cvt_pk_bf16_f32 v44, v44, v45
	v_cvt_pk_bf16_f32 v45, v46, v47
	v_cvt_pk_bf16_f32 v46, v40, v41
	v_add_u32_e32 v40, 0x90, v154
	flat_store_dwordx4 v[108:109], v[104:107]
	v_cvt_pk_bf16_f32 v88, v100, v101
	v_cvt_pk_bf16_f32 v89, v102, v103
	v_cvt_pk_bf16_f32 v90, v96, v97
	v_cvt_pk_bf16_f32 v91, v98, v99
	flat_store_dwordx4 v[92:93], v[76:79] offset:256
	v_cvt_pk_bf16_f32 v74, v80, v81
	v_cvt_pk_bf16_f32 v75, v82, v83
	v_lshl_add_u64 v[76:77], v[72:73], 1, v[150:151]
	v_cvt_pk_bf16_f32 v72, v84, v85
	v_cvt_pk_bf16_f32 v73, v86, v87
	v_cvt_pk_bf16_f32 v71, v66, v67
	v_lshl_add_u64 v[64:65], v[64:65], 1, v[150:151]
	v_cvt_pk_bf16_f32 v47, v42, v43
	v_mad_i64_i32 v[40:41], s[18:19], s20, v40, 0
	v_cvt_pk_bf16_f32 v28, v28, v29
	v_cvt_pk_bf16_f32 v29, v30, v31
	v_cvt_pk_bf16_f32 v30, v24, v25
	v_add_u32_e32 v24, 0xa0, v154
	flat_store_dwordx4 v[92:93], v[88:91]
	flat_store_dwordx4 v[76:77], v[72:75]
	flat_store_dwordx4 v[76:77], v[68:71] offset:256
	v_cvt_pk_bf16_f32 v60, v60, v61
	v_cvt_pk_bf16_f32 v61, v62, v63
	v_cvt_pk_bf16_f32 v62, v56, v57
	v_cvt_pk_bf16_f32 v63, v58, v59
	flat_store_dwordx4 v[64:65], v[44:47] offset:256
	v_cvt_pk_bf16_f32 v31, v26, v27
	v_mad_i64_i32 v[24:25], s[18:19], s20, v24, 0
	v_lshl_add_u64 v[44:45], v[40:41], 1, v[150:151]
	v_cvt_pk_bf16_f32 v12, v12, v13
	v_cvt_pk_bf16_f32 v13, v14, v15
	v_cvt_pk_bf16_f32 v14, v8, v9
	v_add_u32_e32 v8, 0xb0, v154
	flat_store_dwordx4 v[64:65], v[60:63]
	v_cvt_pk_bf16_f32 v40, v52, v53
	v_cvt_pk_bf16_f32 v41, v54, v55
	v_cvt_pk_bf16_f32 v42, v48, v49
	v_cvt_pk_bf16_f32 v43, v50, v51
	flat_store_dwordx4 v[44:45], v[28:31] offset:256
	v_cvt_pk_bf16_f32 v15, v10, v11
	v_mad_i64_i32 v[8:9], s[18:19], s20, v8, 0
	v_lshl_add_u64 v[28:29], v[24:25], 1, v[150:151]
	flat_store_dwordx4 v[44:45], v[40:43]
	v_cvt_pk_bf16_f32 v24, v36, v37
	v_cvt_pk_bf16_f32 v25, v38, v39
	v_cvt_pk_bf16_f32 v26, v32, v33
	v_cvt_pk_bf16_f32 v27, v34, v35
	flat_store_dwordx4 v[28:29], v[12:15] offset:256
	v_cvt_pk_bf16_f32 v10, v16, v17
	v_cvt_pk_bf16_f32 v11, v18, v19
	v_lshl_add_u64 v[12:13], v[8:9], 1, v[150:151]
	v_cvt_pk_bf16_f32 v8, v20, v21
	v_cvt_pk_bf16_f32 v9, v22, v23
	v_cvt_pk_bf16_f32 v4, v4, v5
	v_cvt_pk_bf16_f32 v5, v6, v7
	v_cvt_pk_bf16_f32 v6, v0, v1
	v_cvt_pk_bf16_f32 v7, v2, v3
	s_and_b64 vcc, exec, s[40:41]
	s_mov_b32 s45, s49
	s_mov_b32 s10, s12
	s_mov_b64 s[18:19], s[16:17]
	s_mov_b64 s[20:21], s[14:15]
	flat_store_dwordx4 v[28:29], v[24:27]
	flat_store_dwordx4 v[12:13], v[8:11]
	flat_store_dwordx4 v[12:13], v[4:7] offset:256
	s_cbranch_vccz .LBB1_1526
	s_waitcnt vmcnt(0)
	s_cmpk_gt_u32 s4, 0xff
	s_cbranch_scc1 .LBB1_1533
	s_barrier

; #define PG8_STAGE(bufoff, gbase, voff) do { _Pragma("unroll") for (int _i = 0; _i < 2; ++_i) \
;         __builtin_amdgcn_global_load_lds((const unsigned*)((const char*)(gbase) + (voff)[_i]), (LAS unsigned*)(lds + (bufoff) + ldsw + _i * 8192), 16, 0, 0); } while (0)
; #define PG8_LDA(dst, b, h) do { _Pragma("unroll") for (int m = 0; m < 4; ++m) _Pragma("unroll") for (int k = 0; k < 2; ++k) dst[m][k] = *(const LAS bf16x8*)(lds + PG8_SA(b, h) + aoff + m * 2048 + k * 1024); } while (0)
; #define PG8_LDB(dst, b, h) do { _Pragma("unroll") for (int n = 0; n < 2; ++n) _Pragma("unroll") for (int k = 0; k < 2; ++k) dst[n][k] = *(const LAS bf16x8*)(lds + PG8_SB(b, h) + boff + n * 2048 + k * 1024); } while (0)
; #define PG8_MMA(ai, bj, At, Bt) do { __builtin_amdgcn_s_setprio(1); _Pragma("unroll") for (int m = 0; m < 4; ++m) _Pragma("unroll") for (int n = 0; n < 2; ++n) _Pragma("unroll") for (int k = 0; k < 2; ++k) \
;         acc[ai][bj][m][n] = __builtin_amdgcn_mfma_f32_16x16x32_bf16(Bt[n][k], At[m][k], acc[ai][bj][m][n], 0, 0, 0); __builtin_amdgcn_s_setprio(0); } while (0)
; #define PG8_WAIT_L(n) asm volatile("s_waitcnt lgkmcnt(" #n ")" ::: "memory")
; #define PG8_BAR __builtin_amdgcn_s_barrier()
; #define PG8_SCHED __builtin_amdgcn_sched_barrier(0)
; template <class Map, class Epi>
; DI void gemm_phase(LAS unsigned char* lds, const Map& MP, const Epi& E, const int nM, const int nN, const int K, const int lda, const int ldb) {
;     ...
;             const bool last = (t == nt - 2);
;             const char* a1 = cA + (size_t)(t + 1) * kstep;
;             const char* a2 = last ? nA : cA + (size_t)(t + 2) * kstep; const char* b2 = last ? nB : cB + (size_t)(t + 2) * kstep;
;             const char* a3 = a2 + kstep; const char* b3 = b2 + kstep;
;             PG8_LDB(B0, 0, 0); PG8_SCHED; PG8_LDA(At, 0, 0); PG8_STAGE(PG8_SA(1, 1), a1 + hstepA, voffA);
;             PG8_WAIT_L(8); PG8_BAR; PG8_WAIT_L(0); PG8_MMA(0, 0, At, B0); PG8_BAR; PG8_SCHED;
;             PG8_LDB(B1, 0, 1); PG8_STAGE(PG8_SB(0, 0), b2, voffB);
;             PG8_BAR; PG8_WAIT_L(0); PG8_MMA(0, 1, At, B1); PG8_BAR;
;             PG8_LDA(At, 0, 1); PG8_STAGE(PG8_SA(0, 0), a2, voffA);
;             PG8_BAR; PG8_WAIT_L(0); PG8_MMA(1, 0, At, B0); PG8_BAR; PG8_SCHED;
.LBB1_1764:
	ds_read_b128 v[152:155], v149
	ds_read_b128 v[156:159], v149 offset:1024
	ds_read_b128 v[160:163], v149 offset:2048
	ds_read_b128 v[164:167], v149 offset:3072
	s_add_u32 s12, s10, 0xfff80080
	s_addc_u32 s13, s11, -1
	s_cmp_eq_u32 s3, 28
	s_cselect_b32 s15, s37, s13
	s_cselect_b32 s14, s38, s12
	s_cselect_b32 s13, s39, s48
	s_cselect_b32 s12, s45, s47
	v_lshl_add_u64 v[144:145], s[10:11], 0, v[138:139]
	s_add_i32 m0, s24, 0xc000
	ds_read_b128 v[168:171], v150
	ds_read_b128 v[172:175], v150 offset:1024
	ds_read_b128 v[176:179], v150 offset:2048
	ds_read_b128 v[180:183], v150 offset:3072
	ds_read_b128 v[184:187], v150 offset:4096
	ds_read_b128 v[188:191], v150 offset:5120
	ds_read_b128 v[192:195], v150 offset:6144
	ds_read_b128 v[198:201], v150 offset:7168
	global_load_lds_dwordx4 v[144:145], off
	v_lshl_add_u64 v[144:145], s[10:11], 0, v[136:137]
	s_add_i32 m0, s24, 0xe000
	s_nop 0
	global_load_lds_dwordx4 v[144:145], off
	s_waitcnt lgkmcnt(8)
	s_barrier
	s_setprio 1
	s_waitcnt lgkmcnt(7)
	v_mfma_f32_16x16x32_bf16 v[124:127], v[152:155], v[168:171], v[124:127]
	v_mfma_f32_16x16x32_bf16 v[120:123], v[160:163], v[168:171], v[120:123]
	s_waitcnt lgkmcnt(5)
	v_mfma_f32_16x16x32_bf16 v[108:111], v[152:155], v[176:179], v[108:111]
	v_mfma_f32_16x16x32_bf16 v[104:107], v[160:163], v[176:179], v[104:107]
	s_waitcnt lgkmcnt(3)
	v_mfma_f32_16x16x32_bf16 v[92:95], v[152:155], v[184:187], v[92:95]
	v_mfma_f32_16x16x32_bf16 v[88:91], v[160:163], v[184:187], v[88:91]
	s_waitcnt lgkmcnt(1)
	v_mfma_f32_16x16x32_bf16 v[76:79], v[152:155], v[192:195], v[76:79]
	v_mfma_f32_16x16x32_bf16 v[72:75], v[160:163], v[192:195], v[72:75]
	v_mfma_f32_16x16x32_bf16 v[124:127], v[156:159], v[172:175], v[124:127]
	v_mfma_f32_16x16x32_bf16 v[120:123], v[164:167], v[172:175], v[120:123]
	v_mfma_f32_16x16x32_bf16 v[108:111], v[156:159], v[180:183], v[108:111]
	v_mfma_f32_16x16x32_bf16 v[104:107], v[164:167], v[180:183], v[104:107]
	v_mfma_f32_16x16x32_bf16 v[92:95], v[156:159], v[188:191], v[92:95]
	v_mfma_f32_16x16x32_bf16 v[88:91], v[164:167], v[188:191], v[88:91]
	s_waitcnt lgkmcnt(0)
	v_mfma_f32_16x16x32_bf16 v[76:79], v[156:159], v[198:201], v[76:79]
	v_mfma_f32_16x16x32_bf16 v[72:75], v[164:167], v[198:201], v[72:75]
	s_setprio 0
	s_barrier
	s_add_i32 s49, s35, s22
	v_lshl_add_u64 v[144:145], s[12:13], 0, v[132:133]
	s_mov_b32 m0, s49
	ds_read_b128 v[202:205], v151
	ds_read_b128 v[206:209], v151 offset:1024
	ds_read_b128 v[210:213], v151 offset:2048
	ds_read_b128 v[214:217], v151 offset:3072
	global_load_lds_dwordx4 v[144:145], off
	v_lshl_add_u64 v[218:219], s[12:13], 0, v[128:129]
	s_add_i32 m0, s49, 0x2000
	s_nop 0
	global_load_lds_dwordx4 v[218:219], off
	s_barrier
	s_setprio 1
	s_waitcnt lgkmcnt(3)
	v_mfma_f32_16x16x32_bf16 v[116:119], v[202:205], v[168:171], v[116:119]
	s_waitcnt lgkmcnt(1)
	v_mfma_f32_16x16x32_bf16 v[112:115], v[210:213], v[168:171], v[112:115]
	v_mfma_f32_16x16x32_bf16 v[100:103], v[202:205], v[176:179], v[100:103]
	v_mfma_f32_16x16x32_bf16 v[96:99], v[210:213], v[176:179], v[96:99]
	v_mfma_f32_16x16x32_bf16 v[84:87], v[202:205], v[184:187], v[84:87]
	v_mfma_f32_16x16x32_bf16 v[80:83], v[210:213], v[184:187], v[80:83]
	v_mfma_f32_16x16x32_bf16 v[68:71], v[202:205], v[192:195], v[68:71]
	v_mfma_f32_16x16x32_bf16 v[64:67], v[210:213], v[192:195], v[64:67]
	v_mfma_f32_16x16x32_bf16 v[116:119], v[206:209], v[172:175], v[116:119]
	s_waitcnt lgkmcnt(0)
	v_mfma_f32_16x16x32_bf16 v[112:115], v[214:217], v[172:175], v[112:115]
	v_mfma_f32_16x16x32_bf16 v[100:103], v[206:209], v[180:183], v[100:103]
	v_mfma_f32_16x16x32_bf16 v[96:99], v[214:217], v[180:183], v[96:99]
	v_mfma_f32_16x16x32_bf16 v[84:87], v[206:209], v[188:191], v[84:87]
	v_mfma_f32_16x16x32_bf16 v[80:83], v[214:217], v[188:191], v[80:83]
	v_mfma_f32_16x16x32_bf16 v[68:71], v[206:209], v[198:201], v[68:71]
	v_mfma_f32_16x16x32_bf16 v[64:67], v[214:217], v[198:201], v[64:67]
	s_setprio 0
	s_mov_b32 m0, s24
	v_lshl_add_u64 v[220:221], s[14:15], 0, v[134:135]
	s_barrier
	ds_read_b128 v[168:171], v150 offset:16384
	ds_read_b128 v[172:175], v150 offset:17408
	ds_read_b128 v[176:179], v150 offset:18432
	ds_read_b128 v[180:183], v150 offset:19456
	ds_read_b128 v[184:187], v150 offset:20480
	ds_read_b128 v[188:191], v150 offset:21504
	ds_read_b128 v[192:195], v150 offset:22528
	ds_read_b128 v[198:201], v150 offset:23552
	global_load_lds_dwordx4 v[220:221], off
	v_lshl_add_u64 v[222:223], s[14:15], 0, v[130:131]
	s_mov_b32 m0, s9
	s_nop 0
	global_load_lds_dwordx4 v[222:223], off
	s_barrier
	s_setprio 1
	s_waitcnt lgkmcnt(7)
	v_mfma_f32_16x16x32_bf16 v[60:63], v[152:155], v[168:171], v[60:63]
	v_mfma_f32_16x16x32_bf16 v[56:59], v[160:163], v[168:171], v[56:59]
	s_waitcnt lgkmcnt(5)
	v_mfma_f32_16x16x32_bf16 v[44:47], v[152:155], v[176:179], v[44:47]
	v_mfma_f32_16x16x32_bf16 v[40:43], v[160:163], v[176:179], v[40:43]
	s_waitcnt lgkmcnt(3)
	v_mfma_f32_16x16x32_bf16 v[28:31], v[152:155], v[184:187], v[28:31]
	v_mfma_f32_16x16x32_bf16 v[24:27], v[160:163], v[184:187], v[24:27]
	s_waitcnt lgkmcnt(1)
	v_mfma_f32_16x16x32_bf16 v[12:15], v[152:155], v[192:195], v[12:15]
	v_mfma_f32_16x16x32_bf16 v[8:11], v[160:163], v[192:195], v[8:11]
	v_mfma_f32_16x16x32_bf16 v[60:63], v[156:159], v[172:175], v[60:63]
	v_mfma_f32_16x16x32_bf16 v[56:59], v[164:167], v[172:175], v[56:59]
	v_mfma_f32_16x16x32_bf16 v[44:47], v[156:159], v[180:183], v[44:47]
	v_mfma_f32_16x16x32_bf16 v[40:43], v[164:167], v[180:183], v[40:43]
	v_mfma_f32_16x16x32_bf16 v[28:31], v[156:159], v[188:191], v[28:31]
	v_mfma_f32_16x16x32_bf16 v[24:27], v[164:167], v[188:191], v[24:27]
	s_waitcnt lgkmcnt(0)
	v_mfma_f32_16x16x32_bf16 v[12:15], v[156:159], v[198:201], v[12:15]
	v_mfma_f32_16x16x32_bf16 v[8:11], v[164:167], v[198:201], v[8:11]
	s_setprio 0
	s_barrier
; #define PG8_STAGE(bufoff, gbase, voff) do { _Pragma("unroll") for (int _i = 0; _i < 2; ++_i) \
;         __builtin_amdgcn_global_load_lds((const unsigned*)((const char*)(gbase) + (voff)[_i]), (LAS unsigned*)(lds + (bufoff) + ldsw + _i * 8192), 16, 0, 0); } while (0)
; #define PG8_LDA(dst, b, h) do { _Pragma("unroll") for (int m = 0; m < 4; ++m) _Pragma("unroll") for (int k = 0; k < 2; ++k) dst[m][k] = *(const LAS bf16x8*)(lds + PG8_SA(b, h) + aoff + m * 2048 + k * 1024); } while (0)
; #define PG8_LDB(dst, b, h) do { _Pragma("unroll") for (int n = 0; n < 2; ++n) _Pragma("unroll") for (int k = 0; k < 2; ++k) dst[n][k] = *(const LAS bf16x8*)(lds + PG8_SB(b, h) + boff + n * 2048 + k * 1024); } while (0)
; #define PG8_MMA(ai, bj, At, Bt) do { __builtin_amdgcn_s_setprio(1); _Pragma("unroll") for (int m = 0; m < 4; ++m) _Pragma("unroll") for (int n = 0; n < 2; ++n) _Pragma("unroll") for (int k = 0; k < 2; ++k) \
;         acc[ai][bj][m][n] = __builtin_amdgcn_mfma_f32_16x16x32_bf16(Bt[n][k], At[m][k], acc[ai][bj][m][n], 0, 0, 0); __builtin_amdgcn_s_setprio(0); } while (0)
; #define PG8_WAIT_V(n) asm volatile("s_waitcnt vmcnt(" #n ")" ::: "memory")
; #define PG8_WAIT_L(n) asm volatile("s_waitcnt lgkmcnt(" #n ")" ::: "memory")
; #define PG8_BAR __builtin_amdgcn_s_barrier()
; #define PG8_SCHED __builtin_amdgcn_sched_barrier(0)
; template <class Map, class Epi>
; DI void gemm_phase(LAS unsigned char* lds, const Map& MP, const Epi& E, const int nM, const int nN, const int K, const int lda, const int ldb) {
;     ...
;             PG8_STAGE(PG8_SB(0, 1), b2 + hstepB, voffB);
;             PG8_WAIT_V(6); PG8_BAR; PG8_MMA(1, 1, At, B1); PG8_BAR;
;             PG8_LDB(B0, 1, 0); PG8_SCHED; PG8_LDA(At, 1, 0); PG8_STAGE(PG8_SA(0, 1), a2 + hstepA, voffA);
;             PG8_WAIT_L(8); PG8_BAR; PG8_WAIT_L(0); PG8_MMA(0, 0, At, B0); PG8_BAR; PG8_SCHED;
;             PG8_LDB(B1, 1, 1); PG8_STAGE(PG8_SB(1, 0), b3, voffB);
;             PG8_BAR; PG8_WAIT_L(0); PG8_MMA(0, 1, At, B1); PG8_BAR;
	s_add_u32 s54, s12, 0x80000
	s_addc_u32 s55, s13, 0
	s_add_i32 s49, s36, s22
	v_lshl_add_u64 v[152:153], s[54:55], 0, v[132:133]
	s_mov_b32 m0, s49
	s_nop 0
	global_load_lds_dwordx4 v[152:153], off
	v_lshl_add_u64 v[152:153], s[54:55], 0, v[128:129]
	s_add_i32 m0, s49, 0x2000
	s_nop 0
	global_load_lds_dwordx4 v[152:153], off
	s_waitcnt vmcnt(6)
	s_barrier
	s_setprio 1
	v_mfma_f32_16x16x32_bf16 v[52:55], v[202:205], v[168:171], v[52:55]
	v_mfma_f32_16x16x32_bf16 v[48:51], v[210:213], v[168:171], v[48:51]
	v_mfma_f32_16x16x32_bf16 v[36:39], v[202:205], v[176:179], v[36:39]
	v_mfma_f32_16x16x32_bf16 v[32:35], v[210:213], v[176:179], v[32:35]
	v_mfma_f32_16x16x32_bf16 v[20:23], v[202:205], v[184:187], v[20:23]
	v_mfma_f32_16x16x32_bf16 v[16:19], v[210:213], v[184:187], v[16:19]
	v_mfma_f32_16x16x32_bf16 v[4:7], v[202:205], v[192:195], v[4:7]
	v_mfma_f32_16x16x32_bf16 v[0:3], v[210:213], v[192:195], v[0:3]
	v_mfma_f32_16x16x32_bf16 v[52:55], v[206:209], v[172:175], v[52:55]
	v_mfma_f32_16x16x32_bf16 v[48:51], v[214:217], v[172:175], v[48:51]
	v_mfma_f32_16x16x32_bf16 v[36:39], v[206:209], v[180:183], v[36:39]
	v_mfma_f32_16x16x32_bf16 v[32:35], v[214:217], v[180:183], v[32:35]
	v_mfma_f32_16x16x32_bf16 v[20:23], v[206:209], v[188:191], v[20:23]
	v_mfma_f32_16x16x32_bf16 v[16:19], v[214:217], v[188:191], v[16:19]
	v_mfma_f32_16x16x32_bf16 v[4:7], v[206:209], v[198:201], v[4:7]
	v_mfma_f32_16x16x32_bf16 v[0:3], v[214:217], v[198:201], v[0:3]
	s_setprio 0
	s_add_i32 s49, 0, 0x18000
	v_add_u32_e32 v164, s49, v148
	s_barrier
	ds_read_b128 v[152:155], v164
	ds_read_b128 v[156:159], v164 offset:1024
	ds_read_b128 v[160:163], v164 offset:2048
	ds_read_b128 v[164:167], v164 offset:3072
	s_add_u32 s14, s14, 0x80000
	s_addc_u32 s15, s15, 0
	s_mov_b32 m0, s25
	v_lshl_add_u64 v[202:203], s[14:15], 0, v[134:135]
	ds_read_b128 v[168:171], v150 offset:32768
	ds_read_b128 v[172:175], v150 offset:33792
	ds_read_b128 v[176:179], v150 offset:34816
	ds_read_b128 v[180:183], v150 offset:35840
	ds_read_b128 v[184:187], v150 offset:36864
	ds_read_b128 v[188:191], v150 offset:37888
	ds_read_b128 v[192:195], v150 offset:38912
	ds_read_b128 v[198:201], v150 offset:39936
	global_load_lds_dwordx4 v[202:203], off
	v_lshl_add_u64 v[202:203], s[14:15], 0, v[130:131]
	s_mov_b32 m0, s26
	s_nop 0
	global_load_lds_dwordx4 v[202:203], off
	s_waitcnt lgkmcnt(8)
	s_barrier
	s_setprio 1
	s_waitcnt lgkmcnt(7)
	v_mfma_f32_16x16x32_bf16 v[124:127], v[152:155], v[168:171], v[124:127]
	v_mfma_f32_16x16x32_bf16 v[120:123], v[160:163], v[168:171], v[120:123]
	s_waitcnt lgkmcnt(5)
	v_mfma_f32_16x16x32_bf16 v[108:111], v[152:155], v[176:179], v[108:111]
	v_mfma_f32_16x16x32_bf16 v[104:107], v[160:163], v[176:179], v[104:107]
	s_waitcnt lgkmcnt(3)
	v_mfma_f32_16x16x32_bf16 v[92:95], v[152:155], v[184:187], v[92:95]
	v_mfma_f32_16x16x32_bf16 v[88:91], v[160:163], v[184:187], v[88:91]
	s_waitcnt lgkmcnt(1)
	v_mfma_f32_16x16x32_bf16 v[76:79], v[152:155], v[192:195], v[76:79]
	v_mfma_f32_16x16x32_bf16 v[72:75], v[160:163], v[192:195], v[72:75]
	v_mfma_f32_16x16x32_bf16 v[124:127], v[156:159], v[172:175], v[124:127]
	v_mfma_f32_16x16x32_bf16 v[120:123], v[164:167], v[172:175], v[120:123]
	v_mfma_f32_16x16x32_bf16 v[108:111], v[156:159], v[180:183], v[108:111]
	v_mfma_f32_16x16x32_bf16 v[104:107], v[164:167], v[180:183], v[104:107]
	v_mfma_f32_16x16x32_bf16 v[92:95], v[156:159], v[188:191], v[92:95]
	v_mfma_f32_16x16x32_bf16 v[88:91], v[164:167], v[188:191], v[88:91]
	s_waitcnt lgkmcnt(0)
	v_mfma_f32_16x16x32_bf16 v[76:79], v[156:159], v[198:201], v[76:79]
	v_mfma_f32_16x16x32_bf16 v[72:75], v[164:167], v[198:201], v[72:75]
	s_setprio 0
	s_barrier
	s_add_i32 s14, 0, 0x1c000
	s_add_i32 s15, s49, s22
	v_add_u32_e32 v196, s14, v148
	v_lshl_add_u64 v[144:145], v[144:145], 0, s[42:43]
	s_mov_b32 m0, s15
	ds_read_b128 v[202:205], v196
	ds_read_b128 v[206:209], v196 offset:1024
	ds_read_b128 v[210:213], v196 offset:2048
	ds_read_b128 v[214:217], v196 offset:3072
	global_load_lds_dwordx4 v[144:145], off
	v_lshl_add_u64 v[144:145], v[218:219], 0, s[42:43]
	s_add_i32 m0, s15, 0x2000
	s_nop 0
	global_load_lds_dwordx4 v[144:145], off
	s_barrier
	s_setprio 1
	s_waitcnt lgkmcnt(3)
	v_mfma_f32_16x16x32_bf16 v[116:119], v[202:205], v[168:171], v[116:119]
	s_waitcnt lgkmcnt(1)
	v_mfma_f32_16x16x32_bf16 v[112:115], v[210:213], v[168:171], v[112:115]
	v_mfma_f32_16x16x32_bf16 v[100:103], v[202:205], v[176:179], v[100:103]
	v_mfma_f32_16x16x32_bf16 v[96:99], v[210:213], v[176:179], v[96:99]
	v_mfma_f32_16x16x32_bf16 v[84:87], v[202:205], v[184:187], v[84:87]
	v_mfma_f32_16x16x32_bf16 v[80:83], v[210:213], v[184:187], v[80:83]
	v_mfma_f32_16x16x32_bf16 v[68:71], v[202:205], v[192:195], v[68:71]
	v_mfma_f32_16x16x32_bf16 v[64:67], v[210:213], v[192:195], v[64:67]
	v_mfma_f32_16x16x32_bf16 v[116:119], v[206:209], v[172:175], v[116:119]
	s_waitcnt lgkmcnt(0)
	v_mfma_f32_16x16x32_bf16 v[112:115], v[214:217], v[172:175], v[112:115]
	v_mfma_f32_16x16x32_bf16 v[100:103], v[206:209], v[180:183], v[100:103]
	v_mfma_f32_16x16x32_bf16 v[96:99], v[214:217], v[180:183], v[96:99]
	v_mfma_f32_16x16x32_bf16 v[84:87], v[206:209], v[188:191], v[84:87]
	v_mfma_f32_16x16x32_bf16 v[80:83], v[214:217], v[188:191], v[80:83]
	v_mfma_f32_16x16x32_bf16 v[68:71], v[206:209], v[198:201], v[68:71]
	v_mfma_f32_16x16x32_bf16 v[64:67], v[214:217], v[198:201], v[64:67]
	s_setprio 0
	s_mov_b32 m0, s30
	v_lshl_add_u64 v[144:145], v[220:221], 0, s[42:43]
	s_barrier
; DI unsigned pack2(float a, float b) { f32x2 v = {a, b}; hwbf16x2 r = __builtin_convertvector(v, hwbf16x2); return __builtin_bit_cast(unsigned, r); }
; DI float bflo(unsigned w) { return __uint_as_float(w << 16); }
; DI float bfhi(unsigned w) { return __uint_as_float(w & 0xffff0000u); }
; #define PG8_STAGE(bufoff, gbase, voff) do { _Pragma("unroll") for (int _i = 0; _i < 2; ++_i) \
;         __builtin_amdgcn_global_load_lds((const unsigned*)((const char*)(gbase) + (voff)[_i]), (LAS unsigned*)(lds + (bufoff) + ldsw + _i * 8192), 16, 0, 0); } while (0)
; #define PG8_WAIT_V(n) asm volatile("s_waitcnt vmcnt(" #n ")" ::: "memory")
; #define PG8_WAIT_L(n) asm volatile("s_waitcnt lgkmcnt(" #n ")" ::: "memory")
;     DI void operator()(const f32x4 (&acc)[2][2][4][2], const Unit& u, int wr, int wc, int fr, int fq) const {
;     ...
;             for (int m = 0; m < 4; ++m) { const size_t ro = (size_t)(row0 + ai * HALF + m * 16) * D + col0;
; #pragma unroll
;                 for (int bj = 0; bj < 2; ++bj) {
;                     f32x4 x0, x1;
;                     if constexpr (IB) { const u32x4 w = *(const u32x4*)((const bf16_t*)Xin + ro + bj * HALF);
;                         x0 = (f32x4){bflo(w[0]), bfhi(w[0]), bflo(w[1]), bfhi(w[1])}; x1 = (f32x4){bflo(w[2]), bfhi(w[2]), bflo(w[3]), bfhi(w[3])}; }
;                     else { x0 = *(const f32x4*)((const float*)Xin + ro + bj * HALF); x1 = *(const f32x4*)((const float*)Xin + ro + bj * HALF + 4); }
;                     x0 += acc[ai][bj][m][0] * sc[bj][0]; x1 += acc[ai][bj][m][1] * sc[bj][1];
;                     if constexpr (OB) { u32x4 o; o[0] = pack2(x0[0], x0[1]); o[1] = pack2(x0[2], x0[3]); o[2] = pack2(x1[0], x1[1]); o[3] = pack2(x1[2], x1[3]);
;                         *(u32x4*)((bf16_t*)Xout + ro + bj * HALF) = o; }
;                     else { *(f32x4*)((float*)Xout + ro + bj * HALF) = x0; *(f32x4*)((float*)Xout + ro + bj * HALF + 4) = x1; } } }
; template <class Map, class Epi>
; DI void gemm_phase(LAS unsigned char* lds, const Map& MP, const Epi& E, const int nM, const int nN, const int K, const int lda, const int ldb) {
;     ...
;             PG8_LDA(At, 1, 1); PG8_STAGE(PG8_SA(1, 0), a3, voffA);
;             PG8_BAR; PG8_WAIT_L(0); PG8_MMA(1, 0, At, B0); PG8_BAR; PG8_SCHED;
;             PG8_STAGE(PG8_SB(1, 1), b3 + hstepB, voffB);
;             PG8_WAIT_V(6); PG8_BAR; PG8_MMA(1, 1, At, B1); PG8_BAR;
	ds_read_b128 v[168:171], v150 offset:49152
	ds_read_b128 v[172:175], v150 offset:50176
	ds_read_b128 v[176:179], v150 offset:51200
	ds_read_b128 v[180:183], v150 offset:52224
	ds_read_b128 v[184:187], v150 offset:53248
	ds_read_b128 v[188:191], v150 offset:54272
	ds_read_b128 v[192:195], v150 offset:55296
	ds_read_b128 v[198:201], v150 offset:56320
	global_load_lds_dwordx4 v[144:145], off
	v_lshl_add_u64 v[144:145], v[222:223], 0, s[42:43]
	s_mov_b32 m0, s31
	s_nop 0
	global_load_lds_dwordx4 v[144:145], off
	s_barrier
	s_setprio 1
	s_waitcnt lgkmcnt(7)
	v_mfma_f32_16x16x32_bf16 v[60:63], v[152:155], v[168:171], v[60:63]
	v_mfma_f32_16x16x32_bf16 v[56:59], v[160:163], v[168:171], v[56:59]
	s_waitcnt lgkmcnt(5)
	v_mfma_f32_16x16x32_bf16 v[44:47], v[152:155], v[176:179], v[44:47]
	v_mfma_f32_16x16x32_bf16 v[40:43], v[160:163], v[176:179], v[40:43]
	s_waitcnt lgkmcnt(3)
	v_mfma_f32_16x16x32_bf16 v[28:31], v[152:155], v[184:187], v[28:31]
	v_mfma_f32_16x16x32_bf16 v[24:27], v[160:163], v[184:187], v[24:27]
	s_waitcnt lgkmcnt(1)
	v_mfma_f32_16x16x32_bf16 v[12:15], v[152:155], v[192:195], v[12:15]
	v_mfma_f32_16x16x32_bf16 v[8:11], v[160:163], v[192:195], v[8:11]
	v_mfma_f32_16x16x32_bf16 v[60:63], v[156:159], v[172:175], v[60:63]
	v_mfma_f32_16x16x32_bf16 v[56:59], v[164:167], v[172:175], v[56:59]
	v_mfma_f32_16x16x32_bf16 v[44:47], v[156:159], v[180:183], v[44:47]
	v_mfma_f32_16x16x32_bf16 v[40:43], v[164:167], v[180:183], v[40:43]
	v_mfma_f32_16x16x32_bf16 v[28:31], v[156:159], v[188:191], v[28:31]
	v_mfma_f32_16x16x32_bf16 v[24:27], v[164:167], v[188:191], v[24:27]
	s_waitcnt lgkmcnt(0)
	v_mfma_f32_16x16x32_bf16 v[12:15], v[156:159], v[198:201], v[12:15]
	v_mfma_f32_16x16x32_bf16 v[8:11], v[164:167], v[198:201], v[8:11]
	s_setprio 0
	s_barrier
	s_add_u32 s12, s12, 0x80080
	s_addc_u32 s13, s13, 0
	s_add_i32 s14, s14, s22
	v_lshl_add_u64 v[144:145], s[12:13], 0, v[132:133]
	s_mov_b32 m0, s14
	s_nop 0
	global_load_lds_dwordx4 v[144:145], off
	v_lshl_add_u64 v[144:145], s[12:13], 0, v[128:129]
	s_add_i32 m0, s14, 0x2000
	s_nop 0
	global_load_lds_dwordx4 v[144:145], off
	s_waitcnt vmcnt(6)
	s_barrier
	s_setprio 1
	v_mfma_f32_16x16x32_bf16 v[52:55], v[202:205], v[168:171], v[52:55]
	v_mfma_f32_16x16x32_bf16 v[48:51], v[210:213], v[168:171], v[48:51]
	v_mfma_f32_16x16x32_bf16 v[36:39], v[202:205], v[176:179], v[36:39]
	v_mfma_f32_16x16x32_bf16 v[32:35], v[210:213], v[176:179], v[32:35]
	v_mfma_f32_16x16x32_bf16 v[20:23], v[202:205], v[184:187], v[20:23]
	v_mfma_f32_16x16x32_bf16 v[16:19], v[210:213], v[184:187], v[16:19]
	v_mfma_f32_16x16x32_bf16 v[4:7], v[202:205], v[192:195], v[4:7]
	v_mfma_f32_16x16x32_bf16 v[0:3], v[210:213], v[192:195], v[0:3]
	v_mfma_f32_16x16x32_bf16 v[52:55], v[206:209], v[172:175], v[52:55]
	v_mfma_f32_16x16x32_bf16 v[48:51], v[214:217], v[172:175], v[48:51]
	v_mfma_f32_16x16x32_bf16 v[36:39], v[206:209], v[180:183], v[36:39]
	v_mfma_f32_16x16x32_bf16 v[32:35], v[214:217], v[180:183], v[32:35]
	v_mfma_f32_16x16x32_bf16 v[20:23], v[206:209], v[188:191], v[20:23]
	v_mfma_f32_16x16x32_bf16 v[16:19], v[214:217], v[188:191], v[16:19]
	v_mfma_f32_16x16x32_bf16 v[4:7], v[206:209], v[198:201], v[4:7]
	v_mfma_f32_16x16x32_bf16 v[0:3], v[214:217], v[198:201], v[0:3]
	s_setprio 0
	s_add_i32 s3, s3, 2
	s_add_u32 s47, s47, 0x100
	s_addc_u32 s48, s48, 0
	s_add_u32 s10, s10, 0x100
	s_addc_u32 s11, s11, 0
	s_cmp_gt_u32 s3, 29
	s_barrier
	s_cbranch_scc0 .LBB1_1764
	v_mov_b32_e32 v152, v147
	v_mov_b32_e32 v144, v146
	s_lshl_b32 s2, s2, 8
	s_or_b32 s2, s2, s29
	v_lshl_add_u32 v144, v144, 3, s2
	s_lshl_b32 s2, s8, 8
	s_add_i32 s2, s2, s28
	v_add_u32_e32 v152, s2, v152
	v_ashrrev_i32_e32 v153, 31, v152
	v_lshlrev_b64 v[152:153], 12, v[152:153]
	v_ashrrev_i32_e32 v145, 31, v144
	v_lshl_add_u64 v[152:153], s[4:5], 0, v[152:153]
	v_lshl_add_u64 v[144:145], v[144:145], 1, v[152:153]
	flat_load_dwordx4 v[152:155], v[144:145]
	s_mov_b64 s[2:3], 0x10000
	s_mov_b32 s8, s46
	s_mov_b64 s[10:11], s[6:7]
	s_mov_b64 s[12:13], s[52:53]
	s_waitcnt vmcnt(0) lgkmcnt(0)
	v_lshlrev_b32_e32 v156, 16, v152
	v_and_b32_e32 v157, 0xffff0000, v152
	v_lshlrev_b32_e32 v152, 16, v153
	v_and_b32_e32 v153, 0xffff0000, v153
	v_lshlrev_b32_e32 v158, 16, v154
	v_and_b32_e32 v159, 0xffff0000, v154
	v_lshlrev_b32_e32 v154, 16, v155
	v_and_b32_e32 v155, 0xffff0000, v155
	v_pk_add_f32 v[126:127], v[126:127], v[152:153]
	v_pk_add_f32 v[124:125], v[124:125], v[156:157]
	v_pk_add_f32 v[152:153], v[122:123], v[154:155]
	v_pk_add_f32 v[122:123], v[120:121], v[158:159]
	v_cvt_pk_bf16_f32 v120, v124, v125
	v_cvt_pk_bf16_f32 v121, v126, v127
	v_cvt_pk_bf16_f32 v122, v122, v123
	v_cvt_pk_bf16_f32 v123, v152, v153
	flat_store_dwordx4 v[144:145], v[120:123]
	flat_load_dwordx4 v[120:123], v[144:145] offset:256
	s_waitcnt vmcnt(0) lgkmcnt(0)
	v_lshlrev_b32_e32 v124, 16, v120
	v_and_b32_e32 v125, 0xffff0000, v120
	v_lshlrev_b32_e32 v120, 16, v121
	v_and_b32_e32 v121, 0xffff0000, v121
	v_lshlrev_b32_e32 v126, 16, v122
	v_and_b32_e32 v127, 0xffff0000, v122
	v_lshlrev_b32_e32 v122, 16, v123
	v_and_b32_e32 v123, 0xffff0000, v123
	v_pk_add_f32 v[116:117], v[116:117], v[124:125]
	v_pk_add_f32 v[118:119], v[118:119], v[120:121]
	v_pk_add_f32 v[120:121], v[114:115], v[122:123]
	v_pk_add_f32 v[114:115], v[112:113], v[126:127]
	v_cvt_pk_bf16_f32 v112, v116, v117
	v_lshl_add_u64 v[116:117], v[144:145], 0, s[2:3]
	s_mov_b32 s2, 0x10000
	v_cvt_pk_bf16_f32 v113, v118, v119
	v_add_co_u32_e32 v118, vcc, s2, v144
	v_cvt_pk_bf16_f32 v114, v114, v115
	v_cvt_pk_bf16_f32 v115, v120, v121
	v_addc_co_u32_e32 v119, vcc, 0, v145, vcc
	flat_store_dwordx4 v[144:145], v[112:115] offset:256
	flat_load_dwordx4 v[112:115], v[118:119]
	s_mov_b64 s[2:3], 0x20000
	s_waitcnt vmcnt(0) lgkmcnt(0)
; DI unsigned pack2(float a, float b) { f32x2 v = {a, b}; hwbf16x2 r = __builtin_convertvector(v, hwbf16x2); return __builtin_bit_cast(unsigned, r); }
; DI float bflo(unsigned w) { return __uint_as_float(w << 16); }
; DI float bfhi(unsigned w) { return __uint_as_float(w & 0xffff0000u); }
;     DI void operator()(const f32x4 (&acc)[2][2][4][2], const Unit& u, int wr, int wc, int fr, int fq) const {
;     ...
;             for (int m = 0; m < 4; ++m) { const size_t ro = (size_t)(row0 + ai * HALF + m * 16) * D + col0;
; #pragma unroll
;                 for (int bj = 0; bj < 2; ++bj) {
;                     f32x4 x0, x1;
;                     if constexpr (IB) { const u32x4 w = *(const u32x4*)((const bf16_t*)Xin + ro + bj * HALF);
;                         x0 = (f32x4){bflo(w[0]), bfhi(w[0]), bflo(w[1]), bfhi(w[1])}; x1 = (f32x4){bflo(w[2]), bfhi(w[2]), bflo(w[3]), bfhi(w[3])}; }
;                     else { x0 = *(const f32x4*)((const float*)Xin + ro + bj * HALF); x1 = *(const f32x4*)((const float*)Xin + ro + bj * HALF + 4); }
;                     x0 += acc[ai][bj][m][0] * sc[bj][0]; x1 += acc[ai][bj][m][1] * sc[bj][1];
;                     if constexpr (OB) { u32x4 o; o[0] = pack2(x0[0], x0[1]); o[1] = pack2(x0[2], x0[3]); o[2] = pack2(x1[0], x1[1]); o[3] = pack2(x1[2], x1[3]);
;                         *(u32x4*)((bf16_t*)Xout + ro + bj * HALF) = o; }
;                     else { *(f32x4*)((float*)Xout + ro + bj * HALF) = x0; *(f32x4*)((float*)Xout + ro + bj * HALF + 4) = x1; } } }
	v_lshlrev_b32_e32 v120, 16, v112
	v_and_b32_e32 v121, 0xffff0000, v112
	v_lshlrev_b32_e32 v112, 16, v113
	v_and_b32_e32 v113, 0xffff0000, v113
	v_lshlrev_b32_e32 v122, 16, v114
	v_and_b32_e32 v123, 0xffff0000, v114
	v_lshlrev_b32_e32 v114, 16, v115
	v_and_b32_e32 v115, 0xffff0000, v115
	v_pk_add_f32 v[110:111], v[110:111], v[112:113]
	v_pk_add_f32 v[108:109], v[108:109], v[120:121]
	v_pk_add_f32 v[112:113], v[106:107], v[114:115]
	v_pk_add_f32 v[106:107], v[104:105], v[122:123]
	v_cvt_pk_bf16_f32 v104, v108, v109
	v_cvt_pk_bf16_f32 v105, v110, v111
	v_cvt_pk_bf16_f32 v106, v106, v107
	v_cvt_pk_bf16_f32 v107, v112, v113
	flat_store_dwordx4 v[118:119], v[104:107]
	flat_load_dwordx4 v[104:107], v[116:117] offset:256
	s_waitcnt vmcnt(0) lgkmcnt(0)
	v_lshlrev_b32_e32 v108, 16, v104
	v_and_b32_e32 v109, 0xffff0000, v104
	v_lshlrev_b32_e32 v104, 16, v105
	v_and_b32_e32 v105, 0xffff0000, v105
	v_lshlrev_b32_e32 v110, 16, v106
	v_and_b32_e32 v111, 0xffff0000, v106
	v_lshlrev_b32_e32 v106, 16, v107
	v_and_b32_e32 v107, 0xffff0000, v107
	v_pk_add_f32 v[100:101], v[100:101], v[108:109]
	v_pk_add_f32 v[102:103], v[102:103], v[104:105]
	v_pk_add_f32 v[104:105], v[98:99], v[106:107]
	v_pk_add_f32 v[98:99], v[96:97], v[110:111]
	v_cvt_pk_bf16_f32 v96, v100, v101
	v_lshl_add_u64 v[100:101], v[144:145], 0, s[2:3]
	s_mov_b32 s2, 0x20000
	v_cvt_pk_bf16_f32 v97, v102, v103
	v_add_co_u32_e32 v102, vcc, s2, v144
	v_cvt_pk_bf16_f32 v98, v98, v99
	v_cvt_pk_bf16_f32 v99, v104, v105
	v_addc_co_u32_e32 v103, vcc, 0, v145, vcc
	flat_store_dwordx4 v[116:117], v[96:99] offset:256
	flat_load_dwordx4 v[96:99], v[102:103]
	s_mov_b64 s[2:3], 0x30000
	s_waitcnt vmcnt(0) lgkmcnt(0)
	v_lshlrev_b32_e32 v104, 16, v96
	v_and_b32_e32 v105, 0xffff0000, v96
	v_lshlrev_b32_e32 v96, 16, v97
	v_and_b32_e32 v97, 0xffff0000, v97
	v_lshlrev_b32_e32 v106, 16, v98
	v_and_b32_e32 v107, 0xffff0000, v98
	v_lshlrev_b32_e32 v98, 16, v99
	v_and_b32_e32 v99, 0xffff0000, v99
	v_pk_add_f32 v[94:95], v[94:95], v[96:97]
	v_pk_add_f32 v[92:93], v[92:93], v[104:105]
	v_pk_add_f32 v[96:97], v[90:91], v[98:99]
	v_pk_add_f32 v[90:91], v[88:89], v[106:107]
	v_cvt_pk_bf16_f32 v88, v92, v93
	v_cvt_pk_bf16_f32 v89, v94, v95
	v_cvt_pk_bf16_f32 v90, v90, v91
	v_cvt_pk_bf16_f32 v91, v96, v97
	flat_store_dwordx4 v[102:103], v[88:91]
	flat_load_dwordx4 v[88:91], v[100:101] offset:256
	s_waitcnt vmcnt(0) lgkmcnt(0)
	v_lshlrev_b32_e32 v92, 16, v88
	v_and_b32_e32 v93, 0xffff0000, v88
	v_lshlrev_b32_e32 v88, 16, v89
	v_and_b32_e32 v89, 0xffff0000, v89
	v_lshlrev_b32_e32 v94, 16, v90
	v_and_b32_e32 v95, 0xffff0000, v90
	v_lshlrev_b32_e32 v90, 16, v91
	v_and_b32_e32 v91, 0xffff0000, v91
	v_pk_add_f32 v[86:87], v[86:87], v[88:89]
	v_pk_add_f32 v[84:85], v[84:85], v[92:93]
	v_pk_add_f32 v[88:89], v[82:83], v[90:91]
	v_pk_add_f32 v[82:83], v[80:81], v[94:95]
	v_cvt_pk_bf16_f32 v80, v84, v85
	v_cvt_pk_bf16_f32 v81, v86, v87
	v_cvt_pk_bf16_f32 v82, v82, v83
	v_cvt_pk_bf16_f32 v83, v88, v89
	flat_store_dwordx4 v[100:101], v[80:83] offset:256
	s_nop 1
	v_lshl_add_u64 v[80:81], v[144:145], 0, s[2:3]
	s_mov_b32 s2, 0x30000
	v_add_co_u32_e32 v86, vcc, s2, v144
	s_mov_b64 s[2:3], 0x80000
	s_nop 0
	v_addc_co_u32_e32 v87, vcc, 0, v145, vcc
	flat_load_dwordx4 v[82:85], v[86:87]
	s_waitcnt vmcnt(0) lgkmcnt(0)
	v_lshlrev_b32_e32 v88, 16, v82
	v_and_b32_e32 v89, 0xffff0000, v82
	v_lshlrev_b32_e32 v82, 16, v83
	v_and_b32_e32 v83, 0xffff0000, v83
	v_lshlrev_b32_e32 v90, 16, v84
	v_and_b32_e32 v91, 0xffff0000, v84
	v_lshlrev_b32_e32 v84, 16, v85
	v_and_b32_e32 v85, 0xffff0000, v85
	v_pk_add_f32 v[78:79], v[78:79], v[82:83]
	v_pk_add_f32 v[76:77], v[76:77], v[88:89]
	v_pk_add_f32 v[82:83], v[74:75], v[84:85]
	v_pk_add_f32 v[74:75], v[72:73], v[90:91]
	v_cvt_pk_bf16_f32 v72, v76, v77
	v_cvt_pk_bf16_f32 v73, v78, v79
	v_cvt_pk_bf16_f32 v74, v74, v75
	v_cvt_pk_bf16_f32 v75, v82, v83
	flat_store_dwordx4 v[86:87], v[72:75]
	flat_load_dwordx4 v[72:75], v[80:81] offset:256
	s_waitcnt vmcnt(0) lgkmcnt(0)
	v_lshlrev_b32_e32 v76, 16, v72
	v_and_b32_e32 v77, 0xffff0000, v72
	v_lshlrev_b32_e32 v72, 16, v73
	v_and_b32_e32 v73, 0xffff0000, v73
	v_lshlrev_b32_e32 v78, 16, v74
	v_and_b32_e32 v79, 0xffff0000, v74
	v_lshlrev_b32_e32 v74, 16, v75
	v_and_b32_e32 v75, 0xffff0000, v75
	v_pk_add_f32 v[70:71], v[70:71], v[72:73]
	v_pk_add_f32 v[68:69], v[68:69], v[76:77]
	v_pk_add_f32 v[72:73], v[66:67], v[74:75]
	v_pk_add_f32 v[66:67], v[64:65], v[78:79]
	v_cvt_pk_bf16_f32 v64, v68, v69
	v_cvt_pk_bf16_f32 v65, v70, v71
	v_cvt_pk_bf16_f32 v66, v66, v67
	v_cvt_pk_bf16_f32 v67, v72, v73
	flat_store_dwordx4 v[80:81], v[64:67] offset:256
	s_nop 1
	v_lshl_add_u64 v[64:65], v[144:145], 0, s[2:3]
	s_mov_b32 s2, 0x80000
	v_add_co_u32_e32 v70, vcc, s2, v144
	s_mov_b64 s[2:3], 0x90000
	s_nop 0
	v_addc_co_u32_e32 v71, vcc, 0, v145, vcc
	flat_load_dwordx4 v[66:69], v[70:71]
	s_waitcnt vmcnt(0) lgkmcnt(0)
	v_lshlrev_b32_e32 v72, 16, v66
	v_and_b32_e32 v73, 0xffff0000, v66
	v_lshlrev_b32_e32 v66, 16, v67
	v_and_b32_e32 v67, 0xffff0000, v67
	v_lshlrev_b32_e32 v74, 16, v68
	v_and_b32_e32 v75, 0xffff0000, v68
	v_lshlrev_b32_e32 v68, 16, v69
	v_and_b32_e32 v69, 0xffff0000, v69
	v_pk_add_f32 v[62:63], v[62:63], v[66:67]
	v_pk_add_f32 v[60:61], v[60:61], v[72:73]
	v_pk_add_f32 v[66:67], v[58:59], v[68:69]
	v_pk_add_f32 v[58:59], v[56:57], v[74:75]
	v_cvt_pk_bf16_f32 v56, v60, v61
	v_cvt_pk_bf16_f32 v57, v62, v63
	v_cvt_pk_bf16_f32 v58, v58, v59
	v_cvt_pk_bf16_f32 v59, v66, v67
	flat_store_dwordx4 v[70:71], v[56:59]
	flat_load_dwordx4 v[56:59], v[64:65] offset:256
	s_waitcnt vmcnt(0) lgkmcnt(0)
; DI unsigned pack2(float a, float b) { f32x2 v = {a, b}; hwbf16x2 r = __builtin_convertvector(v, hwbf16x2); return __builtin_bit_cast(unsigned, r); }
; DI float bflo(unsigned w) { return __uint_as_float(w << 16); }
; DI float bfhi(unsigned w) { return __uint_as_float(w & 0xffff0000u); }
; #define PG8_WAIT_V(n) asm volatile("s_waitcnt vmcnt(" #n ")" ::: "memory")
; #define PG8_BAR __builtin_amdgcn_s_barrier()
;     DI void operator()(const f32x4 (&acc)[2][2][4][2], const Unit& u, int wr, int wc, int fr, int fq) const {
;     ...
;             for (int m = 0; m < 4; ++m) { const size_t ro = (size_t)(row0 + ai * HALF + m * 16) * D + col0;
; #pragma unroll
;                 for (int bj = 0; bj < 2; ++bj) {
;                     f32x4 x0, x1;
;                     if constexpr (IB) { const u32x4 w = *(const u32x4*)((const bf16_t*)Xin + ro + bj * HALF);
;                         x0 = (f32x4){bflo(w[0]), bfhi(w[0]), bflo(w[1]), bfhi(w[1])}; x1 = (f32x4){bflo(w[2]), bfhi(w[2]), bflo(w[3]), bfhi(w[3])}; }
;                     else { x0 = *(const f32x4*)((const float*)Xin + ro + bj * HALF); x1 = *(const f32x4*)((const float*)Xin + ro + bj * HALF + 4); }
;                     x0 += acc[ai][bj][m][0] * sc[bj][0]; x1 += acc[ai][bj][m][1] * sc[bj][1];
;                     if constexpr (OB) { u32x4 o; o[0] = pack2(x0[0], x0[1]); o[1] = pack2(x0[2], x0[3]); o[2] = pack2(x1[0], x1[1]); o[3] = pack2(x1[2], x1[3]);
;                         *(u32x4*)((bf16_t*)Xout + ro + bj * HALF) = o; }
;                     else { *(f32x4*)((float*)Xout + ro + bj * HALF) = x0; *(f32x4*)((float*)Xout + ro + bj * HALF + 4) = x1; } } }
; template <class Map, class Epi>
; DI void gemm_phase(LAS unsigned char* lds, const Map& MP, const Epi& E, const int nM, const int nN, const int K, const int lda, const int ldb) {
;     ...
;         cur = nxt; cA = nA; cB = nB; ++ui;
;     }
;     PG8_WAIT_V(0);
;     if (wr == 0) PG8_BAR;
;     PG8_BAR;
	v_lshlrev_b32_e32 v60, 16, v56
	v_and_b32_e32 v61, 0xffff0000, v56
	v_lshlrev_b32_e32 v56, 16, v57
	v_and_b32_e32 v57, 0xffff0000, v57
	v_lshlrev_b32_e32 v62, 16, v58
	v_and_b32_e32 v63, 0xffff0000, v58
	v_lshlrev_b32_e32 v58, 16, v59
	v_and_b32_e32 v59, 0xffff0000, v59
	v_pk_add_f32 v[54:55], v[54:55], v[56:57]
	v_pk_add_f32 v[52:53], v[52:53], v[60:61]
	v_pk_add_f32 v[56:57], v[50:51], v[58:59]
	v_pk_add_f32 v[50:51], v[48:49], v[62:63]
	v_cvt_pk_bf16_f32 v48, v52, v53
	v_cvt_pk_bf16_f32 v49, v54, v55
	v_cvt_pk_bf16_f32 v50, v50, v51
	v_cvt_pk_bf16_f32 v51, v56, v57
	flat_store_dwordx4 v[64:65], v[48:51] offset:256
	s_nop 1
	v_lshl_add_u64 v[48:49], v[144:145], 0, s[2:3]
	s_mov_b32 s2, 0x90000
	v_add_co_u32_e32 v54, vcc, s2, v144
	s_mov_b64 s[2:3], 0xa0000
	s_nop 0
	v_addc_co_u32_e32 v55, vcc, 0, v145, vcc
	flat_load_dwordx4 v[50:53], v[54:55]
	s_waitcnt vmcnt(0) lgkmcnt(0)
	v_lshlrev_b32_e32 v56, 16, v50
	v_and_b32_e32 v57, 0xffff0000, v50
	v_lshlrev_b32_e32 v50, 16, v51
	v_and_b32_e32 v51, 0xffff0000, v51
	v_lshlrev_b32_e32 v58, 16, v52
	v_and_b32_e32 v59, 0xffff0000, v52
	v_lshlrev_b32_e32 v52, 16, v53
	v_and_b32_e32 v53, 0xffff0000, v53
	v_pk_add_f32 v[46:47], v[46:47], v[50:51]
	v_pk_add_f32 v[44:45], v[44:45], v[56:57]
	v_pk_add_f32 v[50:51], v[42:43], v[52:53]
	v_pk_add_f32 v[42:43], v[40:41], v[58:59]
	v_cvt_pk_bf16_f32 v40, v44, v45
	v_cvt_pk_bf16_f32 v41, v46, v47
	v_cvt_pk_bf16_f32 v42, v42, v43
	v_cvt_pk_bf16_f32 v43, v50, v51
	flat_store_dwordx4 v[54:55], v[40:43]
	flat_load_dwordx4 v[40:43], v[48:49] offset:256
	s_waitcnt vmcnt(0) lgkmcnt(0)
	v_lshlrev_b32_e32 v44, 16, v40
	v_and_b32_e32 v45, 0xffff0000, v40
	v_lshlrev_b32_e32 v40, 16, v41
	v_and_b32_e32 v41, 0xffff0000, v41
	v_lshlrev_b32_e32 v46, 16, v42
	v_and_b32_e32 v47, 0xffff0000, v42
	v_lshlrev_b32_e32 v42, 16, v43
	v_and_b32_e32 v43, 0xffff0000, v43
	v_pk_add_f32 v[38:39], v[38:39], v[40:41]
	v_pk_add_f32 v[36:37], v[36:37], v[44:45]
	v_pk_add_f32 v[40:41], v[34:35], v[42:43]
	v_pk_add_f32 v[34:35], v[32:33], v[46:47]
	v_cvt_pk_bf16_f32 v32, v36, v37
	v_cvt_pk_bf16_f32 v33, v38, v39
	v_cvt_pk_bf16_f32 v34, v34, v35
	v_cvt_pk_bf16_f32 v35, v40, v41
	flat_store_dwordx4 v[48:49], v[32:35] offset:256
	s_nop 1
	v_lshl_add_u64 v[32:33], v[144:145], 0, s[2:3]
	s_mov_b32 s2, 0xa0000
	v_add_co_u32_e32 v38, vcc, s2, v144
	s_mov_b64 s[2:3], 0xb0000
	s_nop 0
	v_addc_co_u32_e32 v39, vcc, 0, v145, vcc
	flat_load_dwordx4 v[34:37], v[38:39]
	s_waitcnt vmcnt(0) lgkmcnt(0)
	v_lshlrev_b32_e32 v40, 16, v34
	v_and_b32_e32 v41, 0xffff0000, v34
	v_lshlrev_b32_e32 v34, 16, v35
	v_and_b32_e32 v35, 0xffff0000, v35
	v_lshlrev_b32_e32 v42, 16, v36
	v_and_b32_e32 v43, 0xffff0000, v36
	v_lshlrev_b32_e32 v36, 16, v37
	v_and_b32_e32 v37, 0xffff0000, v37
	v_pk_add_f32 v[30:31], v[30:31], v[34:35]
	v_pk_add_f32 v[28:29], v[28:29], v[40:41]
	v_pk_add_f32 v[34:35], v[26:27], v[36:37]
	v_pk_add_f32 v[26:27], v[24:25], v[42:43]
	v_cvt_pk_bf16_f32 v24, v28, v29
	v_cvt_pk_bf16_f32 v25, v30, v31
	v_cvt_pk_bf16_f32 v26, v26, v27
	v_cvt_pk_bf16_f32 v27, v34, v35
	flat_store_dwordx4 v[38:39], v[24:27]
	flat_load_dwordx4 v[24:27], v[32:33] offset:256
	s_waitcnt vmcnt(0) lgkmcnt(0)
	v_lshlrev_b32_e32 v28, 16, v24
	v_and_b32_e32 v29, 0xffff0000, v24
	v_lshlrev_b32_e32 v24, 16, v25
	v_and_b32_e32 v25, 0xffff0000, v25
	v_lshlrev_b32_e32 v30, 16, v26
	v_and_b32_e32 v31, 0xffff0000, v26
	v_lshlrev_b32_e32 v26, 16, v27
	v_and_b32_e32 v27, 0xffff0000, v27
	v_pk_add_f32 v[22:23], v[22:23], v[24:25]
	v_pk_add_f32 v[20:21], v[20:21], v[28:29]
	v_pk_add_f32 v[24:25], v[18:19], v[26:27]
	v_pk_add_f32 v[18:19], v[16:17], v[30:31]
	v_cvt_pk_bf16_f32 v16, v20, v21
	v_cvt_pk_bf16_f32 v17, v22, v23
	v_cvt_pk_bf16_f32 v18, v18, v19
	v_cvt_pk_bf16_f32 v19, v24, v25
	flat_store_dwordx4 v[32:33], v[16:19] offset:256
	s_nop 1
	v_lshl_add_u64 v[16:17], v[144:145], 0, s[2:3]
	s_mov_b32 s2, 0xb0000
	v_add_co_u32_e32 v22, vcc, s2, v144
	s_mov_b32 s2, s44
	s_nop 0
	v_addc_co_u32_e32 v23, vcc, 0, v145, vcc
	flat_load_dwordx4 v[18:21], v[22:23]
	s_and_b64 vcc, exec, s[40:41]
	s_waitcnt vmcnt(0) lgkmcnt(0)
	v_lshlrev_b32_e32 v24, 16, v18
	v_and_b32_e32 v25, 0xffff0000, v18
	v_lshlrev_b32_e32 v18, 16, v19
	v_and_b32_e32 v19, 0xffff0000, v19
	v_lshlrev_b32_e32 v26, 16, v20
	v_and_b32_e32 v27, 0xffff0000, v20
	v_lshlrev_b32_e32 v20, 16, v21
	v_and_b32_e32 v21, 0xffff0000, v21
	v_pk_add_f32 v[14:15], v[14:15], v[18:19]
	v_pk_add_f32 v[12:13], v[12:13], v[24:25]
	v_pk_add_f32 v[18:19], v[10:11], v[20:21]
	v_pk_add_f32 v[10:11], v[8:9], v[26:27]
	v_cvt_pk_bf16_f32 v8, v12, v13
	v_cvt_pk_bf16_f32 v9, v14, v15
	v_cvt_pk_bf16_f32 v10, v10, v11
	v_cvt_pk_bf16_f32 v11, v18, v19
	flat_store_dwordx4 v[22:23], v[8:11]
	flat_load_dwordx4 v[8:11], v[16:17] offset:256
	s_waitcnt vmcnt(0) lgkmcnt(0)
	v_lshlrev_b32_e32 v12, 16, v8
	v_and_b32_e32 v13, 0xffff0000, v8
	v_lshlrev_b32_e32 v8, 16, v9
	v_and_b32_e32 v9, 0xffff0000, v9
	v_lshlrev_b32_e32 v14, 16, v10
	v_and_b32_e32 v15, 0xffff0000, v10
	v_lshlrev_b32_e32 v10, 16, v11
	v_and_b32_e32 v11, 0xffff0000, v11
	v_pk_add_f32 v[6:7], v[6:7], v[8:9]
	v_pk_add_f32 v[4:5], v[4:5], v[12:13]
	v_pk_add_f32 v[8:9], v[2:3], v[10:11]
	v_pk_add_f32 v[2:3], v[0:1], v[14:15]
	v_cvt_pk_bf16_f32 v0, v4, v5
	v_cvt_pk_bf16_f32 v1, v6, v7
	v_cvt_pk_bf16_f32 v2, v2, v3
	v_cvt_pk_bf16_f32 v3, v8, v9
	flat_store_dwordx4 v[16:17], v[0:3] offset:256
	s_cbranch_vccz .LBB1_1761
	s_waitcnt vmcnt(0)
	s_cmpk_gt_u32 s17, 0xff
	s_cbranch_scc1 .LBB1_1768
	s_barrier

; #define PG8_STAGE(bufoff, gbase, voff) do { _Pragma("unroll") for (int _i = 0; _i < 2; ++_i) \
;         __builtin_amdgcn_global_load_lds((const unsigned*)((const char*)(gbase) + (voff)[_i]), (LAS unsigned*)(lds + (bufoff) + ldsw + _i * 8192), 16, 0, 0); } while (0)
; #define PG8_LDA(dst, b, h) do { _Pragma("unroll") for (int m = 0; m < 4; ++m) _Pragma("unroll") for (int k = 0; k < 2; ++k) dst[m][k] = *(const LAS bf16x8*)(lds + PG8_SA(b, h) + aoff + m * 2048 + k * 1024); } while (0)
; #define PG8_LDB(dst, b, h) do { _Pragma("unroll") for (int n = 0; n < 2; ++n) _Pragma("unroll") for (int k = 0; k < 2; ++k) dst[n][k] = *(const LAS bf16x8*)(lds + PG8_SB(b, h) + boff + n * 2048 + k * 1024); } while (0)
; #define PG8_MMA(ai, bj, At, Bt) do { __builtin_amdgcn_s_setprio(1); _Pragma("unroll") for (int m = 0; m < 4; ++m) _Pragma("unroll") for (int n = 0; n < 2; ++n) _Pragma("unroll") for (int k = 0; k < 2; ++k) \
;         acc[ai][bj][m][n] = __builtin_amdgcn_mfma_f32_16x16x32_bf16(Bt[n][k], At[m][k], acc[ai][bj][m][n], 0, 0, 0); __builtin_amdgcn_s_setprio(0); } while (0)
; #define PG8_WAIT_L(n) asm volatile("s_waitcnt lgkmcnt(" #n ")" ::: "memory")
; #define PG8_BAR __builtin_amdgcn_s_barrier()
; #define PG8_SCHED __builtin_amdgcn_sched_barrier(0)
; template <class Map, class Epi>
; DI void gemm_phase(LAS unsigned char* lds, const Map& MP, const Epi& E, const int nM, const int nN, const int K, const int lda, const int ldb) {
;     ...
;             const bool last = (t == nt - 2);
;             const char* a1 = cA + (size_t)(t + 1) * kstep;
;             const char* a2 = last ? nA : cA + (size_t)(t + 2) * kstep; const char* b2 = last ? nB : cB + (size_t)(t + 2) * kstep;
;             const char* a3 = a2 + kstep; const char* b3 = b2 + kstep;
;             PG8_LDB(B0, 0, 0); PG8_SCHED; PG8_LDA(At, 0, 0); PG8_STAGE(PG8_SA(1, 1), a1 + hstepA, voffA);
;             PG8_WAIT_L(8); PG8_BAR; PG8_WAIT_L(0); PG8_MMA(0, 0, At, B0); PG8_BAR; PG8_SCHED;
;             PG8_LDB(B1, 0, 1); PG8_STAGE(PG8_SB(0, 0), b2, voffB);
;             PG8_BAR; PG8_WAIT_L(0); PG8_MMA(0, 1, At, B1); PG8_BAR;
;             PG8_LDA(At, 0, 1); PG8_STAGE(PG8_SA(0, 0), a2, voffA);
;             PG8_BAR; PG8_WAIT_L(0); PG8_MMA(1, 0, At, B0); PG8_BAR; PG8_SCHED;
.LBB1_1908:
	ds_read_b128 v[80:83], v189
	ds_read_b128 v[84:87], v189 offset:1024
	ds_read_b128 v[88:91], v189 offset:2048
	ds_read_b128 v[92:95], v189 offset:3072
	s_add_u32 s28, s42, 0xfff80080
	s_addc_u32 s29, s43, -1
	s_cmp_eq_u32 s3, 28
	s_cselect_b32 s47, s23, s29
	s_cselect_b32 s46, s58, s28
	s_cselect_b32 s29, s21, vcc_hi
	s_cselect_b32 s28, s59, vcc_lo
	v_lshl_add_u64 v[184:185], s[42:43], 0, v[178:179]
	s_add_i32 m0, s38, 0xc000
	ds_read_b128 v[96:99], v190
	ds_read_b128 v[100:103], v190 offset:1024
	ds_read_b128 v[108:111], v190 offset:2048
	ds_read_b128 v[112:115], v190 offset:3072
	ds_read_b128 v[160:163], v190 offset:4096
	ds_read_b128 v[164:167], v190 offset:5120
	ds_read_b128 v[198:201], v190 offset:6144
	ds_read_b128 v[202:205], v190 offset:7168
	global_load_lds_dwordx4 v[184:185], off
	v_lshl_add_u64 v[184:185], s[42:43], 0, v[176:177]
	s_add_i32 m0, s38, 0xe000
	s_nop 0
	global_load_lds_dwordx4 v[184:185], off
	s_waitcnt lgkmcnt(8)
	s_barrier
	s_setprio 1
	s_waitcnt lgkmcnt(7)
	v_mfma_f32_16x16x32_bf16 v[148:151], v[80:83], v[96:99], v[148:151]
	v_mfma_f32_16x16x32_bf16 v[144:147], v[88:91], v[96:99], v[144:147]
	s_waitcnt lgkmcnt(5)
	v_mfma_f32_16x16x32_bf16 v[136:139], v[80:83], v[108:111], v[136:139]
	v_mfma_f32_16x16x32_bf16 v[128:131], v[88:91], v[108:111], v[128:131]
	s_waitcnt lgkmcnt(3)
	v_mfma_f32_16x16x32_bf16 v[120:123], v[80:83], v[160:163], v[120:123]
	v_mfma_f32_16x16x32_bf16 v[104:107], v[88:91], v[160:163], v[104:107]
	s_waitcnt lgkmcnt(1)
	v_mfma_f32_16x16x32_bf16 v[76:79], v[80:83], v[198:201], v[76:79]
	v_mfma_f32_16x16x32_bf16 v[72:75], v[88:91], v[198:201], v[72:75]
	v_mfma_f32_16x16x32_bf16 v[148:151], v[84:87], v[100:103], v[148:151]
	v_mfma_f32_16x16x32_bf16 v[144:147], v[92:95], v[100:103], v[144:147]
	v_mfma_f32_16x16x32_bf16 v[136:139], v[84:87], v[112:115], v[136:139]
	v_mfma_f32_16x16x32_bf16 v[128:131], v[92:95], v[112:115], v[128:131]
	v_mfma_f32_16x16x32_bf16 v[120:123], v[84:87], v[164:167], v[120:123]
	v_mfma_f32_16x16x32_bf16 v[104:107], v[92:95], v[164:167], v[104:107]
	s_waitcnt lgkmcnt(0)
	v_mfma_f32_16x16x32_bf16 v[76:79], v[84:87], v[202:205], v[76:79]
	v_mfma_f32_16x16x32_bf16 v[72:75], v[92:95], v[202:205], v[72:75]
	s_setprio 0
	s_barrier
	s_add_i32 s68, s2, s54
	v_lshl_add_u64 v[184:185], s[28:29], 0, v[172:173]
	s_mov_b32 m0, s68
	ds_read_b128 v[206:209], v191
	ds_read_b128 v[210:213], v191 offset:1024
	ds_read_b128 v[214:217], v191 offset:2048
	ds_read_b128 v[218:221], v191 offset:3072
	global_load_lds_dwordx4 v[184:185], off
	v_lshl_add_u64 v[194:195], s[28:29], 0, v[168:169]
	s_add_i32 m0, s68, 0x2000
	s_nop 0
	global_load_lds_dwordx4 v[194:195], off
	s_barrier
	s_setprio 1
	s_waitcnt lgkmcnt(3)
	v_mfma_f32_16x16x32_bf16 v[156:159], v[206:209], v[96:99], v[156:159]
	s_waitcnt lgkmcnt(1)
	v_mfma_f32_16x16x32_bf16 v[96:99], v[214:217], v[96:99], v[152:155]
	v_mfma_f32_16x16x32_bf16 v[156:159], v[210:213], v[100:103], v[156:159]
	s_waitcnt lgkmcnt(0)
	v_mfma_f32_16x16x32_bf16 v[96:99], v[218:221], v[100:103], v[96:99]
	v_mfma_f32_16x16x32_bf16 v[100:103], v[206:209], v[108:111], v[140:143]
	v_mfma_f32_16x16x32_bf16 v[108:111], v[214:217], v[108:111], v[132:135]
	v_mfma_f32_16x16x32_bf16 v[116:119], v[214:217], v[160:163], v[116:119]
	v_mfma_f32_16x16x32_bf16 v[68:71], v[206:209], v[198:201], v[68:71]
	v_mfma_f32_16x16x32_bf16 v[64:67], v[214:217], v[198:201], v[64:67]
	v_mfma_f32_16x16x32_bf16 v[100:103], v[210:213], v[112:115], v[100:103]
	v_mfma_f32_16x16x32_bf16 v[108:111], v[218:221], v[112:115], v[108:111]
	v_mfma_f32_16x16x32_bf16 v[112:115], v[206:209], v[160:163], v[124:127]
	v_mfma_f32_16x16x32_bf16 v[116:119], v[218:221], v[164:167], v[116:119]
	v_mfma_f32_16x16x32_bf16 v[68:71], v[210:213], v[202:205], v[68:71]
	v_mfma_f32_16x16x32_bf16 v[64:67], v[218:221], v[202:205], v[64:67]
	v_mfma_f32_16x16x32_bf16 v[112:115], v[210:213], v[164:167], v[112:115]
	s_setprio 0
	s_mov_b32 m0, s38
	v_lshl_add_u64 v[226:227], s[46:47], 0, v[174:175]
	s_barrier
	ds_read_b128 v[124:127], v190 offset:16384
	ds_read_b128 v[132:135], v190 offset:17408
	ds_read_b128 v[140:143], v190 offset:18432
	ds_read_b128 v[152:155], v190 offset:19456
	ds_read_b128 v[160:163], v190 offset:20480
	ds_read_b128 v[164:167], v190 offset:21504
	ds_read_b128 v[198:201], v190 offset:22528
	ds_read_b128 v[202:205], v190 offset:23552
	global_load_lds_dwordx4 v[226:227], off
	v_lshl_add_u64 v[234:235], s[46:47], 0, v[170:171]
	s_mov_b32 m0, s39
	s_nop 0
	global_load_lds_dwordx4 v[234:235], off
	s_barrier
	s_setprio 1
	s_waitcnt lgkmcnt(7)
	v_mfma_f32_16x16x32_bf16 v[60:63], v[80:83], v[124:127], v[60:63]
	v_mfma_f32_16x16x32_bf16 v[48:51], v[88:91], v[124:127], v[48:51]
	s_waitcnt lgkmcnt(5)
	v_mfma_f32_16x16x32_bf16 v[40:43], v[80:83], v[140:143], v[40:43]
	v_mfma_f32_16x16x32_bf16 v[32:35], v[88:91], v[140:143], v[32:35]
	s_waitcnt lgkmcnt(3)
	v_mfma_f32_16x16x32_bf16 v[24:27], v[80:83], v[160:163], v[24:27]
	v_mfma_f32_16x16x32_bf16 v[16:19], v[88:91], v[160:163], v[16:19]
	s_waitcnt lgkmcnt(1)
	v_mfma_f32_16x16x32_bf16 v[12:15], v[80:83], v[198:201], v[12:15]
	v_mfma_f32_16x16x32_bf16 v[8:11], v[88:91], v[198:201], v[8:11]
	v_mfma_f32_16x16x32_bf16 v[60:63], v[84:87], v[132:135], v[60:63]
	v_mfma_f32_16x16x32_bf16 v[48:51], v[92:95], v[132:135], v[48:51]
	v_mfma_f32_16x16x32_bf16 v[40:43], v[84:87], v[152:155], v[40:43]
	v_mfma_f32_16x16x32_bf16 v[32:35], v[92:95], v[152:155], v[32:35]
	v_mfma_f32_16x16x32_bf16 v[24:27], v[84:87], v[164:167], v[24:27]
	v_mfma_f32_16x16x32_bf16 v[16:19], v[92:95], v[164:167], v[16:19]
	s_waitcnt lgkmcnt(0)
	v_mfma_f32_16x16x32_bf16 v[12:15], v[84:87], v[202:205], v[12:15]
	v_mfma_f32_16x16x32_bf16 v[8:11], v[92:95], v[202:205], v[8:11]
	s_setprio 0
	s_barrier
; #define PG8_STAGE(bufoff, gbase, voff) do { _Pragma("unroll") for (int _i = 0; _i < 2; ++_i) \
;         __builtin_amdgcn_global_load_lds((const unsigned*)((const char*)(gbase) + (voff)[_i]), (LAS unsigned*)(lds + (bufoff) + ldsw + _i * 8192), 16, 0, 0); } while (0)
; #define PG8_LDA(dst, b, h) do { _Pragma("unroll") for (int m = 0; m < 4; ++m) _Pragma("unroll") for (int k = 0; k < 2; ++k) dst[m][k] = *(const LAS bf16x8*)(lds + PG8_SA(b, h) + aoff + m * 2048 + k * 1024); } while (0)
; #define PG8_LDB(dst, b, h) do { _Pragma("unroll") for (int n = 0; n < 2; ++n) _Pragma("unroll") for (int k = 0; k < 2; ++k) dst[n][k] = *(const LAS bf16x8*)(lds + PG8_SB(b, h) + boff + n * 2048 + k * 1024); } while (0)
; #define PG8_MMA(ai, bj, At, Bt) do { __builtin_amdgcn_s_setprio(1); _Pragma("unroll") for (int m = 0; m < 4; ++m) _Pragma("unroll") for (int n = 0; n < 2; ++n) _Pragma("unroll") for (int k = 0; k < 2; ++k) \
;         acc[ai][bj][m][n] = __builtin_amdgcn_mfma_f32_16x16x32_bf16(Bt[n][k], At[m][k], acc[ai][bj][m][n], 0, 0, 0); __builtin_amdgcn_s_setprio(0); } while (0)
; #define PG8_WAIT_V(n) asm volatile("s_waitcnt vmcnt(" #n ")" ::: "memory")
; #define PG8_WAIT_L(n) asm volatile("s_waitcnt lgkmcnt(" #n ")" ::: "memory")
; #define PG8_BAR __builtin_amdgcn_s_barrier()
; #define PG8_SCHED __builtin_amdgcn_sched_barrier(0)
; template <class Map, class Epi>
; DI void gemm_phase(LAS unsigned char* lds, const Map& MP, const Epi& E, const int nM, const int nN, const int K, const int lda, const int ldb) {
;     ...
;             PG8_STAGE(PG8_SB(0, 1), b2 + hstepB, voffB);
;             PG8_WAIT_V(6); PG8_BAR; PG8_MMA(1, 1, At, B1); PG8_BAR;
;             PG8_LDB(B0, 1, 0); PG8_SCHED; PG8_LDA(At, 1, 0); PG8_STAGE(PG8_SA(0, 1), a2 + hstepA, voffA);
;             PG8_WAIT_L(8); PG8_BAR; PG8_WAIT_L(0); PG8_MMA(0, 0, At, B0); PG8_BAR; PG8_SCHED;
;             PG8_LDB(B1, 1, 1); PG8_STAGE(PG8_SB(1, 0), b3, voffB);
;             PG8_BAR; PG8_WAIT_L(0); PG8_MMA(0, 1, At, B1); PG8_BAR;
	s_add_u32 s68, s28, 0x80000
	s_addc_u32 s69, s29, 0
	s_add_i32 s70, s31, s54
	v_lshl_add_u64 v[80:81], s[68:69], 0, v[172:173]
	s_mov_b32 m0, s70
	s_nop 0
	global_load_lds_dwordx4 v[80:81], off
	v_lshl_add_u64 v[80:81], s[68:69], 0, v[168:169]
	s_add_i32 m0, s70, 0x2000
	s_nop 0
	global_load_lds_dwordx4 v[80:81], off
	s_waitcnt vmcnt(6)
	s_barrier
	s_setprio 1
	v_mfma_f32_16x16x32_bf16 v[56:59], v[206:209], v[124:127], v[56:59]
	v_mfma_f32_16x16x32_bf16 v[52:55], v[214:217], v[124:127], v[52:55]
	v_mfma_f32_16x16x32_bf16 v[44:47], v[206:209], v[140:143], v[44:47]
	v_mfma_f32_16x16x32_bf16 v[36:39], v[214:217], v[140:143], v[36:39]
	v_mfma_f32_16x16x32_bf16 v[28:31], v[206:209], v[160:163], v[28:31]
	v_mfma_f32_16x16x32_bf16 v[20:23], v[214:217], v[160:163], v[20:23]
	v_mfma_f32_16x16x32_bf16 v[4:7], v[206:209], v[198:201], v[4:7]
	v_mfma_f32_16x16x32_bf16 v[0:3], v[214:217], v[198:201], v[0:3]
	v_mfma_f32_16x16x32_bf16 v[56:59], v[210:213], v[132:135], v[56:59]
	v_mfma_f32_16x16x32_bf16 v[52:55], v[218:221], v[132:135], v[52:55]
	v_mfma_f32_16x16x32_bf16 v[44:47], v[210:213], v[152:155], v[44:47]
	v_mfma_f32_16x16x32_bf16 v[36:39], v[218:221], v[152:155], v[36:39]
	v_mfma_f32_16x16x32_bf16 v[28:31], v[210:213], v[164:167], v[28:31]
	v_mfma_f32_16x16x32_bf16 v[20:23], v[218:221], v[164:167], v[20:23]
	v_mfma_f32_16x16x32_bf16 v[4:7], v[210:213], v[202:205], v[4:7]
	v_mfma_f32_16x16x32_bf16 v[0:3], v[218:221], v[202:205], v[0:3]
	s_setprio 0
	s_add_i32 s68, 0, 0x18000
	v_add_u32_e32 v92, s68, v188
	s_barrier
	ds_read_b128 v[80:83], v92
	ds_read_b128 v[84:87], v92 offset:1024
	ds_read_b128 v[88:91], v92 offset:2048
	ds_read_b128 v[92:95], v92 offset:3072
	s_add_u32 s46, s46, 0x80000
	s_addc_u32 s47, s47, 0
	s_mov_b32 m0, s56
	v_lshl_add_u64 v[140:141], s[46:47], 0, v[174:175]
	ds_read_b128 v[124:127], v190 offset:32768
	ds_read_b128 v[132:135], v190 offset:33792
	ds_read_b128 v[160:163], v190 offset:34816
	ds_read_b128 v[164:167], v190 offset:35840
	ds_read_b128 v[198:201], v190 offset:36864
	ds_read_b128 v[202:205], v190 offset:37888
	ds_read_b128 v[206:209], v190 offset:38912
	ds_read_b128 v[210:213], v190 offset:39936
	global_load_lds_dwordx4 v[140:141], off
	v_lshl_add_u64 v[140:141], s[46:47], 0, v[170:171]
	s_mov_b32 m0, s57
	s_nop 0
	global_load_lds_dwordx4 v[140:141], off
	s_waitcnt lgkmcnt(8)
	s_barrier
	s_setprio 1
	s_waitcnt lgkmcnt(7)
	v_mfma_f32_16x16x32_bf16 v[140:143], v[80:83], v[124:127], v[148:151]
	s_waitcnt lgkmcnt(6)
	v_mfma_f32_16x16x32_bf16 v[148:151], v[84:87], v[132:135], v[140:143]
	v_mfma_f32_16x16x32_bf16 v[140:143], v[88:91], v[124:127], v[144:147]
	s_waitcnt lgkmcnt(5)
	v_mfma_f32_16x16x32_bf16 v[136:139], v[80:83], v[160:163], v[136:139]
	v_mfma_f32_16x16x32_bf16 v[128:131], v[88:91], v[160:163], v[128:131]
	s_waitcnt lgkmcnt(3)
	v_mfma_f32_16x16x32_bf16 v[120:123], v[80:83], v[198:201], v[120:123]
	v_mfma_f32_16x16x32_bf16 v[104:107], v[88:91], v[198:201], v[104:107]
	s_waitcnt lgkmcnt(1)
	v_mfma_f32_16x16x32_bf16 v[76:79], v[80:83], v[206:209], v[76:79]
	v_mfma_f32_16x16x32_bf16 v[72:75], v[88:91], v[206:209], v[72:75]
	v_mfma_f32_16x16x32_bf16 v[144:147], v[92:95], v[132:135], v[140:143]
	v_mfma_f32_16x16x32_bf16 v[136:139], v[84:87], v[164:167], v[136:139]
	v_mfma_f32_16x16x32_bf16 v[128:131], v[92:95], v[164:167], v[128:131]
	v_mfma_f32_16x16x32_bf16 v[120:123], v[84:87], v[202:205], v[120:123]
	v_mfma_f32_16x16x32_bf16 v[104:107], v[92:95], v[202:205], v[104:107]
	s_waitcnt lgkmcnt(0)
	v_mfma_f32_16x16x32_bf16 v[76:79], v[84:87], v[210:213], v[76:79]
	v_mfma_f32_16x16x32_bf16 v[72:75], v[92:95], v[210:213], v[72:75]
	s_setprio 0
	s_barrier
	s_add_i32 s46, 0, 0x1c000
	v_add_u32_e32 v140, s46, v188
	s_add_i32 s47, s68, s54
	ds_read_b128 v[214:217], v140
	ds_read_b128 v[218:221], v140 offset:1024
	ds_read_b128 v[222:225], v140 offset:2048
	ds_read_b128 v[230:233], v140 offset:3072
	v_lshl_add_u64 v[140:141], v[184:185], 0, s[14:15]
	s_mov_b32 m0, s47
	s_nop 0
	global_load_lds_dwordx4 v[140:141], off
	v_lshl_add_u64 v[140:141], v[194:195], 0, s[14:15]
	s_add_i32 m0, s47, 0x2000
	s_nop 0
	global_load_lds_dwordx4 v[140:141], off
	s_barrier
	s_setprio 1
	s_waitcnt lgkmcnt(1)
	v_mfma_f32_16x16x32_bf16 v[96:99], v[222:225], v[124:127], v[96:99]
	v_mfma_f32_16x16x32_bf16 v[140:143], v[214:217], v[124:127], v[156:159]
	s_waitcnt lgkmcnt(0)
	v_mfma_f32_16x16x32_bf16 v[152:155], v[230:233], v[132:135], v[96:99]
	v_mfma_f32_16x16x32_bf16 v[96:99], v[214:217], v[160:163], v[100:103]
	v_mfma_f32_16x16x32_bf16 v[156:159], v[218:221], v[132:135], v[140:143]
	v_mfma_f32_16x16x32_bf16 v[140:143], v[218:221], v[164:167], v[96:99]
	v_mfma_f32_16x16x32_bf16 v[96:99], v[222:225], v[160:163], v[108:111]
	v_mfma_f32_16x16x32_bf16 v[132:135], v[230:233], v[164:167], v[96:99]
	v_mfma_f32_16x16x32_bf16 v[96:99], v[214:217], v[198:201], v[112:115]
	v_mfma_f32_16x16x32_bf16 v[124:127], v[218:221], v[202:205], v[96:99]
	v_mfma_f32_16x16x32_bf16 v[96:99], v[222:225], v[198:201], v[116:119]
	v_mfma_f32_16x16x32_bf16 v[68:71], v[214:217], v[206:209], v[68:71]
	v_mfma_f32_16x16x32_bf16 v[64:67], v[222:225], v[206:209], v[64:67]
	v_mfma_f32_16x16x32_bf16 v[116:119], v[230:233], v[202:205], v[96:99]
	v_mfma_f32_16x16x32_bf16 v[68:71], v[218:221], v[210:213], v[68:71]
	v_mfma_f32_16x16x32_bf16 v[64:67], v[230:233], v[210:213], v[64:67]
	s_setprio 0
	s_mov_b32 m0, s63
	v_lshl_add_u64 v[184:185], v[226:227], 0, s[14:15]
	s_barrier
; #define PG8_STAGE(bufoff, gbase, voff) do { _Pragma("unroll") for (int _i = 0; _i < 2; ++_i) \
;         __builtin_amdgcn_global_load_lds((const unsigned*)((const char*)(gbase) + (voff)[_i]), (LAS unsigned*)(lds + (bufoff) + ldsw + _i * 8192), 16, 0, 0); } while (0)
; #define PG8_LDA(dst, b, h) do { _Pragma("unroll") for (int m = 0; m < 4; ++m) _Pragma("unroll") for (int k = 0; k < 2; ++k) dst[m][k] = *(const LAS bf16x8*)(lds + PG8_SA(b, h) + aoff + m * 2048 + k * 1024); } while (0)
; #define PG8_MMA(ai, bj, At, Bt) do { __builtin_amdgcn_s_setprio(1); _Pragma("unroll") for (int m = 0; m < 4; ++m) _Pragma("unroll") for (int n = 0; n < 2; ++n) _Pragma("unroll") for (int k = 0; k < 2; ++k) \
;         acc[ai][bj][m][n] = __builtin_amdgcn_mfma_f32_16x16x32_bf16(Bt[n][k], At[m][k], acc[ai][bj][m][n], 0, 0, 0); __builtin_amdgcn_s_setprio(0); } while (0)
; #define PG8_WAIT_V(n) asm volatile("s_waitcnt vmcnt(" #n ")" ::: "memory")
; #define PG8_WAIT_L(n) asm volatile("s_waitcnt lgkmcnt(" #n ")" ::: "memory")
; #define PG8_BAR __builtin_amdgcn_s_barrier()
; #define PG8_SCHED __builtin_amdgcn_sched_barrier(0)
; template <class Map, class Epi>
; DI void gemm_phase(LAS unsigned char* lds, const Map& MP, const Epi& E, const int nM, const int nN, const int K, const int lda, const int ldb) {
;     ...
;             PG8_LDA(At, 1, 1); PG8_STAGE(PG8_SA(1, 0), a3, voffA);
;             PG8_BAR; PG8_WAIT_L(0); PG8_MMA(1, 0, At, B0); PG8_BAR; PG8_SCHED;
;             PG8_STAGE(PG8_SB(1, 1), b3 + hstepB, voffB);
;             PG8_WAIT_V(6); PG8_BAR; PG8_MMA(1, 1, At, B1); PG8_BAR;
	ds_read_b128 v[96:99], v190 offset:49152
	ds_read_b128 v[100:103], v190 offset:50176
	ds_read_b128 v[108:111], v190 offset:51200
	ds_read_b128 v[112:115], v190 offset:52224
	ds_read_b128 v[160:163], v190 offset:53248
	ds_read_b128 v[164:167], v190 offset:54272
	ds_read_b128 v[198:201], v190 offset:55296
	ds_read_b128 v[202:205], v190 offset:56320
	global_load_lds_dwordx4 v[184:185], off
	v_lshl_add_u64 v[184:185], v[234:235], 0, s[14:15]
	s_mov_b32 m0, s66
	s_nop 0
	global_load_lds_dwordx4 v[184:185], off
	s_barrier
	s_setprio 1
	s_waitcnt lgkmcnt(7)
	v_mfma_f32_16x16x32_bf16 v[60:63], v[80:83], v[96:99], v[60:63]
	v_mfma_f32_16x16x32_bf16 v[48:51], v[88:91], v[96:99], v[48:51]
	s_waitcnt lgkmcnt(5)
	v_mfma_f32_16x16x32_bf16 v[40:43], v[80:83], v[108:111], v[40:43]
	v_mfma_f32_16x16x32_bf16 v[32:35], v[88:91], v[108:111], v[32:35]
	s_waitcnt lgkmcnt(3)
	v_mfma_f32_16x16x32_bf16 v[24:27], v[80:83], v[160:163], v[24:27]
	v_mfma_f32_16x16x32_bf16 v[16:19], v[88:91], v[160:163], v[16:19]
	s_waitcnt lgkmcnt(1)
	v_mfma_f32_16x16x32_bf16 v[12:15], v[80:83], v[198:201], v[12:15]
	v_mfma_f32_16x16x32_bf16 v[8:11], v[88:91], v[198:201], v[8:11]
	v_mfma_f32_16x16x32_bf16 v[60:63], v[84:87], v[100:103], v[60:63]
	v_mfma_f32_16x16x32_bf16 v[48:51], v[92:95], v[100:103], v[48:51]
	v_mfma_f32_16x16x32_bf16 v[40:43], v[84:87], v[112:115], v[40:43]
	v_mfma_f32_16x16x32_bf16 v[32:35], v[92:95], v[112:115], v[32:35]
	v_mfma_f32_16x16x32_bf16 v[24:27], v[84:87], v[164:167], v[24:27]
	v_mfma_f32_16x16x32_bf16 v[16:19], v[92:95], v[164:167], v[16:19]
	s_waitcnt lgkmcnt(0)
	v_mfma_f32_16x16x32_bf16 v[12:15], v[84:87], v[202:205], v[12:15]
	v_mfma_f32_16x16x32_bf16 v[8:11], v[92:95], v[202:205], v[8:11]
	s_setprio 0
	s_barrier
	s_add_u32 s28, s28, 0x80080
	s_addc_u32 s29, s29, 0
	s_add_i32 s46, s46, s54
	v_lshl_add_u64 v[80:81], s[28:29], 0, v[172:173]
	s_mov_b32 m0, s46
	s_nop 0
	global_load_lds_dwordx4 v[80:81], off
	v_lshl_add_u64 v[80:81], s[28:29], 0, v[168:169]
	s_add_i32 m0, s46, 0x2000
	s_nop 0
	global_load_lds_dwordx4 v[80:81], off
	s_waitcnt vmcnt(6)
	s_barrier
	s_setprio 1
	v_mfma_f32_16x16x32_bf16 v[56:59], v[214:217], v[96:99], v[56:59]
	v_mfma_f32_16x16x32_bf16 v[52:55], v[222:225], v[96:99], v[52:55]
	v_mfma_f32_16x16x32_bf16 v[44:47], v[214:217], v[108:111], v[44:47]
	v_mfma_f32_16x16x32_bf16 v[36:39], v[222:225], v[108:111], v[36:39]
	v_mfma_f32_16x16x32_bf16 v[28:31], v[214:217], v[160:163], v[28:31]
	v_mfma_f32_16x16x32_bf16 v[20:23], v[222:225], v[160:163], v[20:23]
	v_mfma_f32_16x16x32_bf16 v[4:7], v[214:217], v[198:201], v[4:7]
	v_mfma_f32_16x16x32_bf16 v[0:3], v[222:225], v[198:201], v[0:3]
	v_mfma_f32_16x16x32_bf16 v[56:59], v[218:221], v[100:103], v[56:59]
	v_mfma_f32_16x16x32_bf16 v[52:55], v[230:233], v[100:103], v[52:55]
	v_mfma_f32_16x16x32_bf16 v[44:47], v[218:221], v[112:115], v[44:47]
	v_mfma_f32_16x16x32_bf16 v[36:39], v[230:233], v[112:115], v[36:39]
	v_mfma_f32_16x16x32_bf16 v[28:31], v[218:221], v[164:167], v[28:31]
	v_mfma_f32_16x16x32_bf16 v[20:23], v[230:233], v[164:167], v[20:23]
	v_mfma_f32_16x16x32_bf16 v[4:7], v[218:221], v[202:205], v[4:7]
	v_mfma_f32_16x16x32_bf16 v[0:3], v[230:233], v[202:205], v[0:3]
	s_setprio 0
	s_add_i32 s3, s3, 2
	s_add_u32 vcc_lo, vcc_lo, 0x100
	s_addc_u32 vcc_hi, vcc_hi, 0
	s_add_u32 s42, s42, 0x100
	s_addc_u32 s43, s43, 0
	s_cmp_gt_u32 s3, 29
	s_barrier
	s_cbranch_scc0 .LBB1_1908
; DI float silu_mul(float g, float v) { return g * v * __builtin_amdgcn_rcpf(1.0f + __builtin_amdgcn_exp2f(-LOG2E * g)); }
;     DI void operator()(const f32x4 (&acc)[2][2][4][2], const Unit& u, int wr, int wc, int fr, int fq) const {
;         const int row0 = u.pm * BM + wr * 64 + fr, ch0 = u.pn * 128 + wc * 32 + 8 * fq;
;         f32x4 w0[2], w1[2], w2[2], bb[2];
; #pragma unroll
;         for (int n = 0; n < 2; ++n) { w0[n] = *(const f32x4*)(cw + ch0 + 4 * n); w1[n] = *(const f32x4*)(cw + DFF + ch0 + 4 * n); w2[n] = *(const f32x4*)(cw + 2 * DFF + ch0 + 4 * n); bb[n] = *(const f32x4*)(cb + ch0 + 4 * n); }
; #pragma unroll
;         for (int ai = 0; ai < 2; ++ai)
; #pragma unroll
;             for (int m = 0; m < 4; ++m) {
;                 const bool efirst = (m == 0) && (fr == 0), elast = (m == 3) && (fr == 15);
;                 const int row = row0 + ai * HALF + m * 16;
;                 f32x4 gc[2];
; #pragma unroll
;                 for (int n = 0; n < 2; ++n) {
;                     const f32x4 g = acc[ai][0][m][n];
;                     const f32x4 gprev = acc[ai][0][m > 0 ? m - 1 : 0][n], gnext = acc[ai][0][m < 3 ? m + 1 : 3][n];
;                     f32x4 up, dn;
; #pragma unroll
;                     for (int e = 0; e < 4; ++e) {
;                         const float pu = (m > 0 && fr == 15) ? gprev[e] : g[e];
;                         const float pd = (m < 3 && fr == 0) ? gnext[e] : g[e];
;                         up[e] = dpp_ror1(pu); dn[e] = dpp_ror15(pd);
;                     }
;                     if (efirst) up = (f32x4){0.f, 0.f, 0.f, 0.f};
;                     if (elast) dn = (f32x4){0.f, 0.f, 0.f, 0.f};
;                     gc[n] = w0[n] * up + w1[n] * g + w2[n] * dn + bb[n];
;                 }
;                 if (efirst || elast) {
;                     const size_t eo = (size_t)((row >> 6) * 2 + (elast ? 1 : 0)) * DFF + ch0;
; #pragma unroll
;                     for (int n = 0; n < 2; ++n) { *(f32x4*)(EP + eo + 4 * n) = gc[n]; *(f32x4*)(ER + eo + 4 * n) = acc[ai][0][m][n]; *(f32x4*)(EV + eo + 4 * n) = acc[ai][1][m][n]; }
;                 } else {
;                     const f32x4 v0 = acc[ai][1][m][0], v1 = acc[ai][1][m][1];
;                     u32x4 o;
;                     o[0] = pack2(silu_mul(gc[0][0], v0[0]), silu_mul(gc[0][1], v0[1])); o[1] = pack2(silu_mul(gc[0][2], v0[2]), silu_mul(gc[0][3], v0[3]));
	s_lshl_b32 s21, s45, 7
	v_mov_b32_e32 v194, v186
	v_mov_b32_e32 v80, v187
	s_or_b32 s21, s21, s62
	v_mov_b32_e32 v160, 0
	v_lshl_add_u32 v184, v80, 3, s21
	v_ashrrev_i32_e32 v185, 31, v184
	v_lshlrev_b64 v[80:81], 2, v[184:185]
	v_lshl_add_u64 v[84:85], s[4:5], 0, v[80:81]
	v_lshl_add_u64 v[88:89], s[16:17], 0, v[80:81]
	v_lshl_add_u64 v[92:93], s[18:19], 0, v[80:81]
	v_lshl_add_u64 v[112:113], s[6:7], 0, v[80:81]
	global_load_dwordx4 v[80:83], v[84:85], off offset:16
	global_load_dwordx4 v[96:99], v[84:85], off
	s_nop 0
	global_load_dwordx4 v[84:87], v[88:89], off offset:16
	global_load_dwordx4 v[100:103], v[88:89], off
	s_nop 0
	global_load_dwordx4 v[88:91], v[92:93], off offset:16
	global_load_dwordx4 v[108:111], v[92:93], off
	s_nop 0
	global_load_dwordx4 v[92:95], v[112:113], off offset:16
	s_nop 0
	global_load_dwordx4 v[112:115], v[112:113], off
	v_cmp_eq_u32_e32 vcc, 0, v194
	v_mov_b32_e32 v164, 0
	v_mov_b32_e32 v195, 0
	v_cndmask_b32_e32 v161, v148, v136, vcc
	v_cndmask_b32_e32 v162, v149, v137, vcc
	v_cndmask_b32_e32 v163, v150, v138, vcc
	v_mov_b32_dpp v160, v161 row_ror:15 row_mask:0xf bank_mask:0xf
	v_mov_b32_e32 v161, 0
	v_mov_b32_e32 v166, 0
	v_mov_b32_e32 v167, 0
	v_mov_b32_dpp v161, v162 row_ror:15 row_mask:0xf bank_mask:0xf
	v_mov_b32_e32 v162, 0
	v_mov_b32_dpp v164, v150 row_ror:1 row_mask:0xf bank_mask:0xf
	v_cndmask_b32_e32 v165, v151, v139, vcc
	v_mov_b32_dpp v162, v163 row_ror:15 row_mask:0xf bank_mask:0xf
	v_mov_b32_dpp v195, v151 row_ror:1 row_mask:0xf bank_mask:0xf
	v_mov_b32_e32 v163, 0
	v_mov_b32_dpp v166, v148 row_ror:1 row_mask:0xf bank_mask:0xf
	v_mov_b32_dpp v167, v149 row_ror:1 row_mask:0xf bank_mask:0xf
	v_mov_b32_dpp v163, v165 row_ror:15 row_mask:0xf bank_mask:0xf
	v_cndmask_b32_e64 v165, v195, 0, vcc
	v_cndmask_b32_e64 v164, v164, 0, vcc
	v_cndmask_b32_e64 v167, v167, 0, vcc
	v_cndmask_b32_e64 v166, v166, 0, vcc
	v_mov_b32_e32 v195, 0
	v_mov_b32_e32 v196, 0
	v_mov_b32_e32 v198, 0
	v_mov_b32_e32 v200, 0
	v_mov_b32_dpp v195, v144 row_ror:1 row_mask:0xf bank_mask:0xf
	v_mov_b32_dpp v196, v145 row_ror:1 row_mask:0xf bank_mask:0xf
	v_mov_b32_dpp v198, v146 row_ror:1 row_mask:0xf bank_mask:0xf
	v_cndmask_b32_e32 v199, v147, v131, vcc
	v_mov_b32_dpp v200, v147 row_ror:1 row_mask:0xf bank_mask:0xf
	v_cndmask_b32_e64 v198, v198, 0, vcc
	v_cndmask_b32_e64 v201, v196, 0, vcc
	s_lshl_b32 s3, s44, 8
	s_add_i32 s3, s3, s49
	v_add_u32_e32 v193, s3, v194
	v_cmp_ne_u32_e64 s[46:47], 0, v194
	s_waitcnt vmcnt(0)
	v_pk_mul_f32 v[164:165], v[98:99], v[164:165]
	v_pk_mul_f32 v[166:167], v[96:97], v[166:167]
	v_pk_fma_f32 v[164:165], v[150:151], v[102:103], v[164:165]
	v_pk_fma_f32 v[166:167], v[148:149], v[100:101], v[166:167]
	v_pk_fma_f32 v[162:163], v[110:111], v[162:163], v[164:165]
	v_cndmask_b32_e32 v165, v144, v128, vcc
	v_mov_b32_e32 v164, 0
	v_pk_fma_f32 v[160:161], v[108:109], v[160:161], v[166:167]
	v_cndmask_b32_e32 v166, v145, v129, vcc
	v_mov_b32_dpp v164, v165 row_ror:15 row_mask:0xf bank_mask:0xf
	v_mov_b32_e32 v165, 0
	v_cndmask_b32_e32 v167, v146, v130, vcc
	v_pk_add_f32 v[162:163], v[114:115], v[162:163]
	v_mov_b32_dpp v165, v166 row_ror:15 row_mask:0xf bank_mask:0xf
	v_mov_b32_e32 v166, 0
	v_pk_add_f32 v[160:161], v[112:113], v[160:161]
	s_nop 0
	v_mov_b32_dpp v166, v167 row_ror:15 row_mask:0xf bank_mask:0xf
	v_mov_b32_e32 v167, 0
	s_nop 1
	v_mov_b32_dpp v167, v199 row_ror:15 row_mask:0xf bank_mask:0xf
	v_cndmask_b32_e64 v199, v200, 0, vcc
	v_cndmask_b32_e64 v200, v195, 0, vcc
	v_pk_mul_f32 v[200:201], v[80:81], v[200:201]
	v_pk_mul_f32 v[198:199], v[82:83], v[198:199]
	v_pk_fma_f32 v[200:201], v[144:145], v[84:85], v[200:201]
	v_pk_fma_f32 v[198:199], v[146:147], v[86:87], v[198:199]
	v_pk_fma_f32 v[164:165], v[88:89], v[164:165], v[200:201]
	v_pk_fma_f32 v[166:167], v[90:91], v[166:167], v[198:199]
	v_pk_add_f32 v[164:165], v[92:93], v[164:165]
	v_pk_add_f32 v[166:167], v[94:95], v[166:167]
	s_and_saveexec_b64 s[28:29], s[46:47]
	s_xor_b64 s[28:29], exec, s[28:29]
	s_cbranch_execz .LBB1_1911
	v_mul_f32_e32 v195, 0xbfb8aa3b, v160
	v_exp_f32_e32 v195, v195
	v_mul_f32_e32 v196, 0xbfb8aa3b, v161
	v_exp_f32_e32 v196, v196
	v_pk_mul_f32 v[160:161], v[156:157], v[160:161]
	v_add_f32_e32 v195, 1.0, v195
	v_rcp_f32_e32 v198, v195
	v_add_f32_e32 v196, 1.0, v196
	v_mul_f32_e32 v195, 0xbfb8aa3b, v162
	v_rcp_f32_e32 v199, v196
	v_exp_f32_e32 v195, v195
	v_mul_f32_e32 v196, 0xbfb8aa3b, v163
	v_exp_f32_e32 v196, v196
	v_pk_mul_f32 v[160:161], v[160:161], v[198:199]
	v_add_f32_e32 v195, 1.0, v195
	v_rcp_f32_e32 v200, v195
	v_add_f32_e32 v195, 1.0, v196
	v_rcp_f32_e32 v201, v195
	v_cvt_pk_bf16_f32 v160, v160, v161
	v_mul_f32_e32 v161, 0xbfb8aa3b, v164
	v_exp_f32_e32 v195, v161
	v_mul_f32_e32 v161, 0xbfb8aa3b, v165
	v_exp_f32_e32 v196, v161
	v_pk_mul_f32 v[162:163], v[158:159], v[162:163]
	v_pk_mul_f32 v[164:165], v[152:153], v[164:165]
	v_pk_mul_f32 v[162:163], v[162:163], v[200:201]
	s_nop 0
	v_cvt_pk_bf16_f32 v161, v162, v163
	v_add_f32_e32 v162, 1.0, v195
	v_mul_f32_e32 v195, 0xbfb8aa3b, v166
	v_add_f32_e32 v163, 1.0, v196
	v_exp_f32_e32 v195, v195
	v_mul_f32_e32 v196, 0xbfb8aa3b, v167
	v_exp_f32_e32 v196, v196
	v_rcp_f32_e32 v162, v162
	v_add_f32_e32 v195, 1.0, v195
	v_rcp_f32_e32 v198, v195
	v_add_f32_e32 v195, 1.0, v196
	v_rcp_f32_e32 v163, v163
	v_rcp_f32_e32 v199, v195
	v_pk_mul_f32 v[166:167], v[154:155], v[166:167]
	v_pk_mul_f32 v[162:163], v[164:165], v[162:163]
	v_pk_mul_f32 v[164:165], v[166:167], v[198:199]
	v_cvt_pk_bf16_f32 v162, v162, v163
	v_cvt_pk_bf16_f32 v163, v164, v165
	v_mov_b64_e32 v[164:165], s[52:53]
	v_mad_i64_i32 v[164:165], s[42:43], v193, s60, v[164:165]
	v_lshl_add_u64 v[164:165], v[184:185], 1, v[164:165]
	flat_store_dwordx4 v[164:165], v[160:163]

; #define PG8_STAGE(bufoff, gbase, voff) do { _Pragma("unroll") for (int _i = 0; _i < 2; ++_i) \
;         __builtin_amdgcn_global_load_lds((const unsigned*)((const char*)(gbase) + (voff)[_i]), (LAS unsigned*)(lds + (bufoff) + ldsw + _i * 8192), 16, 0, 0); } while (0)
; #define PG8_LDA(dst, b, h) do { _Pragma("unroll") for (int m = 0; m < 4; ++m) _Pragma("unroll") for (int k = 0; k < 2; ++k) dst[m][k] = *(const LAS bf16x8*)(lds + PG8_SA(b, h) + aoff + m * 2048 + k * 1024); } while (0)
; #define PG8_LDB(dst, b, h) do { _Pragma("unroll") for (int n = 0; n < 2; ++n) _Pragma("unroll") for (int k = 0; k < 2; ++k) dst[n][k] = *(const LAS bf16x8*)(lds + PG8_SB(b, h) + boff + n * 2048 + k * 1024); } while (0)
; #define PG8_MMA(ai, bj, At, Bt) do { __builtin_amdgcn_s_setprio(1); _Pragma("unroll") for (int m = 0; m < 4; ++m) _Pragma("unroll") for (int n = 0; n < 2; ++n) _Pragma("unroll") for (int k = 0; k < 2; ++k) \
;         acc[ai][bj][m][n] = __builtin_amdgcn_mfma_f32_16x16x32_bf16(Bt[n][k], At[m][k], acc[ai][bj][m][n], 0, 0, 0); __builtin_amdgcn_s_setprio(0); } while (0)
; #define PG8_WAIT_L(n) asm volatile("s_waitcnt lgkmcnt(" #n ")" ::: "memory")
; #define PG8_BAR __builtin_amdgcn_s_barrier()
; #define PG8_SCHED __builtin_amdgcn_sched_barrier(0)
; template <class Map, class Epi>
; DI void gemm_phase(LAS unsigned char* lds, const Map& MP, const Epi& E, const int nM, const int nN, const int K, const int lda, const int ldb) {
;     ...
;             PG8_LDB(B0, 0, 0); PG8_SCHED; PG8_LDA(At, 0, 0); PG8_STAGE(PG8_SA(1, 1), a1 + hstepA, voffA);
;             PG8_WAIT_L(8); PG8_BAR; PG8_WAIT_L(0); PG8_MMA(0, 0, At, B0); PG8_BAR; PG8_SCHED;
;             PG8_LDB(B1, 0, 1); PG8_STAGE(PG8_SB(0, 0), b2, voffB);
;             PG8_BAR; PG8_WAIT_L(0); PG8_MMA(0, 1, At, B1); PG8_BAR;
;             PG8_LDA(At, 0, 1); PG8_STAGE(PG8_SA(0, 0), a2, voffA);
;             PG8_BAR; PG8_WAIT_L(0); PG8_MMA(1, 0, At, B0); PG8_BAR; PG8_SCHED;
.LBB1_2078:
	ds_read_b128 v[152:155], v149
	ds_read_b128 v[156:159], v149 offset:1024
	ds_read_b128 v[160:163], v149 offset:2048
	ds_read_b128 v[164:167], v149 offset:3072
	s_add_u32 s10, s8, 0x100
	s_addc_u32 s11, s9, 0
	s_cmpk_eq_i32 s3, 0x54
	s_cselect_b32 s15, s43, s11
	s_cselect_b32 s14, s42, s10
	s_cselect_b32 s13, s7, s44
	s_cselect_b32 s12, s6, s39
	v_lshl_add_u64 v[144:145], s[8:9], 0, v[138:139]
	s_add_i32 m0, s24, 0xc000
	ds_read_b128 v[168:171], v150
	ds_read_b128 v[172:175], v150 offset:1024
	ds_read_b128 v[176:179], v150 offset:2048
	ds_read_b128 v[180:183], v150 offset:3072
	ds_read_b128 v[184:187], v150 offset:4096
	ds_read_b128 v[188:191], v150 offset:5120
	ds_read_b128 v[192:195], v150 offset:6144
	ds_read_b128 v[198:201], v150 offset:7168
	global_load_lds_dwordx4 v[144:145], off
	v_lshl_add_u64 v[144:145], s[8:9], 0, v[136:137]
	s_add_i32 m0, s24, 0xe000
	s_nop 0
	global_load_lds_dwordx4 v[144:145], off
	s_waitcnt lgkmcnt(8)
	s_barrier
	s_setprio 1
	s_waitcnt lgkmcnt(7)
	v_mfma_f32_16x16x32_bf16 v[124:127], v[152:155], v[168:171], v[124:127]
	v_mfma_f32_16x16x32_bf16 v[120:123], v[160:163], v[168:171], v[120:123]
	s_waitcnt lgkmcnt(5)
	v_mfma_f32_16x16x32_bf16 v[108:111], v[152:155], v[176:179], v[108:111]
	v_mfma_f32_16x16x32_bf16 v[104:107], v[160:163], v[176:179], v[104:107]
	s_waitcnt lgkmcnt(3)
	v_mfma_f32_16x16x32_bf16 v[92:95], v[152:155], v[184:187], v[92:95]
	v_mfma_f32_16x16x32_bf16 v[88:91], v[160:163], v[184:187], v[88:91]
	s_waitcnt lgkmcnt(1)
	v_mfma_f32_16x16x32_bf16 v[76:79], v[152:155], v[192:195], v[76:79]
	v_mfma_f32_16x16x32_bf16 v[72:75], v[160:163], v[192:195], v[72:75]
	v_mfma_f32_16x16x32_bf16 v[124:127], v[156:159], v[172:175], v[124:127]
	v_mfma_f32_16x16x32_bf16 v[120:123], v[164:167], v[172:175], v[120:123]
	v_mfma_f32_16x16x32_bf16 v[108:111], v[156:159], v[180:183], v[108:111]
	v_mfma_f32_16x16x32_bf16 v[104:107], v[164:167], v[180:183], v[104:107]
	v_mfma_f32_16x16x32_bf16 v[92:95], v[156:159], v[188:191], v[92:95]
	v_mfma_f32_16x16x32_bf16 v[88:91], v[164:167], v[188:191], v[88:91]
	s_waitcnt lgkmcnt(0)
	v_mfma_f32_16x16x32_bf16 v[76:79], v[156:159], v[198:201], v[76:79]
	v_mfma_f32_16x16x32_bf16 v[72:75], v[164:167], v[198:201], v[72:75]
	s_setprio 0
	s_barrier
	s_add_i32 s8, s35, s22
	v_lshl_add_u64 v[144:145], s[12:13], 0, v[132:133]
	s_mov_b32 m0, s8
	ds_read_b128 v[202:205], v151
	ds_read_b128 v[206:209], v151 offset:1024
	ds_read_b128 v[210:213], v151 offset:2048
	ds_read_b128 v[214:217], v151 offset:3072
	global_load_lds_dwordx4 v[144:145], off
	v_lshl_add_u64 v[218:219], s[12:13], 0, v[128:129]
	s_add_i32 m0, s8, 0x2000
	s_nop 0
	global_load_lds_dwordx4 v[218:219], off
	s_barrier
	s_setprio 1
	s_waitcnt lgkmcnt(3)
	v_mfma_f32_16x16x32_bf16 v[116:119], v[202:205], v[168:171], v[116:119]
	s_waitcnt lgkmcnt(1)
	v_mfma_f32_16x16x32_bf16 v[112:115], v[210:213], v[168:171], v[112:115]
	v_mfma_f32_16x16x32_bf16 v[100:103], v[202:205], v[176:179], v[100:103]
	v_mfma_f32_16x16x32_bf16 v[96:99], v[210:213], v[176:179], v[96:99]
	v_mfma_f32_16x16x32_bf16 v[84:87], v[202:205], v[184:187], v[84:87]
	v_mfma_f32_16x16x32_bf16 v[80:83], v[210:213], v[184:187], v[80:83]
	v_mfma_f32_16x16x32_bf16 v[68:71], v[202:205], v[192:195], v[68:71]
	v_mfma_f32_16x16x32_bf16 v[64:67], v[210:213], v[192:195], v[64:67]
	v_mfma_f32_16x16x32_bf16 v[116:119], v[206:209], v[172:175], v[116:119]
	s_waitcnt lgkmcnt(0)
	v_mfma_f32_16x16x32_bf16 v[112:115], v[214:217], v[172:175], v[112:115]
	v_mfma_f32_16x16x32_bf16 v[100:103], v[206:209], v[180:183], v[100:103]
	v_mfma_f32_16x16x32_bf16 v[96:99], v[214:217], v[180:183], v[96:99]
	v_mfma_f32_16x16x32_bf16 v[84:87], v[206:209], v[188:191], v[84:87]
	v_mfma_f32_16x16x32_bf16 v[80:83], v[214:217], v[188:191], v[80:83]
	v_mfma_f32_16x16x32_bf16 v[68:71], v[206:209], v[198:201], v[68:71]
	v_mfma_f32_16x16x32_bf16 v[64:67], v[214:217], v[198:201], v[64:67]
	s_setprio 0
	s_mov_b32 m0, s24
	v_lshl_add_u64 v[220:221], s[14:15], 0, v[134:135]
	s_barrier
	ds_read_b128 v[168:171], v150 offset:16384
	ds_read_b128 v[172:175], v150 offset:17408
	ds_read_b128 v[176:179], v150 offset:18432
	ds_read_b128 v[180:183], v150 offset:19456
	ds_read_b128 v[184:187], v150 offset:20480
	ds_read_b128 v[188:191], v150 offset:21504
	ds_read_b128 v[192:195], v150 offset:22528
	ds_read_b128 v[198:201], v150 offset:23552
	global_load_lds_dwordx4 v[220:221], off
	v_lshl_add_u64 v[222:223], s[14:15], 0, v[130:131]
	s_mov_b32 m0, s25
	s_nop 0
	global_load_lds_dwordx4 v[222:223], off
	s_barrier
	s_setprio 1
	s_waitcnt lgkmcnt(7)
	v_mfma_f32_16x16x32_bf16 v[60:63], v[152:155], v[168:171], v[60:63]
	v_mfma_f32_16x16x32_bf16 v[56:59], v[160:163], v[168:171], v[56:59]
	s_waitcnt lgkmcnt(5)
	v_mfma_f32_16x16x32_bf16 v[44:47], v[152:155], v[176:179], v[44:47]
	v_mfma_f32_16x16x32_bf16 v[40:43], v[160:163], v[176:179], v[40:43]
	s_waitcnt lgkmcnt(3)
	v_mfma_f32_16x16x32_bf16 v[28:31], v[152:155], v[184:187], v[28:31]
	v_mfma_f32_16x16x32_bf16 v[24:27], v[160:163], v[184:187], v[24:27]
	s_waitcnt lgkmcnt(1)
	v_mfma_f32_16x16x32_bf16 v[12:15], v[152:155], v[192:195], v[12:15]
	v_mfma_f32_16x16x32_bf16 v[8:11], v[160:163], v[192:195], v[8:11]
	v_mfma_f32_16x16x32_bf16 v[60:63], v[156:159], v[172:175], v[60:63]
	v_mfma_f32_16x16x32_bf16 v[56:59], v[164:167], v[172:175], v[56:59]
	v_mfma_f32_16x16x32_bf16 v[44:47], v[156:159], v[180:183], v[44:47]
	v_mfma_f32_16x16x32_bf16 v[40:43], v[164:167], v[180:183], v[40:43]
	v_mfma_f32_16x16x32_bf16 v[28:31], v[156:159], v[188:191], v[28:31]
	v_mfma_f32_16x16x32_bf16 v[24:27], v[164:167], v[188:191], v[24:27]
	s_waitcnt lgkmcnt(0)
	v_mfma_f32_16x16x32_bf16 v[12:15], v[156:159], v[198:201], v[12:15]
	v_mfma_f32_16x16x32_bf16 v[8:11], v[164:167], v[198:201], v[8:11]
	s_setprio 0
	s_barrier
; #define PG8_STAGE(bufoff, gbase, voff) do { _Pragma("unroll") for (int _i = 0; _i < 2; ++_i) \
;         __builtin_amdgcn_global_load_lds((const unsigned*)((const char*)(gbase) + (voff)[_i]), (LAS unsigned*)(lds + (bufoff) + ldsw + _i * 8192), 16, 0, 0); } while (0)
; #define PG8_LDA(dst, b, h) do { _Pragma("unroll") for (int m = 0; m < 4; ++m) _Pragma("unroll") for (int k = 0; k < 2; ++k) dst[m][k] = *(const LAS bf16x8*)(lds + PG8_SA(b, h) + aoff + m * 2048 + k * 1024); } while (0)
; #define PG8_LDB(dst, b, h) do { _Pragma("unroll") for (int n = 0; n < 2; ++n) _Pragma("unroll") for (int k = 0; k < 2; ++k) dst[n][k] = *(const LAS bf16x8*)(lds + PG8_SB(b, h) + boff + n * 2048 + k * 1024); } while (0)
; #define PG8_MMA(ai, bj, At, Bt) do { __builtin_amdgcn_s_setprio(1); _Pragma("unroll") for (int m = 0; m < 4; ++m) _Pragma("unroll") for (int n = 0; n < 2; ++n) _Pragma("unroll") for (int k = 0; k < 2; ++k) \
;         acc[ai][bj][m][n] = __builtin_amdgcn_mfma_f32_16x16x32_bf16(Bt[n][k], At[m][k], acc[ai][bj][m][n], 0, 0, 0); __builtin_amdgcn_s_setprio(0); } while (0)
; #define PG8_WAIT_V(n) asm volatile("s_waitcnt vmcnt(" #n ")" ::: "memory")
; #define PG8_WAIT_L(n) asm volatile("s_waitcnt lgkmcnt(" #n ")" ::: "memory")
; #define PG8_BAR __builtin_amdgcn_s_barrier()
; #define PG8_SCHED __builtin_amdgcn_sched_barrier(0)
; template <class Map, class Epi>
; DI void gemm_phase(LAS unsigned char* lds, const Map& MP, const Epi& E, const int nM, const int nN, const int K, const int lda, const int ldb) {
;     ...
;             PG8_STAGE(PG8_SB(0, 1), b2 + hstepB, voffB);
;             PG8_WAIT_V(6); PG8_BAR; PG8_MMA(1, 1, At, B1); PG8_BAR;
;             PG8_LDB(B0, 1, 0); PG8_SCHED; PG8_LDA(At, 1, 0); PG8_STAGE(PG8_SA(0, 1), a2 + hstepA, voffA);
;             PG8_WAIT_L(8); PG8_BAR; PG8_WAIT_L(0); PG8_MMA(0, 0, At, B0); PG8_BAR; PG8_SCHED;
;             PG8_LDB(B1, 1, 1); PG8_STAGE(PG8_SB(1, 0), b3, voffB);
;             PG8_BAR; PG8_WAIT_L(0); PG8_MMA(0, 1, At, B1); PG8_BAR;
	s_add_u32 s8, s12, 0x160000
	s_addc_u32 s9, s13, 0
	s_add_i32 s45, s36, s22
	v_lshl_add_u64 v[152:153], s[8:9], 0, v[132:133]
	s_mov_b32 m0, s45
	s_nop 0
	global_load_lds_dwordx4 v[152:153], off
	v_lshl_add_u64 v[152:153], s[8:9], 0, v[128:129]
	s_add_i32 m0, s45, 0x2000
	s_nop 0
	global_load_lds_dwordx4 v[152:153], off
	s_waitcnt vmcnt(6)
	s_barrier
	s_setprio 1
	v_mfma_f32_16x16x32_bf16 v[52:55], v[202:205], v[168:171], v[52:55]
	v_mfma_f32_16x16x32_bf16 v[48:51], v[210:213], v[168:171], v[48:51]
	v_mfma_f32_16x16x32_bf16 v[36:39], v[202:205], v[176:179], v[36:39]
	v_mfma_f32_16x16x32_bf16 v[32:35], v[210:213], v[176:179], v[32:35]
	v_mfma_f32_16x16x32_bf16 v[20:23], v[202:205], v[184:187], v[20:23]
	v_mfma_f32_16x16x32_bf16 v[16:19], v[210:213], v[184:187], v[16:19]
	v_mfma_f32_16x16x32_bf16 v[4:7], v[202:205], v[192:195], v[4:7]
	v_mfma_f32_16x16x32_bf16 v[0:3], v[210:213], v[192:195], v[0:3]
	v_mfma_f32_16x16x32_bf16 v[52:55], v[206:209], v[172:175], v[52:55]
	v_mfma_f32_16x16x32_bf16 v[48:51], v[214:217], v[172:175], v[48:51]
	v_mfma_f32_16x16x32_bf16 v[36:39], v[206:209], v[180:183], v[36:39]
	v_mfma_f32_16x16x32_bf16 v[32:35], v[214:217], v[180:183], v[32:35]
	v_mfma_f32_16x16x32_bf16 v[20:23], v[206:209], v[188:191], v[20:23]
	v_mfma_f32_16x16x32_bf16 v[16:19], v[214:217], v[188:191], v[16:19]
	v_mfma_f32_16x16x32_bf16 v[4:7], v[206:209], v[198:201], v[4:7]
	v_mfma_f32_16x16x32_bf16 v[0:3], v[214:217], v[198:201], v[0:3]
	s_setprio 0
	s_add_i32 s45, 0, 0x18000
	v_add_u32_e32 v164, s45, v148
	s_barrier
	ds_read_b128 v[152:155], v164
	ds_read_b128 v[156:159], v164 offset:1024
	ds_read_b128 v[160:163], v164 offset:2048
	ds_read_b128 v[164:167], v164 offset:3072
	s_add_u32 s8, s14, 0x160000
	s_addc_u32 s9, s15, 0
	s_mov_b32 m0, s26
	v_lshl_add_u64 v[202:203], s[8:9], 0, v[134:135]
	ds_read_b128 v[168:171], v150 offset:32768
	ds_read_b128 v[172:175], v150 offset:33792
	ds_read_b128 v[176:179], v150 offset:34816
	ds_read_b128 v[180:183], v150 offset:35840
	ds_read_b128 v[184:187], v150 offset:36864
	ds_read_b128 v[188:191], v150 offset:37888
	ds_read_b128 v[192:195], v150 offset:38912
	ds_read_b128 v[198:201], v150 offset:39936
	global_load_lds_dwordx4 v[202:203], off
	v_lshl_add_u64 v[202:203], s[8:9], 0, v[130:131]
	s_mov_b32 m0, s27
	s_nop 0
	global_load_lds_dwordx4 v[202:203], off
	s_waitcnt lgkmcnt(8)
	s_barrier
	s_setprio 1
	s_waitcnt lgkmcnt(7)
	v_mfma_f32_16x16x32_bf16 v[124:127], v[152:155], v[168:171], v[124:127]
	v_mfma_f32_16x16x32_bf16 v[120:123], v[160:163], v[168:171], v[120:123]
	s_waitcnt lgkmcnt(5)
	v_mfma_f32_16x16x32_bf16 v[108:111], v[152:155], v[176:179], v[108:111]
	v_mfma_f32_16x16x32_bf16 v[104:107], v[160:163], v[176:179], v[104:107]
	s_waitcnt lgkmcnt(3)
	v_mfma_f32_16x16x32_bf16 v[92:95], v[152:155], v[184:187], v[92:95]
	v_mfma_f32_16x16x32_bf16 v[88:91], v[160:163], v[184:187], v[88:91]
	s_waitcnt lgkmcnt(1)
	v_mfma_f32_16x16x32_bf16 v[76:79], v[152:155], v[192:195], v[76:79]
	v_mfma_f32_16x16x32_bf16 v[72:75], v[160:163], v[192:195], v[72:75]
	v_mfma_f32_16x16x32_bf16 v[124:127], v[156:159], v[172:175], v[124:127]
	v_mfma_f32_16x16x32_bf16 v[120:123], v[164:167], v[172:175], v[120:123]
	v_mfma_f32_16x16x32_bf16 v[108:111], v[156:159], v[180:183], v[108:111]
	v_mfma_f32_16x16x32_bf16 v[104:107], v[164:167], v[180:183], v[104:107]
	v_mfma_f32_16x16x32_bf16 v[92:95], v[156:159], v[188:191], v[92:95]
	v_mfma_f32_16x16x32_bf16 v[88:91], v[164:167], v[188:191], v[88:91]
	s_waitcnt lgkmcnt(0)
	v_mfma_f32_16x16x32_bf16 v[76:79], v[156:159], v[198:201], v[76:79]
	v_mfma_f32_16x16x32_bf16 v[72:75], v[164:167], v[198:201], v[72:75]
	s_setprio 0
	s_barrier
	s_add_i32 s14, 0, 0x1c000
	s_add_i32 s8, s45, s22
	v_add_u32_e32 v196, s14, v148
	v_lshl_add_u64 v[144:145], v[144:145], 0, s[46:47]
	s_mov_b32 m0, s8
	ds_read_b128 v[202:205], v196
	ds_read_b128 v[206:209], v196 offset:1024
	ds_read_b128 v[210:213], v196 offset:2048
	ds_read_b128 v[214:217], v196 offset:3072
	global_load_lds_dwordx4 v[144:145], off
	v_lshl_add_u64 v[144:145], v[218:219], 0, s[46:47]
	s_add_i32 m0, s8, 0x2000
	s_nop 0
	global_load_lds_dwordx4 v[144:145], off
	s_barrier
	s_setprio 1
	s_waitcnt lgkmcnt(3)
	v_mfma_f32_16x16x32_bf16 v[116:119], v[202:205], v[168:171], v[116:119]
	s_waitcnt lgkmcnt(1)
	v_mfma_f32_16x16x32_bf16 v[112:115], v[210:213], v[168:171], v[112:115]
	v_mfma_f32_16x16x32_bf16 v[100:103], v[202:205], v[176:179], v[100:103]
	v_mfma_f32_16x16x32_bf16 v[96:99], v[210:213], v[176:179], v[96:99]
	v_mfma_f32_16x16x32_bf16 v[84:87], v[202:205], v[184:187], v[84:87]
	v_mfma_f32_16x16x32_bf16 v[80:83], v[210:213], v[184:187], v[80:83]
	v_mfma_f32_16x16x32_bf16 v[68:71], v[202:205], v[192:195], v[68:71]
	v_mfma_f32_16x16x32_bf16 v[64:67], v[210:213], v[192:195], v[64:67]
	v_mfma_f32_16x16x32_bf16 v[116:119], v[206:209], v[172:175], v[116:119]
	s_waitcnt lgkmcnt(0)
	v_mfma_f32_16x16x32_bf16 v[112:115], v[214:217], v[172:175], v[112:115]
	v_mfma_f32_16x16x32_bf16 v[100:103], v[206:209], v[180:183], v[100:103]
	v_mfma_f32_16x16x32_bf16 v[96:99], v[214:217], v[180:183], v[96:99]
	v_mfma_f32_16x16x32_bf16 v[84:87], v[206:209], v[188:191], v[84:87]
	v_mfma_f32_16x16x32_bf16 v[80:83], v[214:217], v[188:191], v[80:83]
	v_mfma_f32_16x16x32_bf16 v[68:71], v[206:209], v[198:201], v[68:71]
	v_mfma_f32_16x16x32_bf16 v[64:67], v[214:217], v[198:201], v[64:67]
	s_setprio 0
	s_mov_b32 m0, s30
	v_lshl_add_u64 v[144:145], v[220:221], 0, s[46:47]
	s_barrier
; DI unsigned pack2(float a, float b) { f32x2 v = {a, b}; hwbf16x2 r = __builtin_convertvector(v, hwbf16x2); return __builtin_bit_cast(unsigned, r); }
; DI float bflo(unsigned w) { return __uint_as_float(w << 16); }
; DI float bfhi(unsigned w) { return __uint_as_float(w & 0xffff0000u); }
; #define PG8_STAGE(bufoff, gbase, voff) do { _Pragma("unroll") for (int _i = 0; _i < 2; ++_i) \
;         __builtin_amdgcn_global_load_lds((const unsigned*)((const char*)(gbase) + (voff)[_i]), (LAS unsigned*)(lds + (bufoff) + ldsw + _i * 8192), 16, 0, 0); } while (0)
; #define PG8_WAIT_V(n) asm volatile("s_waitcnt vmcnt(" #n ")" ::: "memory")
;     DI void operator()(const f32x4 (&acc)[2][2][4][2], const Unit& u, int wr, int wc, int fr, int fq) const {
;     ...
;         for (int ai = 0; ai < 2; ++ai)
; #pragma unroll
;             for (int m = 0; m < 4; ++m) { const size_t ro = (size_t)(row0 + ai * HALF + m * 16) * D + col0;
; #pragma unroll
;                 for (int bj = 0; bj < 2; ++bj) {
;                     f32x4 x0, x1;
;                     if constexpr (IB) { const u32x4 w = *(const u32x4*)((const bf16_t*)Xin + ro + bj * HALF);
;                         x0 = (f32x4){bflo(w[0]), bfhi(w[0]), bflo(w[1]), bfhi(w[1])}; x1 = (f32x4){bflo(w[2]), bfhi(w[2]), bflo(w[3]), bfhi(w[3])}; }
;                     else { x0 = *(const f32x4*)((const float*)Xin + ro + bj * HALF); x1 = *(const f32x4*)((const float*)Xin + ro + bj * HALF + 4); }
;                     x0 += acc[ai][bj][m][0] * sc[bj][0]; x1 += acc[ai][bj][m][1] * sc[bj][1];
;                     if constexpr (OB) { u32x4 o; o[0] = pack2(x0[0], x0[1]); o[1] = pack2(x0[2], x0[3]); o[2] = pack2(x1[0], x1[1]); o[3] = pack2(x1[2], x1[3]);
;                         *(u32x4*)((bf16_t*)Xout + ro + bj * HALF) = o; }
;                     else { *(f32x4*)((float*)Xout + ro + bj * HALF) = x0; *(f32x4*)((float*)Xout + ro + bj * HALF + 4) = x1; } } }
; template <class Map, class Epi>
; DI void gemm_phase(LAS unsigned char* lds, const Map& MP, const Epi& E, const int nM, const int nN, const int K, const int lda, const int ldb) {
;     ...
;             PG8_LDA(At, 1, 1); PG8_STAGE(PG8_SA(1, 0), a3, voffA);
;             PG8_BAR; PG8_WAIT_L(0); PG8_MMA(1, 0, At, B0); PG8_BAR; PG8_SCHED;
;             PG8_STAGE(PG8_SB(1, 1), b3 + hstepB, voffB);
;             PG8_WAIT_V(6); PG8_BAR; PG8_MMA(1, 1, At, B1); PG8_BAR;
	ds_read_b128 v[168:171], v150 offset:49152
	ds_read_b128 v[172:175], v150 offset:50176
	ds_read_b128 v[176:179], v150 offset:51200
	ds_read_b128 v[180:183], v150 offset:52224
	ds_read_b128 v[184:187], v150 offset:53248
	ds_read_b128 v[188:191], v150 offset:54272
	ds_read_b128 v[192:195], v150 offset:55296
	ds_read_b128 v[198:201], v150 offset:56320
	global_load_lds_dwordx4 v[144:145], off
	v_lshl_add_u64 v[144:145], v[222:223], 0, s[46:47]
	s_mov_b32 m0, s31
	s_nop 0
	global_load_lds_dwordx4 v[144:145], off
	s_barrier
	s_setprio 1
	s_waitcnt lgkmcnt(7)
	v_mfma_f32_16x16x32_bf16 v[60:63], v[152:155], v[168:171], v[60:63]
	v_mfma_f32_16x16x32_bf16 v[56:59], v[160:163], v[168:171], v[56:59]
	s_waitcnt lgkmcnt(5)
	v_mfma_f32_16x16x32_bf16 v[44:47], v[152:155], v[176:179], v[44:47]
	v_mfma_f32_16x16x32_bf16 v[40:43], v[160:163], v[176:179], v[40:43]
	s_waitcnt lgkmcnt(3)
	v_mfma_f32_16x16x32_bf16 v[28:31], v[152:155], v[184:187], v[28:31]
	v_mfma_f32_16x16x32_bf16 v[24:27], v[160:163], v[184:187], v[24:27]
	s_waitcnt lgkmcnt(1)
	v_mfma_f32_16x16x32_bf16 v[12:15], v[152:155], v[192:195], v[12:15]
	v_mfma_f32_16x16x32_bf16 v[8:11], v[160:163], v[192:195], v[8:11]
	v_mfma_f32_16x16x32_bf16 v[60:63], v[156:159], v[172:175], v[60:63]
	v_mfma_f32_16x16x32_bf16 v[56:59], v[164:167], v[172:175], v[56:59]
	v_mfma_f32_16x16x32_bf16 v[44:47], v[156:159], v[180:183], v[44:47]
	v_mfma_f32_16x16x32_bf16 v[40:43], v[164:167], v[180:183], v[40:43]
	v_mfma_f32_16x16x32_bf16 v[28:31], v[156:159], v[188:191], v[28:31]
	v_mfma_f32_16x16x32_bf16 v[24:27], v[164:167], v[188:191], v[24:27]
	s_waitcnt lgkmcnt(0)
	v_mfma_f32_16x16x32_bf16 v[12:15], v[156:159], v[198:201], v[12:15]
	v_mfma_f32_16x16x32_bf16 v[8:11], v[164:167], v[198:201], v[8:11]
	s_setprio 0
	s_barrier
	s_add_u32 s8, s12, 0x160080
	s_addc_u32 s9, s13, 0
	s_add_i32 s12, s14, s22
	v_lshl_add_u64 v[144:145], s[8:9], 0, v[132:133]
	s_mov_b32 m0, s12
	s_nop 0
	global_load_lds_dwordx4 v[144:145], off
	v_lshl_add_u64 v[144:145], s[8:9], 0, v[128:129]
	s_add_i32 m0, s12, 0x2000
	s_nop 0
	global_load_lds_dwordx4 v[144:145], off
	s_waitcnt vmcnt(6)
	s_barrier
	s_setprio 1
	v_mfma_f32_16x16x32_bf16 v[52:55], v[202:205], v[168:171], v[52:55]
	v_mfma_f32_16x16x32_bf16 v[48:51], v[210:213], v[168:171], v[48:51]
	v_mfma_f32_16x16x32_bf16 v[36:39], v[202:205], v[176:179], v[36:39]
	v_mfma_f32_16x16x32_bf16 v[32:35], v[210:213], v[176:179], v[32:35]
	v_mfma_f32_16x16x32_bf16 v[20:23], v[202:205], v[184:187], v[20:23]
	v_mfma_f32_16x16x32_bf16 v[16:19], v[210:213], v[184:187], v[16:19]
	v_mfma_f32_16x16x32_bf16 v[4:7], v[202:205], v[192:195], v[4:7]
	v_mfma_f32_16x16x32_bf16 v[0:3], v[210:213], v[192:195], v[0:3]
	v_mfma_f32_16x16x32_bf16 v[52:55], v[206:209], v[172:175], v[52:55]
	v_mfma_f32_16x16x32_bf16 v[48:51], v[214:217], v[172:175], v[48:51]
	v_mfma_f32_16x16x32_bf16 v[36:39], v[206:209], v[180:183], v[36:39]
	v_mfma_f32_16x16x32_bf16 v[32:35], v[214:217], v[180:183], v[32:35]
	v_mfma_f32_16x16x32_bf16 v[20:23], v[206:209], v[188:191], v[20:23]
	v_mfma_f32_16x16x32_bf16 v[16:19], v[214:217], v[188:191], v[16:19]
	v_mfma_f32_16x16x32_bf16 v[4:7], v[206:209], v[198:201], v[4:7]
	v_mfma_f32_16x16x32_bf16 v[0:3], v[214:217], v[198:201], v[0:3]
	s_setprio 0
	s_add_i32 s3, s3, 2
	s_add_u32 s39, s39, 0x100
	s_addc_u32 s44, s44, 0
	s_cmpk_gt_u32 s3, 0x55
	s_mov_b64 s[8:9], s[10:11]
	s_barrier
	s_cbranch_scc0 .LBB1_2078
	v_mov_b32_e32 v152, v147
	v_mov_b32_e32 v144, v146
	s_lshl_b32 s2, s2, 8
	s_add_i32 s2, s2, s29
	s_lshl_b32 s3, s38, 8
	v_add_u32_e32 v152, s2, v152
	s_or_b32 s3, s3, s52
	v_ashrrev_i32_e32 v153, 31, v152
	v_lshl_add_u32 v144, v144, 3, s3
	v_lshlrev_b64 v[152:153], 12, v[152:153]
	v_ashrrev_i32_e32 v145, 31, v144
	v_lshl_add_u64 v[152:153], s[4:5], 0, v[152:153]
	v_lshl_add_u64 v[144:145], v[144:145], 1, v[152:153]
	flat_load_dwordx4 v[152:155], v[144:145]
	s_mov_b64 s[2:3], 0x10000
	s_mov_b32 s38, s37
	s_mov_b64 s[10:11], s[6:7]
	s_mov_b64 s[8:9], s[42:43]
	s_waitcnt vmcnt(0) lgkmcnt(0)
	v_lshlrev_b32_e32 v156, 16, v152
	v_and_b32_e32 v157, 0xffff0000, v152
	v_lshlrev_b32_e32 v152, 16, v153
	v_and_b32_e32 v153, 0xffff0000, v153
	v_lshlrev_b32_e32 v158, 16, v154
	v_and_b32_e32 v159, 0xffff0000, v154
	v_lshlrev_b32_e32 v154, 16, v155
	v_and_b32_e32 v155, 0xffff0000, v155
	v_pk_add_f32 v[126:127], v[126:127], v[152:153]
	v_pk_add_f32 v[124:125], v[124:125], v[156:157]
	v_pk_add_f32 v[152:153], v[122:123], v[154:155]
	v_pk_add_f32 v[122:123], v[120:121], v[158:159]
	v_cvt_pk_bf16_f32 v120, v124, v125
	v_cvt_pk_bf16_f32 v121, v126, v127
	v_cvt_pk_bf16_f32 v122, v122, v123
	v_cvt_pk_bf16_f32 v123, v152, v153
	flat_store_dwordx4 v[144:145], v[120:123]
	flat_load_dwordx4 v[120:123], v[144:145] offset:256
	s_waitcnt vmcnt(0) lgkmcnt(0)
	v_lshlrev_b32_e32 v124, 16, v120
	v_and_b32_e32 v125, 0xffff0000, v120
	v_lshlrev_b32_e32 v120, 16, v121
	v_and_b32_e32 v121, 0xffff0000, v121
	v_lshlrev_b32_e32 v126, 16, v122
	v_and_b32_e32 v127, 0xffff0000, v122
	v_lshlrev_b32_e32 v122, 16, v123
	v_and_b32_e32 v123, 0xffff0000, v123
	v_pk_add_f32 v[116:117], v[116:117], v[124:125]
	v_pk_add_f32 v[118:119], v[118:119], v[120:121]
	v_pk_add_f32 v[120:121], v[114:115], v[122:123]
	v_pk_add_f32 v[114:115], v[112:113], v[126:127]
	v_cvt_pk_bf16_f32 v112, v116, v117
	v_lshl_add_u64 v[116:117], v[144:145], 0, s[2:3]
	s_mov_b32 s2, 0x10000
	v_cvt_pk_bf16_f32 v113, v118, v119
	v_add_co_u32_e32 v118, vcc, s2, v144
	v_cvt_pk_bf16_f32 v114, v114, v115
	v_cvt_pk_bf16_f32 v115, v120, v121
	v_addc_co_u32_e32 v119, vcc, 0, v145, vcc
	flat_store_dwordx4 v[144:145], v[112:115] offset:256
	flat_load_dwordx4 v[112:115], v[118:119]
	s_mov_b64 s[2:3], 0x20000
	s_waitcnt vmcnt(0) lgkmcnt(0)
; DI unsigned pack2(float a, float b) { f32x2 v = {a, b}; hwbf16x2 r = __builtin_convertvector(v, hwbf16x2); return __builtin_bit_cast(unsigned, r); }
; DI float bflo(unsigned w) { return __uint_as_float(w << 16); }
; DI float bfhi(unsigned w) { return __uint_as_float(w & 0xffff0000u); }
;     DI void operator()(const f32x4 (&acc)[2][2][4][2], const Unit& u, int wr, int wc, int fr, int fq) const {
;     ...
;         for (int ai = 0; ai < 2; ++ai)
; #pragma unroll
;             for (int m = 0; m < 4; ++m) { const size_t ro = (size_t)(row0 + ai * HALF + m * 16) * D + col0;
; #pragma unroll
;                 for (int bj = 0; bj < 2; ++bj) {
;                     f32x4 x0, x1;
;                     if constexpr (IB) { const u32x4 w = *(const u32x4*)((const bf16_t*)Xin + ro + bj * HALF);
;                         x0 = (f32x4){bflo(w[0]), bfhi(w[0]), bflo(w[1]), bfhi(w[1])}; x1 = (f32x4){bflo(w[2]), bfhi(w[2]), bflo(w[3]), bfhi(w[3])}; }
;                     else { x0 = *(const f32x4*)((const float*)Xin + ro + bj * HALF); x1 = *(const f32x4*)((const float*)Xin + ro + bj * HALF + 4); }
;                     x0 += acc[ai][bj][m][0] * sc[bj][0]; x1 += acc[ai][bj][m][1] * sc[bj][1];
;                     if constexpr (OB) { u32x4 o; o[0] = pack2(x0[0], x0[1]); o[1] = pack2(x0[2], x0[3]); o[2] = pack2(x1[0], x1[1]); o[3] = pack2(x1[2], x1[3]);
;                         *(u32x4*)((bf16_t*)Xout + ro + bj * HALF) = o; }
;                     else { *(f32x4*)((float*)Xout + ro + bj * HALF) = x0; *(f32x4*)((float*)Xout + ro + bj * HALF + 4) = x1; } } }
	v_lshlrev_b32_e32 v120, 16, v112
	v_and_b32_e32 v121, 0xffff0000, v112
	v_lshlrev_b32_e32 v112, 16, v113
	v_and_b32_e32 v113, 0xffff0000, v113
	v_lshlrev_b32_e32 v122, 16, v114
	v_and_b32_e32 v123, 0xffff0000, v114
	v_lshlrev_b32_e32 v114, 16, v115
	v_and_b32_e32 v115, 0xffff0000, v115
	v_pk_add_f32 v[110:111], v[110:111], v[112:113]
	v_pk_add_f32 v[108:109], v[108:109], v[120:121]
	v_pk_add_f32 v[112:113], v[106:107], v[114:115]
	v_pk_add_f32 v[106:107], v[104:105], v[122:123]
	v_cvt_pk_bf16_f32 v104, v108, v109
	v_cvt_pk_bf16_f32 v105, v110, v111
	v_cvt_pk_bf16_f32 v106, v106, v107
	v_cvt_pk_bf16_f32 v107, v112, v113
	flat_store_dwordx4 v[118:119], v[104:107]
	flat_load_dwordx4 v[104:107], v[116:117] offset:256
	s_waitcnt vmcnt(0) lgkmcnt(0)
	v_lshlrev_b32_e32 v108, 16, v104
	v_and_b32_e32 v109, 0xffff0000, v104
	v_lshlrev_b32_e32 v104, 16, v105
	v_and_b32_e32 v105, 0xffff0000, v105
	v_lshlrev_b32_e32 v110, 16, v106
	v_and_b32_e32 v111, 0xffff0000, v106
	v_lshlrev_b32_e32 v106, 16, v107
	v_and_b32_e32 v107, 0xffff0000, v107
	v_pk_add_f32 v[100:101], v[100:101], v[108:109]
	v_pk_add_f32 v[102:103], v[102:103], v[104:105]
	v_pk_add_f32 v[104:105], v[98:99], v[106:107]
	v_pk_add_f32 v[98:99], v[96:97], v[110:111]
	v_cvt_pk_bf16_f32 v96, v100, v101
	v_lshl_add_u64 v[100:101], v[144:145], 0, s[2:3]
	s_mov_b32 s2, 0x20000
	v_cvt_pk_bf16_f32 v97, v102, v103
	v_add_co_u32_e32 v102, vcc, s2, v144
	v_cvt_pk_bf16_f32 v98, v98, v99
	v_cvt_pk_bf16_f32 v99, v104, v105
	v_addc_co_u32_e32 v103, vcc, 0, v145, vcc
	flat_store_dwordx4 v[116:117], v[96:99] offset:256
	flat_load_dwordx4 v[96:99], v[102:103]
	s_mov_b64 s[2:3], 0x30000
	s_waitcnt vmcnt(0) lgkmcnt(0)
	v_lshlrev_b32_e32 v104, 16, v96
	v_and_b32_e32 v105, 0xffff0000, v96
	v_lshlrev_b32_e32 v96, 16, v97
	v_and_b32_e32 v97, 0xffff0000, v97
	v_lshlrev_b32_e32 v106, 16, v98
	v_and_b32_e32 v107, 0xffff0000, v98
	v_lshlrev_b32_e32 v98, 16, v99
	v_and_b32_e32 v99, 0xffff0000, v99
	v_pk_add_f32 v[94:95], v[94:95], v[96:97]
	v_pk_add_f32 v[92:93], v[92:93], v[104:105]
	v_pk_add_f32 v[96:97], v[90:91], v[98:99]
	v_pk_add_f32 v[90:91], v[88:89], v[106:107]
	v_cvt_pk_bf16_f32 v88, v92, v93
	v_cvt_pk_bf16_f32 v89, v94, v95
	v_cvt_pk_bf16_f32 v90, v90, v91
	v_cvt_pk_bf16_f32 v91, v96, v97
	flat_store_dwordx4 v[102:103], v[88:91]
	flat_load_dwordx4 v[88:91], v[100:101] offset:256
	s_waitcnt vmcnt(0) lgkmcnt(0)
	v_lshlrev_b32_e32 v92, 16, v88
	v_and_b32_e32 v93, 0xffff0000, v88
	v_lshlrev_b32_e32 v88, 16, v89
	v_and_b32_e32 v89, 0xffff0000, v89
	v_lshlrev_b32_e32 v94, 16, v90
	v_and_b32_e32 v95, 0xffff0000, v90
	v_lshlrev_b32_e32 v90, 16, v91
	v_and_b32_e32 v91, 0xffff0000, v91
	v_pk_add_f32 v[86:87], v[86:87], v[88:89]
	v_pk_add_f32 v[84:85], v[84:85], v[92:93]
	v_pk_add_f32 v[88:89], v[82:83], v[90:91]
	v_pk_add_f32 v[82:83], v[80:81], v[94:95]
	v_cvt_pk_bf16_f32 v80, v84, v85
	v_cvt_pk_bf16_f32 v81, v86, v87
	v_cvt_pk_bf16_f32 v82, v82, v83
	v_cvt_pk_bf16_f32 v83, v88, v89
	flat_store_dwordx4 v[100:101], v[80:83] offset:256
	s_nop 1
	v_lshl_add_u64 v[80:81], v[144:145], 0, s[2:3]
	s_mov_b32 s2, 0x30000
	v_add_co_u32_e32 v86, vcc, s2, v144
	s_mov_b64 s[2:3], 0x80000
	s_nop 0
	v_addc_co_u32_e32 v87, vcc, 0, v145, vcc
	flat_load_dwordx4 v[82:85], v[86:87]
	s_waitcnt vmcnt(0) lgkmcnt(0)
	v_lshlrev_b32_e32 v88, 16, v82
	v_and_b32_e32 v89, 0xffff0000, v82
	v_lshlrev_b32_e32 v82, 16, v83
	v_and_b32_e32 v83, 0xffff0000, v83
	v_lshlrev_b32_e32 v90, 16, v84
	v_and_b32_e32 v91, 0xffff0000, v84
	v_lshlrev_b32_e32 v84, 16, v85
	v_and_b32_e32 v85, 0xffff0000, v85
	v_pk_add_f32 v[78:79], v[78:79], v[82:83]
	v_pk_add_f32 v[76:77], v[76:77], v[88:89]
	v_pk_add_f32 v[82:83], v[74:75], v[84:85]
	v_pk_add_f32 v[74:75], v[72:73], v[90:91]
	v_cvt_pk_bf16_f32 v72, v76, v77
	v_cvt_pk_bf16_f32 v73, v78, v79
	v_cvt_pk_bf16_f32 v74, v74, v75
	v_cvt_pk_bf16_f32 v75, v82, v83
	flat_store_dwordx4 v[86:87], v[72:75]
	flat_load_dwordx4 v[72:75], v[80:81] offset:256
	s_waitcnt vmcnt(0) lgkmcnt(0)
	v_lshlrev_b32_e32 v76, 16, v72
	v_and_b32_e32 v77, 0xffff0000, v72
	v_lshlrev_b32_e32 v72, 16, v73
	v_and_b32_e32 v73, 0xffff0000, v73
	v_lshlrev_b32_e32 v78, 16, v74
	v_and_b32_e32 v79, 0xffff0000, v74
	v_lshlrev_b32_e32 v74, 16, v75
	v_and_b32_e32 v75, 0xffff0000, v75
	v_pk_add_f32 v[70:71], v[70:71], v[72:73]
	v_pk_add_f32 v[68:69], v[68:69], v[76:77]
	v_pk_add_f32 v[72:73], v[66:67], v[74:75]
	v_pk_add_f32 v[66:67], v[64:65], v[78:79]
	v_cvt_pk_bf16_f32 v64, v68, v69
	v_cvt_pk_bf16_f32 v65, v70, v71
	v_cvt_pk_bf16_f32 v66, v66, v67
	v_cvt_pk_bf16_f32 v67, v72, v73
	flat_store_dwordx4 v[80:81], v[64:67] offset:256
	s_nop 1
	v_lshl_add_u64 v[64:65], v[144:145], 0, s[2:3]
	s_mov_b32 s2, 0x80000
	v_add_co_u32_e32 v70, vcc, s2, v144
	s_mov_b64 s[2:3], 0x90000
	s_nop 0
	v_addc_co_u32_e32 v71, vcc, 0, v145, vcc
	flat_load_dwordx4 v[66:69], v[70:71]
	s_waitcnt vmcnt(0) lgkmcnt(0)
	v_lshlrev_b32_e32 v72, 16, v66
	v_and_b32_e32 v73, 0xffff0000, v66
	v_lshlrev_b32_e32 v66, 16, v67
	v_and_b32_e32 v67, 0xffff0000, v67
	v_lshlrev_b32_e32 v74, 16, v68
	v_and_b32_e32 v75, 0xffff0000, v68
	v_lshlrev_b32_e32 v68, 16, v69
	v_and_b32_e32 v69, 0xffff0000, v69
	v_pk_add_f32 v[62:63], v[62:63], v[66:67]
	v_pk_add_f32 v[60:61], v[60:61], v[72:73]
	v_pk_add_f32 v[66:67], v[58:59], v[68:69]
	v_pk_add_f32 v[58:59], v[56:57], v[74:75]
	v_cvt_pk_bf16_f32 v56, v60, v61
	v_cvt_pk_bf16_f32 v57, v62, v63
	v_cvt_pk_bf16_f32 v58, v58, v59
	v_cvt_pk_bf16_f32 v59, v66, v67
	flat_store_dwordx4 v[70:71], v[56:59]
	flat_load_dwordx4 v[56:59], v[64:65] offset:256
	s_waitcnt vmcnt(0) lgkmcnt(0)
; DI unsigned pack2(float a, float b) { f32x2 v = {a, b}; hwbf16x2 r = __builtin_convertvector(v, hwbf16x2); return __builtin_bit_cast(unsigned, r); }
; DI float bflo(unsigned w) { return __uint_as_float(w << 16); }
; DI float bfhi(unsigned w) { return __uint_as_float(w & 0xffff0000u); }
;     DI void operator()(const f32x4 (&acc)[2][2][4][2], const Unit& u, int wr, int wc, int fr, int fq) const {
;     ...
;         for (int ai = 0; ai < 2; ++ai)
; #pragma unroll
;             for (int m = 0; m < 4; ++m) { const size_t ro = (size_t)(row0 + ai * HALF + m * 16) * D + col0;
; #pragma unroll
;                 for (int bj = 0; bj < 2; ++bj) {
;                     f32x4 x0, x1;
;                     if constexpr (IB) { const u32x4 w = *(const u32x4*)((const bf16_t*)Xin + ro + bj * HALF);
;                         x0 = (f32x4){bflo(w[0]), bfhi(w[0]), bflo(w[1]), bfhi(w[1])}; x1 = (f32x4){bflo(w[2]), bfhi(w[2]), bflo(w[3]), bfhi(w[3])}; }
;                     else { x0 = *(const f32x4*)((const float*)Xin + ro + bj * HALF); x1 = *(const f32x4*)((const float*)Xin + ro + bj * HALF + 4); }
;                     x0 += acc[ai][bj][m][0] * sc[bj][0]; x1 += acc[ai][bj][m][1] * sc[bj][1];
;                     if constexpr (OB) { u32x4 o; o[0] = pack2(x0[0], x0[1]); o[1] = pack2(x0[2], x0[3]); o[2] = pack2(x1[0], x1[1]); o[3] = pack2(x1[2], x1[3]);
;                         *(u32x4*)((bf16_t*)Xout + ro + bj * HALF) = o; }
;                     else { *(f32x4*)((float*)Xout + ro + bj * HALF) = x0; *(f32x4*)((float*)Xout + ro + bj * HALF + 4) = x1; } } }
	v_lshlrev_b32_e32 v60, 16, v56
	v_and_b32_e32 v61, 0xffff0000, v56
	v_lshlrev_b32_e32 v56, 16, v57
	v_and_b32_e32 v57, 0xffff0000, v57
	v_lshlrev_b32_e32 v62, 16, v58
	v_and_b32_e32 v63, 0xffff0000, v58
	v_lshlrev_b32_e32 v58, 16, v59
	v_and_b32_e32 v59, 0xffff0000, v59
	v_pk_add_f32 v[54:55], v[54:55], v[56:57]
	v_pk_add_f32 v[52:53], v[52:53], v[60:61]
	v_pk_add_f32 v[56:57], v[50:51], v[58:59]
	v_pk_add_f32 v[50:51], v[48:49], v[62:63]
	v_cvt_pk_bf16_f32 v48, v52, v53
	v_cvt_pk_bf16_f32 v49, v54, v55
	v_cvt_pk_bf16_f32 v50, v50, v51
	v_cvt_pk_bf16_f32 v51, v56, v57
	flat_store_dwordx4 v[64:65], v[48:51] offset:256
	s_nop 1
	v_lshl_add_u64 v[48:49], v[144:145], 0, s[2:3]
	s_mov_b32 s2, 0x90000
	v_add_co_u32_e32 v54, vcc, s2, v144
	s_mov_b64 s[2:3], 0xa0000
	s_nop 0
	v_addc_co_u32_e32 v55, vcc, 0, v145, vcc
	flat_load_dwordx4 v[50:53], v[54:55]
	s_waitcnt vmcnt(0) lgkmcnt(0)
	v_lshlrev_b32_e32 v56, 16, v50
	v_and_b32_e32 v57, 0xffff0000, v50
	v_lshlrev_b32_e32 v50, 16, v51
	v_and_b32_e32 v51, 0xffff0000, v51
	v_lshlrev_b32_e32 v58, 16, v52
	v_and_b32_e32 v59, 0xffff0000, v52
	v_lshlrev_b32_e32 v52, 16, v53
	v_and_b32_e32 v53, 0xffff0000, v53
	v_pk_add_f32 v[46:47], v[46:47], v[50:51]
	v_pk_add_f32 v[44:45], v[44:45], v[56:57]
	v_pk_add_f32 v[50:51], v[42:43], v[52:53]
	v_pk_add_f32 v[42:43], v[40:41], v[58:59]
	v_cvt_pk_bf16_f32 v40, v44, v45
	v_cvt_pk_bf16_f32 v41, v46, v47
	v_cvt_pk_bf16_f32 v42, v42, v43
	v_cvt_pk_bf16_f32 v43, v50, v51
	flat_store_dwordx4 v[54:55], v[40:43]
	flat_load_dwordx4 v[40:43], v[48:49] offset:256
	s_waitcnt vmcnt(0) lgkmcnt(0)
	v_lshlrev_b32_e32 v44, 16, v40
	v_and_b32_e32 v45, 0xffff0000, v40
	v_lshlrev_b32_e32 v40, 16, v41
	v_and_b32_e32 v41, 0xffff0000, v41
	v_lshlrev_b32_e32 v46, 16, v42
	v_and_b32_e32 v47, 0xffff0000, v42
	v_lshlrev_b32_e32 v42, 16, v43
	v_and_b32_e32 v43, 0xffff0000, v43
	v_pk_add_f32 v[38:39], v[38:39], v[40:41]
	v_pk_add_f32 v[36:37], v[36:37], v[44:45]
	v_pk_add_f32 v[40:41], v[34:35], v[42:43]
	v_pk_add_f32 v[34:35], v[32:33], v[46:47]
	v_cvt_pk_bf16_f32 v32, v36, v37
	v_cvt_pk_bf16_f32 v33, v38, v39
	v_cvt_pk_bf16_f32 v34, v34, v35
	v_cvt_pk_bf16_f32 v35, v40, v41
	flat_store_dwordx4 v[48:49], v[32:35] offset:256
	s_nop 1
	v_lshl_add_u64 v[32:33], v[144:145], 0, s[2:3]
	s_mov_b32 s2, 0xa0000
	v_add_co_u32_e32 v38, vcc, s2, v144
	s_mov_b64 s[2:3], 0xb0000
	s_nop 0
	v_addc_co_u32_e32 v39, vcc, 0, v145, vcc
	flat_load_dwordx4 v[34:37], v[38:39]
	s_waitcnt vmcnt(0) lgkmcnt(0)
	v_lshlrev_b32_e32 v40, 16, v34
	v_and_b32_e32 v41, 0xffff0000, v34
	v_lshlrev_b32_e32 v34, 16, v35
	v_and_b32_e32 v35, 0xffff0000, v35
	v_lshlrev_b32_e32 v42, 16, v36
	v_and_b32_e32 v43, 0xffff0000, v36
	v_lshlrev_b32_e32 v36, 16, v37
	v_and_b32_e32 v37, 0xffff0000, v37
	v_pk_add_f32 v[30:31], v[30:31], v[34:35]
	v_pk_add_f32 v[28:29], v[28:29], v[40:41]
	v_pk_add_f32 v[34:35], v[26:27], v[36:37]
	v_pk_add_f32 v[26:27], v[24:25], v[42:43]
	v_cvt_pk_bf16_f32 v24, v28, v29
	v_cvt_pk_bf16_f32 v25, v30, v31
	v_cvt_pk_bf16_f32 v26, v26, v27
	v_cvt_pk_bf16_f32 v27, v34, v35
	flat_store_dwordx4 v[38:39], v[24:27]
	flat_load_dwordx4 v[24:27], v[32:33] offset:256
	s_waitcnt vmcnt(0) lgkmcnt(0)
	v_lshlrev_b32_e32 v28, 16, v24
	v_and_b32_e32 v29, 0xffff0000, v24
	v_lshlrev_b32_e32 v24, 16, v25
	v_and_b32_e32 v25, 0xffff0000, v25
	v_lshlrev_b32_e32 v30, 16, v26
	v_and_b32_e32 v31, 0xffff0000, v26
	v_lshlrev_b32_e32 v26, 16, v27
	v_and_b32_e32 v27, 0xffff0000, v27
	v_pk_add_f32 v[22:23], v[22:23], v[24:25]
	v_pk_add_f32 v[20:21], v[20:21], v[28:29]
	v_pk_add_f32 v[24:25], v[18:19], v[26:27]
	v_pk_add_f32 v[18:19], v[16:17], v[30:31]
	v_cvt_pk_bf16_f32 v16, v20, v21
	v_cvt_pk_bf16_f32 v17, v22, v23
	v_cvt_pk_bf16_f32 v18, v18, v19
	v_cvt_pk_bf16_f32 v19, v24, v25
	flat_store_dwordx4 v[32:33], v[16:19] offset:256
	s_nop 1
	v_lshl_add_u64 v[16:17], v[144:145], 0, s[2:3]
	s_mov_b32 s2, 0xb0000
	v_add_co_u32_e32 v22, vcc, s2, v144
	s_mov_b32 s2, s53
	s_nop 0
	v_addc_co_u32_e32 v23, vcc, 0, v145, vcc
	flat_load_dwordx4 v[18:21], v[22:23]
	s_and_b64 vcc, exec, s[40:41]
	s_waitcnt vmcnt(0) lgkmcnt(0)
	v_lshlrev_b32_e32 v24, 16, v18
	v_and_b32_e32 v25, 0xffff0000, v18
	v_lshlrev_b32_e32 v18, 16, v19
	v_and_b32_e32 v19, 0xffff0000, v19
	v_lshlrev_b32_e32 v26, 16, v20
	v_and_b32_e32 v27, 0xffff0000, v20
	v_lshlrev_b32_e32 v20, 16, v21
	v_and_b32_e32 v21, 0xffff0000, v21
	v_pk_add_f32 v[14:15], v[14:15], v[18:19]
	v_pk_add_f32 v[12:13], v[12:13], v[24:25]
	v_pk_add_f32 v[18:19], v[10:11], v[20:21]
	v_pk_add_f32 v[10:11], v[8:9], v[26:27]
	v_cvt_pk_bf16_f32 v8, v12, v13
	v_cvt_pk_bf16_f32 v9, v14, v15
	v_cvt_pk_bf16_f32 v10, v10, v11
	v_cvt_pk_bf16_f32 v11, v18, v19
	flat_store_dwordx4 v[22:23], v[8:11]
	flat_load_dwordx4 v[8:11], v[16:17] offset:256
	s_waitcnt vmcnt(0) lgkmcnt(0)
	v_lshlrev_b32_e32 v12, 16, v8
	v_and_b32_e32 v13, 0xffff0000, v8
	v_lshlrev_b32_e32 v8, 16, v9
	v_and_b32_e32 v9, 0xffff0000, v9
	v_lshlrev_b32_e32 v14, 16, v10
	v_and_b32_e32 v15, 0xffff0000, v10
	v_lshlrev_b32_e32 v10, 16, v11
	v_and_b32_e32 v11, 0xffff0000, v11
	v_pk_add_f32 v[6:7], v[6:7], v[8:9]
	v_pk_add_f32 v[4:5], v[4:5], v[12:13]
	v_pk_add_f32 v[8:9], v[2:3], v[10:11]
	v_pk_add_f32 v[2:3], v[0:1], v[14:15]
	v_cvt_pk_bf16_f32 v0, v4, v5
	v_cvt_pk_bf16_f32 v1, v6, v7
	v_cvt_pk_bf16_f32 v2, v2, v3
	v_cvt_pk_bf16_f32 v3, v8, v9
	flat_store_dwordx4 v[16:17], v[0:3] offset:256
	s_cbranch_vccz .LBB1_2071
	s_waitcnt vmcnt(0)
	s_cmpk_gt_u32 s17, 0xff
	s_cbranch_scc1 .LBB1_2082
	s_barrier

; #define PG8_STAGE(bufoff, gbase, voff) do { _Pragma("unroll") for (int _i = 0; _i < 2; ++_i) \
;         __builtin_amdgcn_global_load_lds((const unsigned*)((const char*)(gbase) + (voff)[_i]), (LAS unsigned*)(lds + (bufoff) + ldsw + _i * 8192), 16, 0, 0); } while (0)
; #define PG8_LDA(dst, b, h) do { _Pragma("unroll") for (int m = 0; m < 4; ++m) _Pragma("unroll") for (int k = 0; k < 2; ++k) dst[m][k] = *(const LAS bf16x8*)(lds + PG8_SA(b, h) + aoff + m * 2048 + k * 1024); } while (0)
; #define PG8_LDB(dst, b, h) do { _Pragma("unroll") for (int n = 0; n < 2; ++n) _Pragma("unroll") for (int k = 0; k < 2; ++k) dst[n][k] = *(const LAS bf16x8*)(lds + PG8_SB(b, h) + boff + n * 2048 + k * 1024); } while (0)
; #define PG8_MMA(ai, bj, At, Bt) do { __builtin_amdgcn_s_setprio(1); _Pragma("unroll") for (int m = 0; m < 4; ++m) _Pragma("unroll") for (int n = 0; n < 2; ++n) _Pragma("unroll") for (int k = 0; k < 2; ++k) \
;         acc[ai][bj][m][n] = __builtin_amdgcn_mfma_f32_16x16x32_bf16(Bt[n][k], At[m][k], acc[ai][bj][m][n], 0, 0, 0); __builtin_amdgcn_s_setprio(0); } while (0)
; #define PG8_WAIT_L(n) asm volatile("s_waitcnt lgkmcnt(" #n ")" ::: "memory")
; #define PG8_BAR __builtin_amdgcn_s_barrier()
; #define PG8_SCHED __builtin_amdgcn_sched_barrier(0)
; template <class Map, class Epi>
; DI void gemm_phase(LAS unsigned char* lds, const Map& MP, const Epi& E, const int nM, const int nN, const int K, const int lda, const int ldb) {
;     ...
;             PG8_LDB(B0, 0, 0); PG8_SCHED; PG8_LDA(At, 0, 0); PG8_STAGE(PG8_SA(1, 1), a1 + hstepA, voffA);
;             PG8_WAIT_L(8); PG8_BAR; PG8_WAIT_L(0); PG8_MMA(0, 0, At, B0); PG8_BAR; PG8_SCHED;
;             PG8_LDB(B1, 0, 1); PG8_STAGE(PG8_SB(0, 0), b2, voffB);
;             PG8_BAR; PG8_WAIT_L(0); PG8_MMA(0, 1, At, B1); PG8_BAR;
;             PG8_LDA(At, 0, 1); PG8_STAGE(PG8_SA(0, 0), a2, voffA);
;             PG8_BAR; PG8_WAIT_L(0); PG8_MMA(1, 0, At, B0); PG8_BAR; PG8_SCHED;
.LBB1_2339:
	ds_read_b128 v[40:43], v165
	ds_read_b128 v[44:47], v165 offset:1024
	ds_read_b128 v[56:59], v165 offset:2048
	ds_read_b128 v[60:63], v165 offset:3072
	s_add_u32 s12, s10, 0xfff80080
	s_addc_u32 s13, s11, -1
	s_cmp_eq_u32 s3, 4
	s_cselect_b32 s15, s38, s13
	s_cselect_b32 s14, s39, s12
	s_cselect_b32 s13, s48, s56
	s_cselect_b32 s12, s49, s53
	v_lshl_add_u64 v[160:161], s[10:11], 0, v[154:155]
	s_add_i32 m0, s9, 0xc000
	ds_read_b128 v[168:171], v166
	ds_read_b128 v[172:175], v166 offset:1024
	ds_read_b128 v[176:179], v166 offset:2048
	ds_read_b128 v[180:183], v166 offset:3072
	ds_read_b128 v[184:187], v166 offset:4096
	ds_read_b128 v[188:191], v166 offset:5120
	ds_read_b128 v[192:195], v166 offset:6144
	ds_read_b128 v[198:201], v166 offset:7168
	global_load_lds_dwordx4 v[160:161], off
	v_lshl_add_u64 v[160:161], s[10:11], 0, v[152:153]
	s_add_i32 m0, s9, 0xe000
	s_nop 0
	global_load_lds_dwordx4 v[160:161], off
	s_waitcnt lgkmcnt(8)
	s_barrier
	s_setprio 1
	s_waitcnt lgkmcnt(7)
	v_mfma_f32_16x16x32_bf16 v[140:143], v[40:43], v[168:171], v[140:143]
	v_mfma_f32_16x16x32_bf16 v[136:139], v[56:59], v[168:171], v[136:139]
	s_waitcnt lgkmcnt(5)
	v_mfma_f32_16x16x32_bf16 v[124:127], v[40:43], v[176:179], v[124:127]
	v_mfma_f32_16x16x32_bf16 v[120:123], v[56:59], v[176:179], v[120:123]
	s_waitcnt lgkmcnt(3)
	v_mfma_f32_16x16x32_bf16 v[108:111], v[40:43], v[184:187], v[108:111]
	v_mfma_f32_16x16x32_bf16 v[104:107], v[56:59], v[184:187], v[104:107]
	s_waitcnt lgkmcnt(1)
	v_mfma_f32_16x16x32_bf16 v[92:95], v[40:43], v[192:195], v[92:95]
	v_mfma_f32_16x16x32_bf16 v[88:91], v[56:59], v[192:195], v[88:91]
	v_mfma_f32_16x16x32_bf16 v[140:143], v[44:47], v[172:175], v[140:143]
	v_mfma_f32_16x16x32_bf16 v[136:139], v[60:63], v[172:175], v[136:139]
	v_mfma_f32_16x16x32_bf16 v[124:127], v[44:47], v[180:183], v[124:127]
	v_mfma_f32_16x16x32_bf16 v[120:123], v[60:63], v[180:183], v[120:123]
	v_mfma_f32_16x16x32_bf16 v[108:111], v[44:47], v[188:191], v[108:111]
	v_mfma_f32_16x16x32_bf16 v[104:107], v[60:63], v[188:191], v[104:107]
	s_waitcnt lgkmcnt(0)
	v_mfma_f32_16x16x32_bf16 v[92:95], v[44:47], v[198:201], v[92:95]
	v_mfma_f32_16x16x32_bf16 v[88:91], v[60:63], v[198:201], v[88:91]
	s_setprio 0
	s_barrier
	s_add_i32 s57, s35, s22
	v_lshl_add_u64 v[160:161], s[12:13], 0, v[148:149]
	s_mov_b32 m0, s57
	ds_read_b128 v[202:205], v167
	ds_read_b128 v[206:209], v167 offset:1024
	ds_read_b128 v[210:213], v167 offset:2048
	ds_read_b128 v[214:217], v167 offset:3072
	global_load_lds_dwordx4 v[160:161], off
	v_lshl_add_u64 v[218:219], s[12:13], 0, v[144:145]
	s_add_i32 m0, s57, 0x2000
	s_nop 0
	global_load_lds_dwordx4 v[218:219], off
	s_barrier
	s_setprio 1
	s_waitcnt lgkmcnt(3)
	v_mfma_f32_16x16x32_bf16 v[132:135], v[202:205], v[168:171], v[132:135]
	s_waitcnt lgkmcnt(1)
	v_mfma_f32_16x16x32_bf16 v[128:131], v[210:213], v[168:171], v[128:131]
	v_mfma_f32_16x16x32_bf16 v[116:119], v[202:205], v[176:179], v[116:119]
	v_mfma_f32_16x16x32_bf16 v[112:115], v[210:213], v[176:179], v[112:115]
	v_mfma_f32_16x16x32_bf16 v[100:103], v[202:205], v[184:187], v[100:103]
	v_mfma_f32_16x16x32_bf16 v[96:99], v[210:213], v[184:187], v[96:99]
	v_mfma_f32_16x16x32_bf16 v[84:87], v[202:205], v[192:195], v[84:87]
	v_mfma_f32_16x16x32_bf16 v[80:83], v[210:213], v[192:195], v[80:83]
	v_mfma_f32_16x16x32_bf16 v[132:135], v[206:209], v[172:175], v[132:135]
	s_waitcnt lgkmcnt(0)
	v_mfma_f32_16x16x32_bf16 v[128:131], v[214:217], v[172:175], v[128:131]
	v_mfma_f32_16x16x32_bf16 v[116:119], v[206:209], v[180:183], v[116:119]
	v_mfma_f32_16x16x32_bf16 v[112:115], v[214:217], v[180:183], v[112:115]
	v_mfma_f32_16x16x32_bf16 v[100:103], v[206:209], v[188:191], v[100:103]
	v_mfma_f32_16x16x32_bf16 v[96:99], v[214:217], v[188:191], v[96:99]
	v_mfma_f32_16x16x32_bf16 v[84:87], v[206:209], v[198:201], v[84:87]
	v_mfma_f32_16x16x32_bf16 v[80:83], v[214:217], v[198:201], v[80:83]
	s_setprio 0
	s_mov_b32 m0, s9
	v_lshl_add_u64 v[220:221], s[14:15], 0, v[150:151]
	s_barrier
	ds_read_b128 v[168:171], v166 offset:16384
	ds_read_b128 v[172:175], v166 offset:17408
	ds_read_b128 v[176:179], v166 offset:18432
	ds_read_b128 v[180:183], v166 offset:19456
	ds_read_b128 v[184:187], v166 offset:20480
	ds_read_b128 v[188:191], v166 offset:21504
	ds_read_b128 v[192:195], v166 offset:22528
	ds_read_b128 v[198:201], v166 offset:23552
	global_load_lds_dwordx4 v[220:221], off
	v_lshl_add_u64 v[222:223], s[14:15], 0, v[146:147]
	s_mov_b32 m0, s24
	s_nop 0
	global_load_lds_dwordx4 v[222:223], off
	s_barrier
	s_setprio 1
	s_waitcnt lgkmcnt(7)
	v_mfma_f32_16x16x32_bf16 v[76:79], v[40:43], v[168:171], v[76:79]
	v_mfma_f32_16x16x32_bf16 v[72:75], v[56:59], v[168:171], v[72:75]
	s_waitcnt lgkmcnt(5)
	v_mfma_f32_16x16x32_bf16 v[52:55], v[40:43], v[176:179], v[52:55]
	v_mfma_f32_16x16x32_bf16 v[48:51], v[56:59], v[176:179], v[48:51]
	s_waitcnt lgkmcnt(3)
	v_mfma_f32_16x16x32_bf16 v[28:31], v[40:43], v[184:187], v[28:31]
	v_mfma_f32_16x16x32_bf16 v[24:27], v[56:59], v[184:187], v[24:27]
	s_waitcnt lgkmcnt(1)
	v_mfma_f32_16x16x32_bf16 v[12:15], v[40:43], v[192:195], v[12:15]
	v_mfma_f32_16x16x32_bf16 v[8:11], v[56:59], v[192:195], v[8:11]
	v_mfma_f32_16x16x32_bf16 v[76:79], v[44:47], v[172:175], v[76:79]
	v_mfma_f32_16x16x32_bf16 v[72:75], v[60:63], v[172:175], v[72:75]
	v_mfma_f32_16x16x32_bf16 v[52:55], v[44:47], v[180:183], v[52:55]
	v_mfma_f32_16x16x32_bf16 v[48:51], v[60:63], v[180:183], v[48:51]
	v_mfma_f32_16x16x32_bf16 v[28:31], v[44:47], v[188:191], v[28:31]
	v_mfma_f32_16x16x32_bf16 v[24:27], v[60:63], v[188:191], v[24:27]
	s_waitcnt lgkmcnt(0)
	v_mfma_f32_16x16x32_bf16 v[12:15], v[44:47], v[198:201], v[12:15]
	v_mfma_f32_16x16x32_bf16 v[8:11], v[60:63], v[198:201], v[8:11]
	s_setprio 0
	s_barrier
; #define PG8_STAGE(bufoff, gbase, voff) do { _Pragma("unroll") for (int _i = 0; _i < 2; ++_i) \
;         __builtin_amdgcn_global_load_lds((const unsigned*)((const char*)(gbase) + (voff)[_i]), (LAS unsigned*)(lds + (bufoff) + ldsw + _i * 8192), 16, 0, 0); } while (0)
; #define PG8_LDA(dst, b, h) do { _Pragma("unroll") for (int m = 0; m < 4; ++m) _Pragma("unroll") for (int k = 0; k < 2; ++k) dst[m][k] = *(const LAS bf16x8*)(lds + PG8_SA(b, h) + aoff + m * 2048 + k * 1024); } while (0)
; #define PG8_LDB(dst, b, h) do { _Pragma("unroll") for (int n = 0; n < 2; ++n) _Pragma("unroll") for (int k = 0; k < 2; ++k) dst[n][k] = *(const LAS bf16x8*)(lds + PG8_SB(b, h) + boff + n * 2048 + k * 1024); } while (0)
; #define PG8_MMA(ai, bj, At, Bt) do { __builtin_amdgcn_s_setprio(1); _Pragma("unroll") for (int m = 0; m < 4; ++m) _Pragma("unroll") for (int n = 0; n < 2; ++n) _Pragma("unroll") for (int k = 0; k < 2; ++k) \
;         acc[ai][bj][m][n] = __builtin_amdgcn_mfma_f32_16x16x32_bf16(Bt[n][k], At[m][k], acc[ai][bj][m][n], 0, 0, 0); __builtin_amdgcn_s_setprio(0); } while (0)
; #define PG8_WAIT_V(n) asm volatile("s_waitcnt vmcnt(" #n ")" ::: "memory")
; #define PG8_WAIT_L(n) asm volatile("s_waitcnt lgkmcnt(" #n ")" ::: "memory")
; #define PG8_BAR __builtin_amdgcn_s_barrier()
; #define PG8_SCHED __builtin_amdgcn_sched_barrier(0)
; template <class Map, class Epi>
; DI void gemm_phase(LAS unsigned char* lds, const Map& MP, const Epi& E, const int nM, const int nN, const int K, const int lda, const int ldb) {
;     ...
;             PG8_STAGE(PG8_SB(0, 1), b2 + hstepB, voffB);
;             PG8_WAIT_V(6); PG8_BAR; PG8_MMA(1, 1, At, B1); PG8_BAR;
;             PG8_LDB(B0, 1, 0); PG8_SCHED; PG8_LDA(At, 1, 0); PG8_STAGE(PG8_SA(0, 1), a2 + hstepA, voffA);
;             PG8_WAIT_L(8); PG8_BAR; PG8_WAIT_L(0); PG8_MMA(0, 0, At, B0); PG8_BAR; PG8_SCHED;
;             PG8_LDB(B1, 1, 1); PG8_STAGE(PG8_SB(1, 0), b3, voffB);
;             PG8_BAR; PG8_WAIT_L(0); PG8_MMA(0, 1, At, B1); PG8_BAR;
	s_add_u32 s58, s12, 0x20000
	s_addc_u32 s59, s13, 0
	s_add_i32 s57, s36, s22
	v_lshl_add_u64 v[40:41], s[58:59], 0, v[148:149]
	s_mov_b32 m0, s57
	s_nop 0
	global_load_lds_dwordx4 v[40:41], off
	v_lshl_add_u64 v[40:41], s[58:59], 0, v[144:145]
	s_add_i32 m0, s57, 0x2000
	s_nop 0
	global_load_lds_dwordx4 v[40:41], off
	s_waitcnt vmcnt(6)
	s_barrier
	s_setprio 1
	v_mfma_f32_16x16x32_bf16 v[36:39], v[202:205], v[176:179], v[36:39]
	v_mfma_f32_16x16x32_bf16 v[32:35], v[210:213], v[176:179], v[32:35]
	v_mfma_f32_16x16x32_bf16 v[20:23], v[202:205], v[184:187], v[20:23]
	v_mfma_f32_16x16x32_bf16 v[16:19], v[210:213], v[184:187], v[16:19]
	v_mfma_f32_16x16x32_bf16 v[4:7], v[202:205], v[192:195], v[4:7]
	v_mfma_f32_16x16x32_bf16 v[0:3], v[210:213], v[192:195], v[0:3]
	v_mfma_f32_16x16x32_bf16 v[40:43], v[202:205], v[168:171], v[68:71]
	v_mfma_f32_16x16x32_bf16 v[44:47], v[210:213], v[168:171], v[64:67]
	v_mfma_f32_16x16x32_bf16 v[36:39], v[206:209], v[180:183], v[36:39]
	v_mfma_f32_16x16x32_bf16 v[32:35], v[214:217], v[180:183], v[32:35]
	v_mfma_f32_16x16x32_bf16 v[20:23], v[206:209], v[188:191], v[20:23]
	v_mfma_f32_16x16x32_bf16 v[16:19], v[214:217], v[188:191], v[16:19]
	v_mfma_f32_16x16x32_bf16 v[4:7], v[206:209], v[198:201], v[4:7]
	v_mfma_f32_16x16x32_bf16 v[0:3], v[214:217], v[198:201], v[0:3]
	v_mfma_f32_16x16x32_bf16 v[40:43], v[206:209], v[172:175], v[40:43]
	v_mfma_f32_16x16x32_bf16 v[44:47], v[214:217], v[172:175], v[44:47]
	s_setprio 0
	s_add_i32 s57, 0, 0x18000
	v_add_u32_e32 v68, s57, v164
	s_barrier
	ds_read_b128 v[56:59], v68
	ds_read_b128 v[60:63], v68 offset:1024
	ds_read_b128 v[64:67], v68 offset:2048
	ds_read_b128 v[68:71], v68 offset:3072
	s_add_u32 s14, s14, 0x80000
	s_addc_u32 s15, s15, 0
	s_mov_b32 m0, s25
	v_lshl_add_u64 v[202:203], s[14:15], 0, v[150:151]
	ds_read_b128 v[168:171], v166 offset:32768
	ds_read_b128 v[172:175], v166 offset:33792
	ds_read_b128 v[176:179], v166 offset:34816
	ds_read_b128 v[180:183], v166 offset:35840
	ds_read_b128 v[184:187], v166 offset:36864
	ds_read_b128 v[188:191], v166 offset:37888
	ds_read_b128 v[192:195], v166 offset:38912
	ds_read_b128 v[198:201], v166 offset:39936
	global_load_lds_dwordx4 v[202:203], off
	v_lshl_add_u64 v[202:203], s[14:15], 0, v[146:147]
	s_mov_b32 m0, s26
	s_nop 0
	global_load_lds_dwordx4 v[202:203], off
	s_waitcnt lgkmcnt(8)
	s_barrier
	s_setprio 1
	s_waitcnt lgkmcnt(7)
	v_mfma_f32_16x16x32_bf16 v[140:143], v[56:59], v[168:171], v[140:143]
	v_mfma_f32_16x16x32_bf16 v[136:139], v[64:67], v[168:171], v[136:139]
	s_waitcnt lgkmcnt(5)
	v_mfma_f32_16x16x32_bf16 v[124:127], v[56:59], v[176:179], v[124:127]
	v_mfma_f32_16x16x32_bf16 v[120:123], v[64:67], v[176:179], v[120:123]
	s_waitcnt lgkmcnt(3)
	v_mfma_f32_16x16x32_bf16 v[108:111], v[56:59], v[184:187], v[108:111]
	v_mfma_f32_16x16x32_bf16 v[104:107], v[64:67], v[184:187], v[104:107]
	s_waitcnt lgkmcnt(1)
	v_mfma_f32_16x16x32_bf16 v[92:95], v[56:59], v[192:195], v[92:95]
	v_mfma_f32_16x16x32_bf16 v[88:91], v[64:67], v[192:195], v[88:91]
	v_mfma_f32_16x16x32_bf16 v[140:143], v[60:63], v[172:175], v[140:143]
	v_mfma_f32_16x16x32_bf16 v[136:139], v[68:71], v[172:175], v[136:139]
	v_mfma_f32_16x16x32_bf16 v[124:127], v[60:63], v[180:183], v[124:127]
	v_mfma_f32_16x16x32_bf16 v[120:123], v[68:71], v[180:183], v[120:123]
	v_mfma_f32_16x16x32_bf16 v[108:111], v[60:63], v[188:191], v[108:111]
	v_mfma_f32_16x16x32_bf16 v[104:107], v[68:71], v[188:191], v[104:107]
	s_waitcnt lgkmcnt(0)
	v_mfma_f32_16x16x32_bf16 v[92:95], v[60:63], v[198:201], v[92:95]
	v_mfma_f32_16x16x32_bf16 v[88:91], v[68:71], v[198:201], v[88:91]
	s_setprio 0
	s_barrier
	s_add_i32 s14, 0, 0x1c000
	s_add_i32 s15, s57, s22
	v_add_u32_e32 v196, s14, v164
	v_lshl_add_u64 v[160:161], v[160:161], 0, s[46:47]
	s_mov_b32 m0, s15
	ds_read_b128 v[202:205], v196
	ds_read_b128 v[206:209], v196 offset:1024
	ds_read_b128 v[210:213], v196 offset:2048
	ds_read_b128 v[214:217], v196 offset:3072
	global_load_lds_dwordx4 v[160:161], off
	v_lshl_add_u64 v[160:161], v[218:219], 0, s[46:47]
	s_add_i32 m0, s15, 0x2000
	s_nop 0
	global_load_lds_dwordx4 v[160:161], off
	s_barrier
	s_setprio 1
	s_waitcnt lgkmcnt(3)
	v_mfma_f32_16x16x32_bf16 v[132:135], v[202:205], v[168:171], v[132:135]
	s_waitcnt lgkmcnt(1)
	v_mfma_f32_16x16x32_bf16 v[128:131], v[210:213], v[168:171], v[128:131]
	v_mfma_f32_16x16x32_bf16 v[116:119], v[202:205], v[176:179], v[116:119]
	v_mfma_f32_16x16x32_bf16 v[112:115], v[210:213], v[176:179], v[112:115]
	v_mfma_f32_16x16x32_bf16 v[100:103], v[202:205], v[184:187], v[100:103]
	v_mfma_f32_16x16x32_bf16 v[96:99], v[210:213], v[184:187], v[96:99]
	v_mfma_f32_16x16x32_bf16 v[84:87], v[202:205], v[192:195], v[84:87]
	v_mfma_f32_16x16x32_bf16 v[80:83], v[210:213], v[192:195], v[80:83]
	v_mfma_f32_16x16x32_bf16 v[132:135], v[206:209], v[172:175], v[132:135]
	s_waitcnt lgkmcnt(0)
	v_mfma_f32_16x16x32_bf16 v[128:131], v[214:217], v[172:175], v[128:131]
	v_mfma_f32_16x16x32_bf16 v[116:119], v[206:209], v[180:183], v[116:119]
	v_mfma_f32_16x16x32_bf16 v[112:115], v[214:217], v[180:183], v[112:115]
	v_mfma_f32_16x16x32_bf16 v[100:103], v[206:209], v[188:191], v[100:103]
	v_mfma_f32_16x16x32_bf16 v[96:99], v[214:217], v[188:191], v[96:99]
	v_mfma_f32_16x16x32_bf16 v[84:87], v[206:209], v[198:201], v[84:87]
	v_mfma_f32_16x16x32_bf16 v[80:83], v[214:217], v[198:201], v[80:83]
	s_setprio 0
	s_mov_b32 m0, s30
	v_lshl_add_u64 v[160:161], v[220:221], 0, s[46:47]
	s_barrier
; DI unsigned pack2(float a, float b) { f32x2 v = {a, b}; hwbf16x2 r = __builtin_convertvector(v, hwbf16x2); return __builtin_bit_cast(unsigned, r); }
; DI float bflo(unsigned w) { return __uint_as_float(w << 16); }
; DI float bfhi(unsigned w) { return __uint_as_float(w & 0xffff0000u); }
; #define PG8_WAIT_V(n) asm volatile("s_waitcnt vmcnt(" #n ")" ::: "memory")
; #define PG8_BAR __builtin_amdgcn_s_barrier()
;     DI void operator()(const f32x4 (&acc)[2][2][4][2], const Unit& u, int wr, int wc, int fr, int fq) const {
;     ...
;         f32x4 sc[2][2];
; #pragma unroll
;         for (int bj = 0; bj < 2; ++bj)
; #pragma unroll
;             for (int n = 0; n < 2; ++n) sc[bj][n] = scale ? *(const f32x4*)(scale + col0 + bj * HALF + 4 * n) : (f32x4){1.f, 1.f, 1.f, 1.f};
; #pragma unroll
;         for (int ai = 0; ai < 2; ++ai)
; #pragma unroll
;             for (int m = 0; m < 4; ++m) { const size_t ro = (size_t)(row0 + ai * HALF + m * 16) * D + col0;
; #pragma unroll
;                 for (int bj = 0; bj < 2; ++bj) {
;                     f32x4 x0, x1;
;                     if constexpr (IB) { const u32x4 w = *(const u32x4*)((const bf16_t*)Xin + ro + bj * HALF);
;                         x0 = (f32x4){bflo(w[0]), bfhi(w[0]), bflo(w[1]), bfhi(w[1])}; x1 = (f32x4){bflo(w[2]), bfhi(w[2]), bflo(w[3]), bfhi(w[3])}; }
;                     else { x0 = *(const f32x4*)((const float*)Xin + ro + bj * HALF); x1 = *(const f32x4*)((const float*)Xin + ro + bj * HALF + 4); }
;                     x0 += acc[ai][bj][m][0] * sc[bj][0]; x1 += acc[ai][bj][m][1] * sc[bj][1];
;                     if constexpr (OB) { u32x4 o; o[0] = pack2(x0[0], x0[1]); o[1] = pack2(x0[2], x0[3]); o[2] = pack2(x1[0], x1[1]); o[3] = pack2(x1[2], x1[3]);
;                         *(u32x4*)((bf16_t*)Xout + ro + bj * HALF) = o; }
;                     else { *(f32x4*)((float*)Xout + ro + bj * HALF) = x0; *(f32x4*)((float*)Xout + ro + bj * HALF + 4) = x1; } } }
; template <class Map, class Epi>
; DI void gemm_phase(LAS unsigned char* lds, const Map& MP, const Epi& E, const int nM, const int nN, const int K, const int lda, const int ldb) {
;     ...
;             PG8_LDA(At, 1, 1); PG8_STAGE(PG8_SA(1, 0), a3, voffA);
;             PG8_BAR; PG8_WAIT_L(0); PG8_MMA(1, 0, At, B0); PG8_BAR; PG8_SCHED;
;             PG8_STAGE(PG8_SB(1, 1), b3 + hstepB, voffB);
;             PG8_WAIT_V(6); PG8_BAR; PG8_MMA(1, 1, At, B1); PG8_BAR;
	ds_read_b128 v[168:171], v166 offset:49152
	ds_read_b128 v[172:175], v166 offset:50176
	ds_read_b128 v[176:179], v166 offset:51200
	ds_read_b128 v[180:183], v166 offset:52224
	ds_read_b128 v[184:187], v166 offset:53248
	ds_read_b128 v[188:191], v166 offset:54272
	ds_read_b128 v[192:195], v166 offset:55296
	ds_read_b128 v[198:201], v166 offset:56320
	global_load_lds_dwordx4 v[160:161], off
	v_lshl_add_u64 v[160:161], v[222:223], 0, s[46:47]
	s_mov_b32 m0, s31
	s_nop 0
	global_load_lds_dwordx4 v[160:161], off
	s_barrier
	s_setprio 1
	s_waitcnt lgkmcnt(7)
	v_mfma_f32_16x16x32_bf16 v[76:79], v[56:59], v[168:171], v[76:79]
	v_mfma_f32_16x16x32_bf16 v[72:75], v[64:67], v[168:171], v[72:75]
	s_waitcnt lgkmcnt(5)
	v_mfma_f32_16x16x32_bf16 v[52:55], v[56:59], v[176:179], v[52:55]
	v_mfma_f32_16x16x32_bf16 v[48:51], v[64:67], v[176:179], v[48:51]
	s_waitcnt lgkmcnt(3)
	v_mfma_f32_16x16x32_bf16 v[28:31], v[56:59], v[184:187], v[28:31]
	v_mfma_f32_16x16x32_bf16 v[24:27], v[64:67], v[184:187], v[24:27]
	s_waitcnt lgkmcnt(1)
	v_mfma_f32_16x16x32_bf16 v[12:15], v[56:59], v[192:195], v[12:15]
	v_mfma_f32_16x16x32_bf16 v[8:11], v[64:67], v[192:195], v[8:11]
	v_mfma_f32_16x16x32_bf16 v[76:79], v[60:63], v[172:175], v[76:79]
	v_mfma_f32_16x16x32_bf16 v[72:75], v[68:71], v[172:175], v[72:75]
	v_mfma_f32_16x16x32_bf16 v[52:55], v[60:63], v[180:183], v[52:55]
	v_mfma_f32_16x16x32_bf16 v[48:51], v[68:71], v[180:183], v[48:51]
	v_mfma_f32_16x16x32_bf16 v[28:31], v[60:63], v[188:191], v[28:31]
	v_mfma_f32_16x16x32_bf16 v[24:27], v[68:71], v[188:191], v[24:27]
	s_waitcnt lgkmcnt(0)
	v_mfma_f32_16x16x32_bf16 v[12:15], v[60:63], v[198:201], v[12:15]
	v_mfma_f32_16x16x32_bf16 v[8:11], v[68:71], v[198:201], v[8:11]
	s_setprio 0
	s_barrier
	s_add_u32 s12, s12, 0x20080
	s_addc_u32 s13, s13, 0
	s_add_i32 s14, s14, s22
	v_lshl_add_u64 v[56:57], s[12:13], 0, v[148:149]
	s_mov_b32 m0, s14
	s_nop 0
	global_load_lds_dwordx4 v[56:57], off
	v_lshl_add_u64 v[56:57], s[12:13], 0, v[144:145]
	s_add_i32 m0, s14, 0x2000
	s_nop 0
	global_load_lds_dwordx4 v[56:57], off
	s_waitcnt vmcnt(6)
	s_barrier
	s_setprio 1
	v_mfma_f32_16x16x32_bf16 v[40:43], v[202:205], v[168:171], v[40:43]
	v_mfma_f32_16x16x32_bf16 v[68:71], v[206:209], v[172:175], v[40:43]
	v_mfma_f32_16x16x32_bf16 v[40:43], v[210:213], v[168:171], v[44:47]
	v_mfma_f32_16x16x32_bf16 v[36:39], v[202:205], v[176:179], v[36:39]
	v_mfma_f32_16x16x32_bf16 v[32:35], v[210:213], v[176:179], v[32:35]
	v_mfma_f32_16x16x32_bf16 v[20:23], v[202:205], v[184:187], v[20:23]
	v_mfma_f32_16x16x32_bf16 v[16:19], v[210:213], v[184:187], v[16:19]
	v_mfma_f32_16x16x32_bf16 v[4:7], v[202:205], v[192:195], v[4:7]
	v_mfma_f32_16x16x32_bf16 v[0:3], v[210:213], v[192:195], v[0:3]
	v_mfma_f32_16x16x32_bf16 v[64:67], v[214:217], v[172:175], v[40:43]
	v_mfma_f32_16x16x32_bf16 v[36:39], v[206:209], v[180:183], v[36:39]
	v_mfma_f32_16x16x32_bf16 v[32:35], v[214:217], v[180:183], v[32:35]
	v_mfma_f32_16x16x32_bf16 v[20:23], v[206:209], v[188:191], v[20:23]
	v_mfma_f32_16x16x32_bf16 v[16:19], v[214:217], v[188:191], v[16:19]
	v_mfma_f32_16x16x32_bf16 v[4:7], v[206:209], v[198:201], v[4:7]
	v_mfma_f32_16x16x32_bf16 v[0:3], v[214:217], v[198:201], v[0:3]
	s_setprio 0
	s_add_i32 s3, s3, 2
	s_add_u32 s53, s53, 0x100
	s_addc_u32 s56, s56, 0
	s_add_u32 s10, s10, 0x100
	s_addc_u32 s11, s11, 0
	s_cmp_gt_u32 s3, 5
	s_barrier
	s_cbranch_scc0 .LBB1_2339
	s_lshl_b32 s2, s2, 8
	v_mov_b32_e32 v40, v163
	v_mov_b32_e32 v168, v162
	s_or_b32 s2, s2, s29
	s_and_b64 vcc, exec, s[40:41]
	v_lshl_add_u32 v160, v40, 3, s2
	s_lshl_b32 s2, s8, 8
	s_add_i32 s2, s2, s28
	v_add_u32_e32 v168, s2, v168
	v_ashrrev_i32_e32 v169, 31, v168
	v_ashrrev_i32_e32 v161, 31, v160
	v_lshlrev_b64 v[168:169], 11, v[168:169]
	v_lshl_add_u64 v[44:45], v[160:161], 2, s[44:45]
	v_lshl_add_u64 v[160:161], v[168:169], 0, v[160:161]
	v_lshlrev_b64 v[160:161], 1, v[160:161]
	v_lshl_add_u64 v[172:173], s[4:5], 0, v[160:161]
	global_load_dwordx4 v[56:59], v[44:45], off offset:16
	global_load_dwordx4 v[60:63], v[44:45], off
	global_load_dwordx4 v[40:43], v[44:45], off offset:528
	s_nop 0
	global_load_dwordx4 v[44:47], v[44:45], off offset:512
	s_mov_b64 s[2:3], 0x10000
	flat_load_dwordx4 v[168:171], v[172:173]
	s_mov_b32 s8, s52
	s_mov_b64 s[10:11], s[54:55]
	s_mov_b64 s[12:13], s[6:7]
	s_waitcnt vmcnt(0) lgkmcnt(0)
	v_lshlrev_b32_e32 v174, 16, v168
	v_and_b32_e32 v175, 0xffff0000, v168
	v_lshlrev_b32_e32 v168, 16, v169
	v_and_b32_e32 v169, 0xffff0000, v169
	v_lshlrev_b32_e32 v176, 16, v170
	v_and_b32_e32 v177, 0xffff0000, v170
	v_lshlrev_b32_e32 v170, 16, v171
	v_and_b32_e32 v171, 0xffff0000, v171
	v_pk_fma_f32 v[142:143], v[142:143], v[62:63], v[168:169]
	v_pk_fma_f32 v[140:141], v[140:141], v[60:61], v[174:175]
	v_pk_fma_f32 v[168:169], v[138:139], v[58:59], v[170:171]
	v_pk_fma_f32 v[138:139], v[136:137], v[56:57], v[176:177]
	v_cvt_pk_bf16_f32 v136, v140, v141
	v_cvt_pk_bf16_f32 v137, v142, v143
	v_cvt_pk_bf16_f32 v138, v138, v139
	v_cvt_pk_bf16_f32 v139, v168, v169
	v_lshl_add_u64 v[140:141], s[42:43], 0, v[160:161]
	flat_store_dwordx4 v[140:141], v[136:139]
	flat_load_dwordx4 v[136:139], v[172:173] offset:256
	s_waitcnt vmcnt(0) lgkmcnt(0)
	v_lshlrev_b32_e32 v142, 16, v136
	v_and_b32_e32 v143, 0xffff0000, v136
	v_lshlrev_b32_e32 v136, 16, v137
	v_and_b32_e32 v137, 0xffff0000, v137
	v_lshlrev_b32_e32 v168, 16, v138
	v_and_b32_e32 v169, 0xffff0000, v138
	v_lshlrev_b32_e32 v138, 16, v139
	v_and_b32_e32 v139, 0xffff0000, v139
	v_pk_fma_f32 v[134:135], v[134:135], v[46:47], v[136:137]
	v_pk_fma_f32 v[132:133], v[132:133], v[44:45], v[142:143]
	v_pk_fma_f32 v[136:137], v[130:131], v[42:43], v[138:139]
	v_pk_fma_f32 v[130:131], v[128:129], v[40:41], v[168:169]
	v_cvt_pk_bf16_f32 v128, v132, v133
	v_cvt_pk_bf16_f32 v129, v134, v135
	v_cvt_pk_bf16_f32 v130, v130, v131
	v_cvt_pk_bf16_f32 v131, v136, v137
	v_lshl_add_u64 v[132:133], v[160:161], 0, s[2:3]
	flat_store_dwordx4 v[140:141], v[128:131] offset:256
	v_lshl_add_u64 v[134:135], s[4:5], 0, v[132:133]
	flat_load_dwordx4 v[128:131], v[134:135]
	s_mov_b64 s[2:3], 0x20000
	s_waitcnt vmcnt(0) lgkmcnt(0)
; DI unsigned pack2(float a, float b) { f32x2 v = {a, b}; hwbf16x2 r = __builtin_convertvector(v, hwbf16x2); return __builtin_bit_cast(unsigned, r); }
; DI float bflo(unsigned w) { return __uint_as_float(w << 16); }
; DI float bfhi(unsigned w) { return __uint_as_float(w & 0xffff0000u); }
;     DI void operator()(const f32x4 (&acc)[2][2][4][2], const Unit& u, int wr, int wc, int fr, int fq) const {
;     ...
;         for (int ai = 0; ai < 2; ++ai)
; #pragma unroll
;             for (int m = 0; m < 4; ++m) { const size_t ro = (size_t)(row0 + ai * HALF + m * 16) * D + col0;
; #pragma unroll
;                 for (int bj = 0; bj < 2; ++bj) {
;                     f32x4 x0, x1;
;                     if constexpr (IB) { const u32x4 w = *(const u32x4*)((const bf16_t*)Xin + ro + bj * HALF);
;                         x0 = (f32x4){bflo(w[0]), bfhi(w[0]), bflo(w[1]), bfhi(w[1])}; x1 = (f32x4){bflo(w[2]), bfhi(w[2]), bflo(w[3]), bfhi(w[3])}; }
;                     else { x0 = *(const f32x4*)((const float*)Xin + ro + bj * HALF); x1 = *(const f32x4*)((const float*)Xin + ro + bj * HALF + 4); }
;                     x0 += acc[ai][bj][m][0] * sc[bj][0]; x1 += acc[ai][bj][m][1] * sc[bj][1];
;                     if constexpr (OB) { u32x4 o; o[0] = pack2(x0[0], x0[1]); o[1] = pack2(x0[2], x0[3]); o[2] = pack2(x1[0], x1[1]); o[3] = pack2(x1[2], x1[3]);
;                         *(u32x4*)((bf16_t*)Xout + ro + bj * HALF) = o; }
;                     else { *(f32x4*)((float*)Xout + ro + bj * HALF) = x0; *(f32x4*)((float*)Xout + ro + bj * HALF + 4) = x1; } } }
	v_lshlrev_b32_e32 v136, 16, v128
	v_and_b32_e32 v137, 0xffff0000, v128
	v_lshlrev_b32_e32 v128, 16, v129
	v_and_b32_e32 v129, 0xffff0000, v129
	v_lshlrev_b32_e32 v138, 16, v130
	v_and_b32_e32 v139, 0xffff0000, v130
	v_lshlrev_b32_e32 v130, 16, v131
	v_and_b32_e32 v131, 0xffff0000, v131
	v_pk_fma_f32 v[126:127], v[126:127], v[62:63], v[128:129]
	v_pk_fma_f32 v[124:125], v[124:125], v[60:61], v[136:137]
	v_pk_fma_f32 v[128:129], v[122:123], v[58:59], v[130:131]
	v_pk_fma_f32 v[122:123], v[120:121], v[56:57], v[138:139]
	v_cvt_pk_bf16_f32 v120, v124, v125
	v_cvt_pk_bf16_f32 v121, v126, v127
	v_cvt_pk_bf16_f32 v122, v122, v123
	v_cvt_pk_bf16_f32 v123, v128, v129
	v_lshl_add_u64 v[124:125], s[42:43], 0, v[132:133]
	flat_store_dwordx4 v[124:125], v[120:123]
	flat_load_dwordx4 v[120:123], v[134:135] offset:256
	s_waitcnt vmcnt(0) lgkmcnt(0)
	v_lshlrev_b32_e32 v126, 16, v120
	v_and_b32_e32 v127, 0xffff0000, v120
	v_lshlrev_b32_e32 v120, 16, v121
	v_and_b32_e32 v121, 0xffff0000, v121
	v_lshlrev_b32_e32 v128, 16, v122
	v_and_b32_e32 v129, 0xffff0000, v122
	v_lshlrev_b32_e32 v122, 16, v123
	v_and_b32_e32 v123, 0xffff0000, v123
	v_pk_fma_f32 v[118:119], v[118:119], v[46:47], v[120:121]
	v_pk_fma_f32 v[116:117], v[116:117], v[44:45], v[126:127]
	v_pk_fma_f32 v[120:121], v[114:115], v[42:43], v[122:123]
	v_pk_fma_f32 v[114:115], v[112:113], v[40:41], v[128:129]
	v_cvt_pk_bf16_f32 v112, v116, v117
	v_cvt_pk_bf16_f32 v113, v118, v119
	v_cvt_pk_bf16_f32 v114, v114, v115
	v_cvt_pk_bf16_f32 v115, v120, v121
	v_lshl_add_u64 v[116:117], v[160:161], 0, s[2:3]
	flat_store_dwordx4 v[124:125], v[112:115] offset:256
	v_lshl_add_u64 v[118:119], s[4:5], 0, v[116:117]
	flat_load_dwordx4 v[112:115], v[118:119]
	s_mov_b64 s[2:3], 0x30000
	s_waitcnt vmcnt(0) lgkmcnt(0)
	v_lshlrev_b32_e32 v120, 16, v112
	v_and_b32_e32 v121, 0xffff0000, v112
	v_lshlrev_b32_e32 v112, 16, v113
	v_and_b32_e32 v113, 0xffff0000, v113
	v_lshlrev_b32_e32 v122, 16, v114
	v_and_b32_e32 v123, 0xffff0000, v114
	v_lshlrev_b32_e32 v114, 16, v115
	v_and_b32_e32 v115, 0xffff0000, v115
	v_pk_fma_f32 v[110:111], v[110:111], v[62:63], v[112:113]
	v_pk_fma_f32 v[108:109], v[108:109], v[60:61], v[120:121]
	v_pk_fma_f32 v[112:113], v[106:107], v[58:59], v[114:115]
	v_pk_fma_f32 v[106:107], v[104:105], v[56:57], v[122:123]
	v_cvt_pk_bf16_f32 v104, v108, v109
	v_cvt_pk_bf16_f32 v105, v110, v111
	v_cvt_pk_bf16_f32 v106, v106, v107
	v_cvt_pk_bf16_f32 v107, v112, v113
	v_lshl_add_u64 v[108:109], s[42:43], 0, v[116:117]
	flat_store_dwordx4 v[108:109], v[104:107]
	flat_load_dwordx4 v[104:107], v[118:119] offset:256
	s_waitcnt vmcnt(0) lgkmcnt(0)
	v_lshlrev_b32_e32 v110, 16, v104
	v_and_b32_e32 v111, 0xffff0000, v104
	v_lshlrev_b32_e32 v104, 16, v105
	v_and_b32_e32 v105, 0xffff0000, v105
	v_lshlrev_b32_e32 v112, 16, v106
	v_and_b32_e32 v113, 0xffff0000, v106
	v_lshlrev_b32_e32 v106, 16, v107
	v_and_b32_e32 v107, 0xffff0000, v107
	v_pk_fma_f32 v[102:103], v[102:103], v[46:47], v[104:105]
	v_pk_fma_f32 v[100:101], v[100:101], v[44:45], v[110:111]
	v_pk_fma_f32 v[104:105], v[98:99], v[42:43], v[106:107]
	v_pk_fma_f32 v[98:99], v[96:97], v[40:41], v[112:113]
	v_cvt_pk_bf16_f32 v96, v100, v101
	v_cvt_pk_bf16_f32 v97, v102, v103
	v_cvt_pk_bf16_f32 v98, v98, v99
	v_cvt_pk_bf16_f32 v99, v104, v105
	v_lshl_add_u64 v[100:101], v[160:161], 0, s[2:3]
	flat_store_dwordx4 v[108:109], v[96:99] offset:256
	v_lshl_add_u64 v[102:103], s[4:5], 0, v[100:101]
	flat_load_dwordx4 v[96:99], v[102:103]
	s_mov_b64 s[2:3], 0x80000
	s_waitcnt vmcnt(0) lgkmcnt(0)
	v_lshlrev_b32_e32 v104, 16, v96
	v_and_b32_e32 v105, 0xffff0000, v96
	v_lshlrev_b32_e32 v96, 16, v97
	v_and_b32_e32 v97, 0xffff0000, v97
	v_lshlrev_b32_e32 v106, 16, v98
	v_and_b32_e32 v107, 0xffff0000, v98
	v_lshlrev_b32_e32 v98, 16, v99
	v_and_b32_e32 v99, 0xffff0000, v99
	v_pk_fma_f32 v[94:95], v[94:95], v[62:63], v[96:97]
	v_pk_fma_f32 v[92:93], v[92:93], v[60:61], v[104:105]
	v_pk_fma_f32 v[96:97], v[90:91], v[58:59], v[98:99]
	v_pk_fma_f32 v[90:91], v[88:89], v[56:57], v[106:107]
	v_cvt_pk_bf16_f32 v88, v92, v93
	v_cvt_pk_bf16_f32 v89, v94, v95
	v_cvt_pk_bf16_f32 v90, v90, v91
	v_cvt_pk_bf16_f32 v91, v96, v97
	v_lshl_add_u64 v[92:93], s[42:43], 0, v[100:101]
	flat_store_dwordx4 v[92:93], v[88:91]
	flat_load_dwordx4 v[88:91], v[102:103] offset:256
	s_waitcnt vmcnt(0) lgkmcnt(0)
	v_lshlrev_b32_e32 v94, 16, v88
	v_and_b32_e32 v95, 0xffff0000, v88
	v_lshlrev_b32_e32 v88, 16, v89
	v_and_b32_e32 v89, 0xffff0000, v89
	v_lshlrev_b32_e32 v96, 16, v90
	v_and_b32_e32 v97, 0xffff0000, v90
	v_lshlrev_b32_e32 v90, 16, v91
	v_and_b32_e32 v91, 0xffff0000, v91
	v_pk_fma_f32 v[86:87], v[86:87], v[46:47], v[88:89]
	v_pk_fma_f32 v[84:85], v[84:85], v[44:45], v[94:95]
	v_pk_fma_f32 v[88:89], v[82:83], v[42:43], v[90:91]
	v_pk_fma_f32 v[82:83], v[80:81], v[40:41], v[96:97]
	v_cvt_pk_bf16_f32 v80, v84, v85
	v_cvt_pk_bf16_f32 v81, v86, v87
	v_cvt_pk_bf16_f32 v82, v82, v83
	v_cvt_pk_bf16_f32 v83, v88, v89
	v_lshl_add_u64 v[84:85], v[160:161], 0, s[2:3]
	flat_store_dwordx4 v[92:93], v[80:83] offset:256
	v_lshl_add_u64 v[86:87], s[4:5], 0, v[84:85]
	flat_load_dwordx4 v[80:83], v[86:87]
	s_mov_b64 s[2:3], 0x90000
	s_waitcnt vmcnt(0) lgkmcnt(0)
	v_lshlrev_b32_e32 v88, 16, v80
	v_and_b32_e32 v89, 0xffff0000, v80
	v_lshlrev_b32_e32 v80, 16, v81
	v_and_b32_e32 v81, 0xffff0000, v81
	v_lshlrev_b32_e32 v90, 16, v82
	v_and_b32_e32 v91, 0xffff0000, v82
	v_lshlrev_b32_e32 v82, 16, v83
	v_and_b32_e32 v83, 0xffff0000, v83
	v_pk_fma_f32 v[78:79], v[78:79], v[62:63], v[80:81]
	v_pk_fma_f32 v[76:77], v[76:77], v[60:61], v[88:89]
	v_pk_fma_f32 v[80:81], v[74:75], v[58:59], v[82:83]
	v_pk_fma_f32 v[74:75], v[72:73], v[56:57], v[90:91]
	v_cvt_pk_bf16_f32 v72, v76, v77
	v_cvt_pk_bf16_f32 v73, v78, v79
	v_cvt_pk_bf16_f32 v74, v74, v75
	v_cvt_pk_bf16_f32 v75, v80, v81
	v_lshl_add_u64 v[76:77], s[42:43], 0, v[84:85]
	flat_store_dwordx4 v[76:77], v[72:75]
	flat_load_dwordx4 v[72:75], v[86:87] offset:256
	s_waitcnt vmcnt(0) lgkmcnt(0)
; DI unsigned pack2(float a, float b) { f32x2 v = {a, b}; hwbf16x2 r = __builtin_convertvector(v, hwbf16x2); return __builtin_bit_cast(unsigned, r); }
; DI float bflo(unsigned w) { return __uint_as_float(w << 16); }
; DI float bfhi(unsigned w) { return __uint_as_float(w & 0xffff0000u); }
;     DI void operator()(const f32x4 (&acc)[2][2][4][2], const Unit& u, int wr, int wc, int fr, int fq) const {
;     ...
;         for (int ai = 0; ai < 2; ++ai)
; #pragma unroll
;             for (int m = 0; m < 4; ++m) { const size_t ro = (size_t)(row0 + ai * HALF + m * 16) * D + col0;
; #pragma unroll
;                 for (int bj = 0; bj < 2; ++bj) {
;                     f32x4 x0, x1;
;                     if constexpr (IB) { const u32x4 w = *(const u32x4*)((const bf16_t*)Xin + ro + bj * HALF);
;                         x0 = (f32x4){bflo(w[0]), bfhi(w[0]), bflo(w[1]), bfhi(w[1])}; x1 = (f32x4){bflo(w[2]), bfhi(w[2]), bflo(w[3]), bfhi(w[3])}; }
;                     else { x0 = *(const f32x4*)((const float*)Xin + ro + bj * HALF); x1 = *(const f32x4*)((const float*)Xin + ro + bj * HALF + 4); }
;                     x0 += acc[ai][bj][m][0] * sc[bj][0]; x1 += acc[ai][bj][m][1] * sc[bj][1];
;                     if constexpr (OB) { u32x4 o; o[0] = pack2(x0[0], x0[1]); o[1] = pack2(x0[2], x0[3]); o[2] = pack2(x1[0], x1[1]); o[3] = pack2(x1[2], x1[3]);
;                         *(u32x4*)((bf16_t*)Xout + ro + bj * HALF) = o; }
;                     else { *(f32x4*)((float*)Xout + ro + bj * HALF) = x0; *(f32x4*)((float*)Xout + ro + bj * HALF + 4) = x1; } } }
	v_lshlrev_b32_e32 v78, 16, v72
	v_and_b32_e32 v79, 0xffff0000, v72
	v_lshlrev_b32_e32 v72, 16, v73
	v_and_b32_e32 v73, 0xffff0000, v73
	v_lshlrev_b32_e32 v80, 16, v74
	v_and_b32_e32 v81, 0xffff0000, v74
	v_lshlrev_b32_e32 v74, 16, v75
	v_and_b32_e32 v75, 0xffff0000, v75
	v_pk_fma_f32 v[70:71], v[70:71], v[46:47], v[72:73]
	v_pk_fma_f32 v[68:69], v[68:69], v[44:45], v[78:79]
	v_pk_fma_f32 v[72:73], v[66:67], v[42:43], v[74:75]
	v_pk_fma_f32 v[66:67], v[64:65], v[40:41], v[80:81]
	v_cvt_pk_bf16_f32 v64, v68, v69
	v_cvt_pk_bf16_f32 v65, v70, v71
	v_cvt_pk_bf16_f32 v66, v66, v67
	v_cvt_pk_bf16_f32 v67, v72, v73
	v_lshl_add_u64 v[68:69], v[160:161], 0, s[2:3]
	flat_store_dwordx4 v[76:77], v[64:67] offset:256
	v_lshl_add_u64 v[70:71], s[4:5], 0, v[68:69]
	flat_load_dwordx4 v[64:67], v[70:71]
	s_mov_b64 s[2:3], 0xa0000
	s_waitcnt vmcnt(0) lgkmcnt(0)
	v_lshlrev_b32_e32 v72, 16, v64
	v_and_b32_e32 v73, 0xffff0000, v64
	v_lshlrev_b32_e32 v64, 16, v65
	v_and_b32_e32 v65, 0xffff0000, v65
	v_lshlrev_b32_e32 v74, 16, v66
	v_and_b32_e32 v75, 0xffff0000, v66
	v_lshlrev_b32_e32 v66, 16, v67
	v_and_b32_e32 v67, 0xffff0000, v67
	v_pk_fma_f32 v[54:55], v[54:55], v[62:63], v[64:65]
	v_pk_fma_f32 v[52:53], v[52:53], v[60:61], v[72:73]
	v_pk_fma_f32 v[64:65], v[50:51], v[58:59], v[66:67]
	v_pk_fma_f32 v[50:51], v[48:49], v[56:57], v[74:75]
	v_cvt_pk_bf16_f32 v48, v52, v53
	v_cvt_pk_bf16_f32 v49, v54, v55
	v_cvt_pk_bf16_f32 v50, v50, v51
	v_cvt_pk_bf16_f32 v51, v64, v65
	v_lshl_add_u64 v[52:53], s[42:43], 0, v[68:69]
	flat_store_dwordx4 v[52:53], v[48:51]
	flat_load_dwordx4 v[48:51], v[70:71] offset:256
	s_waitcnt vmcnt(0) lgkmcnt(0)
	v_lshlrev_b32_e32 v54, 16, v48
	v_and_b32_e32 v55, 0xffff0000, v48
	v_lshlrev_b32_e32 v48, 16, v49
	v_and_b32_e32 v49, 0xffff0000, v49
	v_lshlrev_b32_e32 v64, 16, v50
	v_and_b32_e32 v65, 0xffff0000, v50
	v_lshlrev_b32_e32 v50, 16, v51
	v_and_b32_e32 v51, 0xffff0000, v51
	v_pk_fma_f32 v[38:39], v[38:39], v[46:47], v[48:49]
	v_pk_fma_f32 v[36:37], v[36:37], v[44:45], v[54:55]
	v_pk_fma_f32 v[48:49], v[34:35], v[42:43], v[50:51]
	v_pk_fma_f32 v[34:35], v[32:33], v[40:41], v[64:65]
	v_cvt_pk_bf16_f32 v32, v36, v37
	v_cvt_pk_bf16_f32 v33, v38, v39
	v_cvt_pk_bf16_f32 v34, v34, v35
	v_cvt_pk_bf16_f32 v35, v48, v49
	v_lshl_add_u64 v[36:37], v[160:161], 0, s[2:3]
	flat_store_dwordx4 v[52:53], v[32:35] offset:256
	v_lshl_add_u64 v[38:39], s[4:5], 0, v[36:37]
	flat_load_dwordx4 v[32:35], v[38:39]
	s_mov_b64 s[2:3], 0xb0000
	s_waitcnt vmcnt(0) lgkmcnt(0)
	v_lshlrev_b32_e32 v48, 16, v32
	v_and_b32_e32 v49, 0xffff0000, v32
	v_lshlrev_b32_e32 v32, 16, v33
	v_and_b32_e32 v33, 0xffff0000, v33
	v_lshlrev_b32_e32 v50, 16, v34
	v_and_b32_e32 v51, 0xffff0000, v34
	v_lshlrev_b32_e32 v34, 16, v35
	v_and_b32_e32 v35, 0xffff0000, v35
	v_pk_fma_f32 v[30:31], v[30:31], v[62:63], v[32:33]
	v_pk_fma_f32 v[28:29], v[28:29], v[60:61], v[48:49]
	v_pk_fma_f32 v[32:33], v[26:27], v[58:59], v[34:35]
	v_pk_fma_f32 v[26:27], v[24:25], v[56:57], v[50:51]
	v_cvt_pk_bf16_f32 v24, v28, v29
	v_cvt_pk_bf16_f32 v25, v30, v31
	v_cvt_pk_bf16_f32 v26, v26, v27
	v_cvt_pk_bf16_f32 v27, v32, v33
	v_lshl_add_u64 v[28:29], s[42:43], 0, v[36:37]
	flat_store_dwordx4 v[28:29], v[24:27]
	flat_load_dwordx4 v[24:27], v[38:39] offset:256
	s_waitcnt vmcnt(0) lgkmcnt(0)
	v_lshlrev_b32_e32 v30, 16, v24
	v_and_b32_e32 v31, 0xffff0000, v24
	v_lshlrev_b32_e32 v24, 16, v25
	v_and_b32_e32 v25, 0xffff0000, v25
	v_lshlrev_b32_e32 v32, 16, v26
	v_and_b32_e32 v33, 0xffff0000, v26
	v_lshlrev_b32_e32 v26, 16, v27
	v_and_b32_e32 v27, 0xffff0000, v27
	v_pk_fma_f32 v[22:23], v[22:23], v[46:47], v[24:25]
	v_pk_fma_f32 v[20:21], v[20:21], v[44:45], v[30:31]
	v_pk_fma_f32 v[24:25], v[18:19], v[42:43], v[26:27]
	v_pk_fma_f32 v[18:19], v[16:17], v[40:41], v[32:33]
	v_cvt_pk_bf16_f32 v16, v20, v21
	v_cvt_pk_bf16_f32 v17, v22, v23
	v_cvt_pk_bf16_f32 v18, v18, v19
	v_cvt_pk_bf16_f32 v19, v24, v25
	v_lshl_add_u64 v[20:21], v[160:161], 0, s[2:3]
	flat_store_dwordx4 v[28:29], v[16:19] offset:256
	v_lshl_add_u64 v[22:23], s[4:5], 0, v[20:21]
	flat_load_dwordx4 v[16:19], v[22:23]
	s_mov_b32 s2, s37
	s_waitcnt vmcnt(0) lgkmcnt(0)
	v_lshlrev_b32_e32 v24, 16, v16
	v_and_b32_e32 v25, 0xffff0000, v16
	v_lshlrev_b32_e32 v16, 16, v17
	v_and_b32_e32 v17, 0xffff0000, v17
	v_lshlrev_b32_e32 v26, 16, v18
	v_and_b32_e32 v27, 0xffff0000, v18
	v_lshlrev_b32_e32 v18, 16, v19
	v_and_b32_e32 v19, 0xffff0000, v19
	v_pk_fma_f32 v[14:15], v[14:15], v[62:63], v[16:17]
	v_pk_fma_f32 v[12:13], v[12:13], v[60:61], v[24:25]
	v_pk_fma_f32 v[16:17], v[10:11], v[58:59], v[18:19]
	v_pk_fma_f32 v[10:11], v[8:9], v[56:57], v[26:27]
	v_cvt_pk_bf16_f32 v8, v12, v13
	v_cvt_pk_bf16_f32 v9, v14, v15
	v_cvt_pk_bf16_f32 v10, v10, v11
	v_cvt_pk_bf16_f32 v11, v16, v17
	v_lshl_add_u64 v[12:13], s[42:43], 0, v[20:21]
	flat_store_dwordx4 v[12:13], v[8:11]
	flat_load_dwordx4 v[8:11], v[22:23] offset:256
	s_waitcnt vmcnt(0) lgkmcnt(0)
	v_lshlrev_b32_e32 v14, 16, v8
	v_and_b32_e32 v15, 0xffff0000, v8
	v_lshlrev_b32_e32 v8, 16, v9
	v_and_b32_e32 v9, 0xffff0000, v9
	v_lshlrev_b32_e32 v16, 16, v10
	v_and_b32_e32 v17, 0xffff0000, v10
	v_lshlrev_b32_e32 v10, 16, v11
	v_and_b32_e32 v11, 0xffff0000, v11
	v_pk_fma_f32 v[6:7], v[6:7], v[46:47], v[8:9]
	v_pk_fma_f32 v[4:5], v[4:5], v[44:45], v[14:15]
	v_pk_fma_f32 v[8:9], v[2:3], v[42:43], v[10:11]
	v_pk_fma_f32 v[2:3], v[0:1], v[40:41], v[16:17]
	v_cvt_pk_bf16_f32 v0, v4, v5
	v_cvt_pk_bf16_f32 v1, v6, v7
	v_cvt_pk_bf16_f32 v2, v2, v3
	v_cvt_pk_bf16_f32 v3, v8, v9
	flat_store_dwordx4 v[12:13], v[0:3] offset:256
	s_cbranch_vccz .LBB1_2336
	s_waitcnt vmcnt(0)
	s_cmpk_gt_u32 s17, 0xff
	s_cbranch_scc1 .LBB1_2343
	s_barrier

; #define PG8_STAGE(bufoff, gbase, voff) do { _Pragma("unroll") for (int _i = 0; _i < 2; ++_i) \
;         __builtin_amdgcn_global_load_lds((const unsigned*)((const char*)(gbase) + (voff)[_i]), (LAS unsigned*)(lds + (bufoff) + ldsw + _i * 8192), 16, 0, 0); } while (0)
; #define PG8_LDA(dst, b, h) do { _Pragma("unroll") for (int m = 0; m < 4; ++m) _Pragma("unroll") for (int k = 0; k < 2; ++k) dst[m][k] = *(const LAS bf16x8*)(lds + PG8_SA(b, h) + aoff + m * 2048 + k * 1024); } while (0)
; #define PG8_LDB(dst, b, h) do { _Pragma("unroll") for (int n = 0; n < 2; ++n) _Pragma("unroll") for (int k = 0; k < 2; ++k) dst[n][k] = *(const LAS bf16x8*)(lds + PG8_SB(b, h) + boff + n * 2048 + k * 1024); } while (0)
; #define PG8_MMA(ai, bj, At, Bt) do { __builtin_amdgcn_s_setprio(1); _Pragma("unroll") for (int m = 0; m < 4; ++m) _Pragma("unroll") for (int n = 0; n < 2; ++n) _Pragma("unroll") for (int k = 0; k < 2; ++k) \
;         acc[ai][bj][m][n] = __builtin_amdgcn_mfma_f32_16x16x32_bf16(Bt[n][k], At[m][k], acc[ai][bj][m][n], 0, 0, 0); __builtin_amdgcn_s_setprio(0); } while (0)
; #define PG8_WAIT_L(n) asm volatile("s_waitcnt lgkmcnt(" #n ")" ::: "memory")
; #define PG8_BAR __builtin_amdgcn_s_barrier()
; #define PG8_SCHED __builtin_amdgcn_sched_barrier(0)
; template <class Map, class Epi>
; DI void gemm_phase(LAS unsigned char* lds, const Map& MP, const Epi& E, const int nM, const int nN, const int K, const int lda, const int ldb) {
;     ...
;             PG8_LDB(B0, 0, 0); PG8_SCHED; PG8_LDA(At, 0, 0); PG8_STAGE(PG8_SA(1, 1), a1 + hstepA, voffA);
;             PG8_WAIT_L(8); PG8_BAR; PG8_WAIT_L(0); PG8_MMA(0, 0, At, B0); PG8_BAR; PG8_SCHED;
;             PG8_LDB(B1, 0, 1); PG8_STAGE(PG8_SB(0, 0), b2, voffB);
;             PG8_BAR; PG8_WAIT_L(0); PG8_MMA(0, 1, At, B1); PG8_BAR;
;             PG8_LDA(At, 0, 1); PG8_STAGE(PG8_SA(0, 0), a2, voffA);
;             PG8_BAR; PG8_WAIT_L(0); PG8_MMA(1, 0, At, B0); PG8_BAR; PG8_SCHED;
.LBB1_2483:
	ds_read_b128 v[80:83], v189
	ds_read_b128 v[84:87], v189 offset:1024
	ds_read_b128 v[88:91], v189 offset:2048
	ds_read_b128 v[92:95], v189 offset:3072
	s_add_u32 s28, s42, 0xfff80080
	s_addc_u32 s29, s43, -1
	s_cmp_eq_u32 s3, 28
	s_cselect_b32 s47, s23, s29
	s_cselect_b32 s46, s58, s28
	s_cselect_b32 s29, s21, vcc_hi
	s_cselect_b32 s28, s59, vcc_lo
	v_lshl_add_u64 v[184:185], s[42:43], 0, v[178:179]
	s_add_i32 m0, s38, 0xc000
	ds_read_b128 v[96:99], v190
	ds_read_b128 v[100:103], v190 offset:1024
	ds_read_b128 v[108:111], v190 offset:2048
	ds_read_b128 v[112:115], v190 offset:3072
	ds_read_b128 v[160:163], v190 offset:4096
	ds_read_b128 v[164:167], v190 offset:5120
	ds_read_b128 v[198:201], v190 offset:6144
	ds_read_b128 v[202:205], v190 offset:7168
	global_load_lds_dwordx4 v[184:185], off
	v_lshl_add_u64 v[184:185], s[42:43], 0, v[176:177]
	s_add_i32 m0, s38, 0xe000
	s_nop 0
	global_load_lds_dwordx4 v[184:185], off
	s_waitcnt lgkmcnt(8)
	s_barrier
	s_setprio 1
	s_waitcnt lgkmcnt(7)
	v_mfma_f32_16x16x32_bf16 v[148:151], v[80:83], v[96:99], v[148:151]
	v_mfma_f32_16x16x32_bf16 v[144:147], v[88:91], v[96:99], v[144:147]
	s_waitcnt lgkmcnt(5)
	v_mfma_f32_16x16x32_bf16 v[136:139], v[80:83], v[108:111], v[136:139]
	v_mfma_f32_16x16x32_bf16 v[128:131], v[88:91], v[108:111], v[128:131]
	s_waitcnt lgkmcnt(3)
	v_mfma_f32_16x16x32_bf16 v[120:123], v[80:83], v[160:163], v[120:123]
	v_mfma_f32_16x16x32_bf16 v[104:107], v[88:91], v[160:163], v[104:107]
	s_waitcnt lgkmcnt(1)
	v_mfma_f32_16x16x32_bf16 v[76:79], v[80:83], v[198:201], v[76:79]
	v_mfma_f32_16x16x32_bf16 v[72:75], v[88:91], v[198:201], v[72:75]
	v_mfma_f32_16x16x32_bf16 v[148:151], v[84:87], v[100:103], v[148:151]
	v_mfma_f32_16x16x32_bf16 v[144:147], v[92:95], v[100:103], v[144:147]
	v_mfma_f32_16x16x32_bf16 v[136:139], v[84:87], v[112:115], v[136:139]
	v_mfma_f32_16x16x32_bf16 v[128:131], v[92:95], v[112:115], v[128:131]
	v_mfma_f32_16x16x32_bf16 v[120:123], v[84:87], v[164:167], v[120:123]
	v_mfma_f32_16x16x32_bf16 v[104:107], v[92:95], v[164:167], v[104:107]
	s_waitcnt lgkmcnt(0)
	v_mfma_f32_16x16x32_bf16 v[76:79], v[84:87], v[202:205], v[76:79]
	v_mfma_f32_16x16x32_bf16 v[72:75], v[92:95], v[202:205], v[72:75]
	s_setprio 0
	s_barrier
	s_add_i32 s68, s2, s37
	v_lshl_add_u64 v[184:185], s[28:29], 0, v[172:173]
	s_mov_b32 m0, s68
	ds_read_b128 v[206:209], v191
	ds_read_b128 v[210:213], v191 offset:1024
	ds_read_b128 v[214:217], v191 offset:2048
	ds_read_b128 v[218:221], v191 offset:3072
	global_load_lds_dwordx4 v[184:185], off
	v_lshl_add_u64 v[194:195], s[28:29], 0, v[168:169]
	s_add_i32 m0, s68, 0x2000
	s_nop 0
	global_load_lds_dwordx4 v[194:195], off
	s_barrier
	s_setprio 1
	s_waitcnt lgkmcnt(3)
	v_mfma_f32_16x16x32_bf16 v[156:159], v[206:209], v[96:99], v[156:159]
	s_waitcnt lgkmcnt(1)
	v_mfma_f32_16x16x32_bf16 v[96:99], v[214:217], v[96:99], v[152:155]
	v_mfma_f32_16x16x32_bf16 v[156:159], v[210:213], v[100:103], v[156:159]
	s_waitcnt lgkmcnt(0)
	v_mfma_f32_16x16x32_bf16 v[96:99], v[218:221], v[100:103], v[96:99]
	v_mfma_f32_16x16x32_bf16 v[100:103], v[206:209], v[108:111], v[140:143]
	v_mfma_f32_16x16x32_bf16 v[108:111], v[214:217], v[108:111], v[132:135]
	v_mfma_f32_16x16x32_bf16 v[116:119], v[214:217], v[160:163], v[116:119]
	v_mfma_f32_16x16x32_bf16 v[68:71], v[206:209], v[198:201], v[68:71]
	v_mfma_f32_16x16x32_bf16 v[64:67], v[214:217], v[198:201], v[64:67]
	v_mfma_f32_16x16x32_bf16 v[100:103], v[210:213], v[112:115], v[100:103]
	v_mfma_f32_16x16x32_bf16 v[108:111], v[218:221], v[112:115], v[108:111]
	v_mfma_f32_16x16x32_bf16 v[112:115], v[206:209], v[160:163], v[124:127]
	v_mfma_f32_16x16x32_bf16 v[116:119], v[218:221], v[164:167], v[116:119]
	v_mfma_f32_16x16x32_bf16 v[68:71], v[210:213], v[202:205], v[68:71]
	v_mfma_f32_16x16x32_bf16 v[64:67], v[218:221], v[202:205], v[64:67]
	v_mfma_f32_16x16x32_bf16 v[112:115], v[210:213], v[164:167], v[112:115]
	s_setprio 0
	s_mov_b32 m0, s38
	v_lshl_add_u64 v[230:231], s[46:47], 0, v[174:175]
	s_barrier
	ds_read_b128 v[124:127], v190 offset:16384
	ds_read_b128 v[132:135], v190 offset:17408
	ds_read_b128 v[140:143], v190 offset:18432
	ds_read_b128 v[152:155], v190 offset:19456
	ds_read_b128 v[160:163], v190 offset:20480
	ds_read_b128 v[164:167], v190 offset:21504
	ds_read_b128 v[198:201], v190 offset:22528
	ds_read_b128 v[202:205], v190 offset:23552
	global_load_lds_dwordx4 v[230:231], off
	v_lshl_add_u64 v[232:233], s[46:47], 0, v[170:171]
	s_mov_b32 m0, s39
	s_nop 0
	global_load_lds_dwordx4 v[232:233], off
	s_barrier
	s_setprio 1
	s_waitcnt lgkmcnt(7)
	v_mfma_f32_16x16x32_bf16 v[60:63], v[80:83], v[124:127], v[60:63]
	v_mfma_f32_16x16x32_bf16 v[48:51], v[88:91], v[124:127], v[48:51]
	s_waitcnt lgkmcnt(5)
	v_mfma_f32_16x16x32_bf16 v[40:43], v[80:83], v[140:143], v[40:43]
	v_mfma_f32_16x16x32_bf16 v[32:35], v[88:91], v[140:143], v[32:35]
	s_waitcnt lgkmcnt(3)
	v_mfma_f32_16x16x32_bf16 v[24:27], v[80:83], v[160:163], v[24:27]
	v_mfma_f32_16x16x32_bf16 v[16:19], v[88:91], v[160:163], v[16:19]
	s_waitcnt lgkmcnt(1)
	v_mfma_f32_16x16x32_bf16 v[12:15], v[80:83], v[198:201], v[12:15]
	v_mfma_f32_16x16x32_bf16 v[8:11], v[88:91], v[198:201], v[8:11]
	v_mfma_f32_16x16x32_bf16 v[60:63], v[84:87], v[132:135], v[60:63]
	v_mfma_f32_16x16x32_bf16 v[48:51], v[92:95], v[132:135], v[48:51]
	v_mfma_f32_16x16x32_bf16 v[40:43], v[84:87], v[152:155], v[40:43]
	v_mfma_f32_16x16x32_bf16 v[32:35], v[92:95], v[152:155], v[32:35]
	v_mfma_f32_16x16x32_bf16 v[24:27], v[84:87], v[164:167], v[24:27]
	v_mfma_f32_16x16x32_bf16 v[16:19], v[92:95], v[164:167], v[16:19]
	s_waitcnt lgkmcnt(0)
	v_mfma_f32_16x16x32_bf16 v[12:15], v[84:87], v[202:205], v[12:15]
	v_mfma_f32_16x16x32_bf16 v[8:11], v[92:95], v[202:205], v[8:11]
	s_setprio 0
	s_barrier
; #define PG8_STAGE(bufoff, gbase, voff) do { _Pragma("unroll") for (int _i = 0; _i < 2; ++_i) \
;         __builtin_amdgcn_global_load_lds((const unsigned*)((const char*)(gbase) + (voff)[_i]), (LAS unsigned*)(lds + (bufoff) + ldsw + _i * 8192), 16, 0, 0); } while (0)
; #define PG8_LDA(dst, b, h) do { _Pragma("unroll") for (int m = 0; m < 4; ++m) _Pragma("unroll") for (int k = 0; k < 2; ++k) dst[m][k] = *(const LAS bf16x8*)(lds + PG8_SA(b, h) + aoff + m * 2048 + k * 1024); } while (0)
; #define PG8_LDB(dst, b, h) do { _Pragma("unroll") for (int n = 0; n < 2; ++n) _Pragma("unroll") for (int k = 0; k < 2; ++k) dst[n][k] = *(const LAS bf16x8*)(lds + PG8_SB(b, h) + boff + n * 2048 + k * 1024); } while (0)
; #define PG8_MMA(ai, bj, At, Bt) do { __builtin_amdgcn_s_setprio(1); _Pragma("unroll") for (int m = 0; m < 4; ++m) _Pragma("unroll") for (int n = 0; n < 2; ++n) _Pragma("unroll") for (int k = 0; k < 2; ++k) \
;         acc[ai][bj][m][n] = __builtin_amdgcn_mfma_f32_16x16x32_bf16(Bt[n][k], At[m][k], acc[ai][bj][m][n], 0, 0, 0); __builtin_amdgcn_s_setprio(0); } while (0)
; #define PG8_WAIT_V(n) asm volatile("s_waitcnt vmcnt(" #n ")" ::: "memory")
; #define PG8_WAIT_L(n) asm volatile("s_waitcnt lgkmcnt(" #n ")" ::: "memory")
; #define PG8_BAR __builtin_amdgcn_s_barrier()
; #define PG8_SCHED __builtin_amdgcn_sched_barrier(0)
; template <class Map, class Epi>
; DI void gemm_phase(LAS unsigned char* lds, const Map& MP, const Epi& E, const int nM, const int nN, const int K, const int lda, const int ldb) {
;     ...
;             PG8_STAGE(PG8_SB(0, 1), b2 + hstepB, voffB);
;             PG8_WAIT_V(6); PG8_BAR; PG8_MMA(1, 1, At, B1); PG8_BAR;
;             PG8_LDB(B0, 1, 0); PG8_SCHED; PG8_LDA(At, 1, 0); PG8_STAGE(PG8_SA(0, 1), a2 + hstepA, voffA);
;             PG8_WAIT_L(8); PG8_BAR; PG8_WAIT_L(0); PG8_MMA(0, 0, At, B0); PG8_BAR; PG8_SCHED;
;             PG8_LDB(B1, 1, 1); PG8_STAGE(PG8_SB(1, 0), b3, voffB);
;             PG8_BAR; PG8_WAIT_L(0); PG8_MMA(0, 1, At, B1); PG8_BAR;
	s_add_u32 s68, s28, 0x80000
	s_addc_u32 s69, s29, 0
	s_add_i32 s70, s67, s37
	v_lshl_add_u64 v[80:81], s[68:69], 0, v[172:173]
	s_mov_b32 m0, s70
	s_nop 0
	global_load_lds_dwordx4 v[80:81], off
	v_lshl_add_u64 v[80:81], s[68:69], 0, v[168:169]
	s_add_i32 m0, s70, 0x2000
	s_nop 0
	global_load_lds_dwordx4 v[80:81], off
	s_waitcnt vmcnt(6)
	s_barrier
	s_setprio 1
	v_mfma_f32_16x16x32_bf16 v[56:59], v[206:209], v[124:127], v[56:59]
	v_mfma_f32_16x16x32_bf16 v[52:55], v[214:217], v[124:127], v[52:55]
	v_mfma_f32_16x16x32_bf16 v[44:47], v[206:209], v[140:143], v[44:47]
	v_mfma_f32_16x16x32_bf16 v[36:39], v[214:217], v[140:143], v[36:39]
	v_mfma_f32_16x16x32_bf16 v[28:31], v[206:209], v[160:163], v[28:31]
	v_mfma_f32_16x16x32_bf16 v[20:23], v[214:217], v[160:163], v[20:23]
	v_mfma_f32_16x16x32_bf16 v[4:7], v[206:209], v[198:201], v[4:7]
	v_mfma_f32_16x16x32_bf16 v[0:3], v[214:217], v[198:201], v[0:3]
	v_mfma_f32_16x16x32_bf16 v[56:59], v[210:213], v[132:135], v[56:59]
	v_mfma_f32_16x16x32_bf16 v[52:55], v[218:221], v[132:135], v[52:55]
	v_mfma_f32_16x16x32_bf16 v[44:47], v[210:213], v[152:155], v[44:47]
	v_mfma_f32_16x16x32_bf16 v[36:39], v[218:221], v[152:155], v[36:39]
	v_mfma_f32_16x16x32_bf16 v[28:31], v[210:213], v[164:167], v[28:31]
	v_mfma_f32_16x16x32_bf16 v[20:23], v[218:221], v[164:167], v[20:23]
	v_mfma_f32_16x16x32_bf16 v[4:7], v[210:213], v[202:205], v[4:7]
	v_mfma_f32_16x16x32_bf16 v[0:3], v[218:221], v[202:205], v[0:3]
	s_setprio 0
	s_add_i32 s68, 0, 0x18000
	v_add_u32_e32 v92, s68, v188
	s_barrier
	ds_read_b128 v[80:83], v92
	ds_read_b128 v[84:87], v92 offset:1024
	ds_read_b128 v[88:91], v92 offset:2048
	ds_read_b128 v[92:95], v92 offset:3072
	s_add_u32 s46, s46, 0x80000
	s_addc_u32 s47, s47, 0
	s_mov_b32 m0, s55
	v_lshl_add_u64 v[140:141], s[46:47], 0, v[174:175]
	ds_read_b128 v[124:127], v190 offset:32768
	ds_read_b128 v[132:135], v190 offset:33792
	ds_read_b128 v[160:163], v190 offset:34816
	ds_read_b128 v[164:167], v190 offset:35840
	ds_read_b128 v[198:201], v190 offset:36864
	ds_read_b128 v[202:205], v190 offset:37888
	ds_read_b128 v[206:209], v190 offset:38912
	ds_read_b128 v[210:213], v190 offset:39936
	global_load_lds_dwordx4 v[140:141], off
	v_lshl_add_u64 v[140:141], s[46:47], 0, v[170:171]
	s_mov_b32 m0, s56
	s_nop 0
	global_load_lds_dwordx4 v[140:141], off
	s_waitcnt lgkmcnt(8)
	s_barrier
	s_setprio 1
	s_waitcnt lgkmcnt(7)
	v_mfma_f32_16x16x32_bf16 v[140:143], v[80:83], v[124:127], v[148:151]
	s_waitcnt lgkmcnt(6)
	v_mfma_f32_16x16x32_bf16 v[148:151], v[84:87], v[132:135], v[140:143]
	v_mfma_f32_16x16x32_bf16 v[140:143], v[88:91], v[124:127], v[144:147]
	s_waitcnt lgkmcnt(5)
	v_mfma_f32_16x16x32_bf16 v[136:139], v[80:83], v[160:163], v[136:139]
	v_mfma_f32_16x16x32_bf16 v[128:131], v[88:91], v[160:163], v[128:131]
	s_waitcnt lgkmcnt(3)
	v_mfma_f32_16x16x32_bf16 v[120:123], v[80:83], v[198:201], v[120:123]
	v_mfma_f32_16x16x32_bf16 v[104:107], v[88:91], v[198:201], v[104:107]
	s_waitcnt lgkmcnt(1)
	v_mfma_f32_16x16x32_bf16 v[76:79], v[80:83], v[206:209], v[76:79]
	v_mfma_f32_16x16x32_bf16 v[72:75], v[88:91], v[206:209], v[72:75]
	v_mfma_f32_16x16x32_bf16 v[144:147], v[92:95], v[132:135], v[140:143]
	v_mfma_f32_16x16x32_bf16 v[136:139], v[84:87], v[164:167], v[136:139]
	v_mfma_f32_16x16x32_bf16 v[128:131], v[92:95], v[164:167], v[128:131]
	v_mfma_f32_16x16x32_bf16 v[120:123], v[84:87], v[202:205], v[120:123]
	v_mfma_f32_16x16x32_bf16 v[104:107], v[92:95], v[202:205], v[104:107]
	s_waitcnt lgkmcnt(0)
	v_mfma_f32_16x16x32_bf16 v[76:79], v[84:87], v[210:213], v[76:79]
	v_mfma_f32_16x16x32_bf16 v[72:75], v[92:95], v[210:213], v[72:75]
	s_setprio 0
	s_barrier
	s_add_i32 s46, 0, 0x1c000
	v_add_u32_e32 v140, s46, v188
	s_add_i32 s47, s68, s37
	ds_read_b128 v[214:217], v140
	ds_read_b128 v[218:221], v140 offset:1024
	ds_read_b128 v[222:225], v140 offset:2048
	ds_read_b128 v[226:229], v140 offset:3072
	v_lshl_add_u64 v[140:141], v[184:185], 0, s[14:15]
	s_mov_b32 m0, s47
	s_nop 0
	global_load_lds_dwordx4 v[140:141], off
	v_lshl_add_u64 v[140:141], v[194:195], 0, s[14:15]
	s_add_i32 m0, s47, 0x2000
	s_nop 0
	global_load_lds_dwordx4 v[140:141], off
	s_barrier
	s_setprio 1
	s_waitcnt lgkmcnt(1)
	v_mfma_f32_16x16x32_bf16 v[96:99], v[222:225], v[124:127], v[96:99]
	v_mfma_f32_16x16x32_bf16 v[140:143], v[214:217], v[124:127], v[156:159]
	s_waitcnt lgkmcnt(0)
	v_mfma_f32_16x16x32_bf16 v[152:155], v[226:229], v[132:135], v[96:99]
	v_mfma_f32_16x16x32_bf16 v[96:99], v[214:217], v[160:163], v[100:103]
	v_mfma_f32_16x16x32_bf16 v[156:159], v[218:221], v[132:135], v[140:143]
	v_mfma_f32_16x16x32_bf16 v[140:143], v[218:221], v[164:167], v[96:99]
	v_mfma_f32_16x16x32_bf16 v[96:99], v[222:225], v[160:163], v[108:111]
	v_mfma_f32_16x16x32_bf16 v[132:135], v[226:229], v[164:167], v[96:99]
	v_mfma_f32_16x16x32_bf16 v[96:99], v[214:217], v[198:201], v[112:115]
	v_mfma_f32_16x16x32_bf16 v[124:127], v[218:221], v[202:205], v[96:99]
	v_mfma_f32_16x16x32_bf16 v[96:99], v[222:225], v[198:201], v[116:119]
	v_mfma_f32_16x16x32_bf16 v[68:71], v[214:217], v[206:209], v[68:71]
	v_mfma_f32_16x16x32_bf16 v[64:67], v[222:225], v[206:209], v[64:67]
	v_mfma_f32_16x16x32_bf16 v[116:119], v[226:229], v[202:205], v[96:99]
	v_mfma_f32_16x16x32_bf16 v[68:71], v[218:221], v[210:213], v[68:71]
	v_mfma_f32_16x16x32_bf16 v[64:67], v[226:229], v[210:213], v[64:67]
	s_setprio 0
	s_mov_b32 m0, s62
	v_lshl_add_u64 v[184:185], v[230:231], 0, s[14:15]
	s_barrier
; #define PG8_STAGE(bufoff, gbase, voff) do { _Pragma("unroll") for (int _i = 0; _i < 2; ++_i) \
;         __builtin_amdgcn_global_load_lds((const unsigned*)((const char*)(gbase) + (voff)[_i]), (LAS unsigned*)(lds + (bufoff) + ldsw + _i * 8192), 16, 0, 0); } while (0)
; #define PG8_LDA(dst, b, h) do { _Pragma("unroll") for (int m = 0; m < 4; ++m) _Pragma("unroll") for (int k = 0; k < 2; ++k) dst[m][k] = *(const LAS bf16x8*)(lds + PG8_SA(b, h) + aoff + m * 2048 + k * 1024); } while (0)
; #define PG8_MMA(ai, bj, At, Bt) do { __builtin_amdgcn_s_setprio(1); _Pragma("unroll") for (int m = 0; m < 4; ++m) _Pragma("unroll") for (int n = 0; n < 2; ++n) _Pragma("unroll") for (int k = 0; k < 2; ++k) \
;         acc[ai][bj][m][n] = __builtin_amdgcn_mfma_f32_16x16x32_bf16(Bt[n][k], At[m][k], acc[ai][bj][m][n], 0, 0, 0); __builtin_amdgcn_s_setprio(0); } while (0)
; #define PG8_WAIT_V(n) asm volatile("s_waitcnt vmcnt(" #n ")" ::: "memory")
; #define PG8_WAIT_L(n) asm volatile("s_waitcnt lgkmcnt(" #n ")" ::: "memory")
; #define PG8_BAR __builtin_amdgcn_s_barrier()
; #define PG8_SCHED __builtin_amdgcn_sched_barrier(0)
; template <class Map, class Epi>
; DI void gemm_phase(LAS unsigned char* lds, const Map& MP, const Epi& E, const int nM, const int nN, const int K, const int lda, const int ldb) {
;     ...
;             PG8_LDA(At, 1, 1); PG8_STAGE(PG8_SA(1, 0), a3, voffA);
;             PG8_BAR; PG8_WAIT_L(0); PG8_MMA(1, 0, At, B0); PG8_BAR; PG8_SCHED;
;             PG8_STAGE(PG8_SB(1, 1), b3 + hstepB, voffB);
;             PG8_WAIT_V(6); PG8_BAR; PG8_MMA(1, 1, At, B1); PG8_BAR;
	ds_read_b128 v[96:99], v190 offset:49152
	ds_read_b128 v[100:103], v190 offset:50176
	ds_read_b128 v[108:111], v190 offset:51200
	ds_read_b128 v[112:115], v190 offset:52224
	ds_read_b128 v[160:163], v190 offset:53248
	ds_read_b128 v[164:167], v190 offset:54272
	ds_read_b128 v[198:201], v190 offset:55296
	ds_read_b128 v[202:205], v190 offset:56320
	global_load_lds_dwordx4 v[184:185], off
	v_lshl_add_u64 v[184:185], v[232:233], 0, s[14:15]
	s_mov_b32 m0, s63
	s_nop 0
	global_load_lds_dwordx4 v[184:185], off
	s_barrier
	s_setprio 1
	s_waitcnt lgkmcnt(7)
	v_mfma_f32_16x16x32_bf16 v[60:63], v[80:83], v[96:99], v[60:63]
	v_mfma_f32_16x16x32_bf16 v[48:51], v[88:91], v[96:99], v[48:51]
	s_waitcnt lgkmcnt(5)
	v_mfma_f32_16x16x32_bf16 v[40:43], v[80:83], v[108:111], v[40:43]
	v_mfma_f32_16x16x32_bf16 v[32:35], v[88:91], v[108:111], v[32:35]
	s_waitcnt lgkmcnt(3)
	v_mfma_f32_16x16x32_bf16 v[24:27], v[80:83], v[160:163], v[24:27]
	v_mfma_f32_16x16x32_bf16 v[16:19], v[88:91], v[160:163], v[16:19]
	s_waitcnt lgkmcnt(1)
	v_mfma_f32_16x16x32_bf16 v[12:15], v[80:83], v[198:201], v[12:15]
	v_mfma_f32_16x16x32_bf16 v[8:11], v[88:91], v[198:201], v[8:11]
	v_mfma_f32_16x16x32_bf16 v[60:63], v[84:87], v[100:103], v[60:63]
	v_mfma_f32_16x16x32_bf16 v[48:51], v[92:95], v[100:103], v[48:51]
	v_mfma_f32_16x16x32_bf16 v[40:43], v[84:87], v[112:115], v[40:43]
	v_mfma_f32_16x16x32_bf16 v[32:35], v[92:95], v[112:115], v[32:35]
	v_mfma_f32_16x16x32_bf16 v[24:27], v[84:87], v[164:167], v[24:27]
	v_mfma_f32_16x16x32_bf16 v[16:19], v[92:95], v[164:167], v[16:19]
	s_waitcnt lgkmcnt(0)
	v_mfma_f32_16x16x32_bf16 v[12:15], v[84:87], v[202:205], v[12:15]
	v_mfma_f32_16x16x32_bf16 v[8:11], v[92:95], v[202:205], v[8:11]
	s_setprio 0
	s_barrier
	s_add_u32 s28, s28, 0x80080
	s_addc_u32 s29, s29, 0
	s_add_i32 s46, s46, s37
	v_lshl_add_u64 v[80:81], s[28:29], 0, v[172:173]
	s_mov_b32 m0, s46
	s_nop 0
	global_load_lds_dwordx4 v[80:81], off
	v_lshl_add_u64 v[80:81], s[28:29], 0, v[168:169]
	s_add_i32 m0, s46, 0x2000
	s_nop 0
	global_load_lds_dwordx4 v[80:81], off
	s_waitcnt vmcnt(6)
	s_barrier
	s_setprio 1
	v_mfma_f32_16x16x32_bf16 v[56:59], v[214:217], v[96:99], v[56:59]
	v_mfma_f32_16x16x32_bf16 v[52:55], v[222:225], v[96:99], v[52:55]
	v_mfma_f32_16x16x32_bf16 v[44:47], v[214:217], v[108:111], v[44:47]
	v_mfma_f32_16x16x32_bf16 v[36:39], v[222:225], v[108:111], v[36:39]
	v_mfma_f32_16x16x32_bf16 v[28:31], v[214:217], v[160:163], v[28:31]
	v_mfma_f32_16x16x32_bf16 v[20:23], v[222:225], v[160:163], v[20:23]
	v_mfma_f32_16x16x32_bf16 v[4:7], v[214:217], v[198:201], v[4:7]
	v_mfma_f32_16x16x32_bf16 v[0:3], v[222:225], v[198:201], v[0:3]
	v_mfma_f32_16x16x32_bf16 v[56:59], v[218:221], v[100:103], v[56:59]
	v_mfma_f32_16x16x32_bf16 v[52:55], v[226:229], v[100:103], v[52:55]
	v_mfma_f32_16x16x32_bf16 v[44:47], v[218:221], v[112:115], v[44:47]
	v_mfma_f32_16x16x32_bf16 v[36:39], v[226:229], v[112:115], v[36:39]
	v_mfma_f32_16x16x32_bf16 v[28:31], v[218:221], v[164:167], v[28:31]
	v_mfma_f32_16x16x32_bf16 v[20:23], v[226:229], v[164:167], v[20:23]
	v_mfma_f32_16x16x32_bf16 v[4:7], v[218:221], v[202:205], v[4:7]
	v_mfma_f32_16x16x32_bf16 v[0:3], v[226:229], v[202:205], v[0:3]
	s_setprio 0
	s_add_i32 s3, s3, 2
	s_add_u32 vcc_lo, vcc_lo, 0x100
	s_addc_u32 vcc_hi, vcc_hi, 0
	s_add_u32 s42, s42, 0x100
	s_addc_u32 s43, s43, 0
	s_cmp_gt_u32 s3, 29
	s_barrier
	s_cbranch_scc0 .LBB1_2483
; DI float silu_mul(float g, float v) { return g * v * __builtin_amdgcn_rcpf(1.0f + __builtin_amdgcn_exp2f(-LOG2E * g)); }
;     DI void operator()(const f32x4 (&acc)[2][2][4][2], const Unit& u, int wr, int wc, int fr, int fq) const {
;         const int row0 = u.pm * BM + wr * 64 + fr, ch0 = u.pn * 128 + wc * 32 + 8 * fq;
;         f32x4 w0[2], w1[2], w2[2], bb[2];
; #pragma unroll
;         for (int n = 0; n < 2; ++n) { w0[n] = *(const f32x4*)(cw + ch0 + 4 * n); w1[n] = *(const f32x4*)(cw + DFF + ch0 + 4 * n); w2[n] = *(const f32x4*)(cw + 2 * DFF + ch0 + 4 * n); bb[n] = *(const f32x4*)(cb + ch0 + 4 * n); }
; #pragma unroll
;         for (int ai = 0; ai < 2; ++ai)
; #pragma unroll
;             for (int m = 0; m < 4; ++m) {
;                 const bool efirst = (m == 0) && (fr == 0), elast = (m == 3) && (fr == 15);
;                 const int row = row0 + ai * HALF + m * 16;
;                 f32x4 gc[2];
; #pragma unroll
;                 for (int n = 0; n < 2; ++n) {
;                     const f32x4 g = acc[ai][0][m][n];
;                     const f32x4 gprev = acc[ai][0][m > 0 ? m - 1 : 0][n], gnext = acc[ai][0][m < 3 ? m + 1 : 3][n];
;                     f32x4 up, dn;
; #pragma unroll
;                     for (int e = 0; e < 4; ++e) {
;                         const float pu = (m > 0 && fr == 15) ? gprev[e] : g[e];
;                         const float pd = (m < 3 && fr == 0) ? gnext[e] : g[e];
;                         up[e] = dpp_ror1(pu); dn[e] = dpp_ror15(pd);
;                     }
;                     if (efirst) up = (f32x4){0.f, 0.f, 0.f, 0.f};
;                     if (elast) dn = (f32x4){0.f, 0.f, 0.f, 0.f};
;                     gc[n] = w0[n] * up + w1[n] * g + w2[n] * dn + bb[n];
;                 }
;                 if (efirst || elast) {
;                     const size_t eo = (size_t)((row >> 6) * 2 + (elast ? 1 : 0)) * DFF + ch0;
; #pragma unroll
;                     for (int n = 0; n < 2; ++n) { *(f32x4*)(EP + eo + 4 * n) = gc[n]; *(f32x4*)(ER + eo + 4 * n) = acc[ai][0][m][n]; *(f32x4*)(EV + eo + 4 * n) = acc[ai][1][m][n]; }
;                 } else {
;                     const f32x4 v0 = acc[ai][1][m][0], v1 = acc[ai][1][m][1];
;                     u32x4 o;
;                     o[0] = pack2(silu_mul(gc[0][0], v0[0]), silu_mul(gc[0][1], v0[1])); o[1] = pack2(silu_mul(gc[0][2], v0[2]), silu_mul(gc[0][3], v0[3]));
	s_lshl_b32 s21, s45, 7
	v_mov_b32_e32 v80, v187
	v_mov_b32_e32 v194, v186
	s_or_b32 s21, s21, s57
	v_mov_b32_e32 v160, 0
	v_lshl_add_u32 v184, v80, 3, s21
	v_ashrrev_i32_e32 v185, 31, v184
	v_lshlrev_b64 v[80:81], 2, v[184:185]
	v_lshl_add_u64 v[84:85], s[4:5], 0, v[80:81]
	v_lshl_add_u64 v[88:89], s[16:17], 0, v[80:81]
	v_lshl_add_u64 v[92:93], s[18:19], 0, v[80:81]
	v_lshl_add_u64 v[112:113], s[6:7], 0, v[80:81]
	global_load_dwordx4 v[80:83], v[84:85], off offset:16
	global_load_dwordx4 v[96:99], v[84:85], off
	s_nop 0
	global_load_dwordx4 v[84:87], v[88:89], off offset:16
	global_load_dwordx4 v[100:103], v[88:89], off
	s_nop 0
	global_load_dwordx4 v[88:91], v[92:93], off offset:16
	global_load_dwordx4 v[108:111], v[92:93], off
	s_nop 0
	global_load_dwordx4 v[92:95], v[112:113], off offset:16
	s_nop 0
	global_load_dwordx4 v[112:115], v[112:113], off
	v_cmp_eq_u32_e32 vcc, 0, v194
	v_mov_b32_e32 v164, 0
	v_mov_b32_e32 v195, 0
	v_cndmask_b32_e32 v161, v148, v136, vcc
	v_cndmask_b32_e32 v162, v149, v137, vcc
	v_cndmask_b32_e32 v163, v150, v138, vcc
	v_mov_b32_dpp v160, v161 row_ror:15 row_mask:0xf bank_mask:0xf
	v_mov_b32_e32 v161, 0
	v_mov_b32_e32 v166, 0
	v_mov_b32_e32 v167, 0
	v_mov_b32_dpp v161, v162 row_ror:15 row_mask:0xf bank_mask:0xf
	v_mov_b32_e32 v162, 0
	v_mov_b32_dpp v164, v150 row_ror:1 row_mask:0xf bank_mask:0xf
	v_cndmask_b32_e32 v165, v151, v139, vcc
	v_mov_b32_dpp v162, v163 row_ror:15 row_mask:0xf bank_mask:0xf
	v_mov_b32_dpp v195, v151 row_ror:1 row_mask:0xf bank_mask:0xf
	v_mov_b32_e32 v163, 0
	v_mov_b32_dpp v166, v148 row_ror:1 row_mask:0xf bank_mask:0xf
	v_mov_b32_dpp v167, v149 row_ror:1 row_mask:0xf bank_mask:0xf
	v_mov_b32_dpp v163, v165 row_ror:15 row_mask:0xf bank_mask:0xf
	v_cndmask_b32_e64 v165, v195, 0, vcc
	v_cndmask_b32_e64 v164, v164, 0, vcc
	v_cndmask_b32_e64 v167, v167, 0, vcc
	v_cndmask_b32_e64 v166, v166, 0, vcc
	v_mov_b32_e32 v195, 0
	v_mov_b32_e32 v196, 0
	v_mov_b32_e32 v198, 0
	v_mov_b32_e32 v200, 0
	v_mov_b32_dpp v195, v144 row_ror:1 row_mask:0xf bank_mask:0xf
	v_mov_b32_dpp v196, v145 row_ror:1 row_mask:0xf bank_mask:0xf
	v_mov_b32_dpp v198, v146 row_ror:1 row_mask:0xf bank_mask:0xf
	v_cndmask_b32_e32 v199, v147, v131, vcc
	v_mov_b32_dpp v200, v147 row_ror:1 row_mask:0xf bank_mask:0xf
	v_cndmask_b32_e64 v198, v198, 0, vcc
	v_cndmask_b32_e64 v201, v196, 0, vcc
	s_lshl_b32 s3, s44, 8
	s_add_i32 s3, s3, s49
	v_add_u32_e32 v193, s3, v194
	v_cmp_ne_u32_e64 s[46:47], 0, v194
	s_waitcnt vmcnt(0)
	v_pk_mul_f32 v[164:165], v[98:99], v[164:165]
	v_pk_mul_f32 v[166:167], v[96:97], v[166:167]
	v_pk_fma_f32 v[164:165], v[150:151], v[102:103], v[164:165]
	v_pk_fma_f32 v[166:167], v[148:149], v[100:101], v[166:167]
	v_pk_fma_f32 v[162:163], v[110:111], v[162:163], v[164:165]
	v_cndmask_b32_e32 v165, v144, v128, vcc
	v_mov_b32_e32 v164, 0
	v_pk_fma_f32 v[160:161], v[108:109], v[160:161], v[166:167]
	v_cndmask_b32_e32 v166, v145, v129, vcc
	v_mov_b32_dpp v164, v165 row_ror:15 row_mask:0xf bank_mask:0xf
	v_mov_b32_e32 v165, 0
	v_cndmask_b32_e32 v167, v146, v130, vcc
	v_pk_add_f32 v[162:163], v[114:115], v[162:163]
	v_mov_b32_dpp v165, v166 row_ror:15 row_mask:0xf bank_mask:0xf
	v_mov_b32_e32 v166, 0
	v_pk_add_f32 v[160:161], v[112:113], v[160:161]
	s_nop 0
	v_mov_b32_dpp v166, v167 row_ror:15 row_mask:0xf bank_mask:0xf
	v_mov_b32_e32 v167, 0
	s_nop 1
	v_mov_b32_dpp v167, v199 row_ror:15 row_mask:0xf bank_mask:0xf
	v_cndmask_b32_e64 v199, v200, 0, vcc
	v_cndmask_b32_e64 v200, v195, 0, vcc
	v_pk_mul_f32 v[200:201], v[80:81], v[200:201]
	v_pk_mul_f32 v[198:199], v[82:83], v[198:199]
	v_pk_fma_f32 v[200:201], v[144:145], v[84:85], v[200:201]
	v_pk_fma_f32 v[198:199], v[146:147], v[86:87], v[198:199]
	v_pk_fma_f32 v[164:165], v[88:89], v[164:165], v[200:201]
	v_pk_fma_f32 v[166:167], v[90:91], v[166:167], v[198:199]
	v_pk_add_f32 v[164:165], v[92:93], v[164:165]
	v_pk_add_f32 v[166:167], v[94:95], v[166:167]
	s_and_saveexec_b64 s[28:29], s[46:47]
	s_xor_b64 s[28:29], exec, s[28:29]
	s_cbranch_execz .LBB1_2486
	v_mul_f32_e32 v195, 0xbfb8aa3b, v160
	v_exp_f32_e32 v195, v195
	v_mul_f32_e32 v196, 0xbfb8aa3b, v161
	v_exp_f32_e32 v196, v196
	v_pk_mul_f32 v[160:161], v[156:157], v[160:161]
	v_add_f32_e32 v195, 1.0, v195
	v_rcp_f32_e32 v198, v195
	v_add_f32_e32 v196, 1.0, v196
	v_mul_f32_e32 v195, 0xbfb8aa3b, v162
	v_rcp_f32_e32 v199, v196
	v_exp_f32_e32 v195, v195
	v_mul_f32_e32 v196, 0xbfb8aa3b, v163
	v_exp_f32_e32 v196, v196
	v_pk_mul_f32 v[160:161], v[160:161], v[198:199]
	v_add_f32_e32 v195, 1.0, v195
	v_rcp_f32_e32 v200, v195
	v_add_f32_e32 v195, 1.0, v196
	v_rcp_f32_e32 v201, v195
	v_cvt_pk_bf16_f32 v160, v160, v161
	v_mul_f32_e32 v161, 0xbfb8aa3b, v164
	v_exp_f32_e32 v195, v161
	v_mul_f32_e32 v161, 0xbfb8aa3b, v165
	v_exp_f32_e32 v196, v161
	v_pk_mul_f32 v[162:163], v[158:159], v[162:163]
	v_pk_mul_f32 v[164:165], v[152:153], v[164:165]
	v_pk_mul_f32 v[162:163], v[162:163], v[200:201]
	s_nop 0
	v_cvt_pk_bf16_f32 v161, v162, v163
	v_add_f32_e32 v162, 1.0, v195
	v_mul_f32_e32 v195, 0xbfb8aa3b, v166
	v_add_f32_e32 v163, 1.0, v196
	v_exp_f32_e32 v195, v195
	v_mul_f32_e32 v196, 0xbfb8aa3b, v167
	v_exp_f32_e32 v196, v196
	v_rcp_f32_e32 v162, v162
	v_add_f32_e32 v195, 1.0, v195
	v_rcp_f32_e32 v198, v195
	v_add_f32_e32 v195, 1.0, v196
	v_rcp_f32_e32 v163, v163
	v_rcp_f32_e32 v199, v195
	v_pk_mul_f32 v[166:167], v[154:155], v[166:167]
	v_pk_mul_f32 v[162:163], v[164:165], v[162:163]
	v_pk_mul_f32 v[164:165], v[166:167], v[198:199]
	v_cvt_pk_bf16_f32 v162, v162, v163
	v_cvt_pk_bf16_f32 v163, v164, v165
	v_mov_b64_e32 v[164:165], s[52:53]
	v_mad_i64_i32 v[164:165], s[42:43], v193, s60, v[164:165]
	v_lshl_add_u64 v[164:165], v[184:185], 1, v[164:165]
	flat_store_dwordx4 v[164:165], v[160:163]

; #define PG8_STAGE(bufoff, gbase, voff) do { _Pragma("unroll") for (int _i = 0; _i < 2; ++_i) \
;         __builtin_amdgcn_global_load_lds((const unsigned*)((const char*)(gbase) + (voff)[_i]), (LAS unsigned*)(lds + (bufoff) + ldsw + _i * 8192), 16, 0, 0); } while (0)
; #define PG8_LDA(dst, b, h) do { _Pragma("unroll") for (int m = 0; m < 4; ++m) _Pragma("unroll") for (int k = 0; k < 2; ++k) dst[m][k] = *(const LAS bf16x8*)(lds + PG8_SA(b, h) + aoff + m * 2048 + k * 1024); } while (0)
; #define PG8_LDB(dst, b, h) do { _Pragma("unroll") for (int n = 0; n < 2; ++n) _Pragma("unroll") for (int k = 0; k < 2; ++k) dst[n][k] = *(const LAS bf16x8*)(lds + PG8_SB(b, h) + boff + n * 2048 + k * 1024); } while (0)
; #define PG8_MMA(ai, bj, At, Bt) do { __builtin_amdgcn_s_setprio(1); _Pragma("unroll") for (int m = 0; m < 4; ++m) _Pragma("unroll") for (int n = 0; n < 2; ++n) _Pragma("unroll") for (int k = 0; k < 2; ++k) \
;         acc[ai][bj][m][n] = __builtin_amdgcn_mfma_f32_16x16x32_bf16(Bt[n][k], At[m][k], acc[ai][bj][m][n], 0, 0, 0); __builtin_amdgcn_s_setprio(0); } while (0)
; #define PG8_WAIT_L(n) asm volatile("s_waitcnt lgkmcnt(" #n ")" ::: "memory")
; #define PG8_BAR __builtin_amdgcn_s_barrier()
; #define PG8_SCHED __builtin_amdgcn_sched_barrier(0)
; template <class Map, class Epi>
; DI void gemm_phase(LAS unsigned char* lds, const Map& MP, const Epi& E, const int nM, const int nN, const int K, const int lda, const int ldb) {
;     ...
;             PG8_LDB(B0, 0, 0); PG8_SCHED; PG8_LDA(At, 0, 0); PG8_STAGE(PG8_SA(1, 1), a1 + hstepA, voffA);
;             PG8_WAIT_L(8); PG8_BAR; PG8_WAIT_L(0); PG8_MMA(0, 0, At, B0); PG8_BAR; PG8_SCHED;
;             PG8_LDB(B1, 0, 1); PG8_STAGE(PG8_SB(0, 0), b2, voffB);
;             PG8_BAR; PG8_WAIT_L(0); PG8_MMA(0, 1, At, B1); PG8_BAR;
;             PG8_LDA(At, 0, 1); PG8_STAGE(PG8_SA(0, 0), a2, voffA);
;             PG8_BAR; PG8_WAIT_L(0); PG8_MMA(1, 0, At, B0); PG8_BAR; PG8_SCHED;
.LBB1_2653:
	ds_read_b128 v[152:155], v149
	ds_read_b128 v[156:159], v149 offset:1024
	ds_read_b128 v[160:163], v149 offset:2048
	ds_read_b128 v[164:167], v149 offset:3072
	s_add_u32 s10, s8, 0x100
	s_addc_u32 s11, s9, 0
	s_cmpk_eq_i32 s48, 0x54
	s_cselect_b32 s15, s43, s11
	s_cselect_b32 s14, s42, s10
	s_cselect_b32 s13, s45, s39
	s_cselect_b32 s12, s44, s38
	v_lshl_add_u64 v[144:145], s[8:9], 0, v[138:139]
	s_add_i32 m0, s22, 0xc000
	ds_read_b128 v[168:171], v150
	ds_read_b128 v[172:175], v150 offset:1024
	ds_read_b128 v[176:179], v150 offset:2048
	ds_read_b128 v[180:183], v150 offset:3072
	ds_read_b128 v[184:187], v150 offset:4096
	ds_read_b128 v[188:191], v150 offset:5120
	ds_read_b128 v[192:195], v150 offset:6144
	ds_read_b128 v[196:199], v150 offset:7168
	global_load_lds_dwordx4 v[144:145], off
	v_lshl_add_u64 v[144:145], s[8:9], 0, v[136:137]
	s_add_i32 m0, s22, 0xe000
	s_nop 0
	global_load_lds_dwordx4 v[144:145], off
	s_waitcnt lgkmcnt(8)
	s_barrier
	s_setprio 1
	s_waitcnt lgkmcnt(7)
	v_mfma_f32_16x16x32_bf16 v[124:127], v[152:155], v[168:171], v[124:127]
	v_mfma_f32_16x16x32_bf16 v[120:123], v[160:163], v[168:171], v[120:123]
	s_waitcnt lgkmcnt(5)
	v_mfma_f32_16x16x32_bf16 v[108:111], v[152:155], v[176:179], v[108:111]
	v_mfma_f32_16x16x32_bf16 v[104:107], v[160:163], v[176:179], v[104:107]
	s_waitcnt lgkmcnt(3)
	v_mfma_f32_16x16x32_bf16 v[92:95], v[152:155], v[184:187], v[92:95]
	v_mfma_f32_16x16x32_bf16 v[88:91], v[160:163], v[184:187], v[88:91]
	s_waitcnt lgkmcnt(1)
	v_mfma_f32_16x16x32_bf16 v[76:79], v[152:155], v[192:195], v[76:79]
	v_mfma_f32_16x16x32_bf16 v[72:75], v[160:163], v[192:195], v[72:75]
	v_mfma_f32_16x16x32_bf16 v[124:127], v[156:159], v[172:175], v[124:127]
	v_mfma_f32_16x16x32_bf16 v[120:123], v[164:167], v[172:175], v[120:123]
	v_mfma_f32_16x16x32_bf16 v[108:111], v[156:159], v[180:183], v[108:111]
	v_mfma_f32_16x16x32_bf16 v[104:107], v[164:167], v[180:183], v[104:107]
	v_mfma_f32_16x16x32_bf16 v[92:95], v[156:159], v[188:191], v[92:95]
	v_mfma_f32_16x16x32_bf16 v[88:91], v[164:167], v[188:191], v[88:91]
	s_waitcnt lgkmcnt(0)
	v_mfma_f32_16x16x32_bf16 v[76:79], v[156:159], v[196:199], v[76:79]
	v_mfma_f32_16x16x32_bf16 v[72:75], v[164:167], v[196:199], v[72:75]
	s_setprio 0
	s_barrier
	s_add_i32 s8, s33, s20
	v_lshl_add_u64 v[144:145], s[12:13], 0, v[132:133]
	s_mov_b32 m0, s8
	ds_read_b128 v[200:203], v151
	ds_read_b128 v[204:207], v151 offset:1024
	ds_read_b128 v[208:211], v151 offset:2048
	ds_read_b128 v[212:215], v151 offset:3072
	global_load_lds_dwordx4 v[144:145], off
	v_lshl_add_u64 v[216:217], s[12:13], 0, v[128:129]
	s_add_i32 m0, s8, 0x2000
	s_nop 0
	global_load_lds_dwordx4 v[216:217], off
	s_barrier
	s_setprio 1
	s_waitcnt lgkmcnt(3)
	v_mfma_f32_16x16x32_bf16 v[116:119], v[200:203], v[168:171], v[116:119]
	s_waitcnt lgkmcnt(1)
	v_mfma_f32_16x16x32_bf16 v[112:115], v[208:211], v[168:171], v[112:115]
	v_mfma_f32_16x16x32_bf16 v[100:103], v[200:203], v[176:179], v[100:103]
	v_mfma_f32_16x16x32_bf16 v[96:99], v[208:211], v[176:179], v[96:99]
	v_mfma_f32_16x16x32_bf16 v[84:87], v[200:203], v[184:187], v[84:87]
	v_mfma_f32_16x16x32_bf16 v[80:83], v[208:211], v[184:187], v[80:83]
	v_mfma_f32_16x16x32_bf16 v[68:71], v[200:203], v[192:195], v[68:71]
	v_mfma_f32_16x16x32_bf16 v[64:67], v[208:211], v[192:195], v[64:67]
	v_mfma_f32_16x16x32_bf16 v[116:119], v[204:207], v[172:175], v[116:119]
	s_waitcnt lgkmcnt(0)
	v_mfma_f32_16x16x32_bf16 v[112:115], v[212:215], v[172:175], v[112:115]
	v_mfma_f32_16x16x32_bf16 v[100:103], v[204:207], v[180:183], v[100:103]
	v_mfma_f32_16x16x32_bf16 v[96:99], v[212:215], v[180:183], v[96:99]
	v_mfma_f32_16x16x32_bf16 v[84:87], v[204:207], v[188:191], v[84:87]
	v_mfma_f32_16x16x32_bf16 v[80:83], v[212:215], v[188:191], v[80:83]
	v_mfma_f32_16x16x32_bf16 v[68:71], v[204:207], v[196:199], v[68:71]
	v_mfma_f32_16x16x32_bf16 v[64:67], v[212:215], v[196:199], v[64:67]
	s_setprio 0
	s_mov_b32 m0, s22
	v_lshl_add_u64 v[218:219], s[14:15], 0, v[134:135]
	s_barrier
	ds_read_b128 v[168:171], v150 offset:16384
	ds_read_b128 v[172:175], v150 offset:17408
	ds_read_b128 v[176:179], v150 offset:18432
	ds_read_b128 v[180:183], v150 offset:19456
	ds_read_b128 v[184:187], v150 offset:20480
	ds_read_b128 v[188:191], v150 offset:21504
	ds_read_b128 v[192:195], v150 offset:22528
	ds_read_b128 v[196:199], v150 offset:23552
	global_load_lds_dwordx4 v[218:219], off
	v_lshl_add_u64 v[220:221], s[14:15], 0, v[130:131]
	s_mov_b32 m0, s23
	s_nop 0
	global_load_lds_dwordx4 v[220:221], off
	s_barrier
	s_setprio 1
	s_waitcnt lgkmcnt(7)
	v_mfma_f32_16x16x32_bf16 v[60:63], v[152:155], v[168:171], v[60:63]
	v_mfma_f32_16x16x32_bf16 v[56:59], v[160:163], v[168:171], v[56:59]
	s_waitcnt lgkmcnt(5)
	v_mfma_f32_16x16x32_bf16 v[44:47], v[152:155], v[176:179], v[44:47]
	v_mfma_f32_16x16x32_bf16 v[40:43], v[160:163], v[176:179], v[40:43]
	s_waitcnt lgkmcnt(3)
	v_mfma_f32_16x16x32_bf16 v[28:31], v[152:155], v[184:187], v[28:31]
	v_mfma_f32_16x16x32_bf16 v[24:27], v[160:163], v[184:187], v[24:27]
	s_waitcnt lgkmcnt(1)
	v_mfma_f32_16x16x32_bf16 v[12:15], v[152:155], v[192:195], v[12:15]
	v_mfma_f32_16x16x32_bf16 v[8:11], v[160:163], v[192:195], v[8:11]
	v_mfma_f32_16x16x32_bf16 v[60:63], v[156:159], v[172:175], v[60:63]
	v_mfma_f32_16x16x32_bf16 v[56:59], v[164:167], v[172:175], v[56:59]
	v_mfma_f32_16x16x32_bf16 v[44:47], v[156:159], v[180:183], v[44:47]
	v_mfma_f32_16x16x32_bf16 v[40:43], v[164:167], v[180:183], v[40:43]
	v_mfma_f32_16x16x32_bf16 v[28:31], v[156:159], v[188:191], v[28:31]
	v_mfma_f32_16x16x32_bf16 v[24:27], v[164:167], v[188:191], v[24:27]
	s_waitcnt lgkmcnt(0)
	v_mfma_f32_16x16x32_bf16 v[12:15], v[156:159], v[196:199], v[12:15]
	v_mfma_f32_16x16x32_bf16 v[8:11], v[164:167], v[196:199], v[8:11]
	s_setprio 0
	s_barrier
; #define PG8_STAGE(bufoff, gbase, voff) do { _Pragma("unroll") for (int _i = 0; _i < 2; ++_i) \
;         __builtin_amdgcn_global_load_lds((const unsigned*)((const char*)(gbase) + (voff)[_i]), (LAS unsigned*)(lds + (bufoff) + ldsw + _i * 8192), 16, 0, 0); } while (0)
; #define PG8_LDA(dst, b, h) do { _Pragma("unroll") for (int m = 0; m < 4; ++m) _Pragma("unroll") for (int k = 0; k < 2; ++k) dst[m][k] = *(const LAS bf16x8*)(lds + PG8_SA(b, h) + aoff + m * 2048 + k * 1024); } while (0)
; #define PG8_LDB(dst, b, h) do { _Pragma("unroll") for (int n = 0; n < 2; ++n) _Pragma("unroll") for (int k = 0; k < 2; ++k) dst[n][k] = *(const LAS bf16x8*)(lds + PG8_SB(b, h) + boff + n * 2048 + k * 1024); } while (0)
; #define PG8_MMA(ai, bj, At, Bt) do { __builtin_amdgcn_s_setprio(1); _Pragma("unroll") for (int m = 0; m < 4; ++m) _Pragma("unroll") for (int n = 0; n < 2; ++n) _Pragma("unroll") for (int k = 0; k < 2; ++k) \
;         acc[ai][bj][m][n] = __builtin_amdgcn_mfma_f32_16x16x32_bf16(Bt[n][k], At[m][k], acc[ai][bj][m][n], 0, 0, 0); __builtin_amdgcn_s_setprio(0); } while (0)
; #define PG8_WAIT_V(n) asm volatile("s_waitcnt vmcnt(" #n ")" ::: "memory")
; #define PG8_WAIT_L(n) asm volatile("s_waitcnt lgkmcnt(" #n ")" ::: "memory")
; #define PG8_BAR __builtin_amdgcn_s_barrier()
; #define PG8_SCHED __builtin_amdgcn_sched_barrier(0)
; template <class Map, class Epi>
; DI void gemm_phase(LAS unsigned char* lds, const Map& MP, const Epi& E, const int nM, const int nN, const int K, const int lda, const int ldb) {
;     ...
;             PG8_STAGE(PG8_SB(0, 1), b2 + hstepB, voffB);
;             PG8_WAIT_V(6); PG8_BAR; PG8_MMA(1, 1, At, B1); PG8_BAR;
;             PG8_LDB(B0, 1, 0); PG8_SCHED; PG8_LDA(At, 1, 0); PG8_STAGE(PG8_SA(0, 1), a2 + hstepA, voffA);
;             PG8_WAIT_L(8); PG8_BAR; PG8_WAIT_L(0); PG8_MMA(0, 0, At, B0); PG8_BAR; PG8_SCHED;
;             PG8_LDB(B1, 1, 1); PG8_STAGE(PG8_SB(1, 0), b3, voffB);
;             PG8_BAR; PG8_WAIT_L(0); PG8_MMA(0, 1, At, B1); PG8_BAR;
	s_add_u32 s8, s12, 0x160000
	s_addc_u32 s9, s13, 0
	s_add_i32 s49, s34, s20
	v_lshl_add_u64 v[152:153], s[8:9], 0, v[132:133]
	s_mov_b32 m0, s49
	s_nop 0
	global_load_lds_dwordx4 v[152:153], off
	v_lshl_add_u64 v[152:153], s[8:9], 0, v[128:129]
	s_add_i32 m0, s49, 0x2000
	s_nop 0
	global_load_lds_dwordx4 v[152:153], off
	s_waitcnt vmcnt(6)
	s_barrier
	s_setprio 1
	v_mfma_f32_16x16x32_bf16 v[52:55], v[200:203], v[168:171], v[52:55]
	v_mfma_f32_16x16x32_bf16 v[48:51], v[208:211], v[168:171], v[48:51]
	v_mfma_f32_16x16x32_bf16 v[36:39], v[200:203], v[176:179], v[36:39]
	v_mfma_f32_16x16x32_bf16 v[32:35], v[208:211], v[176:179], v[32:35]
	v_mfma_f32_16x16x32_bf16 v[20:23], v[200:203], v[184:187], v[20:23]
	v_mfma_f32_16x16x32_bf16 v[16:19], v[208:211], v[184:187], v[16:19]
	v_mfma_f32_16x16x32_bf16 v[4:7], v[200:203], v[192:195], v[4:7]
	v_mfma_f32_16x16x32_bf16 v[0:3], v[208:211], v[192:195], v[0:3]
	v_mfma_f32_16x16x32_bf16 v[52:55], v[204:207], v[172:175], v[52:55]
	v_mfma_f32_16x16x32_bf16 v[48:51], v[212:215], v[172:175], v[48:51]
	v_mfma_f32_16x16x32_bf16 v[36:39], v[204:207], v[180:183], v[36:39]
	v_mfma_f32_16x16x32_bf16 v[32:35], v[212:215], v[180:183], v[32:35]
	v_mfma_f32_16x16x32_bf16 v[20:23], v[204:207], v[188:191], v[20:23]
	v_mfma_f32_16x16x32_bf16 v[16:19], v[212:215], v[188:191], v[16:19]
	v_mfma_f32_16x16x32_bf16 v[4:7], v[204:207], v[196:199], v[4:7]
	v_mfma_f32_16x16x32_bf16 v[0:3], v[212:215], v[196:199], v[0:3]
	s_setprio 0
	s_add_i32 s49, 0, 0x18000
	v_add_u32_e32 v164, s49, v148
	s_barrier
	ds_read_b128 v[152:155], v164
	ds_read_b128 v[156:159], v164 offset:1024
	ds_read_b128 v[160:163], v164 offset:2048
	ds_read_b128 v[164:167], v164 offset:3072
	s_add_u32 s8, s14, 0x160000
	s_addc_u32 s9, s15, 0
	s_mov_b32 m0, s24
	v_lshl_add_u64 v[200:201], s[8:9], 0, v[134:135]
	ds_read_b128 v[168:171], v150 offset:32768
	ds_read_b128 v[172:175], v150 offset:33792
	ds_read_b128 v[176:179], v150 offset:34816
	ds_read_b128 v[180:183], v150 offset:35840
	ds_read_b128 v[184:187], v150 offset:36864
	ds_read_b128 v[188:191], v150 offset:37888
	ds_read_b128 v[192:195], v150 offset:38912
	ds_read_b128 v[196:199], v150 offset:39936
	global_load_lds_dwordx4 v[200:201], off
	v_lshl_add_u64 v[200:201], s[8:9], 0, v[130:131]
	s_mov_b32 m0, s25
	s_nop 0
	global_load_lds_dwordx4 v[200:201], off
	s_waitcnt lgkmcnt(8)
	s_barrier
	s_setprio 1
	s_waitcnt lgkmcnt(7)
	v_mfma_f32_16x16x32_bf16 v[124:127], v[152:155], v[168:171], v[124:127]
	v_mfma_f32_16x16x32_bf16 v[120:123], v[160:163], v[168:171], v[120:123]
	s_waitcnt lgkmcnt(5)
	v_mfma_f32_16x16x32_bf16 v[108:111], v[152:155], v[176:179], v[108:111]
	v_mfma_f32_16x16x32_bf16 v[104:107], v[160:163], v[176:179], v[104:107]
	s_waitcnt lgkmcnt(3)
	v_mfma_f32_16x16x32_bf16 v[92:95], v[152:155], v[184:187], v[92:95]
	v_mfma_f32_16x16x32_bf16 v[88:91], v[160:163], v[184:187], v[88:91]
	s_waitcnt lgkmcnt(1)
	v_mfma_f32_16x16x32_bf16 v[76:79], v[152:155], v[192:195], v[76:79]
	v_mfma_f32_16x16x32_bf16 v[72:75], v[160:163], v[192:195], v[72:75]
	v_mfma_f32_16x16x32_bf16 v[124:127], v[156:159], v[172:175], v[124:127]
	v_mfma_f32_16x16x32_bf16 v[120:123], v[164:167], v[172:175], v[120:123]
	v_mfma_f32_16x16x32_bf16 v[108:111], v[156:159], v[180:183], v[108:111]
	v_mfma_f32_16x16x32_bf16 v[104:107], v[164:167], v[180:183], v[104:107]
	v_mfma_f32_16x16x32_bf16 v[92:95], v[156:159], v[188:191], v[92:95]
	v_mfma_f32_16x16x32_bf16 v[88:91], v[164:167], v[188:191], v[88:91]
	s_waitcnt lgkmcnt(0)
	v_mfma_f32_16x16x32_bf16 v[76:79], v[156:159], v[196:199], v[76:79]
	v_mfma_f32_16x16x32_bf16 v[72:75], v[164:167], v[196:199], v[72:75]
	s_setprio 0
	s_barrier
	s_add_i32 s14, 0, 0x1c000
	s_add_i32 s8, s49, s20
	v_add_u32_e32 v212, s14, v148
	v_lshl_add_u64 v[144:145], v[144:145], 0, s[46:47]
	s_mov_b32 m0, s8
	ds_read_b128 v[200:203], v212
	ds_read_b128 v[204:207], v212 offset:1024
	ds_read_b128 v[208:211], v212 offset:2048
	ds_read_b128 v[212:215], v212 offset:3072
	global_load_lds_dwordx4 v[144:145], off
	v_lshl_add_u64 v[144:145], v[216:217], 0, s[46:47]
	s_add_i32 m0, s8, 0x2000
	s_nop 0
	global_load_lds_dwordx4 v[144:145], off
	s_barrier
	s_setprio 1
	s_waitcnt lgkmcnt(3)
	v_mfma_f32_16x16x32_bf16 v[116:119], v[200:203], v[168:171], v[116:119]
	s_waitcnt lgkmcnt(1)
	v_mfma_f32_16x16x32_bf16 v[112:115], v[208:211], v[168:171], v[112:115]
	v_mfma_f32_16x16x32_bf16 v[100:103], v[200:203], v[176:179], v[100:103]
	v_mfma_f32_16x16x32_bf16 v[96:99], v[208:211], v[176:179], v[96:99]
	v_mfma_f32_16x16x32_bf16 v[84:87], v[200:203], v[184:187], v[84:87]
	v_mfma_f32_16x16x32_bf16 v[80:83], v[208:211], v[184:187], v[80:83]
	v_mfma_f32_16x16x32_bf16 v[68:71], v[200:203], v[192:195], v[68:71]
	v_mfma_f32_16x16x32_bf16 v[64:67], v[208:211], v[192:195], v[64:67]
	v_mfma_f32_16x16x32_bf16 v[116:119], v[204:207], v[172:175], v[116:119]
	s_waitcnt lgkmcnt(0)
	v_mfma_f32_16x16x32_bf16 v[112:115], v[212:215], v[172:175], v[112:115]
	v_mfma_f32_16x16x32_bf16 v[100:103], v[204:207], v[180:183], v[100:103]
	v_mfma_f32_16x16x32_bf16 v[96:99], v[212:215], v[180:183], v[96:99]
	v_mfma_f32_16x16x32_bf16 v[84:87], v[204:207], v[188:191], v[84:87]
	v_mfma_f32_16x16x32_bf16 v[80:83], v[212:215], v[188:191], v[80:83]
	v_mfma_f32_16x16x32_bf16 v[68:71], v[204:207], v[196:199], v[68:71]
	v_mfma_f32_16x16x32_bf16 v[64:67], v[212:215], v[196:199], v[64:67]
	s_setprio 0
	s_mov_b32 m0, s29
	v_lshl_add_u64 v[144:145], v[218:219], 0, s[46:47]
	s_barrier
; DI unsigned pack2(float a, float b) { f32x2 v = {a, b}; hwbf16x2 r = __builtin_convertvector(v, hwbf16x2); return __builtin_bit_cast(unsigned, r); }
; DI float bflo(unsigned w) { return __uint_as_float(w << 16); }
; DI float bfhi(unsigned w) { return __uint_as_float(w & 0xffff0000u); }
; #define PG8_STAGE(bufoff, gbase, voff) do { _Pragma("unroll") for (int _i = 0; _i < 2; ++_i) \
;         __builtin_amdgcn_global_load_lds((const unsigned*)((const char*)(gbase) + (voff)[_i]), (LAS unsigned*)(lds + (bufoff) + ldsw + _i * 8192), 16, 0, 0); } while (0)
; #define PG8_WAIT_V(n) asm volatile("s_waitcnt vmcnt(" #n ")" ::: "memory")
;     DI void operator()(const f32x4 (&acc)[2][2][4][2], const Unit& u, int wr, int wc, int fr, int fq) const {
;     ...
;         for (int ai = 0; ai < 2; ++ai)
; #pragma unroll
;             for (int m = 0; m < 4; ++m) { const size_t ro = (size_t)(row0 + ai * HALF + m * 16) * D + col0;
; #pragma unroll
;                 for (int bj = 0; bj < 2; ++bj) {
;                     f32x4 x0, x1;
;                     if constexpr (IB) { const u32x4 w = *(const u32x4*)((const bf16_t*)Xin + ro + bj * HALF);
;                         x0 = (f32x4){bflo(w[0]), bfhi(w[0]), bflo(w[1]), bfhi(w[1])}; x1 = (f32x4){bflo(w[2]), bfhi(w[2]), bflo(w[3]), bfhi(w[3])}; }
;                     else { x0 = *(const f32x4*)((const float*)Xin + ro + bj * HALF); x1 = *(const f32x4*)((const float*)Xin + ro + bj * HALF + 4); }
;                     x0 += acc[ai][bj][m][0] * sc[bj][0]; x1 += acc[ai][bj][m][1] * sc[bj][1];
;                     if constexpr (OB) { u32x4 o; o[0] = pack2(x0[0], x0[1]); o[1] = pack2(x0[2], x0[3]); o[2] = pack2(x1[0], x1[1]); o[3] = pack2(x1[2], x1[3]);
;                         *(u32x4*)((bf16_t*)Xout + ro + bj * HALF) = o; }
;                     else { *(f32x4*)((float*)Xout + ro + bj * HALF) = x0; *(f32x4*)((float*)Xout + ro + bj * HALF + 4) = x1; } } }
; template <class Map, class Epi>
; DI void gemm_phase(LAS unsigned char* lds, const Map& MP, const Epi& E, const int nM, const int nN, const int K, const int lda, const int ldb) {
;     ...
;             PG8_LDA(At, 1, 1); PG8_STAGE(PG8_SA(1, 0), a3, voffA);
;             PG8_BAR; PG8_WAIT_L(0); PG8_MMA(1, 0, At, B0); PG8_BAR; PG8_SCHED;
;             PG8_STAGE(PG8_SB(1, 1), b3 + hstepB, voffB);
;             PG8_WAIT_V(6); PG8_BAR; PG8_MMA(1, 1, At, B1); PG8_BAR;
	ds_read_b128 v[168:171], v150 offset:49152
	ds_read_b128 v[172:175], v150 offset:50176
	ds_read_b128 v[176:179], v150 offset:51200
	ds_read_b128 v[180:183], v150 offset:52224
	ds_read_b128 v[184:187], v150 offset:53248
	ds_read_b128 v[188:191], v150 offset:54272
	ds_read_b128 v[192:195], v150 offset:55296
	ds_read_b128 v[196:199], v150 offset:56320
	global_load_lds_dwordx4 v[144:145], off
	v_lshl_add_u64 v[144:145], v[220:221], 0, s[46:47]
	s_mov_b32 m0, s30
	s_nop 0
	global_load_lds_dwordx4 v[144:145], off
	s_barrier
	s_setprio 1
	s_waitcnt lgkmcnt(7)
	v_mfma_f32_16x16x32_bf16 v[60:63], v[152:155], v[168:171], v[60:63]
	v_mfma_f32_16x16x32_bf16 v[56:59], v[160:163], v[168:171], v[56:59]
	s_waitcnt lgkmcnt(5)
	v_mfma_f32_16x16x32_bf16 v[44:47], v[152:155], v[176:179], v[44:47]
	v_mfma_f32_16x16x32_bf16 v[40:43], v[160:163], v[176:179], v[40:43]
	s_waitcnt lgkmcnt(3)
	v_mfma_f32_16x16x32_bf16 v[28:31], v[152:155], v[184:187], v[28:31]
	v_mfma_f32_16x16x32_bf16 v[24:27], v[160:163], v[184:187], v[24:27]
	s_waitcnt lgkmcnt(1)
	v_mfma_f32_16x16x32_bf16 v[12:15], v[152:155], v[192:195], v[12:15]
	v_mfma_f32_16x16x32_bf16 v[8:11], v[160:163], v[192:195], v[8:11]
	v_mfma_f32_16x16x32_bf16 v[60:63], v[156:159], v[172:175], v[60:63]
	v_mfma_f32_16x16x32_bf16 v[56:59], v[164:167], v[172:175], v[56:59]
	v_mfma_f32_16x16x32_bf16 v[44:47], v[156:159], v[180:183], v[44:47]
	v_mfma_f32_16x16x32_bf16 v[40:43], v[164:167], v[180:183], v[40:43]
	v_mfma_f32_16x16x32_bf16 v[28:31], v[156:159], v[188:191], v[28:31]
	v_mfma_f32_16x16x32_bf16 v[24:27], v[164:167], v[188:191], v[24:27]
	s_waitcnt lgkmcnt(0)
	v_mfma_f32_16x16x32_bf16 v[12:15], v[156:159], v[196:199], v[12:15]
	v_mfma_f32_16x16x32_bf16 v[8:11], v[164:167], v[196:199], v[8:11]
	s_setprio 0
	s_barrier
	s_add_u32 s8, s12, 0x160080
	s_addc_u32 s9, s13, 0
	s_add_i32 s12, s14, s20
	v_lshl_add_u64 v[144:145], s[8:9], 0, v[132:133]
	s_mov_b32 m0, s12
	s_nop 0
	global_load_lds_dwordx4 v[144:145], off
	v_lshl_add_u64 v[144:145], s[8:9], 0, v[128:129]
	s_add_i32 m0, s12, 0x2000
	s_nop 0
	global_load_lds_dwordx4 v[144:145], off
	s_waitcnt vmcnt(6)
	s_barrier
	s_setprio 1
	v_mfma_f32_16x16x32_bf16 v[52:55], v[200:203], v[168:171], v[52:55]
	v_mfma_f32_16x16x32_bf16 v[48:51], v[208:211], v[168:171], v[48:51]
	v_mfma_f32_16x16x32_bf16 v[36:39], v[200:203], v[176:179], v[36:39]
	v_mfma_f32_16x16x32_bf16 v[32:35], v[208:211], v[176:179], v[32:35]
	v_mfma_f32_16x16x32_bf16 v[20:23], v[200:203], v[184:187], v[20:23]
	v_mfma_f32_16x16x32_bf16 v[16:19], v[208:211], v[184:187], v[16:19]
	v_mfma_f32_16x16x32_bf16 v[4:7], v[200:203], v[192:195], v[4:7]
	v_mfma_f32_16x16x32_bf16 v[0:3], v[208:211], v[192:195], v[0:3]
	v_mfma_f32_16x16x32_bf16 v[52:55], v[204:207], v[172:175], v[52:55]
	v_mfma_f32_16x16x32_bf16 v[48:51], v[212:215], v[172:175], v[48:51]
	v_mfma_f32_16x16x32_bf16 v[36:39], v[204:207], v[180:183], v[36:39]
	v_mfma_f32_16x16x32_bf16 v[32:35], v[212:215], v[180:183], v[32:35]
	v_mfma_f32_16x16x32_bf16 v[20:23], v[204:207], v[188:191], v[20:23]
	v_mfma_f32_16x16x32_bf16 v[16:19], v[212:215], v[188:191], v[16:19]
	v_mfma_f32_16x16x32_bf16 v[4:7], v[204:207], v[196:199], v[4:7]
	v_mfma_f32_16x16x32_bf16 v[0:3], v[212:215], v[196:199], v[0:3]
	s_setprio 0
	s_add_i32 s48, s48, 2
	s_add_u32 s38, s38, 0x100
	s_addc_u32 s39, s39, 0
	s_cmpk_gt_u32 s48, 0x55
	s_mov_b64 s[8:9], s[10:11]
	s_barrier
	s_cbranch_scc0 .LBB1_2653
	v_mov_b32_e32 v144, v147
	v_mov_b32_e32 v152, v146
	s_lshl_b32 s2, s2, 8
	s_lshl_b32 s8, s37, 8
	s_add_i32 s2, s2, s27
	s_or_b32 s8, s8, s28
	v_add_u32_e32 v152, s2, v152
	v_lshl_add_u32 v144, v144, 3, s8
	v_ashrrev_i32_e32 v153, 31, v152
	v_ashrrev_i32_e32 v145, 31, v144
	v_lshlrev_b64 v[152:153], 11, v[152:153]
	v_lshl_add_u64 v[144:145], v[152:153], 0, v[144:145]
	v_lshl_add_u64 v[156:157], v[144:145], 1, s[6:7]
	flat_load_dwordx4 v[152:155], v[156:157]
	s_mov_b64 s[8:9], 0x8000
	s_and_b64 vcc, exec, s[40:41]
	s_mov_b32 s37, s35
	s_mov_b32 s2, s36
	s_mov_b64 s[10:11], s[44:45]
	s_waitcnt vmcnt(0) lgkmcnt(0)
	v_lshlrev_b32_e32 v158, 16, v152
	v_and_b32_e32 v159, 0xffff0000, v152
	v_lshlrev_b32_e32 v152, 16, v153
	v_and_b32_e32 v153, 0xffff0000, v153
	v_lshlrev_b32_e32 v160, 16, v154
	v_and_b32_e32 v161, 0xffff0000, v154
	v_lshlrev_b32_e32 v154, 16, v155
	v_and_b32_e32 v155, 0xffff0000, v155
	v_pk_add_f32 v[126:127], v[126:127], v[152:153]
	v_pk_add_f32 v[124:125], v[124:125], v[158:159]
	v_lshl_add_u64 v[152:153], v[144:145], 2, s[4:5]
	v_pk_add_f32 v[122:123], v[122:123], v[154:155]
	v_pk_add_f32 v[120:121], v[120:121], v[160:161]
	global_store_dwordx4 v[152:153], v[124:127], off
	global_store_dwordx4 v[152:153], v[120:123], off offset:16
	flat_load_dwordx4 v[120:123], v[156:157] offset:256
	s_waitcnt vmcnt(0) lgkmcnt(0)
	v_lshlrev_b32_e32 v124, 16, v120
	v_and_b32_e32 v125, 0xffff0000, v120
	v_lshlrev_b32_e32 v120, 16, v121
	v_and_b32_e32 v121, 0xffff0000, v121
	v_lshlrev_b32_e32 v126, 16, v122
	v_and_b32_e32 v127, 0xffff0000, v122
	v_lshlrev_b32_e32 v122, 16, v123
	v_and_b32_e32 v123, 0xffff0000, v123
	v_pk_add_f32 v[118:119], v[118:119], v[120:121]
	v_pk_add_f32 v[116:117], v[116:117], v[124:125]
	v_pk_add_f32 v[114:115], v[114:115], v[122:123]
	v_pk_add_f32 v[112:113], v[112:113], v[126:127]
	global_store_dwordx4 v[152:153], v[116:119], off offset:512
	global_store_dwordx4 v[152:153], v[112:115], off offset:528
	s_nop 0
	v_lshl_add_u64 v[116:117], v[144:145], 0, s[8:9]
	v_lshl_add_u64 v[118:119], v[116:117], 1, s[6:7]
	flat_load_dwordx4 v[112:115], v[118:119]
	s_mov_b64 s[8:9], 0x10000
	s_waitcnt vmcnt(0) lgkmcnt(0)
; DI unsigned pack2(float a, float b) { f32x2 v = {a, b}; hwbf16x2 r = __builtin_convertvector(v, hwbf16x2); return __builtin_bit_cast(unsigned, r); }
; DI float bflo(unsigned w) { return __uint_as_float(w << 16); }
; DI float bfhi(unsigned w) { return __uint_as_float(w & 0xffff0000u); }
;     DI void operator()(const f32x4 (&acc)[2][2][4][2], const Unit& u, int wr, int wc, int fr, int fq) const {
;     ...
;         for (int ai = 0; ai < 2; ++ai)
; #pragma unroll
;             for (int m = 0; m < 4; ++m) { const size_t ro = (size_t)(row0 + ai * HALF + m * 16) * D + col0;
; #pragma unroll
;                 for (int bj = 0; bj < 2; ++bj) {
;                     f32x4 x0, x1;
;                     if constexpr (IB) { const u32x4 w = *(const u32x4*)((const bf16_t*)Xin + ro + bj * HALF);
;                         x0 = (f32x4){bflo(w[0]), bfhi(w[0]), bflo(w[1]), bfhi(w[1])}; x1 = (f32x4){bflo(w[2]), bfhi(w[2]), bflo(w[3]), bfhi(w[3])}; }
;                     else { x0 = *(const f32x4*)((const float*)Xin + ro + bj * HALF); x1 = *(const f32x4*)((const float*)Xin + ro + bj * HALF + 4); }
;                     x0 += acc[ai][bj][m][0] * sc[bj][0]; x1 += acc[ai][bj][m][1] * sc[bj][1];
;                     if constexpr (OB) { u32x4 o; o[0] = pack2(x0[0], x0[1]); o[1] = pack2(x0[2], x0[3]); o[2] = pack2(x1[0], x1[1]); o[3] = pack2(x1[2], x1[3]);
;                         *(u32x4*)((bf16_t*)Xout + ro + bj * HALF) = o; }
;                     else { *(f32x4*)((float*)Xout + ro + bj * HALF) = x0; *(f32x4*)((float*)Xout + ro + bj * HALF + 4) = x1; } } }
	v_lshlrev_b32_e32 v120, 16, v112
	v_and_b32_e32 v121, 0xffff0000, v112
	v_lshlrev_b32_e32 v112, 16, v113
	v_and_b32_e32 v113, 0xffff0000, v113
	v_lshlrev_b32_e32 v122, 16, v114
	v_and_b32_e32 v123, 0xffff0000, v114
	v_lshlrev_b32_e32 v114, 16, v115
	v_and_b32_e32 v115, 0xffff0000, v115
	v_pk_add_f32 v[110:111], v[110:111], v[112:113]
	v_pk_add_f32 v[108:109], v[108:109], v[120:121]
	v_lshl_add_u64 v[112:113], v[116:117], 2, s[4:5]
	v_pk_add_f32 v[106:107], v[106:107], v[114:115]
	v_pk_add_f32 v[104:105], v[104:105], v[122:123]
	global_store_dwordx4 v[112:113], v[108:111], off
	global_store_dwordx4 v[112:113], v[104:107], off offset:16
	flat_load_dwordx4 v[104:107], v[118:119] offset:256
	s_waitcnt vmcnt(0) lgkmcnt(0)
	v_lshlrev_b32_e32 v108, 16, v104
	v_and_b32_e32 v109, 0xffff0000, v104
	v_lshlrev_b32_e32 v104, 16, v105
	v_and_b32_e32 v105, 0xffff0000, v105
	v_lshlrev_b32_e32 v110, 16, v106
	v_and_b32_e32 v111, 0xffff0000, v106
	v_lshlrev_b32_e32 v106, 16, v107
	v_and_b32_e32 v107, 0xffff0000, v107
	v_pk_add_f32 v[102:103], v[102:103], v[104:105]
	v_pk_add_f32 v[100:101], v[100:101], v[108:109]
	v_pk_add_f32 v[98:99], v[98:99], v[106:107]
	v_pk_add_f32 v[96:97], v[96:97], v[110:111]
	global_store_dwordx4 v[112:113], v[100:103], off offset:512
	global_store_dwordx4 v[112:113], v[96:99], off offset:528
	s_nop 0
	v_lshl_add_u64 v[100:101], v[144:145], 0, s[8:9]
	v_lshl_add_u64 v[102:103], v[100:101], 1, s[6:7]
	flat_load_dwordx4 v[96:99], v[102:103]
	s_mov_b64 s[8:9], 0x18000
	s_waitcnt vmcnt(0) lgkmcnt(0)
	v_lshlrev_b32_e32 v104, 16, v96
	v_and_b32_e32 v105, 0xffff0000, v96
	v_lshlrev_b32_e32 v96, 16, v97
	v_and_b32_e32 v97, 0xffff0000, v97
	v_lshlrev_b32_e32 v106, 16, v98
	v_and_b32_e32 v107, 0xffff0000, v98
	v_lshlrev_b32_e32 v98, 16, v99
	v_and_b32_e32 v99, 0xffff0000, v99
	v_pk_add_f32 v[94:95], v[94:95], v[96:97]
	v_pk_add_f32 v[92:93], v[92:93], v[104:105]
	v_lshl_add_u64 v[96:97], v[100:101], 2, s[4:5]
	v_pk_add_f32 v[90:91], v[90:91], v[98:99]
	v_pk_add_f32 v[88:89], v[88:89], v[106:107]
	global_store_dwordx4 v[96:97], v[92:95], off
	global_store_dwordx4 v[96:97], v[88:91], off offset:16
	flat_load_dwordx4 v[88:91], v[102:103] offset:256
	s_waitcnt vmcnt(0) lgkmcnt(0)
	v_lshlrev_b32_e32 v92, 16, v88
	v_and_b32_e32 v93, 0xffff0000, v88
	v_lshlrev_b32_e32 v88, 16, v89
	v_and_b32_e32 v89, 0xffff0000, v89
	v_lshlrev_b32_e32 v94, 16, v90
	v_and_b32_e32 v95, 0xffff0000, v90
	v_lshlrev_b32_e32 v90, 16, v91
	v_and_b32_e32 v91, 0xffff0000, v91
	v_pk_add_f32 v[86:87], v[86:87], v[88:89]
	v_pk_add_f32 v[84:85], v[84:85], v[92:93]
	v_pk_add_f32 v[82:83], v[82:83], v[90:91]
	v_pk_add_f32 v[80:81], v[80:81], v[94:95]
	global_store_dwordx4 v[96:97], v[84:87], off offset:512
	global_store_dwordx4 v[96:97], v[80:83], off offset:528
	s_nop 0
	v_lshl_add_u64 v[84:85], v[144:145], 0, s[8:9]
	v_lshl_add_u64 v[86:87], v[84:85], 1, s[6:7]
	flat_load_dwordx4 v[80:83], v[86:87]
	s_mov_b64 s[8:9], 0x40000
	s_waitcnt vmcnt(0) lgkmcnt(0)
	v_lshlrev_b32_e32 v88, 16, v80
	v_and_b32_e32 v89, 0xffff0000, v80
	v_lshlrev_b32_e32 v80, 16, v81
	v_and_b32_e32 v81, 0xffff0000, v81
	v_lshlrev_b32_e32 v90, 16, v82
	v_and_b32_e32 v91, 0xffff0000, v82
	v_lshlrev_b32_e32 v82, 16, v83
	v_and_b32_e32 v83, 0xffff0000, v83
	v_pk_add_f32 v[78:79], v[78:79], v[80:81]
	v_pk_add_f32 v[76:77], v[76:77], v[88:89]
	v_lshl_add_u64 v[80:81], v[84:85], 2, s[4:5]
	v_pk_add_f32 v[74:75], v[74:75], v[82:83]
	v_pk_add_f32 v[72:73], v[72:73], v[90:91]
	global_store_dwordx4 v[80:81], v[76:79], off
	global_store_dwordx4 v[80:81], v[72:75], off offset:16
	flat_load_dwordx4 v[72:75], v[86:87] offset:256
	s_waitcnt vmcnt(0) lgkmcnt(0)
	v_lshlrev_b32_e32 v76, 16, v72
	v_and_b32_e32 v77, 0xffff0000, v72
	v_lshlrev_b32_e32 v72, 16, v73
	v_and_b32_e32 v73, 0xffff0000, v73
	v_lshlrev_b32_e32 v78, 16, v74
	v_and_b32_e32 v79, 0xffff0000, v74
	v_lshlrev_b32_e32 v74, 16, v75
	v_and_b32_e32 v75, 0xffff0000, v75
	v_pk_add_f32 v[70:71], v[70:71], v[72:73]
	v_pk_add_f32 v[68:69], v[68:69], v[76:77]
	v_pk_add_f32 v[66:67], v[66:67], v[74:75]
	v_pk_add_f32 v[64:65], v[64:65], v[78:79]
	global_store_dwordx4 v[80:81], v[68:71], off offset:512
	global_store_dwordx4 v[80:81], v[64:67], off offset:528
	s_nop 0
	v_lshl_add_u64 v[68:69], v[144:145], 0, s[8:9]
	v_lshl_add_u64 v[70:71], v[68:69], 1, s[6:7]
	flat_load_dwordx4 v[64:67], v[70:71]
	s_mov_b64 s[8:9], 0x48000
	s_waitcnt vmcnt(0) lgkmcnt(0)
	v_lshlrev_b32_e32 v72, 16, v64
	v_and_b32_e32 v73, 0xffff0000, v64
	v_lshlrev_b32_e32 v64, 16, v65
	v_and_b32_e32 v65, 0xffff0000, v65
	v_lshlrev_b32_e32 v74, 16, v66
	v_and_b32_e32 v75, 0xffff0000, v66
	v_lshlrev_b32_e32 v66, 16, v67
	v_and_b32_e32 v67, 0xffff0000, v67
	v_pk_add_f32 v[62:63], v[62:63], v[64:65]
	v_pk_add_f32 v[60:61], v[60:61], v[72:73]
	v_lshl_add_u64 v[64:65], v[68:69], 2, s[4:5]
	v_pk_add_f32 v[58:59], v[58:59], v[66:67]
	v_pk_add_f32 v[56:57], v[56:57], v[74:75]
	global_store_dwordx4 v[64:65], v[60:63], off
	global_store_dwordx4 v[64:65], v[56:59], off offset:16
	flat_load_dwordx4 v[56:59], v[70:71] offset:256
	s_waitcnt vmcnt(0) lgkmcnt(0)
; DI unsigned pack2(float a, float b) { f32x2 v = {a, b}; hwbf16x2 r = __builtin_convertvector(v, hwbf16x2); return __builtin_bit_cast(unsigned, r); }
; DI float bflo(unsigned w) { return __uint_as_float(w << 16); }
; DI float bfhi(unsigned w) { return __uint_as_float(w & 0xffff0000u); }
;     DI void operator()(const f32x4 (&acc)[2][2][4][2], const Unit& u, int wr, int wc, int fr, int fq) const {
;     ...
;         for (int ai = 0; ai < 2; ++ai)
; #pragma unroll
;             for (int m = 0; m < 4; ++m) { const size_t ro = (size_t)(row0 + ai * HALF + m * 16) * D + col0;
; #pragma unroll
;                 for (int bj = 0; bj < 2; ++bj) {
;                     f32x4 x0, x1;
;                     if constexpr (IB) { const u32x4 w = *(const u32x4*)((const bf16_t*)Xin + ro + bj * HALF);
;                         x0 = (f32x4){bflo(w[0]), bfhi(w[0]), bflo(w[1]), bfhi(w[1])}; x1 = (f32x4){bflo(w[2]), bfhi(w[2]), bflo(w[3]), bfhi(w[3])}; }
;                     else { x0 = *(const f32x4*)((const float*)Xin + ro + bj * HALF); x1 = *(const f32x4*)((const float*)Xin + ro + bj * HALF + 4); }
;                     x0 += acc[ai][bj][m][0] * sc[bj][0]; x1 += acc[ai][bj][m][1] * sc[bj][1];
;                     if constexpr (OB) { u32x4 o; o[0] = pack2(x0[0], x0[1]); o[1] = pack2(x0[2], x0[3]); o[2] = pack2(x1[0], x1[1]); o[3] = pack2(x1[2], x1[3]);
;                         *(u32x4*)((bf16_t*)Xout + ro + bj * HALF) = o; }
;                     else { *(f32x4*)((float*)Xout + ro + bj * HALF) = x0; *(f32x4*)((float*)Xout + ro + bj * HALF + 4) = x1; } } }
	v_lshlrev_b32_e32 v60, 16, v56
	v_and_b32_e32 v61, 0xffff0000, v56
	v_lshlrev_b32_e32 v56, 16, v57
	v_and_b32_e32 v57, 0xffff0000, v57
	v_lshlrev_b32_e32 v62, 16, v58
	v_and_b32_e32 v63, 0xffff0000, v58
	v_lshlrev_b32_e32 v58, 16, v59
	v_and_b32_e32 v59, 0xffff0000, v59
	v_pk_add_f32 v[54:55], v[54:55], v[56:57]
	v_pk_add_f32 v[52:53], v[52:53], v[60:61]
	v_pk_add_f32 v[50:51], v[50:51], v[58:59]
	v_pk_add_f32 v[48:49], v[48:49], v[62:63]
	global_store_dwordx4 v[64:65], v[52:55], off offset:512
	global_store_dwordx4 v[64:65], v[48:51], off offset:528
	s_nop 0
	v_lshl_add_u64 v[52:53], v[144:145], 0, s[8:9]
	v_lshl_add_u64 v[54:55], v[52:53], 1, s[6:7]
	flat_load_dwordx4 v[48:51], v[54:55]
	s_mov_b64 s[8:9], 0x50000
	s_waitcnt vmcnt(0) lgkmcnt(0)
	v_lshlrev_b32_e32 v56, 16, v48
	v_and_b32_e32 v57, 0xffff0000, v48
	v_lshlrev_b32_e32 v48, 16, v49
	v_and_b32_e32 v49, 0xffff0000, v49
	v_lshlrev_b32_e32 v58, 16, v50
	v_and_b32_e32 v59, 0xffff0000, v50
	v_lshlrev_b32_e32 v50, 16, v51
	v_and_b32_e32 v51, 0xffff0000, v51
	v_pk_add_f32 v[46:47], v[46:47], v[48:49]
	v_pk_add_f32 v[44:45], v[44:45], v[56:57]
	v_lshl_add_u64 v[48:49], v[52:53], 2, s[4:5]
	v_pk_add_f32 v[42:43], v[42:43], v[50:51]
	v_pk_add_f32 v[40:41], v[40:41], v[58:59]
	global_store_dwordx4 v[48:49], v[44:47], off
	global_store_dwordx4 v[48:49], v[40:43], off offset:16
	flat_load_dwordx4 v[40:43], v[54:55] offset:256
	s_waitcnt vmcnt(0) lgkmcnt(0)
	v_lshlrev_b32_e32 v44, 16, v40
	v_and_b32_e32 v45, 0xffff0000, v40
	v_lshlrev_b32_e32 v40, 16, v41
	v_and_b32_e32 v41, 0xffff0000, v41
	v_lshlrev_b32_e32 v46, 16, v42
	v_and_b32_e32 v47, 0xffff0000, v42
	v_lshlrev_b32_e32 v42, 16, v43
	v_and_b32_e32 v43, 0xffff0000, v43
	v_pk_add_f32 v[38:39], v[38:39], v[40:41]
	v_pk_add_f32 v[36:37], v[36:37], v[44:45]
	v_pk_add_f32 v[34:35], v[34:35], v[42:43]
	v_pk_add_f32 v[32:33], v[32:33], v[46:47]
	global_store_dwordx4 v[48:49], v[36:39], off offset:512
	global_store_dwordx4 v[48:49], v[32:35], off offset:528
	s_nop 0
	v_lshl_add_u64 v[36:37], v[144:145], 0, s[8:9]
	v_lshl_add_u64 v[38:39], v[36:37], 1, s[6:7]
	flat_load_dwordx4 v[32:35], v[38:39]
	s_mov_b64 s[8:9], 0x58000
	s_waitcnt vmcnt(0) lgkmcnt(0)
	v_lshlrev_b32_e32 v40, 16, v32
	v_and_b32_e32 v41, 0xffff0000, v32
	v_lshlrev_b32_e32 v32, 16, v33
	v_and_b32_e32 v33, 0xffff0000, v33
	v_lshlrev_b32_e32 v42, 16, v34
	v_and_b32_e32 v43, 0xffff0000, v34
	v_lshlrev_b32_e32 v34, 16, v35
	v_and_b32_e32 v35, 0xffff0000, v35
	v_pk_add_f32 v[30:31], v[30:31], v[32:33]
	v_pk_add_f32 v[28:29], v[28:29], v[40:41]
	v_lshl_add_u64 v[32:33], v[36:37], 2, s[4:5]
	v_pk_add_f32 v[26:27], v[26:27], v[34:35]
	v_pk_add_f32 v[24:25], v[24:25], v[42:43]
	global_store_dwordx4 v[32:33], v[28:31], off
	global_store_dwordx4 v[32:33], v[24:27], off offset:16
	flat_load_dwordx4 v[24:27], v[38:39] offset:256
	s_waitcnt vmcnt(0) lgkmcnt(0)
	v_lshlrev_b32_e32 v28, 16, v24
	v_and_b32_e32 v29, 0xffff0000, v24
	v_lshlrev_b32_e32 v24, 16, v25
	v_and_b32_e32 v25, 0xffff0000, v25
	v_lshlrev_b32_e32 v30, 16, v26
	v_and_b32_e32 v31, 0xffff0000, v26
	v_lshlrev_b32_e32 v26, 16, v27
	v_and_b32_e32 v27, 0xffff0000, v27
	v_pk_add_f32 v[22:23], v[22:23], v[24:25]
	v_pk_add_f32 v[20:21], v[20:21], v[28:29]
	v_pk_add_f32 v[18:19], v[18:19], v[26:27]
	v_pk_add_f32 v[16:17], v[16:17], v[30:31]
	global_store_dwordx4 v[32:33], v[20:23], off offset:512
	global_store_dwordx4 v[32:33], v[16:19], off offset:528
	s_nop 0
	v_lshl_add_u64 v[20:21], v[144:145], 0, s[8:9]
	v_lshl_add_u64 v[22:23], v[20:21], 1, s[6:7]
	flat_load_dwordx4 v[16:19], v[22:23]
	s_mov_b64 s[8:9], s[42:43]
	s_waitcnt vmcnt(0) lgkmcnt(0)
	v_lshlrev_b32_e32 v24, 16, v16
	v_and_b32_e32 v25, 0xffff0000, v16
	v_lshlrev_b32_e32 v16, 16, v17
	v_and_b32_e32 v17, 0xffff0000, v17
	v_lshlrev_b32_e32 v26, 16, v18
	v_and_b32_e32 v27, 0xffff0000, v18
	v_lshlrev_b32_e32 v18, 16, v19
	v_and_b32_e32 v19, 0xffff0000, v19
	v_pk_add_f32 v[14:15], v[14:15], v[16:17]
	v_pk_add_f32 v[12:13], v[12:13], v[24:25]
	v_lshl_add_u64 v[16:17], v[20:21], 2, s[4:5]
	v_pk_add_f32 v[10:11], v[10:11], v[18:19]
	v_pk_add_f32 v[8:9], v[8:9], v[26:27]
	global_store_dwordx4 v[16:17], v[12:15], off
	global_store_dwordx4 v[16:17], v[8:11], off offset:16
	flat_load_dwordx4 v[8:11], v[22:23] offset:256
	s_waitcnt vmcnt(0) lgkmcnt(0)
	v_lshlrev_b32_e32 v12, 16, v8
	v_and_b32_e32 v13, 0xffff0000, v8
	v_lshlrev_b32_e32 v8, 16, v9
	v_and_b32_e32 v9, 0xffff0000, v9
	v_lshlrev_b32_e32 v14, 16, v10
	v_and_b32_e32 v15, 0xffff0000, v10
	v_lshlrev_b32_e32 v10, 16, v11
	v_and_b32_e32 v11, 0xffff0000, v11
	v_pk_add_f32 v[6:7], v[6:7], v[8:9]
	v_pk_add_f32 v[4:5], v[4:5], v[12:13]
	v_pk_add_f32 v[2:3], v[2:3], v[10:11]
	v_pk_add_f32 v[0:1], v[0:1], v[14:15]
	global_store_dwordx4 v[16:17], v[4:7], off offset:512
	global_store_dwordx4 v[16:17], v[0:3], off offset:528
	s_cbranch_vccz .LBB1_2646
	s_waitcnt vmcnt(0)
	s_cmpk_gt_u32 s3, 0xff
	s_cbranch_scc1 .LBB1_2657
	s_barrier

; template <bool MEGA>
; __global__ void __launch_bounds__(512) fwd_kernel(Params p, int phase) {
	.text
	.p2alignl 8, 3212836864
	.fill 256, 4, 3212836864
